# static s_setprio 1 for waves 4-7 at entry, all 160 per-block s_setprio flips deleted
# baseline (speedup 1.0000x reference)
; #define LAS __attribute__((address_space(3)))
; __global__ void __launch_bounds__(NTHR, 2) fwd_kernel(Args args) {
;     extern __shared__ __attribute__((aligned(16))) unsigned char lds_raw[];
;     LAS unsigned char* lds = (LAS unsigned char*)lds_raw;
;     const int G0 = gridDim.x, bx0 = blockIdx.x;
;     volatile LAS unsigned* bst = (volatile LAS unsigned*)(lds + 133120);
;     unsigned* barw = (unsigned*)args.ws;
;     if (threadIdx.x < 2) bst[threadIdx.x] = 0u;
;     if (MK_MULTI == 0 && bx0 == 0) for (int i = threadIdx.x; i < XCD_BAR_WORDS; i += NTHR) __hip_atomic_store(barw + i, 0u, __ATOMIC_RELAXED, __HIP_MEMORY_SCOPE_AGENT);
_Z10fwd_kernel4Args:
	s_mov_b32 s100, 0
	v_readfirstlane_b32 s101, v0
	s_nop 3
	s_and_b32 s101, s101, 0x3ff
	s_lshr_b32 s101, s101, 6
	s_cmp_ge_u32 s101, 4
	s_cbranch_scc0 .Lprio_done
	s_setprio 1
.Lprio_done:
	s_load_dword s70, s[0:1], 0x108
	s_add_u32 s6, s0, 0x108
	v_and_b32_e32 v171, 0x3ff, v0
	s_mov_b32 s74, s2
	s_addc_u32 s7, s1, 0
	v_cmp_gt_u32_e32 vcc, 2, v171
	s_and_saveexec_b64 s[2:3], vcc
	v_lshl_add_u32 v1, v171, 2, 0
	v_add_u32_e32 v1, 0x20800, v1
	v_mov_b32_e32 v2, 0
	ds_write_b32 v1, v2
	s_or_b64 exec, exec, s[2:3]
	s_load_dwordx2 s[48:49], s[0:1], 0xf8
	s_cmp_lg_u32 s74, 0
	s_cbranch_scc1 .LBB0_6
	v_lshlrev_b32_e32 v2, 2, v171
	v_mov_b32_e32 v3, 0
	v_add_u32_e32 v1, 0xfffffe00, v171
	s_waitcnt lgkmcnt(0)
	v_lshl_add_u64 v[4:5], s[48:49], 0, v[2:3]
	s_mov_b64 s[2:3], 0
	s_mov_b64 s[4:5], 0x800
	s_movk_i32 s8, 0xb7f

; #define PG8_STAGE(bufoff, gbase, voff) do { _Pragma("unroll") for (int _i = 0; _i < 2; ++_i) \
;         __builtin_amdgcn_global_load_lds((const unsigned*)((const char*)(gbase) + (voff)[_i]), (LAS unsigned*)(lds + (bufoff) + ldsw + _i * 8192), 16, 0, 0); } while (0)
; #define PG8_LDA(dst, b, h) do { _Pragma("unroll") for (int m = 0; m < 4; ++m) _Pragma("unroll") for (int k = 0; k < 2; ++k) dst[m][k] = *(const LAS bf16x8*)(lds + PG8_SA(b, h) + aoff + m * 2048 + k * 1024); } while (0)
; #define PG8_LDB(dst, b, h) do { _Pragma("unroll") for (int n = 0; n < 2; ++n) _Pragma("unroll") for (int k = 0; k < 2; ++k) dst[n][k] = *(const LAS bf16x8*)(lds + PG8_SB(b, h) + boff + n * 2048 + k * 1024); } while (0)
; #define PG8_MMA(ai, bj, At, Bt) do { __builtin_amdgcn_s_setprio(1); _Pragma("unroll") for (int m = 0; m < 4; ++m) _Pragma("unroll") for (int n = 0; n < 2; ++n) _Pragma("unroll") for (int k = 0; k < 2; ++k) \
;         acc[ai][bj][m][n] = __builtin_amdgcn_mfma_f32_16x16x32_bf16(Bt[n][k], At[m][k], acc[ai][bj][m][n], 0, 0, 0); __builtin_amdgcn_s_setprio(0); } while (0)
; #define PG8_WAIT_V(n) asm volatile("s_waitcnt vmcnt(" #n ")" ::: "memory")
; #define PG8_WAIT_L(n) asm volatile("s_waitcnt lgkmcnt(" #n ")" ::: "memory")
; #define PG8_BAR __builtin_amdgcn_s_barrier()
; #define PG8_SCHED __builtin_amdgcn_sched_barrier(0)
; template <class Epi, class Sched>
; __device__ __forceinline__ void gemm_phase(const int tid, LAS unsigned char* lds, const int lda, const int ldb, const int K, const Sched& S, const Epi& E) {
;     ...
;             const bool last = (t == nt - 2);
;             const char* a1 = cA + (size_t)(t + 1) * kstep;
;             const char* a2 = last ? nA : cA + (size_t)(t + 2) * kstep; const char* b2 = last ? nB : cB + (size_t)(t + 2) * kstep;
;             const char* a3 = a2 + kstep; const char* b3 = b2 + kstep;
;             PG8_LDB(B0, 0, 0); PG8_LDB(B1, 0, 1); PG8_SCHED; PG8_LDA(At, 0, 0); PG8_STAGE(PG8_SA(1, 1), a1 + hstepA, voffA);
;             PG8_WAIT_V(8); PG8_WAIT_L(0); PG8_BAR; PG8_MMA(0, 0, At, B0); PG8_MMA(0, 1, At, B1); PG8_BAR; PG8_SCHED;
;             PG8_LDA(At, 0, 1); PG8_STAGE(PG8_SB(0, 0), b2, voffB); PG8_STAGE(PG8_SB(0, 1), b2 + hstepB, voffB); PG8_STAGE(PG8_SA(0, 0), a2, voffA);
.LBB0_53:
	s_add_i32 s24, s58, 2
	s_add_u32 s52, s50, 0x100
	s_addc_u32 s53, s51, 0
	s_add_i32 s14, 0, 0x10000
	s_cmp_eq_u32 s68, s58
	s_cselect_b32 s61, s55, s53
	s_cselect_b32 s60, s54, s52
	v_add_u32_e32 v153, s14, v137
	s_cselect_b32 s59, s57, vcc_hi
	s_cselect_b32 s58, s56, vcc_lo
	s_add_i32 s15, 0, 0x14000
	ds_read_b128 v[142:145], v153
	ds_read_b128 v[154:157], v153 offset:1024
	ds_read_b128 v[158:161], v153 offset:2048
	ds_read_b128 v[162:165], v153 offset:3072
	v_add_u32_e32 v153, s15, v137
	ds_read_b128 v[180:183], v153
	ds_read_b128 v[184:187], v153 offset:1024
	ds_read_b128 v[190:193], v153 offset:2048
	ds_read_b128 v[194:197], v153 offset:3072
	v_lshl_add_u64 v[166:167], s[50:51], 0, v[138:139]
	s_add_i32 m0, s26, 0xc000
	ds_read_b128 v[206:209], v152
	ds_read_b128 v[210:213], v152 offset:1024
	ds_read_b128 v[214:217], v152 offset:2048
	ds_read_b128 v[218:221], v152 offset:3072
	ds_read_b128 v[222:225], v152 offset:4096
	ds_read_b128 v[226:229], v152 offset:5120
	ds_read_b128 v[230:233], v152 offset:6144
	ds_read_b128 v[234:237], v152 offset:7168
	global_load_lds_dwordx4 v[166:167], off
	v_lshl_add_u64 v[166:167], s[50:51], 0, v[140:141]
	s_add_i32 m0, s26, 0xe000
	s_nop 0
	global_load_lds_dwordx4 v[166:167], off
	s_waitcnt vmcnt(8)
	s_waitcnt lgkmcnt(0)
	s_barrier
	v_mfma_f32_16x16x32_bf16 v[124:127], v[142:145], v[206:209], v[124:127]
	v_mfma_f32_16x16x32_bf16 v[120:123], v[158:161], v[206:209], v[120:123]
	v_mfma_f32_16x16x32_bf16 v[108:111], v[142:145], v[214:217], v[108:111]
	v_mfma_f32_16x16x32_bf16 v[104:107], v[158:161], v[214:217], v[104:107]
	v_mfma_f32_16x16x32_bf16 v[92:95], v[142:145], v[222:225], v[92:95]
	v_mfma_f32_16x16x32_bf16 v[88:91], v[158:161], v[222:225], v[88:91]
	v_mfma_f32_16x16x32_bf16 v[76:79], v[142:145], v[230:233], v[76:79]
	v_mfma_f32_16x16x32_bf16 v[72:75], v[158:161], v[230:233], v[72:75]
	v_mfma_f32_16x16x32_bf16 v[124:127], v[154:157], v[210:213], v[124:127]
	v_mfma_f32_16x16x32_bf16 v[120:123], v[162:165], v[210:213], v[120:123]
	v_mfma_f32_16x16x32_bf16 v[108:111], v[154:157], v[218:221], v[108:111]
	v_mfma_f32_16x16x32_bf16 v[104:107], v[162:165], v[218:221], v[104:107]
	v_mfma_f32_16x16x32_bf16 v[92:95], v[154:157], v[226:229], v[92:95]
	v_mfma_f32_16x16x32_bf16 v[88:91], v[162:165], v[226:229], v[88:91]
	v_mfma_f32_16x16x32_bf16 v[76:79], v[154:157], v[234:237], v[76:79]
	v_mfma_f32_16x16x32_bf16 v[72:75], v[162:165], v[234:237], v[72:75]
	v_mfma_f32_16x16x32_bf16 v[116:119], v[180:183], v[206:209], v[116:119]
	v_mfma_f32_16x16x32_bf16 v[112:115], v[190:193], v[206:209], v[112:115]
	v_mfma_f32_16x16x32_bf16 v[100:103], v[180:183], v[214:217], v[100:103]
	v_mfma_f32_16x16x32_bf16 v[96:99], v[190:193], v[214:217], v[96:99]
	v_mfma_f32_16x16x32_bf16 v[84:87], v[180:183], v[222:225], v[84:87]
	v_mfma_f32_16x16x32_bf16 v[80:83], v[190:193], v[222:225], v[80:83]
	v_mfma_f32_16x16x32_bf16 v[68:71], v[180:183], v[230:233], v[68:71]
	v_mfma_f32_16x16x32_bf16 v[64:67], v[190:193], v[230:233], v[64:67]
	v_mfma_f32_16x16x32_bf16 v[116:119], v[184:187], v[210:213], v[116:119]
	v_mfma_f32_16x16x32_bf16 v[112:115], v[194:197], v[210:213], v[112:115]
	v_mfma_f32_16x16x32_bf16 v[100:103], v[184:187], v[218:221], v[100:103]
	v_mfma_f32_16x16x32_bf16 v[96:99], v[194:197], v[218:221], v[96:99]
	v_mfma_f32_16x16x32_bf16 v[84:87], v[184:187], v[226:229], v[84:87]
	v_mfma_f32_16x16x32_bf16 v[80:83], v[194:197], v[226:229], v[80:83]
	v_mfma_f32_16x16x32_bf16 v[68:71], v[184:187], v[234:237], v[68:71]
	v_mfma_f32_16x16x32_bf16 v[64:67], v[194:197], v[234:237], v[64:67]
	s_barrier
	s_add_i32 s14, s14, s31
	v_lshl_add_u64 v[166:167], s[58:59], 0, v[130:131]
	s_mov_b32 m0, s14
	ds_read_b128 v[206:209], v152 offset:16384
	ds_read_b128 v[210:213], v152 offset:17408
	ds_read_b128 v[214:217], v152 offset:18432
	ds_read_b128 v[218:221], v152 offset:19456
	ds_read_b128 v[222:225], v152 offset:20480
	ds_read_b128 v[226:229], v152 offset:21504
	ds_read_b128 v[230:233], v152 offset:22528
	ds_read_b128 v[234:237], v152 offset:23552
	global_load_lds_dwordx4 v[166:167], off
	s_add_i32 m0, s14, 0x2000
	s_add_u32 s50, s58, 0xb0000
	v_lshl_add_u64 v[238:239], s[58:59], 0, v[134:135]
	s_addc_u32 s51, s59, 0
	s_add_i32 s14, s15, s31
	global_load_lds_dwordx4 v[238:239], off
	v_lshl_add_u64 v[240:241], s[50:51], 0, v[130:131]
	s_mov_b32 m0, s14
	v_lshl_add_u64 v[242:243], s[60:61], 0, v[132:133]
	global_load_lds_dwordx4 v[240:241], off
	v_lshl_add_u64 v[240:241], s[50:51], 0, v[134:135]
	s_add_i32 m0, s14, 0x2000
	s_nop 0
	global_load_lds_dwordx4 v[240:241], off
	v_lshl_add_u64 v[240:241], s[60:61], 0, v[128:129]
	s_mov_b32 m0, s26
	s_nop 0
	global_load_lds_dwordx4 v[240:241], off
	s_mov_b32 m0, s27
	s_nop 0
	global_load_lds_dwordx4 v[242:243], off
	s_waitcnt vmcnt(8)
	s_waitcnt lgkmcnt(0)
	s_barrier
; #define PG8_STAGE(bufoff, gbase, voff) do { _Pragma("unroll") for (int _i = 0; _i < 2; ++_i) \
;         __builtin_amdgcn_global_load_lds((const unsigned*)((const char*)(gbase) + (voff)[_i]), (LAS unsigned*)(lds + (bufoff) + ldsw + _i * 8192), 16, 0, 0); } while (0)
; #define PG8_LDA(dst, b, h) do { _Pragma("unroll") for (int m = 0; m < 4; ++m) _Pragma("unroll") for (int k = 0; k < 2; ++k) dst[m][k] = *(const LAS bf16x8*)(lds + PG8_SA(b, h) + aoff + m * 2048 + k * 1024); } while (0)
; #define PG8_LDB(dst, b, h) do { _Pragma("unroll") for (int n = 0; n < 2; ++n) _Pragma("unroll") for (int k = 0; k < 2; ++k) dst[n][k] = *(const LAS bf16x8*)(lds + PG8_SB(b, h) + boff + n * 2048 + k * 1024); } while (0)
; #define PG8_MMA(ai, bj, At, Bt) do { __builtin_amdgcn_s_setprio(1); _Pragma("unroll") for (int m = 0; m < 4; ++m) _Pragma("unroll") for (int n = 0; n < 2; ++n) _Pragma("unroll") for (int k = 0; k < 2; ++k) \
;         acc[ai][bj][m][n] = __builtin_amdgcn_mfma_f32_16x16x32_bf16(Bt[n][k], At[m][k], acc[ai][bj][m][n], 0, 0, 0); __builtin_amdgcn_s_setprio(0); } while (0)
; #define PG8_WAIT_V(n) asm volatile("s_waitcnt vmcnt(" #n ")" ::: "memory")
; #define PG8_WAIT_L(n) asm volatile("s_waitcnt lgkmcnt(" #n ")" ::: "memory")
; #define PG8_BAR __builtin_amdgcn_s_barrier()
; #define PG8_SCHED __builtin_amdgcn_sched_barrier(0)
; template <class Epi, class Sched>
; __device__ __forceinline__ void gemm_phase(const int tid, LAS unsigned char* lds, const int lda, const int ldb, const int K, const Sched& S, const Epi& E) {
;     ...
;             PG8_WAIT_V(8); PG8_WAIT_L(0); PG8_BAR; if (!cur.half) { PG8_MMA(1, 0, At, B0); PG8_MMA(1, 1, At, B1); } PG8_BAR; PG8_SCHED;
;             PG8_LDB(B0, 1, 0); PG8_LDB(B1, 1, 1); PG8_SCHED; PG8_LDA(At, 1, 0); PG8_STAGE(PG8_SA(0, 1), a2 + hstepA, voffA);
;             PG8_WAIT_V(8); PG8_WAIT_L(0); PG8_BAR; PG8_MMA(0, 0, At, B0); PG8_MMA(0, 1, At, B1); PG8_BAR; PG8_SCHED;
	v_mfma_f32_16x16x32_bf16 v[60:63], v[142:145], v[206:209], v[60:63]
	v_mfma_f32_16x16x32_bf16 v[56:59], v[158:161], v[206:209], v[56:59]
	v_mfma_f32_16x16x32_bf16 v[44:47], v[142:145], v[214:217], v[44:47]
	v_mfma_f32_16x16x32_bf16 v[40:43], v[158:161], v[214:217], v[40:43]
	v_mfma_f32_16x16x32_bf16 v[28:31], v[142:145], v[222:225], v[28:31]
	v_mfma_f32_16x16x32_bf16 v[24:27], v[158:161], v[222:225], v[24:27]
	v_mfma_f32_16x16x32_bf16 v[12:15], v[142:145], v[230:233], v[12:15]
	v_mfma_f32_16x16x32_bf16 v[8:11], v[158:161], v[230:233], v[8:11]
	v_mfma_f32_16x16x32_bf16 v[60:63], v[154:157], v[210:213], v[60:63]
	v_mfma_f32_16x16x32_bf16 v[56:59], v[162:165], v[210:213], v[56:59]
	v_mfma_f32_16x16x32_bf16 v[44:47], v[154:157], v[218:221], v[44:47]
	v_mfma_f32_16x16x32_bf16 v[40:43], v[162:165], v[218:221], v[40:43]
	v_mfma_f32_16x16x32_bf16 v[28:31], v[154:157], v[226:229], v[28:31]
	v_mfma_f32_16x16x32_bf16 v[24:27], v[162:165], v[226:229], v[24:27]
	v_mfma_f32_16x16x32_bf16 v[12:15], v[154:157], v[234:237], v[12:15]
	v_mfma_f32_16x16x32_bf16 v[8:11], v[162:165], v[234:237], v[8:11]
	v_mfma_f32_16x16x32_bf16 v[52:55], v[180:183], v[206:209], v[52:55]
	v_mfma_f32_16x16x32_bf16 v[48:51], v[190:193], v[206:209], v[48:51]
	v_mfma_f32_16x16x32_bf16 v[36:39], v[180:183], v[214:217], v[36:39]
	v_mfma_f32_16x16x32_bf16 v[32:35], v[190:193], v[214:217], v[32:35]
	v_mfma_f32_16x16x32_bf16 v[20:23], v[180:183], v[222:225], v[20:23]
	v_mfma_f32_16x16x32_bf16 v[16:19], v[190:193], v[222:225], v[16:19]
	v_mfma_f32_16x16x32_bf16 v[4:7], v[180:183], v[230:233], v[4:7]
	v_mfma_f32_16x16x32_bf16 v[0:3], v[190:193], v[230:233], v[0:3]
	v_mfma_f32_16x16x32_bf16 v[52:55], v[184:187], v[210:213], v[52:55]
	v_mfma_f32_16x16x32_bf16 v[48:51], v[194:197], v[210:213], v[48:51]
	v_mfma_f32_16x16x32_bf16 v[36:39], v[184:187], v[218:221], v[36:39]
	v_mfma_f32_16x16x32_bf16 v[32:35], v[194:197], v[218:221], v[32:35]
	v_mfma_f32_16x16x32_bf16 v[20:23], v[184:187], v[226:229], v[20:23]
	v_mfma_f32_16x16x32_bf16 v[16:19], v[194:197], v[226:229], v[16:19]
	v_mfma_f32_16x16x32_bf16 v[4:7], v[184:187], v[234:237], v[4:7]
	v_mfma_f32_16x16x32_bf16 v[0:3], v[194:197], v[234:237], v[0:3]
	s_barrier
	s_add_i32 s14, 0, 0x18000
	v_add_u32_e32 v153, s14, v137
	s_add_i32 s15, 0, 0x1c000
	ds_read_b128 v[142:145], v153
	ds_read_b128 v[154:157], v153 offset:1024
	ds_read_b128 v[158:161], v153 offset:2048
	ds_read_b128 v[162:165], v153 offset:3072
	v_add_u32_e32 v153, s15, v137
	ds_read_b128 v[180:183], v153
	ds_read_b128 v[184:187], v153 offset:1024
	ds_read_b128 v[190:193], v153 offset:2048
	ds_read_b128 v[194:197], v153 offset:3072
	s_add_u32 s50, s60, 0xb0000
	s_addc_u32 s51, s61, 0
	s_mov_b32 m0, s62
	v_lshl_add_u64 v[244:245], s[50:51], 0, v[128:129]
	ds_read_b128 v[206:209], v152 offset:32768
	ds_read_b128 v[210:213], v152 offset:33792
	ds_read_b128 v[214:217], v152 offset:34816
	ds_read_b128 v[218:221], v152 offset:35840
	ds_read_b128 v[222:225], v152 offset:36864
	ds_read_b128 v[226:229], v152 offset:37888
	ds_read_b128 v[230:233], v152 offset:38912
	ds_read_b128 v[234:237], v152 offset:39936
	global_load_lds_dwordx4 v[244:245], off
	v_lshl_add_u64 v[244:245], s[50:51], 0, v[132:133]
	s_mov_b32 m0, s63
	s_nop 0
	global_load_lds_dwordx4 v[244:245], off
	s_waitcnt vmcnt(8)
	s_waitcnt lgkmcnt(0)
	s_barrier
	v_mfma_f32_16x16x32_bf16 v[124:127], v[142:145], v[206:209], v[124:127]
	v_mfma_f32_16x16x32_bf16 v[120:123], v[158:161], v[206:209], v[120:123]
	v_mfma_f32_16x16x32_bf16 v[108:111], v[142:145], v[214:217], v[108:111]
	v_mfma_f32_16x16x32_bf16 v[104:107], v[158:161], v[214:217], v[104:107]
	v_mfma_f32_16x16x32_bf16 v[92:95], v[142:145], v[222:225], v[92:95]
	v_mfma_f32_16x16x32_bf16 v[88:91], v[158:161], v[222:225], v[88:91]
	v_mfma_f32_16x16x32_bf16 v[76:79], v[142:145], v[230:233], v[76:79]
	v_mfma_f32_16x16x32_bf16 v[72:75], v[158:161], v[230:233], v[72:75]
	v_mfma_f32_16x16x32_bf16 v[124:127], v[154:157], v[210:213], v[124:127]
	v_mfma_f32_16x16x32_bf16 v[120:123], v[162:165], v[210:213], v[120:123]
	v_mfma_f32_16x16x32_bf16 v[108:111], v[154:157], v[218:221], v[108:111]
	v_mfma_f32_16x16x32_bf16 v[104:107], v[162:165], v[218:221], v[104:107]
	v_mfma_f32_16x16x32_bf16 v[92:95], v[154:157], v[226:229], v[92:95]
	v_mfma_f32_16x16x32_bf16 v[88:91], v[162:165], v[226:229], v[88:91]
	v_mfma_f32_16x16x32_bf16 v[76:79], v[154:157], v[234:237], v[76:79]
	v_mfma_f32_16x16x32_bf16 v[72:75], v[162:165], v[234:237], v[72:75]
	v_mfma_f32_16x16x32_bf16 v[116:119], v[180:183], v[206:209], v[116:119]
	v_mfma_f32_16x16x32_bf16 v[112:115], v[190:193], v[206:209], v[112:115]
	v_mfma_f32_16x16x32_bf16 v[100:103], v[180:183], v[214:217], v[100:103]
	v_mfma_f32_16x16x32_bf16 v[96:99], v[190:193], v[214:217], v[96:99]
	v_mfma_f32_16x16x32_bf16 v[84:87], v[180:183], v[222:225], v[84:87]
	v_mfma_f32_16x16x32_bf16 v[80:83], v[190:193], v[222:225], v[80:83]
	v_mfma_f32_16x16x32_bf16 v[68:71], v[180:183], v[230:233], v[68:71]
	v_mfma_f32_16x16x32_bf16 v[64:67], v[190:193], v[230:233], v[64:67]
	v_mfma_f32_16x16x32_bf16 v[116:119], v[184:187], v[210:213], v[116:119]
	v_mfma_f32_16x16x32_bf16 v[112:115], v[194:197], v[210:213], v[112:115]
	v_mfma_f32_16x16x32_bf16 v[100:103], v[184:187], v[218:221], v[100:103]
	v_mfma_f32_16x16x32_bf16 v[96:99], v[194:197], v[218:221], v[96:99]
	v_mfma_f32_16x16x32_bf16 v[84:87], v[184:187], v[226:229], v[84:87]
	v_mfma_f32_16x16x32_bf16 v[80:83], v[194:197], v[226:229], v[80:83]
	v_mfma_f32_16x16x32_bf16 v[68:71], v[184:187], v[234:237], v[68:71]
	v_mfma_f32_16x16x32_bf16 v[64:67], v[194:197], v[234:237], v[64:67]
	s_barrier
; #define PG8_STAGE(bufoff, gbase, voff) do { _Pragma("unroll") for (int _i = 0; _i < 2; ++_i) \
;         __builtin_amdgcn_global_load_lds((const unsigned*)((const char*)(gbase) + (voff)[_i]), (LAS unsigned*)(lds + (bufoff) + ldsw + _i * 8192), 16, 0, 0); } while (0)
; #define PG8_LDA(dst, b, h) do { _Pragma("unroll") for (int m = 0; m < 4; ++m) _Pragma("unroll") for (int k = 0; k < 2; ++k) dst[m][k] = *(const LAS bf16x8*)(lds + PG8_SA(b, h) + aoff + m * 2048 + k * 1024); } while (0)
; #define PG8_MMA(ai, bj, At, Bt) do { __builtin_amdgcn_s_setprio(1); _Pragma("unroll") for (int m = 0; m < 4; ++m) _Pragma("unroll") for (int n = 0; n < 2; ++n) _Pragma("unroll") for (int k = 0; k < 2; ++k) \
;         acc[ai][bj][m][n] = __builtin_amdgcn_mfma_f32_16x16x32_bf16(Bt[n][k], At[m][k], acc[ai][bj][m][n], 0, 0, 0); __builtin_amdgcn_s_setprio(0); } while (0)
; #define PG8_WAIT_V(n) asm volatile("s_waitcnt vmcnt(" #n ")" ::: "memory")
; #define PG8_WAIT_L(n) asm volatile("s_waitcnt lgkmcnt(" #n ")" ::: "memory")
; #define PG8_BAR __builtin_amdgcn_s_barrier()
; #define PG8_SCHED __builtin_amdgcn_sched_barrier(0)
; template <class Epi, class Sched>
; __device__ __forceinline__ void gemm_phase(const int tid, LAS unsigned char* lds, const int lda, const int ldb, const int K, const Sched& S, const Epi& E) {
;     ...
;             PG8_LDA(At, 1, 1); PG8_STAGE(PG8_SB(1, 0), b3, voffB); PG8_STAGE(PG8_SB(1, 1), b3 + hstepB, voffB); PG8_STAGE(PG8_SA(1, 0), a3, voffA);
;             PG8_WAIT_V(8); PG8_WAIT_L(0); PG8_BAR; if (!cur.half) { PG8_MMA(1, 0, At, B0); PG8_MMA(1, 1, At, B1); } PG8_BAR; PG8_SCHED;
;         }
	s_add_i32 s14, s14, s31
	v_lshl_add_u64 v[166:167], v[166:167], 0, s[6:7]
	s_mov_b32 m0, s14
	ds_read_b128 v[206:209], v152 offset:49152
	ds_read_b128 v[210:213], v152 offset:50176
	ds_read_b128 v[214:217], v152 offset:51200
	ds_read_b128 v[218:221], v152 offset:52224
	ds_read_b128 v[222:225], v152 offset:53248
	ds_read_b128 v[226:229], v152 offset:54272
	ds_read_b128 v[230:233], v152 offset:55296
	ds_read_b128 v[234:237], v152 offset:56320
	global_load_lds_dwordx4 v[166:167], off
	s_add_i32 m0, s14, 0x2000
	s_add_u32 s50, s58, 0xb0080
	v_lshl_add_u64 v[166:167], v[238:239], 0, s[6:7]
	s_addc_u32 s51, s59, 0
	s_add_i32 s14, s15, s31
	global_load_lds_dwordx4 v[166:167], off
	v_lshl_add_u64 v[166:167], s[50:51], 0, v[130:131]
	s_mov_b32 m0, s14
	s_nop 0
	global_load_lds_dwordx4 v[166:167], off
	v_lshl_add_u64 v[166:167], s[50:51], 0, v[134:135]
	s_add_i32 m0, s14, 0x2000
	s_nop 0
	global_load_lds_dwordx4 v[166:167], off
	v_lshl_add_u64 v[166:167], v[240:241], 0, s[6:7]
	s_mov_b32 m0, s65
	s_nop 0
	global_load_lds_dwordx4 v[166:167], off
	v_lshl_add_u64 v[166:167], v[242:243], 0, s[6:7]
	s_mov_b32 m0, s66
	s_nop 0
	global_load_lds_dwordx4 v[166:167], off
	s_waitcnt vmcnt(8)
	s_waitcnt lgkmcnt(0)
	s_barrier
	v_mfma_f32_16x16x32_bf16 v[60:63], v[142:145], v[206:209], v[60:63]
	v_mfma_f32_16x16x32_bf16 v[56:59], v[158:161], v[206:209], v[56:59]
	v_mfma_f32_16x16x32_bf16 v[44:47], v[142:145], v[214:217], v[44:47]
	v_mfma_f32_16x16x32_bf16 v[40:43], v[158:161], v[214:217], v[40:43]
	v_mfma_f32_16x16x32_bf16 v[28:31], v[142:145], v[222:225], v[28:31]
	v_mfma_f32_16x16x32_bf16 v[24:27], v[158:161], v[222:225], v[24:27]
	v_mfma_f32_16x16x32_bf16 v[12:15], v[142:145], v[230:233], v[12:15]
	v_mfma_f32_16x16x32_bf16 v[8:11], v[158:161], v[230:233], v[8:11]
	v_mfma_f32_16x16x32_bf16 v[60:63], v[154:157], v[210:213], v[60:63]
	v_mfma_f32_16x16x32_bf16 v[56:59], v[162:165], v[210:213], v[56:59]
	v_mfma_f32_16x16x32_bf16 v[44:47], v[154:157], v[218:221], v[44:47]
	v_mfma_f32_16x16x32_bf16 v[40:43], v[162:165], v[218:221], v[40:43]
	v_mfma_f32_16x16x32_bf16 v[28:31], v[154:157], v[226:229], v[28:31]
	v_mfma_f32_16x16x32_bf16 v[24:27], v[162:165], v[226:229], v[24:27]
	v_mfma_f32_16x16x32_bf16 v[12:15], v[154:157], v[234:237], v[12:15]
	v_mfma_f32_16x16x32_bf16 v[8:11], v[162:165], v[234:237], v[8:11]
	v_mfma_f32_16x16x32_bf16 v[52:55], v[180:183], v[206:209], v[52:55]
	v_mfma_f32_16x16x32_bf16 v[48:51], v[190:193], v[206:209], v[48:51]
	v_mfma_f32_16x16x32_bf16 v[36:39], v[180:183], v[214:217], v[36:39]
	v_mfma_f32_16x16x32_bf16 v[32:35], v[190:193], v[214:217], v[32:35]
	v_mfma_f32_16x16x32_bf16 v[20:23], v[180:183], v[222:225], v[20:23]
	v_mfma_f32_16x16x32_bf16 v[16:19], v[190:193], v[222:225], v[16:19]
	v_mfma_f32_16x16x32_bf16 v[4:7], v[180:183], v[230:233], v[4:7]
	v_mfma_f32_16x16x32_bf16 v[0:3], v[190:193], v[230:233], v[0:3]
	v_mfma_f32_16x16x32_bf16 v[52:55], v[184:187], v[210:213], v[52:55]
	v_mfma_f32_16x16x32_bf16 v[48:51], v[194:197], v[210:213], v[48:51]
	v_mfma_f32_16x16x32_bf16 v[36:39], v[184:187], v[218:221], v[36:39]
	v_mfma_f32_16x16x32_bf16 v[32:35], v[194:197], v[218:221], v[32:35]
	v_mfma_f32_16x16x32_bf16 v[20:23], v[184:187], v[226:229], v[20:23]
	v_mfma_f32_16x16x32_bf16 v[16:19], v[194:197], v[226:229], v[16:19]
	v_mfma_f32_16x16x32_bf16 v[4:7], v[184:187], v[234:237], v[4:7]
	v_mfma_f32_16x16x32_bf16 v[0:3], v[194:197], v[234:237], v[0:3]
	s_barrier
	s_add_u32 vcc_lo, vcc_lo, 0x100
	s_addc_u32 vcc_hi, vcc_hi, 0
	s_cmp_ge_i32 s24, s21
	s_mov_b64 s[50:51], s[52:53]
	s_mov_b32 s58, s24
	s_cbranch_scc0 .LBB0_53
	v_readlane_b32 s60, v254, 56
	v_readlane_b32 s61, v254, 57

; #define PG8_STAGE(bufoff, gbase, voff) do { _Pragma("unroll") for (int _i = 0; _i < 2; ++_i) \
;         __builtin_amdgcn_global_load_lds((const unsigned*)((const char*)(gbase) + (voff)[_i]), (LAS unsigned*)(lds + (bufoff) + ldsw + _i * 8192), 16, 0, 0); } while (0)
; #define PG8_LDA(dst, b, h) do { _Pragma("unroll") for (int m = 0; m < 4; ++m) _Pragma("unroll") for (int k = 0; k < 2; ++k) dst[m][k] = *(const LAS bf16x8*)(lds + PG8_SA(b, h) + aoff + m * 2048 + k * 1024); } while (0)
; #define PG8_LDB(dst, b, h) do { _Pragma("unroll") for (int n = 0; n < 2; ++n) _Pragma("unroll") for (int k = 0; k < 2; ++k) dst[n][k] = *(const LAS bf16x8*)(lds + PG8_SB(b, h) + boff + n * 2048 + k * 1024); } while (0)
; #define PG8_MMA(ai, bj, At, Bt) do { __builtin_amdgcn_s_setprio(1); _Pragma("unroll") for (int m = 0; m < 4; ++m) _Pragma("unroll") for (int n = 0; n < 2; ++n) _Pragma("unroll") for (int k = 0; k < 2; ++k) \
;         acc[ai][bj][m][n] = __builtin_amdgcn_mfma_f32_16x16x32_bf16(Bt[n][k], At[m][k], acc[ai][bj][m][n], 0, 0, 0); __builtin_amdgcn_s_setprio(0); } while (0)
; #define PG8_WAIT_V(n) asm volatile("s_waitcnt vmcnt(" #n ")" ::: "memory")
; #define PG8_WAIT_L(n) asm volatile("s_waitcnt lgkmcnt(" #n ")" ::: "memory")
; #define PG8_BAR __builtin_amdgcn_s_barrier()
; #define PG8_SCHED __builtin_amdgcn_sched_barrier(0)
; template <class Epi, class Sched>
; __device__ __forceinline__ void gemm_phase(const int tid, LAS unsigned char* lds, const int lda, const int ldb, const int K, const Sched& S, const Epi& E) {
;     ...
;             const bool last = (t == nt - 2);
;             const char* a1 = cA + (size_t)(t + 1) * kstep;
;             const char* a2 = last ? nA : cA + (size_t)(t + 2) * kstep; const char* b2 = last ? nB : cB + (size_t)(t + 2) * kstep;
;             const char* a3 = a2 + kstep; const char* b3 = b2 + kstep;
;             PG8_LDB(B0, 0, 0); PG8_LDB(B1, 0, 1); PG8_SCHED; PG8_LDA(At, 0, 0); PG8_STAGE(PG8_SA(1, 1), a1 + hstepA, voffA);
;             PG8_WAIT_V(8); PG8_WAIT_L(0); PG8_BAR; PG8_MMA(0, 0, At, B0); PG8_MMA(0, 1, At, B1); PG8_BAR; PG8_SCHED;
;             PG8_LDA(At, 0, 1); PG8_STAGE(PG8_SB(0, 0), b2, voffB); PG8_STAGE(PG8_SB(0, 1), b2 + hstepB, voffB); PG8_STAGE(PG8_SA(0, 0), a2, voffA);
.LBB0_122:
	s_add_i32 vcc_lo, s24, 2
	s_add_u32 s14, s2, 0xfffc0080
	s_addc_u32 s15, s3, -1
	s_add_i32 s22, 0, 0x10000
	s_cmp_eq_u32 s68, s24
	s_cselect_b32 s57, s53, s15
	s_cselect_b32 s56, s52, s14
	v_add_u32_e32 v153, s22, v137
	s_cselect_b32 s51, s55, s75
	s_cselect_b32 s50, s54, s45
	s_add_i32 s14, 0, 0x14000
	ds_read_b128 v[142:145], v153
	ds_read_b128 v[154:157], v153 offset:1024
	ds_read_b128 v[158:161], v153 offset:2048
	ds_read_b128 v[162:165], v153 offset:3072
	v_add_u32_e32 v153, s14, v137
	ds_read_b128 v[180:183], v153
	ds_read_b128 v[184:187], v153 offset:1024
	ds_read_b128 v[190:193], v153 offset:2048
	ds_read_b128 v[194:197], v153 offset:3072
	v_lshl_add_u64 v[166:167], s[2:3], 0, v[138:139]
	s_add_i32 m0, s26, 0xc000
	ds_read_b128 v[206:209], v152
	ds_read_b128 v[210:213], v152 offset:1024
	ds_read_b128 v[214:217], v152 offset:2048
	ds_read_b128 v[218:221], v152 offset:3072
	ds_read_b128 v[222:225], v152 offset:4096
	ds_read_b128 v[226:229], v152 offset:5120
	ds_read_b128 v[230:233], v152 offset:6144
	ds_read_b128 v[234:237], v152 offset:7168
	global_load_lds_dwordx4 v[166:167], off
	v_lshl_add_u64 v[166:167], s[2:3], 0, v[140:141]
	s_add_i32 m0, s26, 0xe000
	s_nop 0
	global_load_lds_dwordx4 v[166:167], off
	s_waitcnt vmcnt(8)
	s_waitcnt lgkmcnt(0)
	s_barrier
	v_mfma_f32_16x16x32_bf16 v[124:127], v[142:145], v[206:209], v[124:127]
	v_mfma_f32_16x16x32_bf16 v[120:123], v[158:161], v[206:209], v[120:123]
	v_mfma_f32_16x16x32_bf16 v[108:111], v[142:145], v[214:217], v[108:111]
	v_mfma_f32_16x16x32_bf16 v[104:107], v[158:161], v[214:217], v[104:107]
	v_mfma_f32_16x16x32_bf16 v[92:95], v[142:145], v[222:225], v[92:95]
	v_mfma_f32_16x16x32_bf16 v[88:91], v[158:161], v[222:225], v[88:91]
	v_mfma_f32_16x16x32_bf16 v[76:79], v[142:145], v[230:233], v[76:79]
	v_mfma_f32_16x16x32_bf16 v[72:75], v[158:161], v[230:233], v[72:75]
	v_mfma_f32_16x16x32_bf16 v[124:127], v[154:157], v[210:213], v[124:127]
	v_mfma_f32_16x16x32_bf16 v[120:123], v[162:165], v[210:213], v[120:123]
	v_mfma_f32_16x16x32_bf16 v[108:111], v[154:157], v[218:221], v[108:111]
	v_mfma_f32_16x16x32_bf16 v[104:107], v[162:165], v[218:221], v[104:107]
	v_mfma_f32_16x16x32_bf16 v[92:95], v[154:157], v[226:229], v[92:95]
	v_mfma_f32_16x16x32_bf16 v[88:91], v[162:165], v[226:229], v[88:91]
	v_mfma_f32_16x16x32_bf16 v[76:79], v[154:157], v[234:237], v[76:79]
	v_mfma_f32_16x16x32_bf16 v[72:75], v[162:165], v[234:237], v[72:75]
	v_mfma_f32_16x16x32_bf16 v[116:119], v[180:183], v[206:209], v[116:119]
	v_mfma_f32_16x16x32_bf16 v[112:115], v[190:193], v[206:209], v[112:115]
	v_mfma_f32_16x16x32_bf16 v[100:103], v[180:183], v[214:217], v[100:103]
	v_mfma_f32_16x16x32_bf16 v[96:99], v[190:193], v[214:217], v[96:99]
	v_mfma_f32_16x16x32_bf16 v[84:87], v[180:183], v[222:225], v[84:87]
	v_mfma_f32_16x16x32_bf16 v[80:83], v[190:193], v[222:225], v[80:83]
	v_mfma_f32_16x16x32_bf16 v[68:71], v[180:183], v[230:233], v[68:71]
	v_mfma_f32_16x16x32_bf16 v[64:67], v[190:193], v[230:233], v[64:67]
	v_mfma_f32_16x16x32_bf16 v[116:119], v[184:187], v[210:213], v[116:119]
	v_mfma_f32_16x16x32_bf16 v[112:115], v[194:197], v[210:213], v[112:115]
	v_mfma_f32_16x16x32_bf16 v[100:103], v[184:187], v[218:221], v[100:103]
	v_mfma_f32_16x16x32_bf16 v[96:99], v[194:197], v[218:221], v[96:99]
	v_mfma_f32_16x16x32_bf16 v[84:87], v[184:187], v[226:229], v[84:87]
	v_mfma_f32_16x16x32_bf16 v[80:83], v[194:197], v[226:229], v[80:83]
	v_mfma_f32_16x16x32_bf16 v[68:71], v[184:187], v[234:237], v[68:71]
	v_mfma_f32_16x16x32_bf16 v[64:67], v[194:197], v[234:237], v[64:67]
	s_barrier
	s_add_i32 s15, s22, s61
	v_lshl_add_u64 v[166:167], s[50:51], 0, v[130:131]
	s_mov_b32 m0, s15
	ds_read_b128 v[206:209], v152 offset:16384
	ds_read_b128 v[210:213], v152 offset:17408
	ds_read_b128 v[214:217], v152 offset:18432
	ds_read_b128 v[218:221], v152 offset:19456
	ds_read_b128 v[222:225], v152 offset:20480
	ds_read_b128 v[226:229], v152 offset:21504
	ds_read_b128 v[230:233], v152 offset:22528
	ds_read_b128 v[234:237], v152 offset:23552
	global_load_lds_dwordx4 v[166:167], off
	s_add_i32 m0, s15, 0x2000
	s_add_u32 s22, s50, 0x40000
	v_lshl_add_u64 v[176:177], s[50:51], 0, v[134:135]
	s_addc_u32 s23, s51, 0
	s_add_i32 s14, s14, s61
	global_load_lds_dwordx4 v[176:177], off
	v_lshl_add_u64 v[238:239], s[22:23], 0, v[130:131]
	s_mov_b32 m0, s14
	v_lshl_add_u64 v[240:241], s[56:57], 0, v[132:133]
	global_load_lds_dwordx4 v[238:239], off
	v_lshl_add_u64 v[238:239], s[22:23], 0, v[134:135]
	s_add_i32 m0, s14, 0x2000
	s_nop 0
	global_load_lds_dwordx4 v[238:239], off
	v_lshl_add_u64 v[238:239], s[56:57], 0, v[128:129]
	s_mov_b32 m0, s26
	s_nop 0
	global_load_lds_dwordx4 v[238:239], off
	s_mov_b32 m0, s27
	s_nop 0
	global_load_lds_dwordx4 v[240:241], off
	s_waitcnt vmcnt(8)
	s_waitcnt lgkmcnt(0)
	s_barrier
; #define PG8_STAGE(bufoff, gbase, voff) do { _Pragma("unroll") for (int _i = 0; _i < 2; ++_i) \
;         __builtin_amdgcn_global_load_lds((const unsigned*)((const char*)(gbase) + (voff)[_i]), (LAS unsigned*)(lds + (bufoff) + ldsw + _i * 8192), 16, 0, 0); } while (0)
; #define PG8_LDA(dst, b, h) do { _Pragma("unroll") for (int m = 0; m < 4; ++m) _Pragma("unroll") for (int k = 0; k < 2; ++k) dst[m][k] = *(const LAS bf16x8*)(lds + PG8_SA(b, h) + aoff + m * 2048 + k * 1024); } while (0)
; #define PG8_LDB(dst, b, h) do { _Pragma("unroll") for (int n = 0; n < 2; ++n) _Pragma("unroll") for (int k = 0; k < 2; ++k) dst[n][k] = *(const LAS bf16x8*)(lds + PG8_SB(b, h) + boff + n * 2048 + k * 1024); } while (0)
; #define PG8_MMA(ai, bj, At, Bt) do { __builtin_amdgcn_s_setprio(1); _Pragma("unroll") for (int m = 0; m < 4; ++m) _Pragma("unroll") for (int n = 0; n < 2; ++n) _Pragma("unroll") for (int k = 0; k < 2; ++k) \
;         acc[ai][bj][m][n] = __builtin_amdgcn_mfma_f32_16x16x32_bf16(Bt[n][k], At[m][k], acc[ai][bj][m][n], 0, 0, 0); __builtin_amdgcn_s_setprio(0); } while (0)
; #define PG8_WAIT_V(n) asm volatile("s_waitcnt vmcnt(" #n ")" ::: "memory")
; #define PG8_WAIT_L(n) asm volatile("s_waitcnt lgkmcnt(" #n ")" ::: "memory")
; #define PG8_BAR __builtin_amdgcn_s_barrier()
; #define PG8_SCHED __builtin_amdgcn_sched_barrier(0)
; template <class Epi, class Sched>
; __device__ __forceinline__ void gemm_phase(const int tid, LAS unsigned char* lds, const int lda, const int ldb, const int K, const Sched& S, const Epi& E) {
;     ...
;             PG8_WAIT_V(8); PG8_WAIT_L(0); PG8_BAR; if (!cur.half) { PG8_MMA(1, 0, At, B0); PG8_MMA(1, 1, At, B1); } PG8_BAR; PG8_SCHED;
;             PG8_LDB(B0, 1, 0); PG8_LDB(B1, 1, 1); PG8_SCHED; PG8_LDA(At, 1, 0); PG8_STAGE(PG8_SA(0, 1), a2 + hstepA, voffA);
;             PG8_WAIT_V(8); PG8_WAIT_L(0); PG8_BAR; PG8_MMA(0, 0, At, B0); PG8_MMA(0, 1, At, B1); PG8_BAR; PG8_SCHED;
	v_mfma_f32_16x16x32_bf16 v[60:63], v[142:145], v[206:209], v[60:63]
	v_mfma_f32_16x16x32_bf16 v[56:59], v[158:161], v[206:209], v[56:59]
	v_mfma_f32_16x16x32_bf16 v[44:47], v[142:145], v[214:217], v[44:47]
	v_mfma_f32_16x16x32_bf16 v[40:43], v[158:161], v[214:217], v[40:43]
	v_mfma_f32_16x16x32_bf16 v[28:31], v[142:145], v[222:225], v[28:31]
	v_mfma_f32_16x16x32_bf16 v[24:27], v[158:161], v[222:225], v[24:27]
	v_mfma_f32_16x16x32_bf16 v[12:15], v[142:145], v[230:233], v[12:15]
	v_mfma_f32_16x16x32_bf16 v[8:11], v[158:161], v[230:233], v[8:11]
	v_mfma_f32_16x16x32_bf16 v[60:63], v[154:157], v[210:213], v[60:63]
	v_mfma_f32_16x16x32_bf16 v[56:59], v[162:165], v[210:213], v[56:59]
	v_mfma_f32_16x16x32_bf16 v[44:47], v[154:157], v[218:221], v[44:47]
	v_mfma_f32_16x16x32_bf16 v[40:43], v[162:165], v[218:221], v[40:43]
	v_mfma_f32_16x16x32_bf16 v[28:31], v[154:157], v[226:229], v[28:31]
	v_mfma_f32_16x16x32_bf16 v[24:27], v[162:165], v[226:229], v[24:27]
	v_mfma_f32_16x16x32_bf16 v[12:15], v[154:157], v[234:237], v[12:15]
	v_mfma_f32_16x16x32_bf16 v[8:11], v[162:165], v[234:237], v[8:11]
	v_mfma_f32_16x16x32_bf16 v[52:55], v[180:183], v[206:209], v[52:55]
	v_mfma_f32_16x16x32_bf16 v[48:51], v[190:193], v[206:209], v[48:51]
	v_mfma_f32_16x16x32_bf16 v[36:39], v[180:183], v[214:217], v[36:39]
	v_mfma_f32_16x16x32_bf16 v[32:35], v[190:193], v[214:217], v[32:35]
	v_mfma_f32_16x16x32_bf16 v[20:23], v[180:183], v[222:225], v[20:23]
	v_mfma_f32_16x16x32_bf16 v[16:19], v[190:193], v[222:225], v[16:19]
	v_mfma_f32_16x16x32_bf16 v[4:7], v[180:183], v[230:233], v[4:7]
	v_mfma_f32_16x16x32_bf16 v[0:3], v[190:193], v[230:233], v[0:3]
	v_mfma_f32_16x16x32_bf16 v[52:55], v[184:187], v[210:213], v[52:55]
	v_mfma_f32_16x16x32_bf16 v[48:51], v[194:197], v[210:213], v[48:51]
	v_mfma_f32_16x16x32_bf16 v[36:39], v[184:187], v[218:221], v[36:39]
	v_mfma_f32_16x16x32_bf16 v[32:35], v[194:197], v[218:221], v[32:35]
	v_mfma_f32_16x16x32_bf16 v[20:23], v[184:187], v[226:229], v[20:23]
	v_mfma_f32_16x16x32_bf16 v[16:19], v[194:197], v[226:229], v[16:19]
	v_mfma_f32_16x16x32_bf16 v[4:7], v[184:187], v[234:237], v[4:7]
	v_mfma_f32_16x16x32_bf16 v[0:3], v[194:197], v[234:237], v[0:3]
	s_barrier
	s_add_i32 s14, 0, 0x18000
	v_add_u32_e32 v153, s14, v137
	s_add_i32 s15, 0, 0x1c000
	ds_read_b128 v[142:145], v153
	ds_read_b128 v[154:157], v153 offset:1024
	ds_read_b128 v[158:161], v153 offset:2048
	ds_read_b128 v[162:165], v153 offset:3072
	v_add_u32_e32 v153, s15, v137
	ds_read_b128 v[180:183], v153
	ds_read_b128 v[184:187], v153 offset:1024
	ds_read_b128 v[190:193], v153 offset:2048
	ds_read_b128 v[194:197], v153 offset:3072
	s_add_u32 s22, s56, 0x40000
	s_addc_u32 s23, s57, 0
	s_mov_b32 m0, s62
	v_lshl_add_u64 v[242:243], s[22:23], 0, v[128:129]
	ds_read_b128 v[206:209], v152 offset:32768
	ds_read_b128 v[210:213], v152 offset:33792
	ds_read_b128 v[214:217], v152 offset:34816
	ds_read_b128 v[218:221], v152 offset:35840
	ds_read_b128 v[222:225], v152 offset:36864
	ds_read_b128 v[226:229], v152 offset:37888
	ds_read_b128 v[230:233], v152 offset:38912
	ds_read_b128 v[234:237], v152 offset:39936
	global_load_lds_dwordx4 v[242:243], off
	v_lshl_add_u64 v[242:243], s[22:23], 0, v[132:133]
	s_mov_b32 m0, s63
	s_nop 0
	global_load_lds_dwordx4 v[242:243], off
	s_waitcnt vmcnt(8)
	s_waitcnt lgkmcnt(0)
	s_barrier
	v_mfma_f32_16x16x32_bf16 v[124:127], v[142:145], v[206:209], v[124:127]
	v_mfma_f32_16x16x32_bf16 v[120:123], v[158:161], v[206:209], v[120:123]
	v_mfma_f32_16x16x32_bf16 v[108:111], v[142:145], v[214:217], v[108:111]
	v_mfma_f32_16x16x32_bf16 v[104:107], v[158:161], v[214:217], v[104:107]
	v_mfma_f32_16x16x32_bf16 v[92:95], v[142:145], v[222:225], v[92:95]
	v_mfma_f32_16x16x32_bf16 v[88:91], v[158:161], v[222:225], v[88:91]
	v_mfma_f32_16x16x32_bf16 v[76:79], v[142:145], v[230:233], v[76:79]
	v_mfma_f32_16x16x32_bf16 v[72:75], v[158:161], v[230:233], v[72:75]
	v_mfma_f32_16x16x32_bf16 v[124:127], v[154:157], v[210:213], v[124:127]
	v_mfma_f32_16x16x32_bf16 v[120:123], v[162:165], v[210:213], v[120:123]
	v_mfma_f32_16x16x32_bf16 v[108:111], v[154:157], v[218:221], v[108:111]
	v_mfma_f32_16x16x32_bf16 v[104:107], v[162:165], v[218:221], v[104:107]
	v_mfma_f32_16x16x32_bf16 v[92:95], v[154:157], v[226:229], v[92:95]
	v_mfma_f32_16x16x32_bf16 v[88:91], v[162:165], v[226:229], v[88:91]
	v_mfma_f32_16x16x32_bf16 v[76:79], v[154:157], v[234:237], v[76:79]
	v_mfma_f32_16x16x32_bf16 v[72:75], v[162:165], v[234:237], v[72:75]
	v_mfma_f32_16x16x32_bf16 v[116:119], v[180:183], v[206:209], v[116:119]
	v_mfma_f32_16x16x32_bf16 v[112:115], v[190:193], v[206:209], v[112:115]
	v_mfma_f32_16x16x32_bf16 v[100:103], v[180:183], v[214:217], v[100:103]
	v_mfma_f32_16x16x32_bf16 v[96:99], v[190:193], v[214:217], v[96:99]
	v_mfma_f32_16x16x32_bf16 v[84:87], v[180:183], v[222:225], v[84:87]
	v_mfma_f32_16x16x32_bf16 v[80:83], v[190:193], v[222:225], v[80:83]
	v_mfma_f32_16x16x32_bf16 v[68:71], v[180:183], v[230:233], v[68:71]
	v_mfma_f32_16x16x32_bf16 v[64:67], v[190:193], v[230:233], v[64:67]
	v_mfma_f32_16x16x32_bf16 v[116:119], v[184:187], v[210:213], v[116:119]
	v_mfma_f32_16x16x32_bf16 v[112:115], v[194:197], v[210:213], v[112:115]
	v_mfma_f32_16x16x32_bf16 v[100:103], v[184:187], v[218:221], v[100:103]
	v_mfma_f32_16x16x32_bf16 v[96:99], v[194:197], v[218:221], v[96:99]
	v_mfma_f32_16x16x32_bf16 v[84:87], v[184:187], v[226:229], v[84:87]
	v_mfma_f32_16x16x32_bf16 v[80:83], v[194:197], v[226:229], v[80:83]
	v_mfma_f32_16x16x32_bf16 v[68:71], v[184:187], v[234:237], v[68:71]
	v_mfma_f32_16x16x32_bf16 v[64:67], v[194:197], v[234:237], v[64:67]
	s_barrier
; #define PG8_STAGE(bufoff, gbase, voff) do { _Pragma("unroll") for (int _i = 0; _i < 2; ++_i) \
;         __builtin_amdgcn_global_load_lds((const unsigned*)((const char*)(gbase) + (voff)[_i]), (LAS unsigned*)(lds + (bufoff) + ldsw + _i * 8192), 16, 0, 0); } while (0)
; #define PG8_LDA(dst, b, h) do { _Pragma("unroll") for (int m = 0; m < 4; ++m) _Pragma("unroll") for (int k = 0; k < 2; ++k) dst[m][k] = *(const LAS bf16x8*)(lds + PG8_SA(b, h) + aoff + m * 2048 + k * 1024); } while (0)
; #define PG8_MMA(ai, bj, At, Bt) do { __builtin_amdgcn_s_setprio(1); _Pragma("unroll") for (int m = 0; m < 4; ++m) _Pragma("unroll") for (int n = 0; n < 2; ++n) _Pragma("unroll") for (int k = 0; k < 2; ++k) \
;         acc[ai][bj][m][n] = __builtin_amdgcn_mfma_f32_16x16x32_bf16(Bt[n][k], At[m][k], acc[ai][bj][m][n], 0, 0, 0); __builtin_amdgcn_s_setprio(0); } while (0)
; #define PG8_WAIT_V(n) asm volatile("s_waitcnt vmcnt(" #n ")" ::: "memory")
; #define PG8_WAIT_L(n) asm volatile("s_waitcnt lgkmcnt(" #n ")" ::: "memory")
; #define PG8_BAR __builtin_amdgcn_s_barrier()
; #define PG8_SCHED __builtin_amdgcn_sched_barrier(0)
; template <class Epi, class Sched>
; __device__ __forceinline__ void gemm_phase(const int tid, LAS unsigned char* lds, const int lda, const int ldb, const int K, const Sched& S, const Epi& E) {
;     ...
;             PG8_LDA(At, 1, 1); PG8_STAGE(PG8_SB(1, 0), b3, voffB); PG8_STAGE(PG8_SB(1, 1), b3 + hstepB, voffB); PG8_STAGE(PG8_SA(1, 0), a3, voffA);
;             PG8_WAIT_V(8); PG8_WAIT_L(0); PG8_BAR; if (!cur.half) { PG8_MMA(1, 0, At, B0); PG8_MMA(1, 1, At, B1); } PG8_BAR; PG8_SCHED;
;         }
	s_add_i32 s14, s14, s61
	v_lshl_add_u64 v[166:167], v[166:167], 0, s[6:7]
	s_mov_b32 m0, s14
	ds_read_b128 v[206:209], v152 offset:49152
	ds_read_b128 v[210:213], v152 offset:50176
	ds_read_b128 v[214:217], v152 offset:51200
	ds_read_b128 v[218:221], v152 offset:52224
	ds_read_b128 v[222:225], v152 offset:53248
	ds_read_b128 v[226:229], v152 offset:54272
	ds_read_b128 v[230:233], v152 offset:55296
	ds_read_b128 v[234:237], v152 offset:56320
	global_load_lds_dwordx4 v[166:167], off
	s_add_i32 m0, s14, 0x2000
	s_add_u32 s22, s50, 0x40080
	v_lshl_add_u64 v[166:167], v[176:177], 0, s[6:7]
	s_addc_u32 s23, s51, 0
	s_add_i32 s14, s15, s61
	global_load_lds_dwordx4 v[166:167], off
	v_lshl_add_u64 v[166:167], s[22:23], 0, v[130:131]
	s_mov_b32 m0, s14
	s_nop 0
	global_load_lds_dwordx4 v[166:167], off
	v_lshl_add_u64 v[166:167], s[22:23], 0, v[134:135]
	s_add_i32 m0, s14, 0x2000
	s_nop 0
	global_load_lds_dwordx4 v[166:167], off
	v_lshl_add_u64 v[166:167], v[238:239], 0, s[6:7]
	s_mov_b32 m0, s65
	s_nop 0
	global_load_lds_dwordx4 v[166:167], off
	v_lshl_add_u64 v[166:167], v[240:241], 0, s[6:7]
	s_mov_b32 m0, s66
	s_nop 0
	global_load_lds_dwordx4 v[166:167], off
	s_waitcnt vmcnt(8)
	s_waitcnt lgkmcnt(0)
	s_barrier
	v_mfma_f32_16x16x32_bf16 v[60:63], v[142:145], v[206:209], v[60:63]
	v_mfma_f32_16x16x32_bf16 v[56:59], v[158:161], v[206:209], v[56:59]
	v_mfma_f32_16x16x32_bf16 v[44:47], v[142:145], v[214:217], v[44:47]
	v_mfma_f32_16x16x32_bf16 v[40:43], v[158:161], v[214:217], v[40:43]
	v_mfma_f32_16x16x32_bf16 v[28:31], v[142:145], v[222:225], v[28:31]
	v_mfma_f32_16x16x32_bf16 v[24:27], v[158:161], v[222:225], v[24:27]
	v_mfma_f32_16x16x32_bf16 v[12:15], v[142:145], v[230:233], v[12:15]
	v_mfma_f32_16x16x32_bf16 v[8:11], v[158:161], v[230:233], v[8:11]
	v_mfma_f32_16x16x32_bf16 v[60:63], v[154:157], v[210:213], v[60:63]
	v_mfma_f32_16x16x32_bf16 v[56:59], v[162:165], v[210:213], v[56:59]
	v_mfma_f32_16x16x32_bf16 v[44:47], v[154:157], v[218:221], v[44:47]
	v_mfma_f32_16x16x32_bf16 v[40:43], v[162:165], v[218:221], v[40:43]
	v_mfma_f32_16x16x32_bf16 v[28:31], v[154:157], v[226:229], v[28:31]
	v_mfma_f32_16x16x32_bf16 v[24:27], v[162:165], v[226:229], v[24:27]
	v_mfma_f32_16x16x32_bf16 v[12:15], v[154:157], v[234:237], v[12:15]
	v_mfma_f32_16x16x32_bf16 v[8:11], v[162:165], v[234:237], v[8:11]
	v_mfma_f32_16x16x32_bf16 v[52:55], v[180:183], v[206:209], v[52:55]
	v_mfma_f32_16x16x32_bf16 v[48:51], v[190:193], v[206:209], v[48:51]
	v_mfma_f32_16x16x32_bf16 v[36:39], v[180:183], v[214:217], v[36:39]
	v_mfma_f32_16x16x32_bf16 v[32:35], v[190:193], v[214:217], v[32:35]
	v_mfma_f32_16x16x32_bf16 v[20:23], v[180:183], v[222:225], v[20:23]
	v_mfma_f32_16x16x32_bf16 v[16:19], v[190:193], v[222:225], v[16:19]
	v_mfma_f32_16x16x32_bf16 v[4:7], v[180:183], v[230:233], v[4:7]
	v_mfma_f32_16x16x32_bf16 v[0:3], v[190:193], v[230:233], v[0:3]
	v_mfma_f32_16x16x32_bf16 v[52:55], v[184:187], v[210:213], v[52:55]
	v_mfma_f32_16x16x32_bf16 v[48:51], v[194:197], v[210:213], v[48:51]
	v_mfma_f32_16x16x32_bf16 v[36:39], v[184:187], v[218:221], v[36:39]
	v_mfma_f32_16x16x32_bf16 v[32:35], v[194:197], v[218:221], v[32:35]
	v_mfma_f32_16x16x32_bf16 v[20:23], v[184:187], v[226:229], v[20:23]
	v_mfma_f32_16x16x32_bf16 v[16:19], v[194:197], v[226:229], v[16:19]
	v_mfma_f32_16x16x32_bf16 v[4:7], v[184:187], v[234:237], v[4:7]
	v_mfma_f32_16x16x32_bf16 v[0:3], v[194:197], v[234:237], v[0:3]
	s_barrier
	s_add_u32 s2, s2, 0x100
	s_addc_u32 s3, s3, 0
	s_add_u32 s45, s45, 0x100
	s_addc_u32 s75, s75, 0
	s_cmp_ge_i32 vcc_lo, s59
	s_mov_b32 s24, vcc_lo
	s_cbranch_scc0 .LBB0_122
	v_readlane_b32 s75, v254, 55

; #define PG8_STAGE(bufoff, gbase, voff) do { _Pragma("unroll") for (int _i = 0; _i < 2; ++_i) \
;         __builtin_amdgcn_global_load_lds((const unsigned*)((const char*)(gbase) + (voff)[_i]), (LAS unsigned*)(lds + (bufoff) + ldsw + _i * 8192), 16, 0, 0); } while (0)
; #define PG8_LDA(dst, b, h) do { _Pragma("unroll") for (int m = 0; m < 4; ++m) _Pragma("unroll") for (int k = 0; k < 2; ++k) dst[m][k] = *(const LAS bf16x8*)(lds + PG8_SA(b, h) + aoff + m * 2048 + k * 1024); } while (0)
; #define PG8_LDB(dst, b, h) do { _Pragma("unroll") for (int n = 0; n < 2; ++n) _Pragma("unroll") for (int k = 0; k < 2; ++k) dst[n][k] = *(const LAS bf16x8*)(lds + PG8_SB(b, h) + boff + n * 2048 + k * 1024); } while (0)
; #define PG8_MMA(ai, bj, At, Bt) do { __builtin_amdgcn_s_setprio(1); _Pragma("unroll") for (int m = 0; m < 4; ++m) _Pragma("unroll") for (int n = 0; n < 2; ++n) _Pragma("unroll") for (int k = 0; k < 2; ++k) \
;         acc[ai][bj][m][n] = __builtin_amdgcn_mfma_f32_16x16x32_bf16(Bt[n][k], At[m][k], acc[ai][bj][m][n], 0, 0, 0); __builtin_amdgcn_s_setprio(0); } while (0)
; #define PG8_WAIT_V(n) asm volatile("s_waitcnt vmcnt(" #n ")" ::: "memory")
; #define PG8_WAIT_L(n) asm volatile("s_waitcnt lgkmcnt(" #n ")" ::: "memory")
; #define PG8_BAR __builtin_amdgcn_s_barrier()
; template <class Epi, class Sched>
; __device__ __forceinline__ void gemm_phase(const int tid, LAS unsigned char* lds, const int lda, const int ldb, const int K, const Sched& S, const Epi& E) {
;     ...
;         for (int t = 0; t < nt; t += 2) {
;             const bool last = (t == nt - 2);
;             const char* a1 = cA + (size_t)(t + 1) * kstep;
;             const char* a2 = last ? nA : cA + (size_t)(t + 2) * kstep; const char* b2 = last ? nB : cB + (size_t)(t + 2) * kstep;
;             const char* a3 = a2 + kstep; const char* b3 = b2 + kstep;
;             PG8_LDB(B0, 0, 0); PG8_LDB(B1, 0, 1); PG8_SCHED; PG8_LDA(At, 0, 0); PG8_STAGE(PG8_SA(1, 1), a1 + hstepA, voffA);
;             PG8_WAIT_V(8); PG8_WAIT_L(0); PG8_BAR; PG8_MMA(0, 0, At, B0); PG8_MMA(0, 1, At, B1); PG8_BAR; PG8_SCHED;
;             PG8_LDA(At, 0, 1); PG8_STAGE(PG8_SB(0, 0), b2, voffB); PG8_STAGE(PG8_SB(0, 1), b2 + hstepB, voffB); PG8_STAGE(PG8_SA(0, 0), a2, voffA);
;             PG8_WAIT_V(8); PG8_WAIT_L(0); PG8_BAR; if (!cur.half) { PG8_MMA(1, 0, At, B0); PG8_MMA(1, 1, At, B1); } PG8_BAR; PG8_SCHED;
.LBB0_195:
	s_andn2_b64 vcc, exec, s[42:43]
	s_cbranch_vccnz .LBB0_203
	s_add_u32 s38, s38, 0x40080
	s_addc_u32 s39, s39, 0
	s_add_u32 s47, s52, 0x100
	s_addc_u32 s67, s53, 0
	s_mov_b32 s52, 0
	s_add_i32 s68, s52, 2
	s_add_u32 s14, s38, 0xfffc0080
	s_addc_u32 s15, s39, -1
	s_add_i32 s24, 0, 0x10000
	s_cmp_eq_u32 s64, s52
	s_cselect_b32 s55, s3, s15
	s_cselect_b32 s54, s2, s14
	v_add_u32_e32 v155, s24, v146
	s_cselect_b32 s53, s23, s67
	s_cselect_b32 s52, s22, s47
	s_add_i32 s14, 0, 0x14000
	ds_read_b128 v[156:159], v155
	ds_read_b128 v[160:163], v155 offset:1024
	ds_read_b128 v[164:167], v155 offset:2048
	ds_read_b128 v[180:183], v155 offset:3072
	v_add_u32_e32 v155, s14, v146
	ds_read_b128 v[184:187], v155
	ds_read_b128 v[190:193], v155 offset:1024
	ds_read_b128 v[194:197], v155 offset:2048
	ds_read_b128 v[206:209], v155 offset:3072
	v_lshl_add_u64 v[242:243], s[38:39], 0, v[136:137]
	s_add_i32 m0, s57, 0xc000
	ds_read_b128 v[210:213], v154
	ds_read_b128 v[214:217], v154 offset:1024
	ds_read_b128 v[218:221], v154 offset:2048
	ds_read_b128 v[222:225], v154 offset:3072
	ds_read_b128 v[226:229], v154 offset:4096
	ds_read_b128 v[230:233], v154 offset:5120
	ds_read_b128 v[234:237], v154 offset:6144
	ds_read_b128 v[238:241], v154 offset:7168
	global_load_lds_dwordx4 v[242:243], off
	v_lshl_add_u64 v[242:243], s[38:39], 0, v[138:139]
	s_add_i32 m0, s57, 0xe000
	s_nop 0
	global_load_lds_dwordx4 v[242:243], off
	s_waitcnt vmcnt(8)
	s_waitcnt lgkmcnt(0)
	s_barrier
	v_mfma_f32_16x16x32_bf16 v[124:127], v[156:159], v[210:213], 0
	v_mfma_f32_16x16x32_bf16 v[120:123], v[164:167], v[210:213], 0
	v_mfma_f32_16x16x32_bf16 v[108:111], v[156:159], v[218:221], 0
	v_mfma_f32_16x16x32_bf16 v[104:107], v[164:167], v[218:221], 0
	v_mfma_f32_16x16x32_bf16 v[92:95], v[156:159], v[226:229], 0
	v_mfma_f32_16x16x32_bf16 v[88:91], v[164:167], v[226:229], 0
	v_mfma_f32_16x16x32_bf16 v[76:79], v[156:159], v[234:237], 0
	v_mfma_f32_16x16x32_bf16 v[72:75], v[164:167], v[234:237], 0
	v_mfma_f32_16x16x32_bf16 v[124:127], v[160:163], v[214:217], v[124:127]
	v_mfma_f32_16x16x32_bf16 v[120:123], v[180:183], v[214:217], v[120:123]
	v_mfma_f32_16x16x32_bf16 v[108:111], v[160:163], v[222:225], v[108:111]
	v_mfma_f32_16x16x32_bf16 v[104:107], v[180:183], v[222:225], v[104:107]
	v_mfma_f32_16x16x32_bf16 v[92:95], v[160:163], v[230:233], v[92:95]
	v_mfma_f32_16x16x32_bf16 v[88:91], v[180:183], v[230:233], v[88:91]
	v_mfma_f32_16x16x32_bf16 v[76:79], v[160:163], v[238:241], v[76:79]
	v_mfma_f32_16x16x32_bf16 v[72:75], v[180:183], v[238:241], v[72:75]
	v_mfma_f32_16x16x32_bf16 v[116:119], v[184:187], v[210:213], 0
	v_mfma_f32_16x16x32_bf16 v[112:115], v[194:197], v[210:213], 0
	v_mfma_f32_16x16x32_bf16 v[100:103], v[184:187], v[218:221], 0
	v_mfma_f32_16x16x32_bf16 v[96:99], v[194:197], v[218:221], 0
	v_mfma_f32_16x16x32_bf16 v[84:87], v[184:187], v[226:229], 0
	v_mfma_f32_16x16x32_bf16 v[80:83], v[194:197], v[226:229], 0
	v_mfma_f32_16x16x32_bf16 v[68:71], v[184:187], v[234:237], 0
	v_mfma_f32_16x16x32_bf16 v[64:67], v[194:197], v[234:237], 0
	v_mfma_f32_16x16x32_bf16 v[116:119], v[190:193], v[214:217], v[116:119]
	v_mfma_f32_16x16x32_bf16 v[112:115], v[206:209], v[214:217], v[112:115]
	v_mfma_f32_16x16x32_bf16 v[100:103], v[190:193], v[222:225], v[100:103]
	v_mfma_f32_16x16x32_bf16 v[96:99], v[206:209], v[222:225], v[96:99]
	v_mfma_f32_16x16x32_bf16 v[84:87], v[190:193], v[230:233], v[84:87]
	v_mfma_f32_16x16x32_bf16 v[80:83], v[206:209], v[230:233], v[80:83]
	v_mfma_f32_16x16x32_bf16 v[68:71], v[190:193], v[238:241], v[68:71]
	v_mfma_f32_16x16x32_bf16 v[64:67], v[206:209], v[238:241], v[64:67]
	s_barrier
	s_add_i32 s15, s24, s56
	v_lshl_add_u64 v[242:243], s[52:53], 0, v[130:131]
	s_mov_b32 m0, s15
	ds_read_b128 v[210:213], v154 offset:16384
	ds_read_b128 v[214:217], v154 offset:17408
	ds_read_b128 v[218:221], v154 offset:18432
	ds_read_b128 v[222:225], v154 offset:19456
	ds_read_b128 v[226:229], v154 offset:20480
	ds_read_b128 v[230:233], v154 offset:21504
	ds_read_b128 v[234:237], v154 offset:22528
	ds_read_b128 v[238:241], v154 offset:23552
	global_load_lds_dwordx4 v[242:243], off
	s_add_i32 m0, s15, 0x2000
	s_add_u32 s70, s52, 0x40000
	v_lshl_add_u64 v[244:245], s[52:53], 0, v[134:135]
	s_addc_u32 s71, s53, 0
	s_add_i32 s14, s14, s56
	global_load_lds_dwordx4 v[244:245], off
	v_lshl_add_u64 v[246:247], s[70:71], 0, v[130:131]
	s_mov_b32 m0, s14
	v_lshl_add_u64 v[248:249], s[54:55], 0, v[132:133]
	global_load_lds_dwordx4 v[246:247], off
	v_lshl_add_u64 v[246:247], s[70:71], 0, v[134:135]
	s_add_i32 m0, s14, 0x2000
	s_nop 0
	global_load_lds_dwordx4 v[246:247], off
	v_lshl_add_u64 v[246:247], s[54:55], 0, v[128:129]
	s_mov_b32 m0, s57
	s_nop 0
	global_load_lds_dwordx4 v[246:247], off
	s_mov_b32 m0, s58
	s_nop 0
	global_load_lds_dwordx4 v[248:249], off
	s_waitcnt vmcnt(8)
	s_waitcnt lgkmcnt(0)
	s_barrier
; #define PG8_STAGE(bufoff, gbase, voff) do { _Pragma("unroll") for (int _i = 0; _i < 2; ++_i) \
;         __builtin_amdgcn_global_load_lds((const unsigned*)((const char*)(gbase) + (voff)[_i]), (LAS unsigned*)(lds + (bufoff) + ldsw + _i * 8192), 16, 0, 0); } while (0)
; #define PG8_LDA(dst, b, h) do { _Pragma("unroll") for (int m = 0; m < 4; ++m) _Pragma("unroll") for (int k = 0; k < 2; ++k) dst[m][k] = *(const LAS bf16x8*)(lds + PG8_SA(b, h) + aoff + m * 2048 + k * 1024); } while (0)
; #define PG8_LDB(dst, b, h) do { _Pragma("unroll") for (int n = 0; n < 2; ++n) _Pragma("unroll") for (int k = 0; k < 2; ++k) dst[n][k] = *(const LAS bf16x8*)(lds + PG8_SB(b, h) + boff + n * 2048 + k * 1024); } while (0)
; #define PG8_MMA(ai, bj, At, Bt) do { __builtin_amdgcn_s_setprio(1); _Pragma("unroll") for (int m = 0; m < 4; ++m) _Pragma("unroll") for (int n = 0; n < 2; ++n) _Pragma("unroll") for (int k = 0; k < 2; ++k) \
;         acc[ai][bj][m][n] = __builtin_amdgcn_mfma_f32_16x16x32_bf16(Bt[n][k], At[m][k], acc[ai][bj][m][n], 0, 0, 0); __builtin_amdgcn_s_setprio(0); } while (0)
; #define PG8_WAIT_V(n) asm volatile("s_waitcnt vmcnt(" #n ")" ::: "memory")
; #define PG8_WAIT_L(n) asm volatile("s_waitcnt lgkmcnt(" #n ")" ::: "memory")
; #define PG8_BAR __builtin_amdgcn_s_barrier()
; #define PG8_SCHED __builtin_amdgcn_sched_barrier(0)
; template <class Epi, class Sched>
; __device__ __forceinline__ void gemm_phase(const int tid, LAS unsigned char* lds, const int lda, const int ldb, const int K, const Sched& S, const Epi& E) {
;     ...
;             PG8_WAIT_V(8); PG8_WAIT_L(0); PG8_BAR; if (!cur.half) { PG8_MMA(1, 0, At, B0); PG8_MMA(1, 1, At, B1); } PG8_BAR; PG8_SCHED;
;             PG8_LDB(B0, 1, 0); PG8_LDB(B1, 1, 1); PG8_SCHED; PG8_LDA(At, 1, 0); PG8_STAGE(PG8_SA(0, 1), a2 + hstepA, voffA);
;             PG8_WAIT_V(8); PG8_WAIT_L(0); PG8_BAR; PG8_MMA(0, 0, At, B0); PG8_MMA(0, 1, At, B1); PG8_BAR; PG8_SCHED;
	v_mfma_f32_16x16x32_bf16 v[60:63], v[156:159], v[210:213], 0
	v_mfma_f32_16x16x32_bf16 v[56:59], v[164:167], v[210:213], 0
	v_mfma_f32_16x16x32_bf16 v[44:47], v[156:159], v[218:221], 0
	v_mfma_f32_16x16x32_bf16 v[40:43], v[164:167], v[218:221], 0
	v_mfma_f32_16x16x32_bf16 v[28:31], v[156:159], v[226:229], 0
	v_mfma_f32_16x16x32_bf16 v[24:27], v[164:167], v[226:229], 0
	v_mfma_f32_16x16x32_bf16 v[12:15], v[156:159], v[234:237], 0
	v_mfma_f32_16x16x32_bf16 v[8:11], v[164:167], v[234:237], 0
	v_mfma_f32_16x16x32_bf16 v[60:63], v[160:163], v[214:217], v[60:63]
	v_mfma_f32_16x16x32_bf16 v[56:59], v[180:183], v[214:217], v[56:59]
	v_mfma_f32_16x16x32_bf16 v[44:47], v[160:163], v[222:225], v[44:47]
	v_mfma_f32_16x16x32_bf16 v[40:43], v[180:183], v[222:225], v[40:43]
	v_mfma_f32_16x16x32_bf16 v[28:31], v[160:163], v[230:233], v[28:31]
	v_mfma_f32_16x16x32_bf16 v[24:27], v[180:183], v[230:233], v[24:27]
	v_mfma_f32_16x16x32_bf16 v[12:15], v[160:163], v[238:241], v[12:15]
	v_mfma_f32_16x16x32_bf16 v[8:11], v[180:183], v[238:241], v[8:11]
	v_mfma_f32_16x16x32_bf16 v[52:55], v[184:187], v[210:213], 0
	v_mfma_f32_16x16x32_bf16 v[48:51], v[194:197], v[210:213], 0
	v_mfma_f32_16x16x32_bf16 v[36:39], v[184:187], v[218:221], 0
	v_mfma_f32_16x16x32_bf16 v[32:35], v[194:197], v[218:221], 0
	v_mfma_f32_16x16x32_bf16 v[20:23], v[184:187], v[226:229], 0
	v_mfma_f32_16x16x32_bf16 v[16:19], v[194:197], v[226:229], 0
	v_mfma_f32_16x16x32_bf16 v[4:7], v[184:187], v[234:237], 0
	v_mfma_f32_16x16x32_bf16 v[0:3], v[194:197], v[234:237], 0
	v_mfma_f32_16x16x32_bf16 v[52:55], v[190:193], v[214:217], v[52:55]
	v_mfma_f32_16x16x32_bf16 v[48:51], v[206:209], v[214:217], v[48:51]
	v_mfma_f32_16x16x32_bf16 v[36:39], v[190:193], v[222:225], v[36:39]
	v_mfma_f32_16x16x32_bf16 v[32:35], v[206:209], v[222:225], v[32:35]
	v_mfma_f32_16x16x32_bf16 v[20:23], v[190:193], v[230:233], v[20:23]
	v_mfma_f32_16x16x32_bf16 v[16:19], v[206:209], v[230:233], v[16:19]
	v_mfma_f32_16x16x32_bf16 v[4:7], v[190:193], v[238:241], v[4:7]
	v_mfma_f32_16x16x32_bf16 v[0:3], v[206:209], v[238:241], v[0:3]
	s_barrier
	s_add_i32 s14, 0, 0x18000
	v_add_u32_e32 v155, s14, v146
	s_add_i32 s15, 0, 0x1c000
	ds_read_b128 v[156:159], v155
	ds_read_b128 v[160:163], v155 offset:1024
	ds_read_b128 v[164:167], v155 offset:2048
	ds_read_b128 v[180:183], v155 offset:3072
	v_add_u32_e32 v155, s15, v146
	ds_read_b128 v[184:187], v155
	ds_read_b128 v[190:193], v155 offset:1024
	ds_read_b128 v[194:197], v155 offset:2048
	ds_read_b128 v[206:209], v155 offset:3072
	s_add_u32 s54, s54, 0x40000
	s_addc_u32 s55, s55, 0
	s_mov_b32 m0, s59
	v_lshl_add_u64 v[250:251], s[54:55], 0, v[128:129]
	ds_read_b128 v[210:213], v154 offset:32768
	ds_read_b128 v[214:217], v154 offset:33792
	ds_read_b128 v[218:221], v154 offset:34816
	ds_read_b128 v[222:225], v154 offset:35840
	ds_read_b128 v[226:229], v154 offset:36864
	ds_read_b128 v[230:233], v154 offset:37888
	ds_read_b128 v[234:237], v154 offset:38912
	ds_read_b128 v[238:241], v154 offset:39936
	global_load_lds_dwordx4 v[250:251], off
	v_lshl_add_u64 v[250:251], s[54:55], 0, v[132:133]
	s_mov_b32 m0, s60
	s_nop 0
	global_load_lds_dwordx4 v[250:251], off
	s_waitcnt vmcnt(8)
	s_waitcnt lgkmcnt(0)
	s_barrier
	v_mfma_f32_16x16x32_bf16 v[124:127], v[156:159], v[210:213], v[124:127]
	v_mfma_f32_16x16x32_bf16 v[120:123], v[164:167], v[210:213], v[120:123]
	v_mfma_f32_16x16x32_bf16 v[108:111], v[156:159], v[218:221], v[108:111]
	v_mfma_f32_16x16x32_bf16 v[104:107], v[164:167], v[218:221], v[104:107]
	v_mfma_f32_16x16x32_bf16 v[92:95], v[156:159], v[226:229], v[92:95]
	v_mfma_f32_16x16x32_bf16 v[88:91], v[164:167], v[226:229], v[88:91]
	v_mfma_f32_16x16x32_bf16 v[76:79], v[156:159], v[234:237], v[76:79]
	v_mfma_f32_16x16x32_bf16 v[72:75], v[164:167], v[234:237], v[72:75]
	v_mfma_f32_16x16x32_bf16 v[124:127], v[160:163], v[214:217], v[124:127]
	v_mfma_f32_16x16x32_bf16 v[120:123], v[180:183], v[214:217], v[120:123]
	v_mfma_f32_16x16x32_bf16 v[108:111], v[160:163], v[222:225], v[108:111]
	v_mfma_f32_16x16x32_bf16 v[104:107], v[180:183], v[222:225], v[104:107]
	v_mfma_f32_16x16x32_bf16 v[92:95], v[160:163], v[230:233], v[92:95]
	v_mfma_f32_16x16x32_bf16 v[88:91], v[180:183], v[230:233], v[88:91]
	v_mfma_f32_16x16x32_bf16 v[76:79], v[160:163], v[238:241], v[76:79]
	v_mfma_f32_16x16x32_bf16 v[72:75], v[180:183], v[238:241], v[72:75]
	v_mfma_f32_16x16x32_bf16 v[116:119], v[184:187], v[210:213], v[116:119]
	v_mfma_f32_16x16x32_bf16 v[112:115], v[194:197], v[210:213], v[112:115]
	v_mfma_f32_16x16x32_bf16 v[100:103], v[184:187], v[218:221], v[100:103]
	v_mfma_f32_16x16x32_bf16 v[96:99], v[194:197], v[218:221], v[96:99]
	v_mfma_f32_16x16x32_bf16 v[84:87], v[184:187], v[226:229], v[84:87]
	v_mfma_f32_16x16x32_bf16 v[80:83], v[194:197], v[226:229], v[80:83]
	v_mfma_f32_16x16x32_bf16 v[68:71], v[184:187], v[234:237], v[68:71]
	v_mfma_f32_16x16x32_bf16 v[64:67], v[194:197], v[234:237], v[64:67]
	v_mfma_f32_16x16x32_bf16 v[116:119], v[190:193], v[214:217], v[116:119]
	v_mfma_f32_16x16x32_bf16 v[112:115], v[206:209], v[214:217], v[112:115]
	v_mfma_f32_16x16x32_bf16 v[100:103], v[190:193], v[222:225], v[100:103]
	v_mfma_f32_16x16x32_bf16 v[96:99], v[206:209], v[222:225], v[96:99]
	v_mfma_f32_16x16x32_bf16 v[84:87], v[190:193], v[230:233], v[84:87]
	v_mfma_f32_16x16x32_bf16 v[80:83], v[206:209], v[230:233], v[80:83]
	v_mfma_f32_16x16x32_bf16 v[68:71], v[190:193], v[238:241], v[68:71]
	v_mfma_f32_16x16x32_bf16 v[64:67], v[206:209], v[238:241], v[64:67]
	s_barrier
; #define PG8_STAGE(bufoff, gbase, voff) do { _Pragma("unroll") for (int _i = 0; _i < 2; ++_i) \
;         __builtin_amdgcn_global_load_lds((const unsigned*)((const char*)(gbase) + (voff)[_i]), (LAS unsigned*)(lds + (bufoff) + ldsw + _i * 8192), 16, 0, 0); } while (0)
; #define PG8_LDA(dst, b, h) do { _Pragma("unroll") for (int m = 0; m < 4; ++m) _Pragma("unroll") for (int k = 0; k < 2; ++k) dst[m][k] = *(const LAS bf16x8*)(lds + PG8_SA(b, h) + aoff + m * 2048 + k * 1024); } while (0)
; #define PG8_LDB(dst, b, h) do { _Pragma("unroll") for (int n = 0; n < 2; ++n) _Pragma("unroll") for (int k = 0; k < 2; ++k) dst[n][k] = *(const LAS bf16x8*)(lds + PG8_SB(b, h) + boff + n * 2048 + k * 1024); } while (0)
; #define PG8_MMA(ai, bj, At, Bt) do { __builtin_amdgcn_s_setprio(1); _Pragma("unroll") for (int m = 0; m < 4; ++m) _Pragma("unroll") for (int n = 0; n < 2; ++n) _Pragma("unroll") for (int k = 0; k < 2; ++k) \
;         acc[ai][bj][m][n] = __builtin_amdgcn_mfma_f32_16x16x32_bf16(Bt[n][k], At[m][k], acc[ai][bj][m][n], 0, 0, 0); __builtin_amdgcn_s_setprio(0); } while (0)
; #define PG8_WAIT_V(n) asm volatile("s_waitcnt vmcnt(" #n ")" ::: "memory")
; #define PG8_WAIT_L(n) asm volatile("s_waitcnt lgkmcnt(" #n ")" ::: "memory")
; #define PG8_BAR __builtin_amdgcn_s_barrier()
; template <class Epi, class Sched>
; __device__ __forceinline__ void gemm_phase(const int tid, LAS unsigned char* lds, const int lda, const int ldb, const int K, const Sched& S, const Epi& E) {
;     ...
;         for (int t = 0; t < nt; t += 2) {
;             const bool last = (t == nt - 2);
;             const char* a1 = cA + (size_t)(t + 1) * kstep;
;             const char* a2 = last ? nA : cA + (size_t)(t + 2) * kstep; const char* b2 = last ? nB : cB + (size_t)(t + 2) * kstep;
;             const char* a3 = a2 + kstep; const char* b3 = b2 + kstep;
;             PG8_LDB(B0, 0, 0); PG8_LDB(B1, 0, 1); PG8_SCHED; PG8_LDA(At, 0, 0); PG8_STAGE(PG8_SA(1, 1), a1 + hstepA, voffA);
;             PG8_WAIT_V(8); PG8_WAIT_L(0); PG8_BAR; PG8_MMA(0, 0, At, B0); PG8_MMA(0, 1, At, B1); PG8_BAR; PG8_SCHED;
;     ...
;             PG8_LDA(At, 1, 1); PG8_STAGE(PG8_SB(1, 0), b3, voffB); PG8_STAGE(PG8_SB(1, 1), b3 + hstepB, voffB); PG8_STAGE(PG8_SA(1, 0), a3, voffA);
;             PG8_WAIT_V(8); PG8_WAIT_L(0); PG8_BAR; if (!cur.half) { PG8_MMA(1, 0, At, B0); PG8_MMA(1, 1, At, B1); } PG8_BAR; PG8_SCHED;
	s_add_i32 s14, s14, s56
	v_lshl_add_u64 v[242:243], v[242:243], 0, s[6:7]
	s_mov_b32 m0, s14
	ds_read_b128 v[210:213], v154 offset:49152
	ds_read_b128 v[214:217], v154 offset:50176
	ds_read_b128 v[218:221], v154 offset:51200
	ds_read_b128 v[222:225], v154 offset:52224
	ds_read_b128 v[226:229], v154 offset:53248
	ds_read_b128 v[230:233], v154 offset:54272
	ds_read_b128 v[234:237], v154 offset:55296
	ds_read_b128 v[238:241], v154 offset:56320
	global_load_lds_dwordx4 v[242:243], off
	s_add_i32 m0, s14, 0x2000
	s_add_u32 s52, s52, 0x40080
	v_lshl_add_u64 v[242:243], v[244:245], 0, s[6:7]
	s_addc_u32 s53, s53, 0
	s_add_i32 s14, s15, s56
	global_load_lds_dwordx4 v[242:243], off
	v_lshl_add_u64 v[242:243], s[52:53], 0, v[130:131]
	s_mov_b32 m0, s14
	s_nop 0
	global_load_lds_dwordx4 v[242:243], off
	v_lshl_add_u64 v[242:243], s[52:53], 0, v[134:135]
	s_add_i32 m0, s14, 0x2000
	s_nop 0
	global_load_lds_dwordx4 v[242:243], off
	v_lshl_add_u64 v[242:243], v[246:247], 0, s[6:7]
	s_mov_b32 m0, s61
	s_nop 0
	global_load_lds_dwordx4 v[242:243], off
	v_lshl_add_u64 v[242:243], v[248:249], 0, s[6:7]
	s_mov_b32 m0, s62
	s_nop 0
	global_load_lds_dwordx4 v[242:243], off
	s_waitcnt vmcnt(8)
	s_waitcnt lgkmcnt(0)
	s_barrier
	v_mfma_f32_16x16x32_bf16 v[60:63], v[156:159], v[210:213], v[60:63]
	v_mfma_f32_16x16x32_bf16 v[56:59], v[164:167], v[210:213], v[56:59]
	v_mfma_f32_16x16x32_bf16 v[44:47], v[156:159], v[218:221], v[44:47]
	v_mfma_f32_16x16x32_bf16 v[40:43], v[164:167], v[218:221], v[40:43]
	v_mfma_f32_16x16x32_bf16 v[28:31], v[156:159], v[226:229], v[28:31]
	v_mfma_f32_16x16x32_bf16 v[24:27], v[164:167], v[226:229], v[24:27]
	v_mfma_f32_16x16x32_bf16 v[12:15], v[156:159], v[234:237], v[12:15]
	v_mfma_f32_16x16x32_bf16 v[8:11], v[164:167], v[234:237], v[8:11]
	v_mfma_f32_16x16x32_bf16 v[60:63], v[160:163], v[214:217], v[60:63]
	v_mfma_f32_16x16x32_bf16 v[56:59], v[180:183], v[214:217], v[56:59]
	v_mfma_f32_16x16x32_bf16 v[44:47], v[160:163], v[222:225], v[44:47]
	v_mfma_f32_16x16x32_bf16 v[40:43], v[180:183], v[222:225], v[40:43]
	v_mfma_f32_16x16x32_bf16 v[28:31], v[160:163], v[230:233], v[28:31]
	v_mfma_f32_16x16x32_bf16 v[24:27], v[180:183], v[230:233], v[24:27]
	v_mfma_f32_16x16x32_bf16 v[12:15], v[160:163], v[238:241], v[12:15]
	v_mfma_f32_16x16x32_bf16 v[8:11], v[180:183], v[238:241], v[8:11]
	v_mfma_f32_16x16x32_bf16 v[52:55], v[184:187], v[210:213], v[52:55]
	v_mfma_f32_16x16x32_bf16 v[48:51], v[194:197], v[210:213], v[48:51]
	v_mfma_f32_16x16x32_bf16 v[36:39], v[184:187], v[218:221], v[36:39]
	v_mfma_f32_16x16x32_bf16 v[32:35], v[194:197], v[218:221], v[32:35]
	v_mfma_f32_16x16x32_bf16 v[20:23], v[184:187], v[226:229], v[20:23]
	v_mfma_f32_16x16x32_bf16 v[16:19], v[194:197], v[226:229], v[16:19]
	v_mfma_f32_16x16x32_bf16 v[4:7], v[184:187], v[234:237], v[4:7]
	v_mfma_f32_16x16x32_bf16 v[0:3], v[194:197], v[234:237], v[0:3]
	v_mfma_f32_16x16x32_bf16 v[52:55], v[190:193], v[214:217], v[52:55]
	v_mfma_f32_16x16x32_bf16 v[48:51], v[206:209], v[214:217], v[48:51]
	v_mfma_f32_16x16x32_bf16 v[36:39], v[190:193], v[222:225], v[36:39]
	v_mfma_f32_16x16x32_bf16 v[32:35], v[206:209], v[222:225], v[32:35]
	v_mfma_f32_16x16x32_bf16 v[20:23], v[190:193], v[230:233], v[20:23]
	v_mfma_f32_16x16x32_bf16 v[16:19], v[206:209], v[230:233], v[16:19]
	v_mfma_f32_16x16x32_bf16 v[4:7], v[190:193], v[238:241], v[4:7]
	v_mfma_f32_16x16x32_bf16 v[0:3], v[206:209], v[238:241], v[0:3]
	s_barrier
	s_add_u32 s38, s38, 0x100
	s_addc_u32 s39, s39, 0
	s_add_u32 s47, s47, 0x100
	s_addc_u32 s67, s67, 0
	s_cmp_ge_i32 s68, s4
	s_mov_b32 s52, s68
	s_cbranch_scc1 .Lkexit_197
.LBB0_197:
	s_add_i32 s68, s52, 2
	s_add_u32 s14, s38, 0xfffc0080
	s_addc_u32 s15, s39, -1
	s_add_i32 s24, 0, 0x10000
	s_cmp_eq_u32 s64, s52
	s_cselect_b32 s55, s3, s15
	s_cselect_b32 s54, s2, s14
	v_add_u32_e32 v155, s24, v146
	s_cselect_b32 s53, s23, s67
	s_cselect_b32 s52, s22, s47
	s_add_i32 s14, 0, 0x14000
	ds_read_b128 v[156:159], v155
	ds_read_b128 v[160:163], v155 offset:1024
	ds_read_b128 v[164:167], v155 offset:2048
	ds_read_b128 v[180:183], v155 offset:3072
	v_add_u32_e32 v155, s14, v146
	ds_read_b128 v[184:187], v155
	ds_read_b128 v[190:193], v155 offset:1024
	ds_read_b128 v[194:197], v155 offset:2048
	ds_read_b128 v[206:209], v155 offset:3072
	v_lshl_add_u64 v[242:243], s[38:39], 0, v[136:137]
	s_add_i32 m0, s57, 0xc000
	ds_read_b128 v[210:213], v154
	ds_read_b128 v[214:217], v154 offset:1024
	ds_read_b128 v[218:221], v154 offset:2048
	ds_read_b128 v[222:225], v154 offset:3072
	ds_read_b128 v[226:229], v154 offset:4096
	ds_read_b128 v[230:233], v154 offset:5120
	ds_read_b128 v[234:237], v154 offset:6144
	ds_read_b128 v[238:241], v154 offset:7168
	global_load_lds_dwordx4 v[242:243], off
	v_lshl_add_u64 v[242:243], s[38:39], 0, v[138:139]
	s_add_i32 m0, s57, 0xe000
	s_nop 0
	global_load_lds_dwordx4 v[242:243], off
	s_waitcnt vmcnt(8)
	s_waitcnt lgkmcnt(0)
	s_barrier
; #define PG8_STAGE(bufoff, gbase, voff) do { _Pragma("unroll") for (int _i = 0; _i < 2; ++_i) \
;         __builtin_amdgcn_global_load_lds((const unsigned*)((const char*)(gbase) + (voff)[_i]), (LAS unsigned*)(lds + (bufoff) + ldsw + _i * 8192), 16, 0, 0); } while (0)
; #define PG8_LDA(dst, b, h) do { _Pragma("unroll") for (int m = 0; m < 4; ++m) _Pragma("unroll") for (int k = 0; k < 2; ++k) dst[m][k] = *(const LAS bf16x8*)(lds + PG8_SA(b, h) + aoff + m * 2048 + k * 1024); } while (0)
; #define PG8_LDB(dst, b, h) do { _Pragma("unroll") for (int n = 0; n < 2; ++n) _Pragma("unroll") for (int k = 0; k < 2; ++k) dst[n][k] = *(const LAS bf16x8*)(lds + PG8_SB(b, h) + boff + n * 2048 + k * 1024); } while (0)
; #define PG8_MMA(ai, bj, At, Bt) do { __builtin_amdgcn_s_setprio(1); _Pragma("unroll") for (int m = 0; m < 4; ++m) _Pragma("unroll") for (int n = 0; n < 2; ++n) _Pragma("unroll") for (int k = 0; k < 2; ++k) \
;         acc[ai][bj][m][n] = __builtin_amdgcn_mfma_f32_16x16x32_bf16(Bt[n][k], At[m][k], acc[ai][bj][m][n], 0, 0, 0); __builtin_amdgcn_s_setprio(0); } while (0)
; #define PG8_WAIT_V(n) asm volatile("s_waitcnt vmcnt(" #n ")" ::: "memory")
; #define PG8_WAIT_L(n) asm volatile("s_waitcnt lgkmcnt(" #n ")" ::: "memory")
; #define PG8_BAR __builtin_amdgcn_s_barrier()
; #define PG8_SCHED __builtin_amdgcn_sched_barrier(0)
; template <class Epi, class Sched>
; __device__ __forceinline__ void gemm_phase(const int tid, LAS unsigned char* lds, const int lda, const int ldb, const int K, const Sched& S, const Epi& E) {
;     ...
;             PG8_WAIT_V(8); PG8_WAIT_L(0); PG8_BAR; PG8_MMA(0, 0, At, B0); PG8_MMA(0, 1, At, B1); PG8_BAR; PG8_SCHED;
;             PG8_LDA(At, 0, 1); PG8_STAGE(PG8_SB(0, 0), b2, voffB); PG8_STAGE(PG8_SB(0, 1), b2 + hstepB, voffB); PG8_STAGE(PG8_SA(0, 0), a2, voffA);
;             PG8_WAIT_V(8); PG8_WAIT_L(0); PG8_BAR; if (!cur.half) { PG8_MMA(1, 0, At, B0); PG8_MMA(1, 1, At, B1); } PG8_BAR; PG8_SCHED;
;             PG8_LDB(B0, 1, 0); PG8_LDB(B1, 1, 1); PG8_SCHED; PG8_LDA(At, 1, 0); PG8_STAGE(PG8_SA(0, 1), a2 + hstepA, voffA);
;             PG8_WAIT_V(8); PG8_WAIT_L(0); PG8_BAR; PG8_MMA(0, 0, At, B0); PG8_MMA(0, 1, At, B1); PG8_BAR; PG8_SCHED;
	v_mfma_f32_16x16x32_bf16 v[124:127], v[156:159], v[210:213], v[124:127]
	v_mfma_f32_16x16x32_bf16 v[120:123], v[164:167], v[210:213], v[120:123]
	v_mfma_f32_16x16x32_bf16 v[108:111], v[156:159], v[218:221], v[108:111]
	v_mfma_f32_16x16x32_bf16 v[104:107], v[164:167], v[218:221], v[104:107]
	v_mfma_f32_16x16x32_bf16 v[92:95], v[156:159], v[226:229], v[92:95]
	v_mfma_f32_16x16x32_bf16 v[88:91], v[164:167], v[226:229], v[88:91]
	v_mfma_f32_16x16x32_bf16 v[76:79], v[156:159], v[234:237], v[76:79]
	v_mfma_f32_16x16x32_bf16 v[72:75], v[164:167], v[234:237], v[72:75]
	v_mfma_f32_16x16x32_bf16 v[124:127], v[160:163], v[214:217], v[124:127]
	v_mfma_f32_16x16x32_bf16 v[120:123], v[180:183], v[214:217], v[120:123]
	v_mfma_f32_16x16x32_bf16 v[108:111], v[160:163], v[222:225], v[108:111]
	v_mfma_f32_16x16x32_bf16 v[104:107], v[180:183], v[222:225], v[104:107]
	v_mfma_f32_16x16x32_bf16 v[92:95], v[160:163], v[230:233], v[92:95]
	v_mfma_f32_16x16x32_bf16 v[88:91], v[180:183], v[230:233], v[88:91]
	v_mfma_f32_16x16x32_bf16 v[76:79], v[160:163], v[238:241], v[76:79]
	v_mfma_f32_16x16x32_bf16 v[72:75], v[180:183], v[238:241], v[72:75]
	v_mfma_f32_16x16x32_bf16 v[116:119], v[184:187], v[210:213], v[116:119]
	v_mfma_f32_16x16x32_bf16 v[112:115], v[194:197], v[210:213], v[112:115]
	v_mfma_f32_16x16x32_bf16 v[100:103], v[184:187], v[218:221], v[100:103]
	v_mfma_f32_16x16x32_bf16 v[96:99], v[194:197], v[218:221], v[96:99]
	v_mfma_f32_16x16x32_bf16 v[84:87], v[184:187], v[226:229], v[84:87]
	v_mfma_f32_16x16x32_bf16 v[80:83], v[194:197], v[226:229], v[80:83]
	v_mfma_f32_16x16x32_bf16 v[68:71], v[184:187], v[234:237], v[68:71]
	v_mfma_f32_16x16x32_bf16 v[64:67], v[194:197], v[234:237], v[64:67]
	v_mfma_f32_16x16x32_bf16 v[116:119], v[190:193], v[214:217], v[116:119]
	v_mfma_f32_16x16x32_bf16 v[112:115], v[206:209], v[214:217], v[112:115]
	v_mfma_f32_16x16x32_bf16 v[100:103], v[190:193], v[222:225], v[100:103]
	v_mfma_f32_16x16x32_bf16 v[96:99], v[206:209], v[222:225], v[96:99]
	v_mfma_f32_16x16x32_bf16 v[84:87], v[190:193], v[230:233], v[84:87]
	v_mfma_f32_16x16x32_bf16 v[80:83], v[206:209], v[230:233], v[80:83]
	v_mfma_f32_16x16x32_bf16 v[68:71], v[190:193], v[238:241], v[68:71]
	v_mfma_f32_16x16x32_bf16 v[64:67], v[206:209], v[238:241], v[64:67]
	s_barrier
	s_add_i32 s15, s24, s56
	v_lshl_add_u64 v[242:243], s[52:53], 0, v[130:131]
	s_mov_b32 m0, s15
	ds_read_b128 v[210:213], v154 offset:16384
	ds_read_b128 v[214:217], v154 offset:17408
	ds_read_b128 v[218:221], v154 offset:18432
	ds_read_b128 v[222:225], v154 offset:19456
	ds_read_b128 v[226:229], v154 offset:20480
	ds_read_b128 v[230:233], v154 offset:21504
	ds_read_b128 v[234:237], v154 offset:22528
	ds_read_b128 v[238:241], v154 offset:23552
	global_load_lds_dwordx4 v[242:243], off
	s_add_i32 m0, s15, 0x2000
	s_add_u32 s70, s52, 0x40000
	v_lshl_add_u64 v[244:245], s[52:53], 0, v[134:135]
	s_addc_u32 s71, s53, 0
	s_add_i32 s14, s14, s56
	global_load_lds_dwordx4 v[244:245], off
	v_lshl_add_u64 v[246:247], s[70:71], 0, v[130:131]
	s_mov_b32 m0, s14
	v_lshl_add_u64 v[248:249], s[54:55], 0, v[132:133]
	global_load_lds_dwordx4 v[246:247], off
	v_lshl_add_u64 v[246:247], s[70:71], 0, v[134:135]
	s_add_i32 m0, s14, 0x2000
	s_nop 0
	global_load_lds_dwordx4 v[246:247], off
	v_lshl_add_u64 v[246:247], s[54:55], 0, v[128:129]
	s_mov_b32 m0, s57
	s_nop 0
	global_load_lds_dwordx4 v[246:247], off
	s_mov_b32 m0, s58
	s_nop 0
	global_load_lds_dwordx4 v[248:249], off
	s_waitcnt vmcnt(8)
	s_waitcnt lgkmcnt(0)
	s_barrier
	v_mfma_f32_16x16x32_bf16 v[60:63], v[156:159], v[210:213], v[60:63]
	v_mfma_f32_16x16x32_bf16 v[56:59], v[164:167], v[210:213], v[56:59]
	v_mfma_f32_16x16x32_bf16 v[44:47], v[156:159], v[218:221], v[44:47]
	v_mfma_f32_16x16x32_bf16 v[40:43], v[164:167], v[218:221], v[40:43]
	v_mfma_f32_16x16x32_bf16 v[28:31], v[156:159], v[226:229], v[28:31]
	v_mfma_f32_16x16x32_bf16 v[24:27], v[164:167], v[226:229], v[24:27]
	v_mfma_f32_16x16x32_bf16 v[12:15], v[156:159], v[234:237], v[12:15]
	v_mfma_f32_16x16x32_bf16 v[8:11], v[164:167], v[234:237], v[8:11]
	v_mfma_f32_16x16x32_bf16 v[60:63], v[160:163], v[214:217], v[60:63]
	v_mfma_f32_16x16x32_bf16 v[56:59], v[180:183], v[214:217], v[56:59]
	v_mfma_f32_16x16x32_bf16 v[44:47], v[160:163], v[222:225], v[44:47]
	v_mfma_f32_16x16x32_bf16 v[40:43], v[180:183], v[222:225], v[40:43]
	v_mfma_f32_16x16x32_bf16 v[28:31], v[160:163], v[230:233], v[28:31]
	v_mfma_f32_16x16x32_bf16 v[24:27], v[180:183], v[230:233], v[24:27]
	v_mfma_f32_16x16x32_bf16 v[12:15], v[160:163], v[238:241], v[12:15]
	v_mfma_f32_16x16x32_bf16 v[8:11], v[180:183], v[238:241], v[8:11]
	v_mfma_f32_16x16x32_bf16 v[52:55], v[184:187], v[210:213], v[52:55]
	v_mfma_f32_16x16x32_bf16 v[48:51], v[194:197], v[210:213], v[48:51]
	v_mfma_f32_16x16x32_bf16 v[36:39], v[184:187], v[218:221], v[36:39]
	v_mfma_f32_16x16x32_bf16 v[32:35], v[194:197], v[218:221], v[32:35]
	v_mfma_f32_16x16x32_bf16 v[20:23], v[184:187], v[226:229], v[20:23]
	v_mfma_f32_16x16x32_bf16 v[16:19], v[194:197], v[226:229], v[16:19]
	v_mfma_f32_16x16x32_bf16 v[4:7], v[184:187], v[234:237], v[4:7]
	v_mfma_f32_16x16x32_bf16 v[0:3], v[194:197], v[234:237], v[0:3]
	v_mfma_f32_16x16x32_bf16 v[52:55], v[190:193], v[214:217], v[52:55]
	v_mfma_f32_16x16x32_bf16 v[48:51], v[206:209], v[214:217], v[48:51]
	v_mfma_f32_16x16x32_bf16 v[36:39], v[190:193], v[222:225], v[36:39]
	v_mfma_f32_16x16x32_bf16 v[32:35], v[206:209], v[222:225], v[32:35]
	v_mfma_f32_16x16x32_bf16 v[20:23], v[190:193], v[230:233], v[20:23]
	v_mfma_f32_16x16x32_bf16 v[16:19], v[206:209], v[230:233], v[16:19]
	v_mfma_f32_16x16x32_bf16 v[4:7], v[190:193], v[238:241], v[4:7]
	v_mfma_f32_16x16x32_bf16 v[0:3], v[206:209], v[238:241], v[0:3]
	s_barrier
; #define PG8_STAGE(bufoff, gbase, voff) do { _Pragma("unroll") for (int _i = 0; _i < 2; ++_i) \
;         __builtin_amdgcn_global_load_lds((const unsigned*)((const char*)(gbase) + (voff)[_i]), (LAS unsigned*)(lds + (bufoff) + ldsw + _i * 8192), 16, 0, 0); } while (0)
; #define PG8_LDA(dst, b, h) do { _Pragma("unroll") for (int m = 0; m < 4; ++m) _Pragma("unroll") for (int k = 0; k < 2; ++k) dst[m][k] = *(const LAS bf16x8*)(lds + PG8_SA(b, h) + aoff + m * 2048 + k * 1024); } while (0)
; #define PG8_LDB(dst, b, h) do { _Pragma("unroll") for (int n = 0; n < 2; ++n) _Pragma("unroll") for (int k = 0; k < 2; ++k) dst[n][k] = *(const LAS bf16x8*)(lds + PG8_SB(b, h) + boff + n * 2048 + k * 1024); } while (0)
; #define PG8_MMA(ai, bj, At, Bt) do { __builtin_amdgcn_s_setprio(1); _Pragma("unroll") for (int m = 0; m < 4; ++m) _Pragma("unroll") for (int n = 0; n < 2; ++n) _Pragma("unroll") for (int k = 0; k < 2; ++k) \
;         acc[ai][bj][m][n] = __builtin_amdgcn_mfma_f32_16x16x32_bf16(Bt[n][k], At[m][k], acc[ai][bj][m][n], 0, 0, 0); __builtin_amdgcn_s_setprio(0); } while (0)
; #define PG8_WAIT_V(n) asm volatile("s_waitcnt vmcnt(" #n ")" ::: "memory")
; #define PG8_WAIT_L(n) asm volatile("s_waitcnt lgkmcnt(" #n ")" ::: "memory")
; #define PG8_BAR __builtin_amdgcn_s_barrier()
; #define PG8_SCHED __builtin_amdgcn_sched_barrier(0)
; template <class Epi, class Sched>
; __device__ __forceinline__ void gemm_phase(const int tid, LAS unsigned char* lds, const int lda, const int ldb, const int K, const Sched& S, const Epi& E) {
;     ...
;             PG8_LDB(B0, 1, 0); PG8_LDB(B1, 1, 1); PG8_SCHED; PG8_LDA(At, 1, 0); PG8_STAGE(PG8_SA(0, 1), a2 + hstepA, voffA);
;             PG8_WAIT_V(8); PG8_WAIT_L(0); PG8_BAR; PG8_MMA(0, 0, At, B0); PG8_MMA(0, 1, At, B1); PG8_BAR; PG8_SCHED;
;             PG8_LDA(At, 1, 1); PG8_STAGE(PG8_SB(1, 0), b3, voffB); PG8_STAGE(PG8_SB(1, 1), b3 + hstepB, voffB); PG8_STAGE(PG8_SA(1, 0), a3, voffA);
;             PG8_WAIT_V(8); PG8_WAIT_L(0); PG8_BAR; if (!cur.half) { PG8_MMA(1, 0, At, B0); PG8_MMA(1, 1, At, B1); } PG8_BAR; PG8_SCHED;
	s_add_i32 s14, 0, 0x18000
	v_add_u32_e32 v155, s14, v146
	s_add_i32 s15, 0, 0x1c000
	ds_read_b128 v[156:159], v155
	ds_read_b128 v[160:163], v155 offset:1024
	ds_read_b128 v[164:167], v155 offset:2048
	ds_read_b128 v[180:183], v155 offset:3072
	v_add_u32_e32 v155, s15, v146
	ds_read_b128 v[184:187], v155
	ds_read_b128 v[190:193], v155 offset:1024
	ds_read_b128 v[194:197], v155 offset:2048
	ds_read_b128 v[206:209], v155 offset:3072
	s_add_u32 s54, s54, 0x40000
	s_addc_u32 s55, s55, 0
	s_mov_b32 m0, s59
	v_lshl_add_u64 v[250:251], s[54:55], 0, v[128:129]
	ds_read_b128 v[210:213], v154 offset:32768
	ds_read_b128 v[214:217], v154 offset:33792
	ds_read_b128 v[218:221], v154 offset:34816
	ds_read_b128 v[222:225], v154 offset:35840
	ds_read_b128 v[226:229], v154 offset:36864
	ds_read_b128 v[230:233], v154 offset:37888
	ds_read_b128 v[234:237], v154 offset:38912
	ds_read_b128 v[238:241], v154 offset:39936
	global_load_lds_dwordx4 v[250:251], off
	v_lshl_add_u64 v[250:251], s[54:55], 0, v[132:133]
	s_mov_b32 m0, s60
	s_nop 0
	global_load_lds_dwordx4 v[250:251], off
	s_waitcnt vmcnt(8)
	s_waitcnt lgkmcnt(0)
	s_barrier
	v_mfma_f32_16x16x32_bf16 v[124:127], v[156:159], v[210:213], v[124:127]
	v_mfma_f32_16x16x32_bf16 v[120:123], v[164:167], v[210:213], v[120:123]
	v_mfma_f32_16x16x32_bf16 v[108:111], v[156:159], v[218:221], v[108:111]
	v_mfma_f32_16x16x32_bf16 v[104:107], v[164:167], v[218:221], v[104:107]
	v_mfma_f32_16x16x32_bf16 v[92:95], v[156:159], v[226:229], v[92:95]
	v_mfma_f32_16x16x32_bf16 v[88:91], v[164:167], v[226:229], v[88:91]
	v_mfma_f32_16x16x32_bf16 v[76:79], v[156:159], v[234:237], v[76:79]
	v_mfma_f32_16x16x32_bf16 v[72:75], v[164:167], v[234:237], v[72:75]
	v_mfma_f32_16x16x32_bf16 v[124:127], v[160:163], v[214:217], v[124:127]
	v_mfma_f32_16x16x32_bf16 v[120:123], v[180:183], v[214:217], v[120:123]
	v_mfma_f32_16x16x32_bf16 v[108:111], v[160:163], v[222:225], v[108:111]
	v_mfma_f32_16x16x32_bf16 v[104:107], v[180:183], v[222:225], v[104:107]
	v_mfma_f32_16x16x32_bf16 v[92:95], v[160:163], v[230:233], v[92:95]
	v_mfma_f32_16x16x32_bf16 v[88:91], v[180:183], v[230:233], v[88:91]
	v_mfma_f32_16x16x32_bf16 v[76:79], v[160:163], v[238:241], v[76:79]
	v_mfma_f32_16x16x32_bf16 v[72:75], v[180:183], v[238:241], v[72:75]
	v_mfma_f32_16x16x32_bf16 v[116:119], v[184:187], v[210:213], v[116:119]
	v_mfma_f32_16x16x32_bf16 v[112:115], v[194:197], v[210:213], v[112:115]
	v_mfma_f32_16x16x32_bf16 v[100:103], v[184:187], v[218:221], v[100:103]
	v_mfma_f32_16x16x32_bf16 v[96:99], v[194:197], v[218:221], v[96:99]
	v_mfma_f32_16x16x32_bf16 v[84:87], v[184:187], v[226:229], v[84:87]
	v_mfma_f32_16x16x32_bf16 v[80:83], v[194:197], v[226:229], v[80:83]
	v_mfma_f32_16x16x32_bf16 v[68:71], v[184:187], v[234:237], v[68:71]
	v_mfma_f32_16x16x32_bf16 v[64:67], v[194:197], v[234:237], v[64:67]
	v_mfma_f32_16x16x32_bf16 v[116:119], v[190:193], v[214:217], v[116:119]
	v_mfma_f32_16x16x32_bf16 v[112:115], v[206:209], v[214:217], v[112:115]
	v_mfma_f32_16x16x32_bf16 v[100:103], v[190:193], v[222:225], v[100:103]
	v_mfma_f32_16x16x32_bf16 v[96:99], v[206:209], v[222:225], v[96:99]
	v_mfma_f32_16x16x32_bf16 v[84:87], v[190:193], v[230:233], v[84:87]
	v_mfma_f32_16x16x32_bf16 v[80:83], v[206:209], v[230:233], v[80:83]
	v_mfma_f32_16x16x32_bf16 v[68:71], v[190:193], v[238:241], v[68:71]
	v_mfma_f32_16x16x32_bf16 v[64:67], v[206:209], v[238:241], v[64:67]
	s_barrier
	s_add_i32 s14, s14, s56
	v_lshl_add_u64 v[242:243], v[242:243], 0, s[6:7]
	s_mov_b32 m0, s14
	ds_read_b128 v[210:213], v154 offset:49152
	ds_read_b128 v[214:217], v154 offset:50176
	ds_read_b128 v[218:221], v154 offset:51200
	ds_read_b128 v[222:225], v154 offset:52224
	ds_read_b128 v[226:229], v154 offset:53248
	ds_read_b128 v[230:233], v154 offset:54272
	ds_read_b128 v[234:237], v154 offset:55296
	ds_read_b128 v[238:241], v154 offset:56320
	global_load_lds_dwordx4 v[242:243], off
	s_add_i32 m0, s14, 0x2000
	s_add_u32 s52, s52, 0x40080
	v_lshl_add_u64 v[242:243], v[244:245], 0, s[6:7]
	s_addc_u32 s53, s53, 0
	s_add_i32 s14, s15, s56
	global_load_lds_dwordx4 v[242:243], off
	v_lshl_add_u64 v[242:243], s[52:53], 0, v[130:131]
	s_mov_b32 m0, s14
	s_nop 0
	global_load_lds_dwordx4 v[242:243], off
	v_lshl_add_u64 v[242:243], s[52:53], 0, v[134:135]
	s_add_i32 m0, s14, 0x2000
	s_nop 0
	global_load_lds_dwordx4 v[242:243], off
	v_lshl_add_u64 v[242:243], v[246:247], 0, s[6:7]
	s_mov_b32 m0, s61
	s_nop 0
	global_load_lds_dwordx4 v[242:243], off
	v_lshl_add_u64 v[242:243], v[248:249], 0, s[6:7]
	s_mov_b32 m0, s62
	s_nop 0
	global_load_lds_dwordx4 v[242:243], off
	s_waitcnt vmcnt(8)
	s_waitcnt lgkmcnt(0)
	s_barrier
	v_mfma_f32_16x16x32_bf16 v[60:63], v[156:159], v[210:213], v[60:63]
	v_mfma_f32_16x16x32_bf16 v[56:59], v[164:167], v[210:213], v[56:59]
	v_mfma_f32_16x16x32_bf16 v[44:47], v[156:159], v[218:221], v[44:47]
	v_mfma_f32_16x16x32_bf16 v[40:43], v[164:167], v[218:221], v[40:43]
	v_mfma_f32_16x16x32_bf16 v[28:31], v[156:159], v[226:229], v[28:31]
	v_mfma_f32_16x16x32_bf16 v[24:27], v[164:167], v[226:229], v[24:27]
	v_mfma_f32_16x16x32_bf16 v[12:15], v[156:159], v[234:237], v[12:15]
	v_mfma_f32_16x16x32_bf16 v[8:11], v[164:167], v[234:237], v[8:11]
	v_mfma_f32_16x16x32_bf16 v[60:63], v[160:163], v[214:217], v[60:63]
	v_mfma_f32_16x16x32_bf16 v[56:59], v[180:183], v[214:217], v[56:59]
	v_mfma_f32_16x16x32_bf16 v[44:47], v[160:163], v[222:225], v[44:47]
	v_mfma_f32_16x16x32_bf16 v[40:43], v[180:183], v[222:225], v[40:43]
	v_mfma_f32_16x16x32_bf16 v[28:31], v[160:163], v[230:233], v[28:31]
	v_mfma_f32_16x16x32_bf16 v[24:27], v[180:183], v[230:233], v[24:27]
	v_mfma_f32_16x16x32_bf16 v[12:15], v[160:163], v[238:241], v[12:15]
	v_mfma_f32_16x16x32_bf16 v[8:11], v[180:183], v[238:241], v[8:11]
	v_mfma_f32_16x16x32_bf16 v[52:55], v[184:187], v[210:213], v[52:55]
	v_mfma_f32_16x16x32_bf16 v[48:51], v[194:197], v[210:213], v[48:51]
	v_mfma_f32_16x16x32_bf16 v[36:39], v[184:187], v[218:221], v[36:39]
	v_mfma_f32_16x16x32_bf16 v[32:35], v[194:197], v[218:221], v[32:35]
	v_mfma_f32_16x16x32_bf16 v[20:23], v[184:187], v[226:229], v[20:23]
	v_mfma_f32_16x16x32_bf16 v[16:19], v[194:197], v[226:229], v[16:19]
	v_mfma_f32_16x16x32_bf16 v[4:7], v[184:187], v[234:237], v[4:7]
	v_mfma_f32_16x16x32_bf16 v[0:3], v[194:197], v[234:237], v[0:3]
	v_mfma_f32_16x16x32_bf16 v[52:55], v[190:193], v[214:217], v[52:55]
	v_mfma_f32_16x16x32_bf16 v[48:51], v[206:209], v[214:217], v[48:51]
	v_mfma_f32_16x16x32_bf16 v[36:39], v[190:193], v[222:225], v[36:39]
	v_mfma_f32_16x16x32_bf16 v[32:35], v[206:209], v[222:225], v[32:35]
	v_mfma_f32_16x16x32_bf16 v[20:23], v[190:193], v[230:233], v[20:23]
	v_mfma_f32_16x16x32_bf16 v[16:19], v[206:209], v[230:233], v[16:19]
	v_mfma_f32_16x16x32_bf16 v[4:7], v[190:193], v[238:241], v[4:7]
	v_mfma_f32_16x16x32_bf16 v[0:3], v[206:209], v[238:241], v[0:3]
	s_barrier
	s_add_u32 s38, s38, 0x100
	s_addc_u32 s39, s39, 0
	s_add_u32 s47, s47, 0x100
	s_addc_u32 s67, s67, 0
	s_cmp_ge_i32 s68, s4
	s_mov_b32 s52, s68
	s_cbranch_scc0 .LBB0_197

; #define PG8_STAGE(bufoff, gbase, voff) do { _Pragma("unroll") for (int _i = 0; _i < 2; ++_i) \
;         __builtin_amdgcn_global_load_lds((const unsigned*)((const char*)(gbase) + (voff)[_i]), (LAS unsigned*)(lds + (bufoff) + ldsw + _i * 8192), 16, 0, 0); } while (0)
; #define PG8_LDA(dst, b, h) do { _Pragma("unroll") for (int m = 0; m < 4; ++m) _Pragma("unroll") for (int k = 0; k < 2; ++k) dst[m][k] = *(const LAS bf16x8*)(lds + PG8_SA(b, h) + aoff + m * 2048 + k * 1024); } while (0)
; #define PG8_LDB(dst, b, h) do { _Pragma("unroll") for (int n = 0; n < 2; ++n) _Pragma("unroll") for (int k = 0; k < 2; ++k) dst[n][k] = *(const LAS bf16x8*)(lds + PG8_SB(b, h) + boff + n * 2048 + k * 1024); } while (0)
; #define PG8_MMA(ai, bj, At, Bt) do { __builtin_amdgcn_s_setprio(1); _Pragma("unroll") for (int m = 0; m < 4; ++m) _Pragma("unroll") for (int n = 0; n < 2; ++n) _Pragma("unroll") for (int k = 0; k < 2; ++k) \
;         acc[ai][bj][m][n] = __builtin_amdgcn_mfma_f32_16x16x32_bf16(Bt[n][k], At[m][k], acc[ai][bj][m][n], 0, 0, 0); __builtin_amdgcn_s_setprio(0); } while (0)
; #define PG8_WAIT_V(n) asm volatile("s_waitcnt vmcnt(" #n ")" ::: "memory")
; #define PG8_WAIT_L(n) asm volatile("s_waitcnt lgkmcnt(" #n ")" ::: "memory")
; #define PG8_BAR __builtin_amdgcn_s_barrier()
; template <class Epi, class Sched>
; __device__ __forceinline__ void gemm_phase(const int tid, LAS unsigned char* lds, const int lda, const int ldb, const int K, const Sched& S, const Epi& E) {
;     ...
;         for (int t = 0; t < nt; t += 2) {
;             const bool last = (t == nt - 2);
;             const char* a1 = cA + (size_t)(t + 1) * kstep;
;             const char* a2 = last ? nA : cA + (size_t)(t + 2) * kstep; const char* b2 = last ? nB : cB + (size_t)(t + 2) * kstep;
;             const char* a3 = a2 + kstep; const char* b3 = b2 + kstep;
;             PG8_LDB(B0, 0, 0); PG8_LDB(B1, 0, 1); PG8_SCHED; PG8_LDA(At, 0, 0); PG8_STAGE(PG8_SA(1, 1), a1 + hstepA, voffA);
;             PG8_WAIT_V(8); PG8_WAIT_L(0); PG8_BAR; PG8_MMA(0, 0, At, B0); PG8_MMA(0, 1, At, B1); PG8_BAR; PG8_SCHED;
;             PG8_LDA(At, 0, 1); PG8_STAGE(PG8_SB(0, 0), b2, voffB); PG8_STAGE(PG8_SB(0, 1), b2 + hstepB, voffB); PG8_STAGE(PG8_SA(0, 0), a2, voffA);
;             PG8_WAIT_V(8); PG8_WAIT_L(0); PG8_BAR; if (!cur.half) { PG8_MMA(1, 0, At, B0); PG8_MMA(1, 1, At, B1); } PG8_BAR; PG8_SCHED;
.LBB0_213:
	s_andn2_b64 vcc, exec, s[40:41]
	s_cbranch_vccnz .LBB0_221
	s_add_u32 s54, s54, 0x40080
	s_addc_u32 s55, s55, 0
	s_add_u32 s23, s56, 0x100
	v_mov_b64_e32 v[204:205], 0xff
	v_mov_b64_e32 v[174:175], 0x100
	v_mov_b64_e32 v[172:173], 0x1ff
	v_mov_b64_e32 v[178:179], 0x200
	s_addc_u32 s27, s57, 0
	s_mov_b32 s45, 0
	s_add_i32 s69, s45, 2
	s_add_u32 s14, s54, 0xfffc0080
	s_addc_u32 s15, s55, -1
	s_add_i32 s24, 0, 0x10000
	s_cmp_eq_u32 s68, s45
	s_cselect_b32 s59, s53, s15
	s_cselect_b32 s58, s52, s14
	v_add_u32_e32 v176, s24, v151
	s_cselect_b32 s57, s3, s27
	s_cselect_b32 s56, s2, s23
	s_add_i32 s14, 0, 0x14000
	ds_read_b128 v[140:143], v176
	ds_read_b128 v[144:147], v176 offset:1024
	ds_read_b128 v[180:183], v176 offset:2048
	ds_read_b128 v[184:187], v176 offset:3072
	v_add_u32_e32 v176, s14, v151
	ds_read_b128 v[190:193], v176
	ds_read_b128 v[194:197], v176 offset:1024
	ds_read_b128 v[206:209], v176 offset:2048
	ds_read_b128 v[210:213], v176 offset:3072
	v_lshl_add_u64 v[246:247], s[54:55], 0, v[136:137]
	s_add_i32 m0, s51, 0xc000
	ds_read_b128 v[214:217], v166
	ds_read_b128 v[218:221], v166 offset:1024
	ds_read_b128 v[222:225], v166 offset:2048
	ds_read_b128 v[226:229], v166 offset:3072
	ds_read_b128 v[230:233], v166 offset:4096
	ds_read_b128 v[234:237], v166 offset:5120
	ds_read_b128 v[238:241], v166 offset:6144
	ds_read_b128 v[242:245], v166 offset:7168
	global_load_lds_dwordx4 v[246:247], off
	v_lshl_add_u64 v[246:247], s[54:55], 0, v[138:139]
	s_add_i32 m0, s51, 0xe000
	s_nop 0
	global_load_lds_dwordx4 v[246:247], off
	s_waitcnt vmcnt(8)
	s_waitcnt lgkmcnt(0)
	s_barrier
	v_mfma_f32_16x16x32_bf16 v[124:127], v[140:143], v[214:217], 0
	v_mfma_f32_16x16x32_bf16 v[120:123], v[180:183], v[214:217], 0
	v_mfma_f32_16x16x32_bf16 v[116:119], v[140:143], v[222:225], 0
	v_mfma_f32_16x16x32_bf16 v[112:115], v[180:183], v[222:225], 0
	v_mfma_f32_16x16x32_bf16 v[108:111], v[140:143], v[230:233], 0
	v_mfma_f32_16x16x32_bf16 v[104:107], v[180:183], v[230:233], 0
	v_mfma_f32_16x16x32_bf16 v[100:103], v[140:143], v[238:241], 0
	v_mfma_f32_16x16x32_bf16 v[96:99], v[180:183], v[238:241], 0
	v_mfma_f32_16x16x32_bf16 v[124:127], v[144:147], v[218:221], v[124:127]
	v_mfma_f32_16x16x32_bf16 v[120:123], v[184:187], v[218:221], v[120:123]
	v_mfma_f32_16x16x32_bf16 v[116:119], v[144:147], v[226:229], v[116:119]
	v_mfma_f32_16x16x32_bf16 v[112:115], v[184:187], v[226:229], v[112:115]
	v_mfma_f32_16x16x32_bf16 v[108:111], v[144:147], v[234:237], v[108:111]
	v_mfma_f32_16x16x32_bf16 v[104:107], v[184:187], v[234:237], v[104:107]
	v_mfma_f32_16x16x32_bf16 v[100:103], v[144:147], v[242:245], v[100:103]
	v_mfma_f32_16x16x32_bf16 v[96:99], v[184:187], v[242:245], v[96:99]
	v_mfma_f32_16x16x32_bf16 v[60:63], v[190:193], v[214:217], 0
	v_mfma_f32_16x16x32_bf16 v[56:59], v[206:209], v[214:217], 0
	v_mfma_f32_16x16x32_bf16 v[52:55], v[190:193], v[222:225], 0
	v_mfma_f32_16x16x32_bf16 v[48:51], v[206:209], v[222:225], 0
	v_mfma_f32_16x16x32_bf16 v[44:47], v[190:193], v[230:233], 0
	v_mfma_f32_16x16x32_bf16 v[40:43], v[206:209], v[230:233], 0
	v_mfma_f32_16x16x32_bf16 v[36:39], v[190:193], v[238:241], 0
	v_mfma_f32_16x16x32_bf16 v[32:35], v[206:209], v[238:241], 0
	v_mfma_f32_16x16x32_bf16 v[60:63], v[194:197], v[218:221], v[60:63]
	v_mfma_f32_16x16x32_bf16 v[56:59], v[210:213], v[218:221], v[56:59]
	v_mfma_f32_16x16x32_bf16 v[52:55], v[194:197], v[226:229], v[52:55]
	v_mfma_f32_16x16x32_bf16 v[48:51], v[210:213], v[226:229], v[48:51]
	v_mfma_f32_16x16x32_bf16 v[44:47], v[194:197], v[234:237], v[44:47]
	v_mfma_f32_16x16x32_bf16 v[40:43], v[210:213], v[234:237], v[40:43]
	v_mfma_f32_16x16x32_bf16 v[36:39], v[194:197], v[242:245], v[36:39]
	v_mfma_f32_16x16x32_bf16 v[32:35], v[210:213], v[242:245], v[32:35]
	s_barrier
	s_add_i32 s15, s24, s60
	v_lshl_add_u64 v[246:247], s[56:57], 0, v[132:133]
	s_mov_b32 m0, s15
	ds_read_b128 v[214:217], v166 offset:16384
	ds_read_b128 v[218:221], v166 offset:17408
	ds_read_b128 v[222:225], v166 offset:18432
	ds_read_b128 v[226:229], v166 offset:19456
	ds_read_b128 v[230:233], v166 offset:20480
	ds_read_b128 v[234:237], v166 offset:21504
	ds_read_b128 v[238:241], v166 offset:22528
	ds_read_b128 v[242:245], v166 offset:23552
	global_load_lds_dwordx4 v[246:247], off
	s_add_i32 m0, s15, 0x2000
	s_add_u32 s70, s56, 0x40000
	v_lshl_add_u64 v[248:249], s[56:57], 0, v[128:129]
	s_addc_u32 s71, s57, 0
	s_add_i32 s14, s14, s60
	global_load_lds_dwordx4 v[248:249], off
	v_lshl_add_u64 v[250:251], s[70:71], 0, v[132:133]
	s_mov_b32 m0, s14
	v_lshl_add_u64 v[252:253], s[58:59], 0, v[130:131]
	global_load_lds_dwordx4 v[250:251], off
	v_lshl_add_u64 v[250:251], s[70:71], 0, v[128:129]
	s_add_i32 m0, s14, 0x2000
	s_nop 0
	global_load_lds_dwordx4 v[250:251], off
	v_lshl_add_u64 v[250:251], s[58:59], 0, v[134:135]
	s_mov_b32 m0, s51
	s_nop 0
	global_load_lds_dwordx4 v[250:251], off
	s_mov_b32 m0, s62
	s_nop 0
	global_load_lds_dwordx4 v[252:253], off
	s_waitcnt vmcnt(8)
	s_waitcnt lgkmcnt(0)
	s_barrier
; #define PG8_STAGE(bufoff, gbase, voff) do { _Pragma("unroll") for (int _i = 0; _i < 2; ++_i) \
;         __builtin_amdgcn_global_load_lds((const unsigned*)((const char*)(gbase) + (voff)[_i]), (LAS unsigned*)(lds + (bufoff) + ldsw + _i * 8192), 16, 0, 0); } while (0)
; #define PG8_LDA(dst, b, h) do { _Pragma("unroll") for (int m = 0; m < 4; ++m) _Pragma("unroll") for (int k = 0; k < 2; ++k) dst[m][k] = *(const LAS bf16x8*)(lds + PG8_SA(b, h) + aoff + m * 2048 + k * 1024); } while (0)
; #define PG8_LDB(dst, b, h) do { _Pragma("unroll") for (int n = 0; n < 2; ++n) _Pragma("unroll") for (int k = 0; k < 2; ++k) dst[n][k] = *(const LAS bf16x8*)(lds + PG8_SB(b, h) + boff + n * 2048 + k * 1024); } while (0)
; #define PG8_MMA(ai, bj, At, Bt) do { __builtin_amdgcn_s_setprio(1); _Pragma("unroll") for (int m = 0; m < 4; ++m) _Pragma("unroll") for (int n = 0; n < 2; ++n) _Pragma("unroll") for (int k = 0; k < 2; ++k) \
;         acc[ai][bj][m][n] = __builtin_amdgcn_mfma_f32_16x16x32_bf16(Bt[n][k], At[m][k], acc[ai][bj][m][n], 0, 0, 0); __builtin_amdgcn_s_setprio(0); } while (0)
; #define PG8_WAIT_V(n) asm volatile("s_waitcnt vmcnt(" #n ")" ::: "memory")
; #define PG8_WAIT_L(n) asm volatile("s_waitcnt lgkmcnt(" #n ")" ::: "memory")
; #define PG8_BAR __builtin_amdgcn_s_barrier()
; #define PG8_SCHED __builtin_amdgcn_sched_barrier(0)
; template <class Epi, class Sched>
; __device__ __forceinline__ void gemm_phase(const int tid, LAS unsigned char* lds, const int lda, const int ldb, const int K, const Sched& S, const Epi& E) {
;     ...
;             PG8_WAIT_V(8); PG8_WAIT_L(0); PG8_BAR; if (!cur.half) { PG8_MMA(1, 0, At, B0); PG8_MMA(1, 1, At, B1); } PG8_BAR; PG8_SCHED;
;             PG8_LDB(B0, 1, 0); PG8_LDB(B1, 1, 1); PG8_SCHED; PG8_LDA(At, 1, 0); PG8_STAGE(PG8_SA(0, 1), a2 + hstepA, voffA);
;             PG8_WAIT_V(8); PG8_WAIT_L(0); PG8_BAR; PG8_MMA(0, 0, At, B0); PG8_MMA(0, 1, At, B1); PG8_BAR; PG8_SCHED;
	v_mfma_f32_16x16x32_bf16 v[92:95], v[140:143], v[214:217], 0
	v_mfma_f32_16x16x32_bf16 v[88:91], v[180:183], v[214:217], 0
	v_mfma_f32_16x16x32_bf16 v[84:87], v[140:143], v[222:225], 0
	v_mfma_f32_16x16x32_bf16 v[80:83], v[180:183], v[222:225], 0
	v_mfma_f32_16x16x32_bf16 v[76:79], v[140:143], v[230:233], 0
	v_mfma_f32_16x16x32_bf16 v[72:75], v[180:183], v[230:233], 0
	v_mfma_f32_16x16x32_bf16 v[68:71], v[140:143], v[238:241], 0
	v_mfma_f32_16x16x32_bf16 v[64:67], v[180:183], v[238:241], 0
	v_mfma_f32_16x16x32_bf16 v[92:95], v[144:147], v[218:221], v[92:95]
	v_mfma_f32_16x16x32_bf16 v[88:91], v[184:187], v[218:221], v[88:91]
	v_mfma_f32_16x16x32_bf16 v[84:87], v[144:147], v[226:229], v[84:87]
	v_mfma_f32_16x16x32_bf16 v[80:83], v[184:187], v[226:229], v[80:83]
	v_mfma_f32_16x16x32_bf16 v[76:79], v[144:147], v[234:237], v[76:79]
	v_mfma_f32_16x16x32_bf16 v[72:75], v[184:187], v[234:237], v[72:75]
	v_mfma_f32_16x16x32_bf16 v[68:71], v[144:147], v[242:245], v[68:71]
	v_mfma_f32_16x16x32_bf16 v[64:67], v[184:187], v[242:245], v[64:67]
	v_mfma_f32_16x16x32_bf16 v[28:31], v[190:193], v[214:217], 0
	v_mfma_f32_16x16x32_bf16 v[24:27], v[206:209], v[214:217], 0
	v_mfma_f32_16x16x32_bf16 v[20:23], v[190:193], v[222:225], 0
	v_mfma_f32_16x16x32_bf16 v[16:19], v[206:209], v[222:225], 0
	v_mfma_f32_16x16x32_bf16 v[12:15], v[190:193], v[230:233], 0
	v_mfma_f32_16x16x32_bf16 v[8:11], v[206:209], v[230:233], 0
	v_mfma_f32_16x16x32_bf16 v[4:7], v[190:193], v[238:241], 0
	v_mfma_f32_16x16x32_bf16 v[0:3], v[206:209], v[238:241], 0
	v_mfma_f32_16x16x32_bf16 v[28:31], v[194:197], v[218:221], v[28:31]
	v_mfma_f32_16x16x32_bf16 v[24:27], v[210:213], v[218:221], v[24:27]
	v_mfma_f32_16x16x32_bf16 v[20:23], v[194:197], v[226:229], v[20:23]
	v_mfma_f32_16x16x32_bf16 v[16:19], v[210:213], v[226:229], v[16:19]
	v_mfma_f32_16x16x32_bf16 v[12:15], v[194:197], v[234:237], v[12:15]
	v_mfma_f32_16x16x32_bf16 v[8:11], v[210:213], v[234:237], v[8:11]
	v_mfma_f32_16x16x32_bf16 v[4:7], v[194:197], v[242:245], v[4:7]
	v_mfma_f32_16x16x32_bf16 v[0:3], v[210:213], v[242:245], v[0:3]
	s_barrier
	s_add_i32 s14, 0, 0x18000
	v_add_u32_e32 v176, s14, v151
	s_add_i32 s15, 0, 0x1c000
	ds_read_b128 v[140:143], v176
	ds_read_b128 v[144:147], v176 offset:1024
	ds_read_b128 v[180:183], v176 offset:2048
	ds_read_b128 v[184:187], v176 offset:3072
	v_add_u32_e32 v176, s15, v151
	ds_read_b128 v[190:193], v176
	ds_read_b128 v[194:197], v176 offset:1024
	ds_read_b128 v[206:209], v176 offset:2048
	ds_read_b128 v[210:213], v176 offset:3072
	s_add_u32 s58, s58, 0x40000
	s_addc_u32 s59, s59, 0
	s_mov_b32 m0, s63
	v_lshl_add_u64 v[176:177], s[58:59], 0, v[134:135]
	ds_read_b128 v[214:217], v166 offset:32768
	ds_read_b128 v[218:221], v166 offset:33792
	ds_read_b128 v[222:225], v166 offset:34816
	ds_read_b128 v[226:229], v166 offset:35840
	ds_read_b128 v[230:233], v166 offset:36864
	ds_read_b128 v[234:237], v166 offset:37888
	ds_read_b128 v[238:241], v166 offset:38912
	ds_read_b128 v[242:245], v166 offset:39936
	global_load_lds_dwordx4 v[176:177], off
	v_lshl_add_u64 v[176:177], s[58:59], 0, v[130:131]
	s_mov_b32 m0, s64
	s_nop 0
	global_load_lds_dwordx4 v[176:177], off
	s_waitcnt vmcnt(8)
	s_waitcnt lgkmcnt(0)
	s_barrier
	v_mfma_f32_16x16x32_bf16 v[124:127], v[140:143], v[214:217], v[124:127]
	v_mfma_f32_16x16x32_bf16 v[120:123], v[180:183], v[214:217], v[120:123]
	v_mfma_f32_16x16x32_bf16 v[116:119], v[140:143], v[222:225], v[116:119]
	v_mfma_f32_16x16x32_bf16 v[112:115], v[180:183], v[222:225], v[112:115]
	v_mfma_f32_16x16x32_bf16 v[108:111], v[140:143], v[230:233], v[108:111]
	v_mfma_f32_16x16x32_bf16 v[104:107], v[180:183], v[230:233], v[104:107]
	v_mfma_f32_16x16x32_bf16 v[100:103], v[140:143], v[238:241], v[100:103]
	v_mfma_f32_16x16x32_bf16 v[96:99], v[180:183], v[238:241], v[96:99]
	v_mfma_f32_16x16x32_bf16 v[124:127], v[144:147], v[218:221], v[124:127]
	v_mfma_f32_16x16x32_bf16 v[120:123], v[184:187], v[218:221], v[120:123]
	v_mfma_f32_16x16x32_bf16 v[116:119], v[144:147], v[226:229], v[116:119]
	v_mfma_f32_16x16x32_bf16 v[112:115], v[184:187], v[226:229], v[112:115]
	v_mfma_f32_16x16x32_bf16 v[108:111], v[144:147], v[234:237], v[108:111]
	v_mfma_f32_16x16x32_bf16 v[104:107], v[184:187], v[234:237], v[104:107]
	v_mfma_f32_16x16x32_bf16 v[100:103], v[144:147], v[242:245], v[100:103]
	v_mfma_f32_16x16x32_bf16 v[96:99], v[184:187], v[242:245], v[96:99]
	v_mfma_f32_16x16x32_bf16 v[60:63], v[190:193], v[214:217], v[60:63]
	v_mfma_f32_16x16x32_bf16 v[56:59], v[206:209], v[214:217], v[56:59]
	v_mfma_f32_16x16x32_bf16 v[52:55], v[190:193], v[222:225], v[52:55]
	v_mfma_f32_16x16x32_bf16 v[48:51], v[206:209], v[222:225], v[48:51]
	v_mfma_f32_16x16x32_bf16 v[44:47], v[190:193], v[230:233], v[44:47]
	v_mfma_f32_16x16x32_bf16 v[40:43], v[206:209], v[230:233], v[40:43]
	v_mfma_f32_16x16x32_bf16 v[36:39], v[190:193], v[238:241], v[36:39]
	v_mfma_f32_16x16x32_bf16 v[32:35], v[206:209], v[238:241], v[32:35]
	v_mfma_f32_16x16x32_bf16 v[60:63], v[194:197], v[218:221], v[60:63]
	v_mfma_f32_16x16x32_bf16 v[56:59], v[210:213], v[218:221], v[56:59]
	v_mfma_f32_16x16x32_bf16 v[52:55], v[194:197], v[226:229], v[52:55]
	v_mfma_f32_16x16x32_bf16 v[48:51], v[210:213], v[226:229], v[48:51]
	v_mfma_f32_16x16x32_bf16 v[44:47], v[194:197], v[234:237], v[44:47]
	v_mfma_f32_16x16x32_bf16 v[40:43], v[210:213], v[234:237], v[40:43]
	v_mfma_f32_16x16x32_bf16 v[36:39], v[194:197], v[242:245], v[36:39]
	v_mfma_f32_16x16x32_bf16 v[32:35], v[210:213], v[242:245], v[32:35]
	s_barrier
; #define PG8_STAGE(bufoff, gbase, voff) do { _Pragma("unroll") for (int _i = 0; _i < 2; ++_i) \
;         __builtin_amdgcn_global_load_lds((const unsigned*)((const char*)(gbase) + (voff)[_i]), (LAS unsigned*)(lds + (bufoff) + ldsw + _i * 8192), 16, 0, 0); } while (0)
; #define PG8_LDA(dst, b, h) do { _Pragma("unroll") for (int m = 0; m < 4; ++m) _Pragma("unroll") for (int k = 0; k < 2; ++k) dst[m][k] = *(const LAS bf16x8*)(lds + PG8_SA(b, h) + aoff + m * 2048 + k * 1024); } while (0)
; #define PG8_LDB(dst, b, h) do { _Pragma("unroll") for (int n = 0; n < 2; ++n) _Pragma("unroll") for (int k = 0; k < 2; ++k) dst[n][k] = *(const LAS bf16x8*)(lds + PG8_SB(b, h) + boff + n * 2048 + k * 1024); } while (0)
; #define PG8_MMA(ai, bj, At, Bt) do { __builtin_amdgcn_s_setprio(1); _Pragma("unroll") for (int m = 0; m < 4; ++m) _Pragma("unroll") for (int n = 0; n < 2; ++n) _Pragma("unroll") for (int k = 0; k < 2; ++k) \
;         acc[ai][bj][m][n] = __builtin_amdgcn_mfma_f32_16x16x32_bf16(Bt[n][k], At[m][k], acc[ai][bj][m][n], 0, 0, 0); __builtin_amdgcn_s_setprio(0); } while (0)
; #define PG8_WAIT_V(n) asm volatile("s_waitcnt vmcnt(" #n ")" ::: "memory")
; #define PG8_WAIT_L(n) asm volatile("s_waitcnt lgkmcnt(" #n ")" ::: "memory")
; #define PG8_BAR __builtin_amdgcn_s_barrier()
; template <class Epi, class Sched>
; __device__ __forceinline__ void gemm_phase(const int tid, LAS unsigned char* lds, const int lda, const int ldb, const int K, const Sched& S, const Epi& E) {
;     ...
;         for (int t = 0; t < nt; t += 2) {
;             const bool last = (t == nt - 2);
;             const char* a1 = cA + (size_t)(t + 1) * kstep;
;             const char* a2 = last ? nA : cA + (size_t)(t + 2) * kstep; const char* b2 = last ? nB : cB + (size_t)(t + 2) * kstep;
;             const char* a3 = a2 + kstep; const char* b3 = b2 + kstep;
;             PG8_LDB(B0, 0, 0); PG8_LDB(B1, 0, 1); PG8_SCHED; PG8_LDA(At, 0, 0); PG8_STAGE(PG8_SA(1, 1), a1 + hstepA, voffA);
;             PG8_WAIT_V(8); PG8_WAIT_L(0); PG8_BAR; PG8_MMA(0, 0, At, B0); PG8_MMA(0, 1, At, B1); PG8_BAR; PG8_SCHED;
;     ...
;             PG8_LDA(At, 1, 1); PG8_STAGE(PG8_SB(1, 0), b3, voffB); PG8_STAGE(PG8_SB(1, 1), b3 + hstepB, voffB); PG8_STAGE(PG8_SA(1, 0), a3, voffA);
;             PG8_WAIT_V(8); PG8_WAIT_L(0); PG8_BAR; if (!cur.half) { PG8_MMA(1, 0, At, B0); PG8_MMA(1, 1, At, B1); } PG8_BAR; PG8_SCHED;
	s_add_i32 s14, s14, s60
	v_lshl_add_u64 v[176:177], v[246:247], 0, s[6:7]
	s_mov_b32 m0, s14
	ds_read_b128 v[214:217], v166 offset:49152
	ds_read_b128 v[218:221], v166 offset:50176
	ds_read_b128 v[222:225], v166 offset:51200
	ds_read_b128 v[226:229], v166 offset:52224
	ds_read_b128 v[230:233], v166 offset:53248
	ds_read_b128 v[234:237], v166 offset:54272
	ds_read_b128 v[238:241], v166 offset:55296
	ds_read_b128 v[242:245], v166 offset:56320
	global_load_lds_dwordx4 v[176:177], off
	s_add_i32 m0, s14, 0x2000
	s_add_u32 s56, s56, 0x40080
	v_lshl_add_u64 v[176:177], v[248:249], 0, s[6:7]
	s_addc_u32 s57, s57, 0
	s_add_i32 s14, s15, s60
	global_load_lds_dwordx4 v[176:177], off
	v_lshl_add_u64 v[176:177], s[56:57], 0, v[132:133]
	s_mov_b32 m0, s14
	s_nop 0
	global_load_lds_dwordx4 v[176:177], off
	v_lshl_add_u64 v[176:177], s[56:57], 0, v[128:129]
	s_add_i32 m0, s14, 0x2000
	s_nop 0
	global_load_lds_dwordx4 v[176:177], off
	v_lshl_add_u64 v[176:177], v[250:251], 0, s[6:7]
	s_mov_b32 m0, s65
	s_nop 0
	global_load_lds_dwordx4 v[176:177], off
	v_lshl_add_u64 v[176:177], v[252:253], 0, s[6:7]
	s_mov_b32 m0, s66
	s_nop 0
	global_load_lds_dwordx4 v[176:177], off
	s_waitcnt vmcnt(8)
	s_waitcnt lgkmcnt(0)
	s_barrier
	v_mfma_f32_16x16x32_bf16 v[92:95], v[140:143], v[214:217], v[92:95]
	v_mfma_f32_16x16x32_bf16 v[88:91], v[180:183], v[214:217], v[88:91]
	v_mfma_f32_16x16x32_bf16 v[84:87], v[140:143], v[222:225], v[84:87]
	v_mfma_f32_16x16x32_bf16 v[80:83], v[180:183], v[222:225], v[80:83]
	v_mfma_f32_16x16x32_bf16 v[76:79], v[140:143], v[230:233], v[76:79]
	v_mfma_f32_16x16x32_bf16 v[72:75], v[180:183], v[230:233], v[72:75]
	v_mfma_f32_16x16x32_bf16 v[68:71], v[140:143], v[238:241], v[68:71]
	v_mfma_f32_16x16x32_bf16 v[64:67], v[180:183], v[238:241], v[64:67]
	v_mfma_f32_16x16x32_bf16 v[92:95], v[144:147], v[218:221], v[92:95]
	v_mfma_f32_16x16x32_bf16 v[88:91], v[184:187], v[218:221], v[88:91]
	v_mfma_f32_16x16x32_bf16 v[84:87], v[144:147], v[226:229], v[84:87]
	v_mfma_f32_16x16x32_bf16 v[80:83], v[184:187], v[226:229], v[80:83]
	v_mfma_f32_16x16x32_bf16 v[76:79], v[144:147], v[234:237], v[76:79]
	v_mfma_f32_16x16x32_bf16 v[72:75], v[184:187], v[234:237], v[72:75]
	v_mfma_f32_16x16x32_bf16 v[68:71], v[144:147], v[242:245], v[68:71]
	v_mfma_f32_16x16x32_bf16 v[64:67], v[184:187], v[242:245], v[64:67]
	v_mfma_f32_16x16x32_bf16 v[28:31], v[190:193], v[214:217], v[28:31]
	v_mfma_f32_16x16x32_bf16 v[24:27], v[206:209], v[214:217], v[24:27]
	v_mfma_f32_16x16x32_bf16 v[20:23], v[190:193], v[222:225], v[20:23]
	v_mfma_f32_16x16x32_bf16 v[16:19], v[206:209], v[222:225], v[16:19]
	v_mfma_f32_16x16x32_bf16 v[12:15], v[190:193], v[230:233], v[12:15]
	v_mfma_f32_16x16x32_bf16 v[8:11], v[206:209], v[230:233], v[8:11]
	v_mfma_f32_16x16x32_bf16 v[4:7], v[190:193], v[238:241], v[4:7]
	v_mfma_f32_16x16x32_bf16 v[0:3], v[206:209], v[238:241], v[0:3]
	v_mfma_f32_16x16x32_bf16 v[28:31], v[194:197], v[218:221], v[28:31]
	v_mfma_f32_16x16x32_bf16 v[24:27], v[210:213], v[218:221], v[24:27]
	v_mfma_f32_16x16x32_bf16 v[20:23], v[194:197], v[226:229], v[20:23]
	v_mfma_f32_16x16x32_bf16 v[16:19], v[210:213], v[226:229], v[16:19]
	v_mfma_f32_16x16x32_bf16 v[12:15], v[194:197], v[234:237], v[12:15]
	v_mfma_f32_16x16x32_bf16 v[8:11], v[210:213], v[234:237], v[8:11]
	v_mfma_f32_16x16x32_bf16 v[4:7], v[194:197], v[242:245], v[4:7]
	v_mfma_f32_16x16x32_bf16 v[0:3], v[210:213], v[242:245], v[0:3]
	s_barrier
	s_add_u32 s54, s54, 0x100
	s_addc_u32 s55, s55, 0
	s_add_u32 s23, s23, 0x100
	s_addc_u32 s27, s27, 0
	s_cmp_ge_i32 s69, s13
	s_mov_b32 s45, s69
	s_cbranch_scc1 .Lkexit_215
.LBB0_215:
	s_add_i32 s69, s45, 2
	s_add_u32 s14, s54, 0xfffc0080
	s_addc_u32 s15, s55, -1
	s_add_i32 s24, 0, 0x10000
	s_cmp_eq_u32 s68, s45
	s_cselect_b32 s59, s53, s15
	s_cselect_b32 s58, s52, s14
	v_add_u32_e32 v176, s24, v151
	s_cselect_b32 s57, s3, s27
	s_cselect_b32 s56, s2, s23
	s_add_i32 s14, 0, 0x14000
	ds_read_b128 v[140:143], v176
	ds_read_b128 v[144:147], v176 offset:1024
	ds_read_b128 v[180:183], v176 offset:2048
	ds_read_b128 v[184:187], v176 offset:3072
	v_add_u32_e32 v176, s14, v151
	ds_read_b128 v[190:193], v176
	ds_read_b128 v[194:197], v176 offset:1024
	ds_read_b128 v[206:209], v176 offset:2048
	ds_read_b128 v[210:213], v176 offset:3072
	v_lshl_add_u64 v[246:247], s[54:55], 0, v[136:137]
	s_add_i32 m0, s51, 0xc000
	ds_read_b128 v[214:217], v166
	ds_read_b128 v[218:221], v166 offset:1024
	ds_read_b128 v[222:225], v166 offset:2048
	ds_read_b128 v[226:229], v166 offset:3072
	ds_read_b128 v[230:233], v166 offset:4096
	ds_read_b128 v[234:237], v166 offset:5120
	ds_read_b128 v[238:241], v166 offset:6144
	ds_read_b128 v[242:245], v166 offset:7168
	global_load_lds_dwordx4 v[246:247], off
	v_lshl_add_u64 v[246:247], s[54:55], 0, v[138:139]
	s_add_i32 m0, s51, 0xe000
	s_nop 0
	global_load_lds_dwordx4 v[246:247], off
	s_waitcnt vmcnt(8)
	s_waitcnt lgkmcnt(0)
	s_barrier
; #define PG8_STAGE(bufoff, gbase, voff) do { _Pragma("unroll") for (int _i = 0; _i < 2; ++_i) \
;         __builtin_amdgcn_global_load_lds((const unsigned*)((const char*)(gbase) + (voff)[_i]), (LAS unsigned*)(lds + (bufoff) + ldsw + _i * 8192), 16, 0, 0); } while (0)
; #define PG8_LDA(dst, b, h) do { _Pragma("unroll") for (int m = 0; m < 4; ++m) _Pragma("unroll") for (int k = 0; k < 2; ++k) dst[m][k] = *(const LAS bf16x8*)(lds + PG8_SA(b, h) + aoff + m * 2048 + k * 1024); } while (0)
; #define PG8_LDB(dst, b, h) do { _Pragma("unroll") for (int n = 0; n < 2; ++n) _Pragma("unroll") for (int k = 0; k < 2; ++k) dst[n][k] = *(const LAS bf16x8*)(lds + PG8_SB(b, h) + boff + n * 2048 + k * 1024); } while (0)
; #define PG8_MMA(ai, bj, At, Bt) do { __builtin_amdgcn_s_setprio(1); _Pragma("unroll") for (int m = 0; m < 4; ++m) _Pragma("unroll") for (int n = 0; n < 2; ++n) _Pragma("unroll") for (int k = 0; k < 2; ++k) \
;         acc[ai][bj][m][n] = __builtin_amdgcn_mfma_f32_16x16x32_bf16(Bt[n][k], At[m][k], acc[ai][bj][m][n], 0, 0, 0); __builtin_amdgcn_s_setprio(0); } while (0)
; #define PG8_WAIT_V(n) asm volatile("s_waitcnt vmcnt(" #n ")" ::: "memory")
; #define PG8_WAIT_L(n) asm volatile("s_waitcnt lgkmcnt(" #n ")" ::: "memory")
; #define PG8_BAR __builtin_amdgcn_s_barrier()
; #define PG8_SCHED __builtin_amdgcn_sched_barrier(0)
; template <class Epi, class Sched>
; __device__ __forceinline__ void gemm_phase(const int tid, LAS unsigned char* lds, const int lda, const int ldb, const int K, const Sched& S, const Epi& E) {
;     ...
;             PG8_WAIT_V(8); PG8_WAIT_L(0); PG8_BAR; PG8_MMA(0, 0, At, B0); PG8_MMA(0, 1, At, B1); PG8_BAR; PG8_SCHED;
;             PG8_LDA(At, 0, 1); PG8_STAGE(PG8_SB(0, 0), b2, voffB); PG8_STAGE(PG8_SB(0, 1), b2 + hstepB, voffB); PG8_STAGE(PG8_SA(0, 0), a2, voffA);
;             PG8_WAIT_V(8); PG8_WAIT_L(0); PG8_BAR; if (!cur.half) { PG8_MMA(1, 0, At, B0); PG8_MMA(1, 1, At, B1); } PG8_BAR; PG8_SCHED;
;             PG8_LDB(B0, 1, 0); PG8_LDB(B1, 1, 1); PG8_SCHED; PG8_LDA(At, 1, 0); PG8_STAGE(PG8_SA(0, 1), a2 + hstepA, voffA);
;             PG8_WAIT_V(8); PG8_WAIT_L(0); PG8_BAR; PG8_MMA(0, 0, At, B0); PG8_MMA(0, 1, At, B1); PG8_BAR; PG8_SCHED;
	v_mfma_f32_16x16x32_bf16 v[124:127], v[140:143], v[214:217], v[124:127]
	v_mfma_f32_16x16x32_bf16 v[120:123], v[180:183], v[214:217], v[120:123]
	v_mfma_f32_16x16x32_bf16 v[116:119], v[140:143], v[222:225], v[116:119]
	v_mfma_f32_16x16x32_bf16 v[112:115], v[180:183], v[222:225], v[112:115]
	v_mfma_f32_16x16x32_bf16 v[108:111], v[140:143], v[230:233], v[108:111]
	v_mfma_f32_16x16x32_bf16 v[104:107], v[180:183], v[230:233], v[104:107]
	v_mfma_f32_16x16x32_bf16 v[100:103], v[140:143], v[238:241], v[100:103]
	v_mfma_f32_16x16x32_bf16 v[96:99], v[180:183], v[238:241], v[96:99]
	v_mfma_f32_16x16x32_bf16 v[124:127], v[144:147], v[218:221], v[124:127]
	v_mfma_f32_16x16x32_bf16 v[120:123], v[184:187], v[218:221], v[120:123]
	v_mfma_f32_16x16x32_bf16 v[116:119], v[144:147], v[226:229], v[116:119]
	v_mfma_f32_16x16x32_bf16 v[112:115], v[184:187], v[226:229], v[112:115]
	v_mfma_f32_16x16x32_bf16 v[108:111], v[144:147], v[234:237], v[108:111]
	v_mfma_f32_16x16x32_bf16 v[104:107], v[184:187], v[234:237], v[104:107]
	v_mfma_f32_16x16x32_bf16 v[100:103], v[144:147], v[242:245], v[100:103]
	v_mfma_f32_16x16x32_bf16 v[96:99], v[184:187], v[242:245], v[96:99]
	v_mfma_f32_16x16x32_bf16 v[60:63], v[190:193], v[214:217], v[60:63]
	v_mfma_f32_16x16x32_bf16 v[56:59], v[206:209], v[214:217], v[56:59]
	v_mfma_f32_16x16x32_bf16 v[52:55], v[190:193], v[222:225], v[52:55]
	v_mfma_f32_16x16x32_bf16 v[48:51], v[206:209], v[222:225], v[48:51]
	v_mfma_f32_16x16x32_bf16 v[44:47], v[190:193], v[230:233], v[44:47]
	v_mfma_f32_16x16x32_bf16 v[40:43], v[206:209], v[230:233], v[40:43]
	v_mfma_f32_16x16x32_bf16 v[36:39], v[190:193], v[238:241], v[36:39]
	v_mfma_f32_16x16x32_bf16 v[32:35], v[206:209], v[238:241], v[32:35]
	v_mfma_f32_16x16x32_bf16 v[60:63], v[194:197], v[218:221], v[60:63]
	v_mfma_f32_16x16x32_bf16 v[56:59], v[210:213], v[218:221], v[56:59]
	v_mfma_f32_16x16x32_bf16 v[52:55], v[194:197], v[226:229], v[52:55]
	v_mfma_f32_16x16x32_bf16 v[48:51], v[210:213], v[226:229], v[48:51]
	v_mfma_f32_16x16x32_bf16 v[44:47], v[194:197], v[234:237], v[44:47]
	v_mfma_f32_16x16x32_bf16 v[40:43], v[210:213], v[234:237], v[40:43]
	v_mfma_f32_16x16x32_bf16 v[36:39], v[194:197], v[242:245], v[36:39]
	v_mfma_f32_16x16x32_bf16 v[32:35], v[210:213], v[242:245], v[32:35]
	s_barrier
	s_add_i32 s15, s24, s60
	v_lshl_add_u64 v[246:247], s[56:57], 0, v[132:133]
	s_mov_b32 m0, s15
	ds_read_b128 v[214:217], v166 offset:16384
	ds_read_b128 v[218:221], v166 offset:17408
	ds_read_b128 v[222:225], v166 offset:18432
	ds_read_b128 v[226:229], v166 offset:19456
	ds_read_b128 v[230:233], v166 offset:20480
	ds_read_b128 v[234:237], v166 offset:21504
	ds_read_b128 v[238:241], v166 offset:22528
	ds_read_b128 v[242:245], v166 offset:23552
	global_load_lds_dwordx4 v[246:247], off
	s_add_i32 m0, s15, 0x2000
	s_add_u32 s70, s56, 0x40000
	v_lshl_add_u64 v[248:249], s[56:57], 0, v[128:129]
	s_addc_u32 s71, s57, 0
	s_add_i32 s14, s14, s60
	global_load_lds_dwordx4 v[248:249], off
	v_lshl_add_u64 v[250:251], s[70:71], 0, v[132:133]
	s_mov_b32 m0, s14
	v_lshl_add_u64 v[252:253], s[58:59], 0, v[130:131]
	global_load_lds_dwordx4 v[250:251], off
	v_lshl_add_u64 v[250:251], s[70:71], 0, v[128:129]
	s_add_i32 m0, s14, 0x2000
	s_nop 0
	global_load_lds_dwordx4 v[250:251], off
	v_lshl_add_u64 v[250:251], s[58:59], 0, v[134:135]
	s_mov_b32 m0, s51
	s_nop 0
	global_load_lds_dwordx4 v[250:251], off
	s_mov_b32 m0, s62
	s_nop 0
	global_load_lds_dwordx4 v[252:253], off
	s_waitcnt vmcnt(8)
	s_waitcnt lgkmcnt(0)
	s_barrier
	v_mfma_f32_16x16x32_bf16 v[92:95], v[140:143], v[214:217], v[92:95]
	v_mfma_f32_16x16x32_bf16 v[88:91], v[180:183], v[214:217], v[88:91]
	v_mfma_f32_16x16x32_bf16 v[84:87], v[140:143], v[222:225], v[84:87]
	v_mfma_f32_16x16x32_bf16 v[80:83], v[180:183], v[222:225], v[80:83]
	v_mfma_f32_16x16x32_bf16 v[76:79], v[140:143], v[230:233], v[76:79]
	v_mfma_f32_16x16x32_bf16 v[72:75], v[180:183], v[230:233], v[72:75]
	v_mfma_f32_16x16x32_bf16 v[68:71], v[140:143], v[238:241], v[68:71]
	v_mfma_f32_16x16x32_bf16 v[64:67], v[180:183], v[238:241], v[64:67]
	v_mfma_f32_16x16x32_bf16 v[92:95], v[144:147], v[218:221], v[92:95]
	v_mfma_f32_16x16x32_bf16 v[88:91], v[184:187], v[218:221], v[88:91]
	v_mfma_f32_16x16x32_bf16 v[84:87], v[144:147], v[226:229], v[84:87]
	v_mfma_f32_16x16x32_bf16 v[80:83], v[184:187], v[226:229], v[80:83]
	v_mfma_f32_16x16x32_bf16 v[76:79], v[144:147], v[234:237], v[76:79]
	v_mfma_f32_16x16x32_bf16 v[72:75], v[184:187], v[234:237], v[72:75]
	v_mfma_f32_16x16x32_bf16 v[68:71], v[144:147], v[242:245], v[68:71]
	v_mfma_f32_16x16x32_bf16 v[64:67], v[184:187], v[242:245], v[64:67]
	v_mfma_f32_16x16x32_bf16 v[28:31], v[190:193], v[214:217], v[28:31]
	v_mfma_f32_16x16x32_bf16 v[24:27], v[206:209], v[214:217], v[24:27]
	v_mfma_f32_16x16x32_bf16 v[20:23], v[190:193], v[222:225], v[20:23]
	v_mfma_f32_16x16x32_bf16 v[16:19], v[206:209], v[222:225], v[16:19]
	v_mfma_f32_16x16x32_bf16 v[12:15], v[190:193], v[230:233], v[12:15]
	v_mfma_f32_16x16x32_bf16 v[8:11], v[206:209], v[230:233], v[8:11]
	v_mfma_f32_16x16x32_bf16 v[4:7], v[190:193], v[238:241], v[4:7]
	v_mfma_f32_16x16x32_bf16 v[0:3], v[206:209], v[238:241], v[0:3]
	v_mfma_f32_16x16x32_bf16 v[28:31], v[194:197], v[218:221], v[28:31]
	v_mfma_f32_16x16x32_bf16 v[24:27], v[210:213], v[218:221], v[24:27]
	v_mfma_f32_16x16x32_bf16 v[20:23], v[194:197], v[226:229], v[20:23]
	v_mfma_f32_16x16x32_bf16 v[16:19], v[210:213], v[226:229], v[16:19]
	v_mfma_f32_16x16x32_bf16 v[12:15], v[194:197], v[234:237], v[12:15]
	v_mfma_f32_16x16x32_bf16 v[8:11], v[210:213], v[234:237], v[8:11]
	v_mfma_f32_16x16x32_bf16 v[4:7], v[194:197], v[242:245], v[4:7]
	v_mfma_f32_16x16x32_bf16 v[0:3], v[210:213], v[242:245], v[0:3]
	s_barrier
; #define PG8_STAGE(bufoff, gbase, voff) do { _Pragma("unroll") for (int _i = 0; _i < 2; ++_i) \
;         __builtin_amdgcn_global_load_lds((const unsigned*)((const char*)(gbase) + (voff)[_i]), (LAS unsigned*)(lds + (bufoff) + ldsw + _i * 8192), 16, 0, 0); } while (0)
; #define PG8_LDA(dst, b, h) do { _Pragma("unroll") for (int m = 0; m < 4; ++m) _Pragma("unroll") for (int k = 0; k < 2; ++k) dst[m][k] = *(const LAS bf16x8*)(lds + PG8_SA(b, h) + aoff + m * 2048 + k * 1024); } while (0)
; #define PG8_LDB(dst, b, h) do { _Pragma("unroll") for (int n = 0; n < 2; ++n) _Pragma("unroll") for (int k = 0; k < 2; ++k) dst[n][k] = *(const LAS bf16x8*)(lds + PG8_SB(b, h) + boff + n * 2048 + k * 1024); } while (0)
; #define PG8_MMA(ai, bj, At, Bt) do { __builtin_amdgcn_s_setprio(1); _Pragma("unroll") for (int m = 0; m < 4; ++m) _Pragma("unroll") for (int n = 0; n < 2; ++n) _Pragma("unroll") for (int k = 0; k < 2; ++k) \
;         acc[ai][bj][m][n] = __builtin_amdgcn_mfma_f32_16x16x32_bf16(Bt[n][k], At[m][k], acc[ai][bj][m][n], 0, 0, 0); __builtin_amdgcn_s_setprio(0); } while (0)
; #define PG8_WAIT_V(n) asm volatile("s_waitcnt vmcnt(" #n ")" ::: "memory")
; #define PG8_WAIT_L(n) asm volatile("s_waitcnt lgkmcnt(" #n ")" ::: "memory")
; #define PG8_BAR __builtin_amdgcn_s_barrier()
; #define PG8_SCHED __builtin_amdgcn_sched_barrier(0)
; template <class Epi, class Sched>
; __device__ __forceinline__ void gemm_phase(const int tid, LAS unsigned char* lds, const int lda, const int ldb, const int K, const Sched& S, const Epi& E) {
;     ...
;             PG8_LDB(B0, 1, 0); PG8_LDB(B1, 1, 1); PG8_SCHED; PG8_LDA(At, 1, 0); PG8_STAGE(PG8_SA(0, 1), a2 + hstepA, voffA);
;             PG8_WAIT_V(8); PG8_WAIT_L(0); PG8_BAR; PG8_MMA(0, 0, At, B0); PG8_MMA(0, 1, At, B1); PG8_BAR; PG8_SCHED;
;             PG8_LDA(At, 1, 1); PG8_STAGE(PG8_SB(1, 0), b3, voffB); PG8_STAGE(PG8_SB(1, 1), b3 + hstepB, voffB); PG8_STAGE(PG8_SA(1, 0), a3, voffA);
;             PG8_WAIT_V(8); PG8_WAIT_L(0); PG8_BAR; if (!cur.half) { PG8_MMA(1, 0, At, B0); PG8_MMA(1, 1, At, B1); } PG8_BAR; PG8_SCHED;
	s_add_i32 s14, 0, 0x18000
	v_add_u32_e32 v176, s14, v151
	s_add_i32 s15, 0, 0x1c000
	ds_read_b128 v[140:143], v176
	ds_read_b128 v[144:147], v176 offset:1024
	ds_read_b128 v[180:183], v176 offset:2048
	ds_read_b128 v[184:187], v176 offset:3072
	v_add_u32_e32 v176, s15, v151
	ds_read_b128 v[190:193], v176
	ds_read_b128 v[194:197], v176 offset:1024
	ds_read_b128 v[206:209], v176 offset:2048
	ds_read_b128 v[210:213], v176 offset:3072
	s_add_u32 s58, s58, 0x40000
	s_addc_u32 s59, s59, 0
	s_mov_b32 m0, s63
	v_lshl_add_u64 v[176:177], s[58:59], 0, v[134:135]
	ds_read_b128 v[214:217], v166 offset:32768
	ds_read_b128 v[218:221], v166 offset:33792
	ds_read_b128 v[222:225], v166 offset:34816
	ds_read_b128 v[226:229], v166 offset:35840
	ds_read_b128 v[230:233], v166 offset:36864
	ds_read_b128 v[234:237], v166 offset:37888
	ds_read_b128 v[238:241], v166 offset:38912
	ds_read_b128 v[242:245], v166 offset:39936
	global_load_lds_dwordx4 v[176:177], off
	v_lshl_add_u64 v[176:177], s[58:59], 0, v[130:131]
	s_mov_b32 m0, s64
	s_nop 0
	global_load_lds_dwordx4 v[176:177], off
	s_waitcnt vmcnt(8)
	s_waitcnt lgkmcnt(0)
	s_barrier
	v_mfma_f32_16x16x32_bf16 v[124:127], v[140:143], v[214:217], v[124:127]
	v_mfma_f32_16x16x32_bf16 v[120:123], v[180:183], v[214:217], v[120:123]
	v_mfma_f32_16x16x32_bf16 v[116:119], v[140:143], v[222:225], v[116:119]
	v_mfma_f32_16x16x32_bf16 v[112:115], v[180:183], v[222:225], v[112:115]
	v_mfma_f32_16x16x32_bf16 v[108:111], v[140:143], v[230:233], v[108:111]
	v_mfma_f32_16x16x32_bf16 v[104:107], v[180:183], v[230:233], v[104:107]
	v_mfma_f32_16x16x32_bf16 v[100:103], v[140:143], v[238:241], v[100:103]
	v_mfma_f32_16x16x32_bf16 v[96:99], v[180:183], v[238:241], v[96:99]
	v_mfma_f32_16x16x32_bf16 v[124:127], v[144:147], v[218:221], v[124:127]
	v_mfma_f32_16x16x32_bf16 v[120:123], v[184:187], v[218:221], v[120:123]
	v_mfma_f32_16x16x32_bf16 v[116:119], v[144:147], v[226:229], v[116:119]
	v_mfma_f32_16x16x32_bf16 v[112:115], v[184:187], v[226:229], v[112:115]
	v_mfma_f32_16x16x32_bf16 v[108:111], v[144:147], v[234:237], v[108:111]
	v_mfma_f32_16x16x32_bf16 v[104:107], v[184:187], v[234:237], v[104:107]
	v_mfma_f32_16x16x32_bf16 v[100:103], v[144:147], v[242:245], v[100:103]
	v_mfma_f32_16x16x32_bf16 v[96:99], v[184:187], v[242:245], v[96:99]
	v_mfma_f32_16x16x32_bf16 v[60:63], v[190:193], v[214:217], v[60:63]
	v_mfma_f32_16x16x32_bf16 v[56:59], v[206:209], v[214:217], v[56:59]
	v_mfma_f32_16x16x32_bf16 v[52:55], v[190:193], v[222:225], v[52:55]
	v_mfma_f32_16x16x32_bf16 v[48:51], v[206:209], v[222:225], v[48:51]
	v_mfma_f32_16x16x32_bf16 v[44:47], v[190:193], v[230:233], v[44:47]
	v_mfma_f32_16x16x32_bf16 v[40:43], v[206:209], v[230:233], v[40:43]
	v_mfma_f32_16x16x32_bf16 v[36:39], v[190:193], v[238:241], v[36:39]
	v_mfma_f32_16x16x32_bf16 v[32:35], v[206:209], v[238:241], v[32:35]
	v_mfma_f32_16x16x32_bf16 v[60:63], v[194:197], v[218:221], v[60:63]
	v_mfma_f32_16x16x32_bf16 v[56:59], v[210:213], v[218:221], v[56:59]
	v_mfma_f32_16x16x32_bf16 v[52:55], v[194:197], v[226:229], v[52:55]
	v_mfma_f32_16x16x32_bf16 v[48:51], v[210:213], v[226:229], v[48:51]
	v_mfma_f32_16x16x32_bf16 v[44:47], v[194:197], v[234:237], v[44:47]
	v_mfma_f32_16x16x32_bf16 v[40:43], v[210:213], v[234:237], v[40:43]
	v_mfma_f32_16x16x32_bf16 v[36:39], v[194:197], v[242:245], v[36:39]
	v_mfma_f32_16x16x32_bf16 v[32:35], v[210:213], v[242:245], v[32:35]
	s_barrier
	s_add_i32 s14, s14, s60
	v_lshl_add_u64 v[176:177], v[246:247], 0, s[6:7]
	s_mov_b32 m0, s14
	ds_read_b128 v[214:217], v166 offset:49152
	ds_read_b128 v[218:221], v166 offset:50176
	ds_read_b128 v[222:225], v166 offset:51200
	ds_read_b128 v[226:229], v166 offset:52224
	ds_read_b128 v[230:233], v166 offset:53248
	ds_read_b128 v[234:237], v166 offset:54272
	ds_read_b128 v[238:241], v166 offset:55296
	ds_read_b128 v[242:245], v166 offset:56320
	global_load_lds_dwordx4 v[176:177], off
	s_add_i32 m0, s14, 0x2000
	s_add_u32 s56, s56, 0x40080
	v_lshl_add_u64 v[176:177], v[248:249], 0, s[6:7]
	s_addc_u32 s57, s57, 0
	s_add_i32 s14, s15, s60
	global_load_lds_dwordx4 v[176:177], off
	v_lshl_add_u64 v[176:177], s[56:57], 0, v[132:133]
	s_mov_b32 m0, s14
	s_nop 0
	global_load_lds_dwordx4 v[176:177], off
	v_lshl_add_u64 v[176:177], s[56:57], 0, v[128:129]
	s_add_i32 m0, s14, 0x2000
	s_nop 0
	global_load_lds_dwordx4 v[176:177], off
	v_lshl_add_u64 v[176:177], v[250:251], 0, s[6:7]
	s_mov_b32 m0, s65
	s_nop 0
	global_load_lds_dwordx4 v[176:177], off
	v_lshl_add_u64 v[176:177], v[252:253], 0, s[6:7]
	s_mov_b32 m0, s66
	s_nop 0
	global_load_lds_dwordx4 v[176:177], off
	s_waitcnt vmcnt(8)
	s_waitcnt lgkmcnt(0)
	s_barrier
	v_mfma_f32_16x16x32_bf16 v[92:95], v[140:143], v[214:217], v[92:95]
	v_mfma_f32_16x16x32_bf16 v[88:91], v[180:183], v[214:217], v[88:91]
	v_mfma_f32_16x16x32_bf16 v[84:87], v[140:143], v[222:225], v[84:87]
	v_mfma_f32_16x16x32_bf16 v[80:83], v[180:183], v[222:225], v[80:83]
	v_mfma_f32_16x16x32_bf16 v[76:79], v[140:143], v[230:233], v[76:79]
	v_mfma_f32_16x16x32_bf16 v[72:75], v[180:183], v[230:233], v[72:75]
	v_mfma_f32_16x16x32_bf16 v[68:71], v[140:143], v[238:241], v[68:71]
	v_mfma_f32_16x16x32_bf16 v[64:67], v[180:183], v[238:241], v[64:67]
	v_mfma_f32_16x16x32_bf16 v[92:95], v[144:147], v[218:221], v[92:95]
	v_mfma_f32_16x16x32_bf16 v[88:91], v[184:187], v[218:221], v[88:91]
	v_mfma_f32_16x16x32_bf16 v[84:87], v[144:147], v[226:229], v[84:87]
	v_mfma_f32_16x16x32_bf16 v[80:83], v[184:187], v[226:229], v[80:83]
	v_mfma_f32_16x16x32_bf16 v[76:79], v[144:147], v[234:237], v[76:79]
	v_mfma_f32_16x16x32_bf16 v[72:75], v[184:187], v[234:237], v[72:75]
	v_mfma_f32_16x16x32_bf16 v[68:71], v[144:147], v[242:245], v[68:71]
	v_mfma_f32_16x16x32_bf16 v[64:67], v[184:187], v[242:245], v[64:67]
	v_mfma_f32_16x16x32_bf16 v[28:31], v[190:193], v[214:217], v[28:31]
	v_mfma_f32_16x16x32_bf16 v[24:27], v[206:209], v[214:217], v[24:27]
	v_mfma_f32_16x16x32_bf16 v[20:23], v[190:193], v[222:225], v[20:23]
	v_mfma_f32_16x16x32_bf16 v[16:19], v[206:209], v[222:225], v[16:19]
	v_mfma_f32_16x16x32_bf16 v[12:15], v[190:193], v[230:233], v[12:15]
	v_mfma_f32_16x16x32_bf16 v[8:11], v[206:209], v[230:233], v[8:11]
	v_mfma_f32_16x16x32_bf16 v[4:7], v[190:193], v[238:241], v[4:7]
	v_mfma_f32_16x16x32_bf16 v[0:3], v[206:209], v[238:241], v[0:3]
	v_mfma_f32_16x16x32_bf16 v[28:31], v[194:197], v[218:221], v[28:31]
	v_mfma_f32_16x16x32_bf16 v[24:27], v[210:213], v[218:221], v[24:27]
	v_mfma_f32_16x16x32_bf16 v[20:23], v[194:197], v[226:229], v[20:23]
	v_mfma_f32_16x16x32_bf16 v[16:19], v[210:213], v[226:229], v[16:19]
	v_mfma_f32_16x16x32_bf16 v[12:15], v[194:197], v[234:237], v[12:15]
	v_mfma_f32_16x16x32_bf16 v[8:11], v[210:213], v[234:237], v[8:11]
	v_mfma_f32_16x16x32_bf16 v[4:7], v[194:197], v[242:245], v[4:7]
	v_mfma_f32_16x16x32_bf16 v[0:3], v[210:213], v[242:245], v[0:3]
	s_barrier
	s_add_u32 s54, s54, 0x100
	s_addc_u32 s55, s55, 0
	s_add_u32 s23, s23, 0x100
	s_addc_u32 s27, s27, 0
	s_cmp_ge_i32 s69, s13
	s_mov_b32 s45, s69
	s_cbranch_scc0 .LBB0_215

; #define PG8_STAGE(bufoff, gbase, voff) do { _Pragma("unroll") for (int _i = 0; _i < 2; ++_i) \
;         __builtin_amdgcn_global_load_lds((const unsigned*)((const char*)(gbase) + (voff)[_i]), (LAS unsigned*)(lds + (bufoff) + ldsw + _i * 8192), 16, 0, 0); } while (0)
; #define PG8_LDA(dst, b, h) do { _Pragma("unroll") for (int m = 0; m < 4; ++m) _Pragma("unroll") for (int k = 0; k < 2; ++k) dst[m][k] = *(const LAS bf16x8*)(lds + PG8_SA(b, h) + aoff + m * 2048 + k * 1024); } while (0)
; #define PG8_LDB(dst, b, h) do { _Pragma("unroll") for (int n = 0; n < 2; ++n) _Pragma("unroll") for (int k = 0; k < 2; ++k) dst[n][k] = *(const LAS bf16x8*)(lds + PG8_SB(b, h) + boff + n * 2048 + k * 1024); } while (0)
; #define PG8_MMA(ai, bj, At, Bt) do { __builtin_amdgcn_s_setprio(1); _Pragma("unroll") for (int m = 0; m < 4; ++m) _Pragma("unroll") for (int n = 0; n < 2; ++n) _Pragma("unroll") for (int k = 0; k < 2; ++k) \
;         acc[ai][bj][m][n] = __builtin_amdgcn_mfma_f32_16x16x32_bf16(Bt[n][k], At[m][k], acc[ai][bj][m][n], 0, 0, 0); __builtin_amdgcn_s_setprio(0); } while (0)
; #define PG8_WAIT_V(n) asm volatile("s_waitcnt vmcnt(" #n ")" ::: "memory")
; #define PG8_WAIT_L(n) asm volatile("s_waitcnt lgkmcnt(" #n ")" ::: "memory")
; #define PG8_BAR __builtin_amdgcn_s_barrier()
; template <class Epi, class Sched>
; __device__ __forceinline__ void gemm_phase(const int tid, LAS unsigned char* lds, const int lda, const int ldb, const int K, const Sched& S, const Epi& E) {
;     ...
;         for (int t = 0; t < nt; t += 2) {
;             const bool last = (t == nt - 2);
;             const char* a1 = cA + (size_t)(t + 1) * kstep;
;             const char* a2 = last ? nA : cA + (size_t)(t + 2) * kstep; const char* b2 = last ? nB : cB + (size_t)(t + 2) * kstep;
;             const char* a3 = a2 + kstep; const char* b3 = b2 + kstep;
;             PG8_LDB(B0, 0, 0); PG8_LDB(B1, 0, 1); PG8_SCHED; PG8_LDA(At, 0, 0); PG8_STAGE(PG8_SA(1, 1), a1 + hstepA, voffA);
;             PG8_WAIT_V(8); PG8_WAIT_L(0); PG8_BAR; PG8_MMA(0, 0, At, B0); PG8_MMA(0, 1, At, B1); PG8_BAR; PG8_SCHED;
;             PG8_LDA(At, 0, 1); PG8_STAGE(PG8_SB(0, 0), b2, voffB); PG8_STAGE(PG8_SB(0, 1), b2 + hstepB, voffB); PG8_STAGE(PG8_SA(0, 0), a2, voffA);
;             PG8_WAIT_V(8); PG8_WAIT_L(0); PG8_BAR; if (!cur.half) { PG8_MMA(1, 0, At, B0); PG8_MMA(1, 1, At, B1); } PG8_BAR; PG8_SCHED;
.LBB0_309:
	s_andn2_b64 vcc, exec, s[56:57]
	s_cbranch_vccnz .LBB0_312
	s_add_u32 s66, s66, 0x40080
	s_addc_u32 s67, s67, 0
	s_add_u32 s53, s68, 0x100
	s_addc_u32 s61, s69, 0
	s_mov_b32 s68, 0
	s_add_i32 vcc_lo, s68, 2
	s_add_u32 s14, s66, 0xfffc0080
	s_addc_u32 s15, s67, -1
	s_add_i32 s24, 0, 0x10000
	s_cmp_eq_u32 s45, s68
	s_cselect_b32 s71, s3, s15
	s_cselect_b32 s70, s2, s14
	s_cselect_b32 s69, s39, s61
	s_cselect_b32 s68, s38, s53
	s_add_i32 s14, 0, 0x14000
	v_add_u32_e32 v150, s24, v163
	v_add_u32_e32 v176, s14, v163
	ds_read_b128 v[104:107], v150
	ds_read_b128 v[112:115], v150 offset:1024
	ds_read_b128 v[136:139], v150 offset:2048
	ds_read_b128 v[150:153], v150 offset:3072
	ds_read_b128 v[154:157], v176
	ds_read_b128 v[158:161], v176 offset:1024
	ds_read_b128 v[182:185], v176 offset:2048
	ds_read_b128 v[190:193], v176 offset:3072
	v_lshl_add_u64 v[176:177], s[66:67], 0, v[146:147]
	s_add_i32 m0, s72, 0xc000
	ds_read_b128 v[194:197], v180
	ds_read_b128 v[206:209], v180 offset:1024
	ds_read_b128 v[210:213], v180 offset:2048
	ds_read_b128 v[214:217], v180 offset:3072
	ds_read_b128 v[218:221], v180 offset:4096
	ds_read_b128 v[222:225], v180 offset:5120
	ds_read_b128 v[226:229], v180 offset:6144
	ds_read_b128 v[230:233], v180 offset:7168
	global_load_lds_dwordx4 v[176:177], off
	v_lshl_add_u64 v[176:177], s[66:67], 0, v[148:149]
	s_add_i32 m0, s72, 0xe000
	s_nop 0
	global_load_lds_dwordx4 v[176:177], off
	s_waitcnt vmcnt(8)
	s_waitcnt lgkmcnt(0)
	s_barrier
	v_mfma_f32_16x16x32_bf16 v[132:135], v[104:107], v[194:197], 0
	v_mfma_f32_16x16x32_bf16 v[60:63], v[136:139], v[194:197], 0
	v_mfma_f32_16x16x32_bf16 v[124:127], v[104:107], v[210:213], 0
	v_mfma_f32_16x16x32_bf16 v[52:55], v[136:139], v[210:213], 0
	v_mfma_f32_16x16x32_bf16 v[116:119], v[104:107], v[218:221], 0
	v_mfma_f32_16x16x32_bf16 v[44:47], v[136:139], v[218:221], 0
	v_mfma_f32_16x16x32_bf16 v[100:103], v[104:107], v[226:229], 0
	v_mfma_f32_16x16x32_bf16 v[36:39], v[136:139], v[226:229], 0
	v_mfma_f32_16x16x32_bf16 v[132:135], v[112:115], v[206:209], v[132:135]
	v_mfma_f32_16x16x32_bf16 v[60:63], v[150:153], v[206:209], v[60:63]
	v_mfma_f32_16x16x32_bf16 v[124:127], v[112:115], v[214:217], v[124:127]
	v_mfma_f32_16x16x32_bf16 v[52:55], v[150:153], v[214:217], v[52:55]
	v_mfma_f32_16x16x32_bf16 v[116:119], v[112:115], v[222:225], v[116:119]
	v_mfma_f32_16x16x32_bf16 v[44:47], v[150:153], v[222:225], v[44:47]
	v_mfma_f32_16x16x32_bf16 v[100:103], v[112:115], v[230:233], v[100:103]
	v_mfma_f32_16x16x32_bf16 v[36:39], v[150:153], v[230:233], v[36:39]
	v_mfma_f32_16x16x32_bf16 v[128:131], v[154:157], v[194:197], 0
	v_mfma_f32_16x16x32_bf16 v[56:59], v[182:185], v[194:197], 0
	v_mfma_f32_16x16x32_bf16 v[120:123], v[154:157], v[210:213], 0
	v_mfma_f32_16x16x32_bf16 v[48:51], v[182:185], v[210:213], 0
	v_mfma_f32_16x16x32_bf16 v[108:111], v[154:157], v[218:221], 0
	v_mfma_f32_16x16x32_bf16 v[40:43], v[182:185], v[218:221], 0
	v_mfma_f32_16x16x32_bf16 v[96:99], v[154:157], v[226:229], 0
	v_mfma_f32_16x16x32_bf16 v[32:35], v[182:185], v[226:229], 0
	v_mfma_f32_16x16x32_bf16 v[128:131], v[158:161], v[206:209], v[128:131]
	v_mfma_f32_16x16x32_bf16 v[56:59], v[190:193], v[206:209], v[56:59]
	v_mfma_f32_16x16x32_bf16 v[120:123], v[158:161], v[214:217], v[120:123]
	v_mfma_f32_16x16x32_bf16 v[48:51], v[190:193], v[214:217], v[48:51]
	v_mfma_f32_16x16x32_bf16 v[108:111], v[158:161], v[222:225], v[108:111]
	v_mfma_f32_16x16x32_bf16 v[40:43], v[190:193], v[222:225], v[40:43]
	v_mfma_f32_16x16x32_bf16 v[96:99], v[158:161], v[230:233], v[96:99]
	v_mfma_f32_16x16x32_bf16 v[32:35], v[190:193], v[230:233], v[32:35]
	s_barrier
	s_add_i32 s15, s24, s31
	v_lshl_add_u64 v[176:177], s[68:69], 0, v[168:169]
	s_mov_b32 m0, s15
	ds_read_b128 v[194:197], v180 offset:16384
	ds_read_b128 v[206:209], v180 offset:17408
	ds_read_b128 v[210:213], v180 offset:18432
	ds_read_b128 v[214:217], v180 offset:19456
	ds_read_b128 v[218:221], v180 offset:20480
	ds_read_b128 v[222:225], v180 offset:21504
	ds_read_b128 v[226:229], v180 offset:22528
	ds_read_b128 v[230:233], v180 offset:23552
	global_load_lds_dwordx4 v[176:177], off
	s_add_i32 m0, s15, 0x2000
	s_add_u32 s42, s68, 0x10000
	v_lshl_add_u64 v[186:187], s[68:69], 0, v[144:145]
	s_addc_u32 s43, s69, 0
	s_add_i32 s14, s14, s31
	global_load_lds_dwordx4 v[186:187], off
	v_lshl_add_u64 v[234:235], s[42:43], 0, v[168:169]
	s_mov_b32 m0, s14
	v_lshl_add_u64 v[236:237], s[70:71], 0, v[142:143]
	global_load_lds_dwordx4 v[234:235], off
	v_lshl_add_u64 v[234:235], s[42:43], 0, v[144:145]
	s_add_i32 m0, s14, 0x2000
	s_nop 0
	global_load_lds_dwordx4 v[234:235], off
	v_lshl_add_u64 v[234:235], s[70:71], 0, v[140:141]
	s_mov_b32 m0, s72
	s_nop 0
	global_load_lds_dwordx4 v[234:235], off
	s_mov_b32 m0, s73
	s_nop 0
	global_load_lds_dwordx4 v[236:237], off
	s_waitcnt vmcnt(8)
	s_waitcnt lgkmcnt(0)
	s_barrier
; #define PG8_STAGE(bufoff, gbase, voff) do { _Pragma("unroll") for (int _i = 0; _i < 2; ++_i) \
;         __builtin_amdgcn_global_load_lds((const unsigned*)((const char*)(gbase) + (voff)[_i]), (LAS unsigned*)(lds + (bufoff) + ldsw + _i * 8192), 16, 0, 0); } while (0)
; #define PG8_LDA(dst, b, h) do { _Pragma("unroll") for (int m = 0; m < 4; ++m) _Pragma("unroll") for (int k = 0; k < 2; ++k) dst[m][k] = *(const LAS bf16x8*)(lds + PG8_SA(b, h) + aoff + m * 2048 + k * 1024); } while (0)
; #define PG8_LDB(dst, b, h) do { _Pragma("unroll") for (int n = 0; n < 2; ++n) _Pragma("unroll") for (int k = 0; k < 2; ++k) dst[n][k] = *(const LAS bf16x8*)(lds + PG8_SB(b, h) + boff + n * 2048 + k * 1024); } while (0)
; #define PG8_MMA(ai, bj, At, Bt) do { __builtin_amdgcn_s_setprio(1); _Pragma("unroll") for (int m = 0; m < 4; ++m) _Pragma("unroll") for (int n = 0; n < 2; ++n) _Pragma("unroll") for (int k = 0; k < 2; ++k) \
;         acc[ai][bj][m][n] = __builtin_amdgcn_mfma_f32_16x16x32_bf16(Bt[n][k], At[m][k], acc[ai][bj][m][n], 0, 0, 0); __builtin_amdgcn_s_setprio(0); } while (0)
; #define PG8_WAIT_V(n) asm volatile("s_waitcnt vmcnt(" #n ")" ::: "memory")
; #define PG8_WAIT_L(n) asm volatile("s_waitcnt lgkmcnt(" #n ")" ::: "memory")
; #define PG8_BAR __builtin_amdgcn_s_barrier()
; #define PG8_SCHED __builtin_amdgcn_sched_barrier(0)
; template <class Epi, class Sched>
; __device__ __forceinline__ void gemm_phase(const int tid, LAS unsigned char* lds, const int lda, const int ldb, const int K, const Sched& S, const Epi& E) {
;     ...
;             PG8_WAIT_V(8); PG8_WAIT_L(0); PG8_BAR; if (!cur.half) { PG8_MMA(1, 0, At, B0); PG8_MMA(1, 1, At, B1); } PG8_BAR; PG8_SCHED;
;             PG8_LDB(B0, 1, 0); PG8_LDB(B1, 1, 1); PG8_SCHED; PG8_LDA(At, 1, 0); PG8_STAGE(PG8_SA(0, 1), a2 + hstepA, voffA);
;             PG8_WAIT_V(8); PG8_WAIT_L(0); PG8_BAR; PG8_MMA(0, 0, At, B0); PG8_MMA(0, 1, At, B1); PG8_BAR; PG8_SCHED;
	v_mfma_f32_16x16x32_bf16 v[92:95], v[104:107], v[194:197], 0
	v_mfma_f32_16x16x32_bf16 v[28:31], v[136:139], v[194:197], 0
	v_mfma_f32_16x16x32_bf16 v[84:87], v[104:107], v[210:213], 0
	v_mfma_f32_16x16x32_bf16 v[20:23], v[136:139], v[210:213], 0
	v_mfma_f32_16x16x32_bf16 v[76:79], v[104:107], v[218:221], 0
	v_mfma_f32_16x16x32_bf16 v[12:15], v[136:139], v[218:221], 0
	v_mfma_f32_16x16x32_bf16 v[68:71], v[104:107], v[226:229], 0
	v_mfma_f32_16x16x32_bf16 v[4:7], v[136:139], v[226:229], 0
	v_mfma_f32_16x16x32_bf16 v[92:95], v[112:115], v[206:209], v[92:95]
	v_mfma_f32_16x16x32_bf16 v[28:31], v[150:153], v[206:209], v[28:31]
	v_mfma_f32_16x16x32_bf16 v[84:87], v[112:115], v[214:217], v[84:87]
	v_mfma_f32_16x16x32_bf16 v[20:23], v[150:153], v[214:217], v[20:23]
	v_mfma_f32_16x16x32_bf16 v[76:79], v[112:115], v[222:225], v[76:79]
	v_mfma_f32_16x16x32_bf16 v[12:15], v[150:153], v[222:225], v[12:15]
	v_mfma_f32_16x16x32_bf16 v[68:71], v[112:115], v[230:233], v[68:71]
	v_mfma_f32_16x16x32_bf16 v[4:7], v[150:153], v[230:233], v[4:7]
	v_mfma_f32_16x16x32_bf16 v[88:91], v[154:157], v[194:197], 0
	v_mfma_f32_16x16x32_bf16 v[24:27], v[182:185], v[194:197], 0
	v_mfma_f32_16x16x32_bf16 v[80:83], v[154:157], v[210:213], 0
	v_mfma_f32_16x16x32_bf16 v[16:19], v[182:185], v[210:213], 0
	v_mfma_f32_16x16x32_bf16 v[72:75], v[154:157], v[218:221], 0
	v_mfma_f32_16x16x32_bf16 v[8:11], v[182:185], v[218:221], 0
	v_mfma_f32_16x16x32_bf16 v[64:67], v[154:157], v[226:229], 0
	v_mfma_f32_16x16x32_bf16 v[0:3], v[182:185], v[226:229], 0
	v_mfma_f32_16x16x32_bf16 v[88:91], v[158:161], v[206:209], v[88:91]
	v_mfma_f32_16x16x32_bf16 v[24:27], v[190:193], v[206:209], v[24:27]
	v_mfma_f32_16x16x32_bf16 v[80:83], v[158:161], v[214:217], v[80:83]
	v_mfma_f32_16x16x32_bf16 v[16:19], v[190:193], v[214:217], v[16:19]
	v_mfma_f32_16x16x32_bf16 v[72:75], v[158:161], v[222:225], v[72:75]
	v_mfma_f32_16x16x32_bf16 v[8:11], v[190:193], v[222:225], v[8:11]
	v_mfma_f32_16x16x32_bf16 v[64:67], v[158:161], v[230:233], v[64:67]
	v_mfma_f32_16x16x32_bf16 v[0:3], v[190:193], v[230:233], v[0:3]
	s_barrier
	s_add_i32 s14, 0, 0x18000
	s_add_i32 s15, 0, 0x1c000
	v_add_u32_e32 v150, s14, v163
	v_add_u32_e32 v181, s15, v163
	ds_read_b128 v[104:107], v150
	ds_read_b128 v[112:115], v150 offset:1024
	ds_read_b128 v[136:139], v150 offset:2048
	ds_read_b128 v[150:153], v150 offset:3072
	ds_read_b128 v[154:157], v181
	ds_read_b128 v[158:161], v181 offset:1024
	ds_read_b128 v[182:185], v181 offset:2048
	ds_read_b128 v[190:193], v181 offset:3072
	s_add_u32 s42, s70, 0x40000
	s_addc_u32 s43, s71, 0
	s_mov_b32 m0, s74
	v_lshl_add_u64 v[238:239], s[42:43], 0, v[140:141]
	ds_read_b128 v[194:197], v180 offset:32768
	ds_read_b128 v[206:209], v180 offset:33792
	ds_read_b128 v[210:213], v180 offset:34816
	ds_read_b128 v[214:217], v180 offset:35840
	ds_read_b128 v[218:221], v180 offset:36864
	ds_read_b128 v[222:225], v180 offset:37888
	ds_read_b128 v[226:229], v180 offset:38912
	ds_read_b128 v[230:233], v180 offset:39936
	global_load_lds_dwordx4 v[238:239], off
	v_lshl_add_u64 v[238:239], s[42:43], 0, v[142:143]
	s_mov_b32 m0, s75
	s_nop 0
	global_load_lds_dwordx4 v[238:239], off
	s_waitcnt vmcnt(8)
	s_waitcnt lgkmcnt(0)
	s_barrier
	v_mfma_f32_16x16x32_bf16 v[132:135], v[104:107], v[194:197], v[132:135]
	v_mfma_f32_16x16x32_bf16 v[60:63], v[136:139], v[194:197], v[60:63]
	v_mfma_f32_16x16x32_bf16 v[124:127], v[104:107], v[210:213], v[124:127]
	v_mfma_f32_16x16x32_bf16 v[52:55], v[136:139], v[210:213], v[52:55]
	v_mfma_f32_16x16x32_bf16 v[116:119], v[104:107], v[218:221], v[116:119]
	v_mfma_f32_16x16x32_bf16 v[44:47], v[136:139], v[218:221], v[44:47]
	v_mfma_f32_16x16x32_bf16 v[100:103], v[104:107], v[226:229], v[100:103]
	v_mfma_f32_16x16x32_bf16 v[36:39], v[136:139], v[226:229], v[36:39]
	v_mfma_f32_16x16x32_bf16 v[132:135], v[112:115], v[206:209], v[132:135]
	v_mfma_f32_16x16x32_bf16 v[60:63], v[150:153], v[206:209], v[60:63]
	v_mfma_f32_16x16x32_bf16 v[124:127], v[112:115], v[214:217], v[124:127]
	v_mfma_f32_16x16x32_bf16 v[52:55], v[150:153], v[214:217], v[52:55]
	v_mfma_f32_16x16x32_bf16 v[116:119], v[112:115], v[222:225], v[116:119]
	v_mfma_f32_16x16x32_bf16 v[44:47], v[150:153], v[222:225], v[44:47]
	v_mfma_f32_16x16x32_bf16 v[100:103], v[112:115], v[230:233], v[100:103]
	v_mfma_f32_16x16x32_bf16 v[36:39], v[150:153], v[230:233], v[36:39]
	v_mfma_f32_16x16x32_bf16 v[128:131], v[154:157], v[194:197], v[128:131]
	v_mfma_f32_16x16x32_bf16 v[56:59], v[182:185], v[194:197], v[56:59]
	v_mfma_f32_16x16x32_bf16 v[120:123], v[154:157], v[210:213], v[120:123]
	v_mfma_f32_16x16x32_bf16 v[48:51], v[182:185], v[210:213], v[48:51]
	v_mfma_f32_16x16x32_bf16 v[108:111], v[154:157], v[218:221], v[108:111]
	v_mfma_f32_16x16x32_bf16 v[40:43], v[182:185], v[218:221], v[40:43]
	v_mfma_f32_16x16x32_bf16 v[96:99], v[154:157], v[226:229], v[96:99]
	v_mfma_f32_16x16x32_bf16 v[32:35], v[182:185], v[226:229], v[32:35]
	v_mfma_f32_16x16x32_bf16 v[128:131], v[158:161], v[206:209], v[128:131]
	v_mfma_f32_16x16x32_bf16 v[56:59], v[190:193], v[206:209], v[56:59]
	v_mfma_f32_16x16x32_bf16 v[120:123], v[158:161], v[214:217], v[120:123]
	v_mfma_f32_16x16x32_bf16 v[48:51], v[190:193], v[214:217], v[48:51]
	v_mfma_f32_16x16x32_bf16 v[108:111], v[158:161], v[222:225], v[108:111]
	v_mfma_f32_16x16x32_bf16 v[40:43], v[190:193], v[222:225], v[40:43]
	v_mfma_f32_16x16x32_bf16 v[96:99], v[158:161], v[230:233], v[96:99]
	v_mfma_f32_16x16x32_bf16 v[32:35], v[190:193], v[230:233], v[32:35]
	s_barrier
; #define PG8_STAGE(bufoff, gbase, voff) do { _Pragma("unroll") for (int _i = 0; _i < 2; ++_i) \
;         __builtin_amdgcn_global_load_lds((const unsigned*)((const char*)(gbase) + (voff)[_i]), (LAS unsigned*)(lds + (bufoff) + ldsw + _i * 8192), 16, 0, 0); } while (0)
; #define PG8_LDA(dst, b, h) do { _Pragma("unroll") for (int m = 0; m < 4; ++m) _Pragma("unroll") for (int k = 0; k < 2; ++k) dst[m][k] = *(const LAS bf16x8*)(lds + PG8_SA(b, h) + aoff + m * 2048 + k * 1024); } while (0)
; #define PG8_LDB(dst, b, h) do { _Pragma("unroll") for (int n = 0; n < 2; ++n) _Pragma("unroll") for (int k = 0; k < 2; ++k) dst[n][k] = *(const LAS bf16x8*)(lds + PG8_SB(b, h) + boff + n * 2048 + k * 1024); } while (0)
; #define PG8_MMA(ai, bj, At, Bt) do { __builtin_amdgcn_s_setprio(1); _Pragma("unroll") for (int m = 0; m < 4; ++m) _Pragma("unroll") for (int n = 0; n < 2; ++n) _Pragma("unroll") for (int k = 0; k < 2; ++k) \
;         acc[ai][bj][m][n] = __builtin_amdgcn_mfma_f32_16x16x32_bf16(Bt[n][k], At[m][k], acc[ai][bj][m][n], 0, 0, 0); __builtin_amdgcn_s_setprio(0); } while (0)
; #define PG8_WAIT_V(n) asm volatile("s_waitcnt vmcnt(" #n ")" ::: "memory")
; #define PG8_WAIT_L(n) asm volatile("s_waitcnt lgkmcnt(" #n ")" ::: "memory")
; #define PG8_BAR __builtin_amdgcn_s_barrier()
; template <class Epi, class Sched>
; __device__ __forceinline__ void gemm_phase(const int tid, LAS unsigned char* lds, const int lda, const int ldb, const int K, const Sched& S, const Epi& E) {
;     ...
;         for (int t = 0; t < nt; t += 2) {
;             const bool last = (t == nt - 2);
;             const char* a1 = cA + (size_t)(t + 1) * kstep;
;             const char* a2 = last ? nA : cA + (size_t)(t + 2) * kstep; const char* b2 = last ? nB : cB + (size_t)(t + 2) * kstep;
;             const char* a3 = a2 + kstep; const char* b3 = b2 + kstep;
;             PG8_LDB(B0, 0, 0); PG8_LDB(B1, 0, 1); PG8_SCHED; PG8_LDA(At, 0, 0); PG8_STAGE(PG8_SA(1, 1), a1 + hstepA, voffA);
;             PG8_WAIT_V(8); PG8_WAIT_L(0); PG8_BAR; PG8_MMA(0, 0, At, B0); PG8_MMA(0, 1, At, B1); PG8_BAR; PG8_SCHED;
;     ...
;             PG8_LDA(At, 1, 1); PG8_STAGE(PG8_SB(1, 0), b3, voffB); PG8_STAGE(PG8_SB(1, 1), b3 + hstepB, voffB); PG8_STAGE(PG8_SA(1, 0), a3, voffA);
;             PG8_WAIT_V(8); PG8_WAIT_L(0); PG8_BAR; if (!cur.half) { PG8_MMA(1, 0, At, B0); PG8_MMA(1, 1, At, B1); } PG8_BAR; PG8_SCHED;
	s_add_i32 s14, s14, s31
	v_lshl_add_u64 v[176:177], v[176:177], 0, s[6:7]
	s_mov_b32 m0, s14
	ds_read_b128 v[194:197], v180 offset:49152
	ds_read_b128 v[206:209], v180 offset:50176
	ds_read_b128 v[210:213], v180 offset:51200
	ds_read_b128 v[214:217], v180 offset:52224
	ds_read_b128 v[218:221], v180 offset:53248
	ds_read_b128 v[222:225], v180 offset:54272
	ds_read_b128 v[226:229], v180 offset:55296
	ds_read_b128 v[230:233], v180 offset:56320
	global_load_lds_dwordx4 v[176:177], off
	s_add_i32 m0, s14, 0x2000
	s_add_u32 s42, s68, 0x10080
	v_lshl_add_u64 v[176:177], v[186:187], 0, s[6:7]
	s_addc_u32 s43, s69, 0
	s_add_i32 s14, s15, s31
	global_load_lds_dwordx4 v[176:177], off
	v_lshl_add_u64 v[176:177], s[42:43], 0, v[168:169]
	s_mov_b32 m0, s14
	s_nop 0
	global_load_lds_dwordx4 v[176:177], off
	v_lshl_add_u64 v[176:177], s[42:43], 0, v[144:145]
	s_add_i32 m0, s14, 0x2000
	s_nop 0
	global_load_lds_dwordx4 v[176:177], off
	v_lshl_add_u64 v[176:177], v[234:235], 0, s[6:7]
	s_mov_b32 m0, s20
	s_nop 0
	global_load_lds_dwordx4 v[176:177], off
	v_lshl_add_u64 v[176:177], v[236:237], 0, s[6:7]
	s_mov_b32 m0, s13
	s_nop 0
	global_load_lds_dwordx4 v[176:177], off
	s_waitcnt vmcnt(8)
	s_waitcnt lgkmcnt(0)
	s_barrier
	v_mfma_f32_16x16x32_bf16 v[92:95], v[104:107], v[194:197], v[92:95]
	v_mfma_f32_16x16x32_bf16 v[28:31], v[136:139], v[194:197], v[28:31]
	v_mfma_f32_16x16x32_bf16 v[84:87], v[104:107], v[210:213], v[84:87]
	v_mfma_f32_16x16x32_bf16 v[20:23], v[136:139], v[210:213], v[20:23]
	v_mfma_f32_16x16x32_bf16 v[76:79], v[104:107], v[218:221], v[76:79]
	v_mfma_f32_16x16x32_bf16 v[12:15], v[136:139], v[218:221], v[12:15]
	v_mfma_f32_16x16x32_bf16 v[68:71], v[104:107], v[226:229], v[68:71]
	v_mfma_f32_16x16x32_bf16 v[4:7], v[136:139], v[226:229], v[4:7]
	v_mfma_f32_16x16x32_bf16 v[92:95], v[112:115], v[206:209], v[92:95]
	v_mfma_f32_16x16x32_bf16 v[28:31], v[150:153], v[206:209], v[28:31]
	v_mfma_f32_16x16x32_bf16 v[84:87], v[112:115], v[214:217], v[84:87]
	v_mfma_f32_16x16x32_bf16 v[20:23], v[150:153], v[214:217], v[20:23]
	v_mfma_f32_16x16x32_bf16 v[76:79], v[112:115], v[222:225], v[76:79]
	v_mfma_f32_16x16x32_bf16 v[12:15], v[150:153], v[222:225], v[12:15]
	v_mfma_f32_16x16x32_bf16 v[68:71], v[112:115], v[230:233], v[68:71]
	v_mfma_f32_16x16x32_bf16 v[4:7], v[150:153], v[230:233], v[4:7]
	v_mfma_f32_16x16x32_bf16 v[88:91], v[154:157], v[194:197], v[88:91]
	v_mfma_f32_16x16x32_bf16 v[24:27], v[182:185], v[194:197], v[24:27]
	v_mfma_f32_16x16x32_bf16 v[80:83], v[154:157], v[210:213], v[80:83]
	v_mfma_f32_16x16x32_bf16 v[16:19], v[182:185], v[210:213], v[16:19]
	v_mfma_f32_16x16x32_bf16 v[72:75], v[154:157], v[218:221], v[72:75]
	v_mfma_f32_16x16x32_bf16 v[8:11], v[182:185], v[218:221], v[8:11]
	v_mfma_f32_16x16x32_bf16 v[64:67], v[154:157], v[226:229], v[64:67]
	v_mfma_f32_16x16x32_bf16 v[0:3], v[182:185], v[226:229], v[0:3]
	v_mfma_f32_16x16x32_bf16 v[88:91], v[158:161], v[206:209], v[88:91]
	v_mfma_f32_16x16x32_bf16 v[24:27], v[190:193], v[206:209], v[24:27]
	v_mfma_f32_16x16x32_bf16 v[80:83], v[158:161], v[214:217], v[80:83]
	v_mfma_f32_16x16x32_bf16 v[16:19], v[190:193], v[214:217], v[16:19]
	v_mfma_f32_16x16x32_bf16 v[72:75], v[158:161], v[222:225], v[72:75]
	v_mfma_f32_16x16x32_bf16 v[8:11], v[190:193], v[222:225], v[8:11]
	v_mfma_f32_16x16x32_bf16 v[64:67], v[158:161], v[230:233], v[64:67]
	v_mfma_f32_16x16x32_bf16 v[0:3], v[190:193], v[230:233], v[0:3]
	s_barrier
	s_add_u32 s66, s66, 0x100
	s_addc_u32 s67, s67, 0
	s_add_u32 s53, s53, 0x100
	s_addc_u32 s61, s61, 0
	s_cmp_ge_i32 vcc_lo, s29
	s_mov_b32 s68, vcc_lo
	s_cbranch_scc1 .Lkexit_311
.LBB0_311:
	s_add_i32 vcc_lo, s68, 2
	s_add_u32 s14, s66, 0xfffc0080
	s_addc_u32 s15, s67, -1
	s_add_i32 s24, 0, 0x10000
	s_cmp_eq_u32 s45, s68
	s_cselect_b32 s71, s3, s15
	s_cselect_b32 s70, s2, s14
	s_cselect_b32 s69, s39, s61
	s_cselect_b32 s68, s38, s53
	s_add_i32 s14, 0, 0x14000
	v_add_u32_e32 v150, s24, v163
	v_add_u32_e32 v176, s14, v163
	ds_read_b128 v[104:107], v150
	ds_read_b128 v[112:115], v150 offset:1024
	ds_read_b128 v[136:139], v150 offset:2048
	ds_read_b128 v[150:153], v150 offset:3072
	ds_read_b128 v[154:157], v176
	ds_read_b128 v[158:161], v176 offset:1024
	ds_read_b128 v[182:185], v176 offset:2048
	ds_read_b128 v[190:193], v176 offset:3072
	v_lshl_add_u64 v[176:177], s[66:67], 0, v[146:147]
	s_add_i32 m0, s72, 0xc000
	ds_read_b128 v[194:197], v180
	ds_read_b128 v[206:209], v180 offset:1024
	ds_read_b128 v[210:213], v180 offset:2048
	ds_read_b128 v[214:217], v180 offset:3072
	ds_read_b128 v[218:221], v180 offset:4096
	ds_read_b128 v[222:225], v180 offset:5120
	ds_read_b128 v[226:229], v180 offset:6144
	ds_read_b128 v[230:233], v180 offset:7168
	global_load_lds_dwordx4 v[176:177], off
	v_lshl_add_u64 v[176:177], s[66:67], 0, v[148:149]
	s_add_i32 m0, s72, 0xe000
	s_nop 0
	global_load_lds_dwordx4 v[176:177], off
	s_waitcnt vmcnt(8)
	s_waitcnt lgkmcnt(0)
	s_barrier
; #define PG8_STAGE(bufoff, gbase, voff) do { _Pragma("unroll") for (int _i = 0; _i < 2; ++_i) \
;         __builtin_amdgcn_global_load_lds((const unsigned*)((const char*)(gbase) + (voff)[_i]), (LAS unsigned*)(lds + (bufoff) + ldsw + _i * 8192), 16, 0, 0); } while (0)
; #define PG8_LDA(dst, b, h) do { _Pragma("unroll") for (int m = 0; m < 4; ++m) _Pragma("unroll") for (int k = 0; k < 2; ++k) dst[m][k] = *(const LAS bf16x8*)(lds + PG8_SA(b, h) + aoff + m * 2048 + k * 1024); } while (0)
; #define PG8_LDB(dst, b, h) do { _Pragma("unroll") for (int n = 0; n < 2; ++n) _Pragma("unroll") for (int k = 0; k < 2; ++k) dst[n][k] = *(const LAS bf16x8*)(lds + PG8_SB(b, h) + boff + n * 2048 + k * 1024); } while (0)
; #define PG8_MMA(ai, bj, At, Bt) do { __builtin_amdgcn_s_setprio(1); _Pragma("unroll") for (int m = 0; m < 4; ++m) _Pragma("unroll") for (int n = 0; n < 2; ++n) _Pragma("unroll") for (int k = 0; k < 2; ++k) \
;         acc[ai][bj][m][n] = __builtin_amdgcn_mfma_f32_16x16x32_bf16(Bt[n][k], At[m][k], acc[ai][bj][m][n], 0, 0, 0); __builtin_amdgcn_s_setprio(0); } while (0)
; #define PG8_WAIT_V(n) asm volatile("s_waitcnt vmcnt(" #n ")" ::: "memory")
; #define PG8_WAIT_L(n) asm volatile("s_waitcnt lgkmcnt(" #n ")" ::: "memory")
; #define PG8_BAR __builtin_amdgcn_s_barrier()
; #define PG8_SCHED __builtin_amdgcn_sched_barrier(0)
; template <class Epi, class Sched>
; __device__ __forceinline__ void gemm_phase(const int tid, LAS unsigned char* lds, const int lda, const int ldb, const int K, const Sched& S, const Epi& E) {
;     ...
;             PG8_WAIT_V(8); PG8_WAIT_L(0); PG8_BAR; PG8_MMA(0, 0, At, B0); PG8_MMA(0, 1, At, B1); PG8_BAR; PG8_SCHED;
;             PG8_LDA(At, 0, 1); PG8_STAGE(PG8_SB(0, 0), b2, voffB); PG8_STAGE(PG8_SB(0, 1), b2 + hstepB, voffB); PG8_STAGE(PG8_SA(0, 0), a2, voffA);
;             PG8_WAIT_V(8); PG8_WAIT_L(0); PG8_BAR; if (!cur.half) { PG8_MMA(1, 0, At, B0); PG8_MMA(1, 1, At, B1); } PG8_BAR; PG8_SCHED;
;             PG8_LDB(B0, 1, 0); PG8_LDB(B1, 1, 1); PG8_SCHED; PG8_LDA(At, 1, 0); PG8_STAGE(PG8_SA(0, 1), a2 + hstepA, voffA);
;             PG8_WAIT_V(8); PG8_WAIT_L(0); PG8_BAR; PG8_MMA(0, 0, At, B0); PG8_MMA(0, 1, At, B1); PG8_BAR; PG8_SCHED;
	v_mfma_f32_16x16x32_bf16 v[132:135], v[104:107], v[194:197], v[132:135]
	v_mfma_f32_16x16x32_bf16 v[60:63], v[136:139], v[194:197], v[60:63]
	v_mfma_f32_16x16x32_bf16 v[124:127], v[104:107], v[210:213], v[124:127]
	v_mfma_f32_16x16x32_bf16 v[52:55], v[136:139], v[210:213], v[52:55]
	v_mfma_f32_16x16x32_bf16 v[116:119], v[104:107], v[218:221], v[116:119]
	v_mfma_f32_16x16x32_bf16 v[44:47], v[136:139], v[218:221], v[44:47]
	v_mfma_f32_16x16x32_bf16 v[100:103], v[104:107], v[226:229], v[100:103]
	v_mfma_f32_16x16x32_bf16 v[36:39], v[136:139], v[226:229], v[36:39]
	v_mfma_f32_16x16x32_bf16 v[132:135], v[112:115], v[206:209], v[132:135]
	v_mfma_f32_16x16x32_bf16 v[60:63], v[150:153], v[206:209], v[60:63]
	v_mfma_f32_16x16x32_bf16 v[124:127], v[112:115], v[214:217], v[124:127]
	v_mfma_f32_16x16x32_bf16 v[52:55], v[150:153], v[214:217], v[52:55]
	v_mfma_f32_16x16x32_bf16 v[116:119], v[112:115], v[222:225], v[116:119]
	v_mfma_f32_16x16x32_bf16 v[44:47], v[150:153], v[222:225], v[44:47]
	v_mfma_f32_16x16x32_bf16 v[100:103], v[112:115], v[230:233], v[100:103]
	v_mfma_f32_16x16x32_bf16 v[36:39], v[150:153], v[230:233], v[36:39]
	v_mfma_f32_16x16x32_bf16 v[128:131], v[154:157], v[194:197], v[128:131]
	v_mfma_f32_16x16x32_bf16 v[56:59], v[182:185], v[194:197], v[56:59]
	v_mfma_f32_16x16x32_bf16 v[120:123], v[154:157], v[210:213], v[120:123]
	v_mfma_f32_16x16x32_bf16 v[48:51], v[182:185], v[210:213], v[48:51]
	v_mfma_f32_16x16x32_bf16 v[108:111], v[154:157], v[218:221], v[108:111]
	v_mfma_f32_16x16x32_bf16 v[40:43], v[182:185], v[218:221], v[40:43]
	v_mfma_f32_16x16x32_bf16 v[96:99], v[154:157], v[226:229], v[96:99]
	v_mfma_f32_16x16x32_bf16 v[32:35], v[182:185], v[226:229], v[32:35]
	v_mfma_f32_16x16x32_bf16 v[128:131], v[158:161], v[206:209], v[128:131]
	v_mfma_f32_16x16x32_bf16 v[56:59], v[190:193], v[206:209], v[56:59]
	v_mfma_f32_16x16x32_bf16 v[120:123], v[158:161], v[214:217], v[120:123]
	v_mfma_f32_16x16x32_bf16 v[48:51], v[190:193], v[214:217], v[48:51]
	v_mfma_f32_16x16x32_bf16 v[108:111], v[158:161], v[222:225], v[108:111]
	v_mfma_f32_16x16x32_bf16 v[40:43], v[190:193], v[222:225], v[40:43]
	v_mfma_f32_16x16x32_bf16 v[96:99], v[158:161], v[230:233], v[96:99]
	v_mfma_f32_16x16x32_bf16 v[32:35], v[190:193], v[230:233], v[32:35]
	s_barrier
	s_add_i32 s15, s24, s31
	v_lshl_add_u64 v[176:177], s[68:69], 0, v[168:169]
	s_mov_b32 m0, s15
	ds_read_b128 v[194:197], v180 offset:16384
	ds_read_b128 v[206:209], v180 offset:17408
	ds_read_b128 v[210:213], v180 offset:18432
	ds_read_b128 v[214:217], v180 offset:19456
	ds_read_b128 v[218:221], v180 offset:20480
	ds_read_b128 v[222:225], v180 offset:21504
	ds_read_b128 v[226:229], v180 offset:22528
	ds_read_b128 v[230:233], v180 offset:23552
	global_load_lds_dwordx4 v[176:177], off
	s_add_i32 m0, s15, 0x2000
	s_add_u32 s42, s68, 0x10000
	v_lshl_add_u64 v[186:187], s[68:69], 0, v[144:145]
	s_addc_u32 s43, s69, 0
	s_add_i32 s14, s14, s31
	global_load_lds_dwordx4 v[186:187], off
	v_lshl_add_u64 v[234:235], s[42:43], 0, v[168:169]
	s_mov_b32 m0, s14
	v_lshl_add_u64 v[236:237], s[70:71], 0, v[142:143]
	global_load_lds_dwordx4 v[234:235], off
	v_lshl_add_u64 v[234:235], s[42:43], 0, v[144:145]
	s_add_i32 m0, s14, 0x2000
	s_nop 0
	global_load_lds_dwordx4 v[234:235], off
	v_lshl_add_u64 v[234:235], s[70:71], 0, v[140:141]
	s_mov_b32 m0, s72
	s_nop 0
	global_load_lds_dwordx4 v[234:235], off
	s_mov_b32 m0, s73
	s_nop 0
	global_load_lds_dwordx4 v[236:237], off
	s_waitcnt vmcnt(8)
	s_waitcnt lgkmcnt(0)
	s_barrier
	v_mfma_f32_16x16x32_bf16 v[92:95], v[104:107], v[194:197], v[92:95]
	v_mfma_f32_16x16x32_bf16 v[28:31], v[136:139], v[194:197], v[28:31]
	v_mfma_f32_16x16x32_bf16 v[84:87], v[104:107], v[210:213], v[84:87]
	v_mfma_f32_16x16x32_bf16 v[20:23], v[136:139], v[210:213], v[20:23]
	v_mfma_f32_16x16x32_bf16 v[76:79], v[104:107], v[218:221], v[76:79]
	v_mfma_f32_16x16x32_bf16 v[12:15], v[136:139], v[218:221], v[12:15]
	v_mfma_f32_16x16x32_bf16 v[68:71], v[104:107], v[226:229], v[68:71]
	v_mfma_f32_16x16x32_bf16 v[4:7], v[136:139], v[226:229], v[4:7]
	v_mfma_f32_16x16x32_bf16 v[92:95], v[112:115], v[206:209], v[92:95]
	v_mfma_f32_16x16x32_bf16 v[28:31], v[150:153], v[206:209], v[28:31]
	v_mfma_f32_16x16x32_bf16 v[84:87], v[112:115], v[214:217], v[84:87]
	v_mfma_f32_16x16x32_bf16 v[20:23], v[150:153], v[214:217], v[20:23]
	v_mfma_f32_16x16x32_bf16 v[76:79], v[112:115], v[222:225], v[76:79]
	v_mfma_f32_16x16x32_bf16 v[12:15], v[150:153], v[222:225], v[12:15]
	v_mfma_f32_16x16x32_bf16 v[68:71], v[112:115], v[230:233], v[68:71]
	v_mfma_f32_16x16x32_bf16 v[4:7], v[150:153], v[230:233], v[4:7]
	v_mfma_f32_16x16x32_bf16 v[88:91], v[154:157], v[194:197], v[88:91]
	v_mfma_f32_16x16x32_bf16 v[24:27], v[182:185], v[194:197], v[24:27]
	v_mfma_f32_16x16x32_bf16 v[80:83], v[154:157], v[210:213], v[80:83]
	v_mfma_f32_16x16x32_bf16 v[16:19], v[182:185], v[210:213], v[16:19]
	v_mfma_f32_16x16x32_bf16 v[72:75], v[154:157], v[218:221], v[72:75]
	v_mfma_f32_16x16x32_bf16 v[8:11], v[182:185], v[218:221], v[8:11]
	v_mfma_f32_16x16x32_bf16 v[64:67], v[154:157], v[226:229], v[64:67]
	v_mfma_f32_16x16x32_bf16 v[0:3], v[182:185], v[226:229], v[0:3]
	v_mfma_f32_16x16x32_bf16 v[88:91], v[158:161], v[206:209], v[88:91]
	v_mfma_f32_16x16x32_bf16 v[24:27], v[190:193], v[206:209], v[24:27]
	v_mfma_f32_16x16x32_bf16 v[80:83], v[158:161], v[214:217], v[80:83]
	v_mfma_f32_16x16x32_bf16 v[16:19], v[190:193], v[214:217], v[16:19]
	v_mfma_f32_16x16x32_bf16 v[72:75], v[158:161], v[222:225], v[72:75]
	v_mfma_f32_16x16x32_bf16 v[8:11], v[190:193], v[222:225], v[8:11]
	v_mfma_f32_16x16x32_bf16 v[64:67], v[158:161], v[230:233], v[64:67]
	v_mfma_f32_16x16x32_bf16 v[0:3], v[190:193], v[230:233], v[0:3]
	s_barrier
; #define PG8_STAGE(bufoff, gbase, voff) do { _Pragma("unroll") for (int _i = 0; _i < 2; ++_i) \
;         __builtin_amdgcn_global_load_lds((const unsigned*)((const char*)(gbase) + (voff)[_i]), (LAS unsigned*)(lds + (bufoff) + ldsw + _i * 8192), 16, 0, 0); } while (0)
; #define PG8_LDA(dst, b, h) do { _Pragma("unroll") for (int m = 0; m < 4; ++m) _Pragma("unroll") for (int k = 0; k < 2; ++k) dst[m][k] = *(const LAS bf16x8*)(lds + PG8_SA(b, h) + aoff + m * 2048 + k * 1024); } while (0)
; #define PG8_LDB(dst, b, h) do { _Pragma("unroll") for (int n = 0; n < 2; ++n) _Pragma("unroll") for (int k = 0; k < 2; ++k) dst[n][k] = *(const LAS bf16x8*)(lds + PG8_SB(b, h) + boff + n * 2048 + k * 1024); } while (0)
; #define PG8_MMA(ai, bj, At, Bt) do { __builtin_amdgcn_s_setprio(1); _Pragma("unroll") for (int m = 0; m < 4; ++m) _Pragma("unroll") for (int n = 0; n < 2; ++n) _Pragma("unroll") for (int k = 0; k < 2; ++k) \
;         acc[ai][bj][m][n] = __builtin_amdgcn_mfma_f32_16x16x32_bf16(Bt[n][k], At[m][k], acc[ai][bj][m][n], 0, 0, 0); __builtin_amdgcn_s_setprio(0); } while (0)
; #define PG8_WAIT_V(n) asm volatile("s_waitcnt vmcnt(" #n ")" ::: "memory")
; #define PG8_WAIT_L(n) asm volatile("s_waitcnt lgkmcnt(" #n ")" ::: "memory")
; #define PG8_BAR __builtin_amdgcn_s_barrier()
; #define PG8_SCHED __builtin_amdgcn_sched_barrier(0)
; template <class Epi, class Sched>
; __device__ __forceinline__ void gemm_phase(const int tid, LAS unsigned char* lds, const int lda, const int ldb, const int K, const Sched& S, const Epi& E) {
;     ...
;             PG8_LDB(B0, 1, 0); PG8_LDB(B1, 1, 1); PG8_SCHED; PG8_LDA(At, 1, 0); PG8_STAGE(PG8_SA(0, 1), a2 + hstepA, voffA);
;             PG8_WAIT_V(8); PG8_WAIT_L(0); PG8_BAR; PG8_MMA(0, 0, At, B0); PG8_MMA(0, 1, At, B1); PG8_BAR; PG8_SCHED;
;             PG8_LDA(At, 1, 1); PG8_STAGE(PG8_SB(1, 0), b3, voffB); PG8_STAGE(PG8_SB(1, 1), b3 + hstepB, voffB); PG8_STAGE(PG8_SA(1, 0), a3, voffA);
;             PG8_WAIT_V(8); PG8_WAIT_L(0); PG8_BAR; if (!cur.half) { PG8_MMA(1, 0, At, B0); PG8_MMA(1, 1, At, B1); } PG8_BAR; PG8_SCHED;
	s_add_i32 s14, 0, 0x18000
	s_add_i32 s15, 0, 0x1c000
	v_add_u32_e32 v150, s14, v163
	v_add_u32_e32 v181, s15, v163
	ds_read_b128 v[104:107], v150
	ds_read_b128 v[112:115], v150 offset:1024
	ds_read_b128 v[136:139], v150 offset:2048
	ds_read_b128 v[150:153], v150 offset:3072
	ds_read_b128 v[154:157], v181
	ds_read_b128 v[158:161], v181 offset:1024
	ds_read_b128 v[182:185], v181 offset:2048
	ds_read_b128 v[190:193], v181 offset:3072
	s_add_u32 s42, s70, 0x40000
	s_addc_u32 s43, s71, 0
	s_mov_b32 m0, s74
	v_lshl_add_u64 v[238:239], s[42:43], 0, v[140:141]
	ds_read_b128 v[194:197], v180 offset:32768
	ds_read_b128 v[206:209], v180 offset:33792
	ds_read_b128 v[210:213], v180 offset:34816
	ds_read_b128 v[214:217], v180 offset:35840
	ds_read_b128 v[218:221], v180 offset:36864
	ds_read_b128 v[222:225], v180 offset:37888
	ds_read_b128 v[226:229], v180 offset:38912
	ds_read_b128 v[230:233], v180 offset:39936
	global_load_lds_dwordx4 v[238:239], off
	v_lshl_add_u64 v[238:239], s[42:43], 0, v[142:143]
	s_mov_b32 m0, s75
	s_nop 0
	global_load_lds_dwordx4 v[238:239], off
	s_waitcnt vmcnt(8)
	s_waitcnt lgkmcnt(0)
	s_barrier
	v_mfma_f32_16x16x32_bf16 v[132:135], v[104:107], v[194:197], v[132:135]
	v_mfma_f32_16x16x32_bf16 v[60:63], v[136:139], v[194:197], v[60:63]
	v_mfma_f32_16x16x32_bf16 v[124:127], v[104:107], v[210:213], v[124:127]
	v_mfma_f32_16x16x32_bf16 v[52:55], v[136:139], v[210:213], v[52:55]
	v_mfma_f32_16x16x32_bf16 v[116:119], v[104:107], v[218:221], v[116:119]
	v_mfma_f32_16x16x32_bf16 v[44:47], v[136:139], v[218:221], v[44:47]
	v_mfma_f32_16x16x32_bf16 v[100:103], v[104:107], v[226:229], v[100:103]
	v_mfma_f32_16x16x32_bf16 v[36:39], v[136:139], v[226:229], v[36:39]
	v_mfma_f32_16x16x32_bf16 v[132:135], v[112:115], v[206:209], v[132:135]
	v_mfma_f32_16x16x32_bf16 v[60:63], v[150:153], v[206:209], v[60:63]
	v_mfma_f32_16x16x32_bf16 v[124:127], v[112:115], v[214:217], v[124:127]
	v_mfma_f32_16x16x32_bf16 v[52:55], v[150:153], v[214:217], v[52:55]
	v_mfma_f32_16x16x32_bf16 v[116:119], v[112:115], v[222:225], v[116:119]
	v_mfma_f32_16x16x32_bf16 v[44:47], v[150:153], v[222:225], v[44:47]
	v_mfma_f32_16x16x32_bf16 v[100:103], v[112:115], v[230:233], v[100:103]
	v_mfma_f32_16x16x32_bf16 v[36:39], v[150:153], v[230:233], v[36:39]
	v_mfma_f32_16x16x32_bf16 v[128:131], v[154:157], v[194:197], v[128:131]
	v_mfma_f32_16x16x32_bf16 v[56:59], v[182:185], v[194:197], v[56:59]
	v_mfma_f32_16x16x32_bf16 v[120:123], v[154:157], v[210:213], v[120:123]
	v_mfma_f32_16x16x32_bf16 v[48:51], v[182:185], v[210:213], v[48:51]
	v_mfma_f32_16x16x32_bf16 v[108:111], v[154:157], v[218:221], v[108:111]
	v_mfma_f32_16x16x32_bf16 v[40:43], v[182:185], v[218:221], v[40:43]
	v_mfma_f32_16x16x32_bf16 v[96:99], v[154:157], v[226:229], v[96:99]
	v_mfma_f32_16x16x32_bf16 v[32:35], v[182:185], v[226:229], v[32:35]
	v_mfma_f32_16x16x32_bf16 v[128:131], v[158:161], v[206:209], v[128:131]
	v_mfma_f32_16x16x32_bf16 v[56:59], v[190:193], v[206:209], v[56:59]
	v_mfma_f32_16x16x32_bf16 v[120:123], v[158:161], v[214:217], v[120:123]
	v_mfma_f32_16x16x32_bf16 v[48:51], v[190:193], v[214:217], v[48:51]
	v_mfma_f32_16x16x32_bf16 v[108:111], v[158:161], v[222:225], v[108:111]
	v_mfma_f32_16x16x32_bf16 v[40:43], v[190:193], v[222:225], v[40:43]
	v_mfma_f32_16x16x32_bf16 v[96:99], v[158:161], v[230:233], v[96:99]
	v_mfma_f32_16x16x32_bf16 v[32:35], v[190:193], v[230:233], v[32:35]
	s_barrier
	s_add_i32 s14, s14, s31
	v_lshl_add_u64 v[176:177], v[176:177], 0, s[6:7]
	s_mov_b32 m0, s14
	ds_read_b128 v[194:197], v180 offset:49152
	ds_read_b128 v[206:209], v180 offset:50176
	ds_read_b128 v[210:213], v180 offset:51200
	ds_read_b128 v[214:217], v180 offset:52224
	ds_read_b128 v[218:221], v180 offset:53248
	ds_read_b128 v[222:225], v180 offset:54272
	ds_read_b128 v[226:229], v180 offset:55296
	ds_read_b128 v[230:233], v180 offset:56320
	global_load_lds_dwordx4 v[176:177], off
	s_add_i32 m0, s14, 0x2000
	s_add_u32 s42, s68, 0x10080
	v_lshl_add_u64 v[176:177], v[186:187], 0, s[6:7]
	s_addc_u32 s43, s69, 0
	s_add_i32 s14, s15, s31
	global_load_lds_dwordx4 v[176:177], off
	v_lshl_add_u64 v[176:177], s[42:43], 0, v[168:169]
	s_mov_b32 m0, s14
	s_nop 0
	global_load_lds_dwordx4 v[176:177], off
	v_lshl_add_u64 v[176:177], s[42:43], 0, v[144:145]
	s_add_i32 m0, s14, 0x2000
	s_nop 0
	global_load_lds_dwordx4 v[176:177], off
	v_lshl_add_u64 v[176:177], v[234:235], 0, s[6:7]
	s_mov_b32 m0, s20
	s_nop 0
	global_load_lds_dwordx4 v[176:177], off
	v_lshl_add_u64 v[176:177], v[236:237], 0, s[6:7]
	s_mov_b32 m0, s13
	s_nop 0
	global_load_lds_dwordx4 v[176:177], off
	s_waitcnt vmcnt(8)
	s_waitcnt lgkmcnt(0)
	s_barrier
	v_mfma_f32_16x16x32_bf16 v[92:95], v[104:107], v[194:197], v[92:95]
	v_mfma_f32_16x16x32_bf16 v[28:31], v[136:139], v[194:197], v[28:31]
	v_mfma_f32_16x16x32_bf16 v[84:87], v[104:107], v[210:213], v[84:87]
	v_mfma_f32_16x16x32_bf16 v[20:23], v[136:139], v[210:213], v[20:23]
	v_mfma_f32_16x16x32_bf16 v[76:79], v[104:107], v[218:221], v[76:79]
	v_mfma_f32_16x16x32_bf16 v[12:15], v[136:139], v[218:221], v[12:15]
	v_mfma_f32_16x16x32_bf16 v[68:71], v[104:107], v[226:229], v[68:71]
	v_mfma_f32_16x16x32_bf16 v[4:7], v[136:139], v[226:229], v[4:7]
	v_mfma_f32_16x16x32_bf16 v[92:95], v[112:115], v[206:209], v[92:95]
	v_mfma_f32_16x16x32_bf16 v[28:31], v[150:153], v[206:209], v[28:31]
	v_mfma_f32_16x16x32_bf16 v[84:87], v[112:115], v[214:217], v[84:87]
	v_mfma_f32_16x16x32_bf16 v[20:23], v[150:153], v[214:217], v[20:23]
	v_mfma_f32_16x16x32_bf16 v[76:79], v[112:115], v[222:225], v[76:79]
	v_mfma_f32_16x16x32_bf16 v[12:15], v[150:153], v[222:225], v[12:15]
	v_mfma_f32_16x16x32_bf16 v[68:71], v[112:115], v[230:233], v[68:71]
	v_mfma_f32_16x16x32_bf16 v[4:7], v[150:153], v[230:233], v[4:7]
	v_mfma_f32_16x16x32_bf16 v[88:91], v[154:157], v[194:197], v[88:91]
	v_mfma_f32_16x16x32_bf16 v[24:27], v[182:185], v[194:197], v[24:27]
	v_mfma_f32_16x16x32_bf16 v[80:83], v[154:157], v[210:213], v[80:83]
	v_mfma_f32_16x16x32_bf16 v[16:19], v[182:185], v[210:213], v[16:19]
	v_mfma_f32_16x16x32_bf16 v[72:75], v[154:157], v[218:221], v[72:75]
	v_mfma_f32_16x16x32_bf16 v[8:11], v[182:185], v[218:221], v[8:11]
	v_mfma_f32_16x16x32_bf16 v[64:67], v[154:157], v[226:229], v[64:67]
	v_mfma_f32_16x16x32_bf16 v[0:3], v[182:185], v[226:229], v[0:3]
	v_mfma_f32_16x16x32_bf16 v[88:91], v[158:161], v[206:209], v[88:91]
	v_mfma_f32_16x16x32_bf16 v[24:27], v[190:193], v[206:209], v[24:27]
	v_mfma_f32_16x16x32_bf16 v[80:83], v[158:161], v[214:217], v[80:83]
	v_mfma_f32_16x16x32_bf16 v[16:19], v[190:193], v[214:217], v[16:19]
	v_mfma_f32_16x16x32_bf16 v[72:75], v[158:161], v[222:225], v[72:75]
	v_mfma_f32_16x16x32_bf16 v[8:11], v[190:193], v[222:225], v[8:11]
	v_mfma_f32_16x16x32_bf16 v[64:67], v[158:161], v[230:233], v[64:67]
	v_mfma_f32_16x16x32_bf16 v[0:3], v[190:193], v[230:233], v[0:3]
	s_barrier
	s_add_u32 s66, s66, 0x100
	s_addc_u32 s67, s67, 0
	s_add_u32 s53, s53, 0x100
	s_addc_u32 s61, s61, 0
	s_cmp_ge_i32 vcc_lo, s29
	s_mov_b32 s68, vcc_lo
	s_cbranch_scc0 .LBB0_311

; #define PG8_STAGE(bufoff, gbase, voff) do { _Pragma("unroll") for (int _i = 0; _i < 2; ++_i) \
;         __builtin_amdgcn_global_load_lds((const unsigned*)((const char*)(gbase) + (voff)[_i]), (LAS unsigned*)(lds + (bufoff) + ldsw + _i * 8192), 16, 0, 0); } while (0)
; #define PG8_LDA(dst, b, h) do { _Pragma("unroll") for (int m = 0; m < 4; ++m) _Pragma("unroll") for (int k = 0; k < 2; ++k) dst[m][k] = *(const LAS bf16x8*)(lds + PG8_SA(b, h) + aoff + m * 2048 + k * 1024); } while (0)
; #define PG8_LDB(dst, b, h) do { _Pragma("unroll") for (int n = 0; n < 2; ++n) _Pragma("unroll") for (int k = 0; k < 2; ++k) dst[n][k] = *(const LAS bf16x8*)(lds + PG8_SB(b, h) + boff + n * 2048 + k * 1024); } while (0)
; #define PG8_MMA(ai, bj, At, Bt) do { __builtin_amdgcn_s_setprio(1); _Pragma("unroll") for (int m = 0; m < 4; ++m) _Pragma("unroll") for (int n = 0; n < 2; ++n) _Pragma("unroll") for (int k = 0; k < 2; ++k) \
;         acc[ai][bj][m][n] = __builtin_amdgcn_mfma_f32_16x16x32_bf16(Bt[n][k], At[m][k], acc[ai][bj][m][n], 0, 0, 0); __builtin_amdgcn_s_setprio(0); } while (0)
; #define PG8_WAIT_V(n) asm volatile("s_waitcnt vmcnt(" #n ")" ::: "memory")
; #define PG8_WAIT_L(n) asm volatile("s_waitcnt lgkmcnt(" #n ")" ::: "memory")
; #define PG8_BAR __builtin_amdgcn_s_barrier()
; template <class Epi, class Sched>
; __device__ __forceinline__ void gemm_phase(const int tid, LAS unsigned char* lds, const int lda, const int ldb, const int K, const Sched& S, const Epi& E) {
;     ...
;         for (int t = 0; t < nt; t += 2) {
;             const bool last = (t == nt - 2);
;             const char* a1 = cA + (size_t)(t + 1) * kstep;
;             const char* a2 = last ? nA : cA + (size_t)(t + 2) * kstep; const char* b2 = last ? nB : cB + (size_t)(t + 2) * kstep;
;             const char* a3 = a2 + kstep; const char* b3 = b2 + kstep;
;             PG8_LDB(B0, 0, 0); PG8_LDB(B1, 0, 1); PG8_SCHED; PG8_LDA(At, 0, 0); PG8_STAGE(PG8_SA(1, 1), a1 + hstepA, voffA);
;             PG8_WAIT_V(8); PG8_WAIT_L(0); PG8_BAR; PG8_MMA(0, 0, At, B0); PG8_MMA(0, 1, At, B1); PG8_BAR; PG8_SCHED;
;             PG8_LDA(At, 0, 1); PG8_STAGE(PG8_SB(0, 0), b2, voffB); PG8_STAGE(PG8_SB(0, 1), b2 + hstepB, voffB); PG8_STAGE(PG8_SA(0, 0), a2, voffA);
;             PG8_WAIT_V(8); PG8_WAIT_L(0); PG8_BAR; if (!cur.half) { PG8_MMA(1, 0, At, B0); PG8_MMA(1, 1, At, B1); } PG8_BAR; PG8_SCHED;
.LBB0_619:
	s_add_i32 s72, s24, 2
	s_add_u32 s14, s48, 0xfffc0080
	s_addc_u32 s15, s49, -1
	s_add_i32 s73, 0, 0x10000
	s_cmp_eq_u32 s66, s24
	s_cselect_b32 s57, s53, s15
	s_cselect_b32 s56, s52, s14
	v_add_u32_e32 v153, s73, v137
	s_cselect_b32 s51, s55, s71
	s_cselect_b32 s50, s54, s43
	s_add_i32 s14, 0, 0x14000
	ds_read_b128 v[142:145], v153
	ds_read_b128 v[154:157], v153 offset:1024
	ds_read_b128 v[158:161], v153 offset:2048
	ds_read_b128 v[162:165], v153 offset:3072
	v_add_u32_e32 v153, s14, v137
	ds_read_b128 v[180:183], v153
	ds_read_b128 v[184:187], v153 offset:1024
	ds_read_b128 v[190:193], v153 offset:2048
	ds_read_b128 v[194:197], v153 offset:3072
	v_lshl_add_u64 v[166:167], s[48:49], 0, v[138:139]
	s_add_i32 m0, s26, 0xc000
	ds_read_b128 v[206:209], v152
	ds_read_b128 v[210:213], v152 offset:1024
	ds_read_b128 v[214:217], v152 offset:2048
	ds_read_b128 v[218:221], v152 offset:3072
	ds_read_b128 v[222:225], v152 offset:4096
	ds_read_b128 v[226:229], v152 offset:5120
	ds_read_b128 v[230:233], v152 offset:6144
	ds_read_b128 v[234:237], v152 offset:7168
	global_load_lds_dwordx4 v[166:167], off
	v_lshl_add_u64 v[166:167], s[48:49], 0, v[140:141]
	s_add_i32 m0, s26, 0xe000
	s_nop 0
	global_load_lds_dwordx4 v[166:167], off
	s_waitcnt vmcnt(8)
	s_waitcnt lgkmcnt(0)
	s_barrier
	v_mfma_f32_16x16x32_bf16 v[124:127], v[142:145], v[206:209], v[124:127]
	v_mfma_f32_16x16x32_bf16 v[120:123], v[158:161], v[206:209], v[120:123]
	v_mfma_f32_16x16x32_bf16 v[108:111], v[142:145], v[214:217], v[108:111]
	v_mfma_f32_16x16x32_bf16 v[104:107], v[158:161], v[214:217], v[104:107]
	v_mfma_f32_16x16x32_bf16 v[92:95], v[142:145], v[222:225], v[92:95]
	v_mfma_f32_16x16x32_bf16 v[88:91], v[158:161], v[222:225], v[88:91]
	v_mfma_f32_16x16x32_bf16 v[76:79], v[142:145], v[230:233], v[76:79]
	v_mfma_f32_16x16x32_bf16 v[72:75], v[158:161], v[230:233], v[72:75]
	v_mfma_f32_16x16x32_bf16 v[124:127], v[154:157], v[210:213], v[124:127]
	v_mfma_f32_16x16x32_bf16 v[120:123], v[162:165], v[210:213], v[120:123]
	v_mfma_f32_16x16x32_bf16 v[108:111], v[154:157], v[218:221], v[108:111]
	v_mfma_f32_16x16x32_bf16 v[104:107], v[162:165], v[218:221], v[104:107]
	v_mfma_f32_16x16x32_bf16 v[92:95], v[154:157], v[226:229], v[92:95]
	v_mfma_f32_16x16x32_bf16 v[88:91], v[162:165], v[226:229], v[88:91]
	v_mfma_f32_16x16x32_bf16 v[76:79], v[154:157], v[234:237], v[76:79]
	v_mfma_f32_16x16x32_bf16 v[72:75], v[162:165], v[234:237], v[72:75]
	v_mfma_f32_16x16x32_bf16 v[116:119], v[180:183], v[206:209], v[116:119]
	v_mfma_f32_16x16x32_bf16 v[112:115], v[190:193], v[206:209], v[112:115]
	v_mfma_f32_16x16x32_bf16 v[100:103], v[180:183], v[214:217], v[100:103]
	v_mfma_f32_16x16x32_bf16 v[96:99], v[190:193], v[214:217], v[96:99]
	v_mfma_f32_16x16x32_bf16 v[84:87], v[180:183], v[222:225], v[84:87]
	v_mfma_f32_16x16x32_bf16 v[80:83], v[190:193], v[222:225], v[80:83]
	v_mfma_f32_16x16x32_bf16 v[68:71], v[180:183], v[230:233], v[68:71]
	v_mfma_f32_16x16x32_bf16 v[64:67], v[190:193], v[230:233], v[64:67]
	v_mfma_f32_16x16x32_bf16 v[116:119], v[184:187], v[210:213], v[116:119]
	v_mfma_f32_16x16x32_bf16 v[112:115], v[194:197], v[210:213], v[112:115]
	v_mfma_f32_16x16x32_bf16 v[100:103], v[184:187], v[218:221], v[100:103]
	v_mfma_f32_16x16x32_bf16 v[96:99], v[194:197], v[218:221], v[96:99]
	v_mfma_f32_16x16x32_bf16 v[84:87], v[184:187], v[226:229], v[84:87]
	v_mfma_f32_16x16x32_bf16 v[80:83], v[194:197], v[226:229], v[80:83]
	v_mfma_f32_16x16x32_bf16 v[68:71], v[184:187], v[234:237], v[68:71]
	v_mfma_f32_16x16x32_bf16 v[64:67], v[194:197], v[234:237], v[64:67]
	s_barrier
	s_add_i32 s15, s73, s59
	v_lshl_add_u64 v[166:167], s[50:51], 0, v[130:131]
	s_mov_b32 m0, s15
	ds_read_b128 v[206:209], v152 offset:16384
	ds_read_b128 v[210:213], v152 offset:17408
	ds_read_b128 v[214:217], v152 offset:18432
	ds_read_b128 v[218:221], v152 offset:19456
	ds_read_b128 v[222:225], v152 offset:20480
	ds_read_b128 v[226:229], v152 offset:21504
	ds_read_b128 v[230:233], v152 offset:22528
	ds_read_b128 v[234:237], v152 offset:23552
	global_load_lds_dwordx4 v[166:167], off
	s_add_i32 m0, s15, 0x2000
	s_add_u32 s74, s50, 0x40000
	v_lshl_add_u64 v[176:177], s[50:51], 0, v[134:135]
	s_addc_u32 s75, s51, 0
	s_add_i32 s14, s14, s59
	global_load_lds_dwordx4 v[176:177], off
	v_lshl_add_u64 v[238:239], s[74:75], 0, v[130:131]
	s_mov_b32 m0, s14
	v_lshl_add_u64 v[240:241], s[56:57], 0, v[132:133]
	global_load_lds_dwordx4 v[238:239], off
	v_lshl_add_u64 v[238:239], s[74:75], 0, v[134:135]
	s_add_i32 m0, s14, 0x2000
	s_nop 0
	global_load_lds_dwordx4 v[238:239], off
	v_lshl_add_u64 v[238:239], s[56:57], 0, v[128:129]
	s_mov_b32 m0, s26
	s_nop 0
	global_load_lds_dwordx4 v[238:239], off
	s_mov_b32 m0, s27
	s_nop 0
	global_load_lds_dwordx4 v[240:241], off
	s_waitcnt vmcnt(8)
	s_waitcnt lgkmcnt(0)
	s_barrier
; #define PG8_STAGE(bufoff, gbase, voff) do { _Pragma("unroll") for (int _i = 0; _i < 2; ++_i) \
;         __builtin_amdgcn_global_load_lds((const unsigned*)((const char*)(gbase) + (voff)[_i]), (LAS unsigned*)(lds + (bufoff) + ldsw + _i * 8192), 16, 0, 0); } while (0)
; #define PG8_LDA(dst, b, h) do { _Pragma("unroll") for (int m = 0; m < 4; ++m) _Pragma("unroll") for (int k = 0; k < 2; ++k) dst[m][k] = *(const LAS bf16x8*)(lds + PG8_SA(b, h) + aoff + m * 2048 + k * 1024); } while (0)
; #define PG8_LDB(dst, b, h) do { _Pragma("unroll") for (int n = 0; n < 2; ++n) _Pragma("unroll") for (int k = 0; k < 2; ++k) dst[n][k] = *(const LAS bf16x8*)(lds + PG8_SB(b, h) + boff + n * 2048 + k * 1024); } while (0)
; #define PG8_MMA(ai, bj, At, Bt) do { __builtin_amdgcn_s_setprio(1); _Pragma("unroll") for (int m = 0; m < 4; ++m) _Pragma("unroll") for (int n = 0; n < 2; ++n) _Pragma("unroll") for (int k = 0; k < 2; ++k) \
;         acc[ai][bj][m][n] = __builtin_amdgcn_mfma_f32_16x16x32_bf16(Bt[n][k], At[m][k], acc[ai][bj][m][n], 0, 0, 0); __builtin_amdgcn_s_setprio(0); } while (0)
; #define PG8_WAIT_V(n) asm volatile("s_waitcnt vmcnt(" #n ")" ::: "memory")
; #define PG8_WAIT_L(n) asm volatile("s_waitcnt lgkmcnt(" #n ")" ::: "memory")
; #define PG8_BAR __builtin_amdgcn_s_barrier()
; #define PG8_SCHED __builtin_amdgcn_sched_barrier(0)
; template <class Epi, class Sched>
; __device__ __forceinline__ void gemm_phase(const int tid, LAS unsigned char* lds, const int lda, const int ldb, const int K, const Sched& S, const Epi& E) {
;     ...
;             PG8_WAIT_V(8); PG8_WAIT_L(0); PG8_BAR; if (!cur.half) { PG8_MMA(1, 0, At, B0); PG8_MMA(1, 1, At, B1); } PG8_BAR; PG8_SCHED;
;             PG8_LDB(B0, 1, 0); PG8_LDB(B1, 1, 1); PG8_SCHED; PG8_LDA(At, 1, 0); PG8_STAGE(PG8_SA(0, 1), a2 + hstepA, voffA);
;             PG8_WAIT_V(8); PG8_WAIT_L(0); PG8_BAR; PG8_MMA(0, 0, At, B0); PG8_MMA(0, 1, At, B1); PG8_BAR; PG8_SCHED;
	v_mfma_f32_16x16x32_bf16 v[60:63], v[142:145], v[206:209], v[60:63]
	v_mfma_f32_16x16x32_bf16 v[56:59], v[158:161], v[206:209], v[56:59]
	v_mfma_f32_16x16x32_bf16 v[44:47], v[142:145], v[214:217], v[44:47]
	v_mfma_f32_16x16x32_bf16 v[40:43], v[158:161], v[214:217], v[40:43]
	v_mfma_f32_16x16x32_bf16 v[28:31], v[142:145], v[222:225], v[28:31]
	v_mfma_f32_16x16x32_bf16 v[24:27], v[158:161], v[222:225], v[24:27]
	v_mfma_f32_16x16x32_bf16 v[12:15], v[142:145], v[230:233], v[12:15]
	v_mfma_f32_16x16x32_bf16 v[8:11], v[158:161], v[230:233], v[8:11]
	v_mfma_f32_16x16x32_bf16 v[60:63], v[154:157], v[210:213], v[60:63]
	v_mfma_f32_16x16x32_bf16 v[56:59], v[162:165], v[210:213], v[56:59]
	v_mfma_f32_16x16x32_bf16 v[44:47], v[154:157], v[218:221], v[44:47]
	v_mfma_f32_16x16x32_bf16 v[40:43], v[162:165], v[218:221], v[40:43]
	v_mfma_f32_16x16x32_bf16 v[28:31], v[154:157], v[226:229], v[28:31]
	v_mfma_f32_16x16x32_bf16 v[24:27], v[162:165], v[226:229], v[24:27]
	v_mfma_f32_16x16x32_bf16 v[12:15], v[154:157], v[234:237], v[12:15]
	v_mfma_f32_16x16x32_bf16 v[8:11], v[162:165], v[234:237], v[8:11]
	v_mfma_f32_16x16x32_bf16 v[52:55], v[180:183], v[206:209], v[52:55]
	v_mfma_f32_16x16x32_bf16 v[48:51], v[190:193], v[206:209], v[48:51]
	v_mfma_f32_16x16x32_bf16 v[36:39], v[180:183], v[214:217], v[36:39]
	v_mfma_f32_16x16x32_bf16 v[32:35], v[190:193], v[214:217], v[32:35]
	v_mfma_f32_16x16x32_bf16 v[20:23], v[180:183], v[222:225], v[20:23]
	v_mfma_f32_16x16x32_bf16 v[16:19], v[190:193], v[222:225], v[16:19]
	v_mfma_f32_16x16x32_bf16 v[4:7], v[180:183], v[230:233], v[4:7]
	v_mfma_f32_16x16x32_bf16 v[0:3], v[190:193], v[230:233], v[0:3]
	v_mfma_f32_16x16x32_bf16 v[52:55], v[184:187], v[210:213], v[52:55]
	v_mfma_f32_16x16x32_bf16 v[48:51], v[194:197], v[210:213], v[48:51]
	v_mfma_f32_16x16x32_bf16 v[36:39], v[184:187], v[218:221], v[36:39]
	v_mfma_f32_16x16x32_bf16 v[32:35], v[194:197], v[218:221], v[32:35]
	v_mfma_f32_16x16x32_bf16 v[20:23], v[184:187], v[226:229], v[20:23]
	v_mfma_f32_16x16x32_bf16 v[16:19], v[194:197], v[226:229], v[16:19]
	v_mfma_f32_16x16x32_bf16 v[4:7], v[184:187], v[234:237], v[4:7]
	v_mfma_f32_16x16x32_bf16 v[0:3], v[194:197], v[234:237], v[0:3]
	s_barrier
	s_add_i32 s14, 0, 0x18000
	v_add_u32_e32 v153, s14, v137
	s_add_i32 s15, 0, 0x1c000
	ds_read_b128 v[142:145], v153
	ds_read_b128 v[154:157], v153 offset:1024
	ds_read_b128 v[158:161], v153 offset:2048
	ds_read_b128 v[162:165], v153 offset:3072
	v_add_u32_e32 v153, s15, v137
	ds_read_b128 v[180:183], v153
	ds_read_b128 v[184:187], v153 offset:1024
	ds_read_b128 v[190:193], v153 offset:2048
	ds_read_b128 v[194:197], v153 offset:3072
	s_add_u32 s56, s56, 0x40000
	s_addc_u32 s57, s57, 0
	s_mov_b32 m0, s60
	v_lshl_add_u64 v[242:243], s[56:57], 0, v[128:129]
	ds_read_b128 v[206:209], v152 offset:32768
	ds_read_b128 v[210:213], v152 offset:33792
	ds_read_b128 v[214:217], v152 offset:34816
	ds_read_b128 v[218:221], v152 offset:35840
	ds_read_b128 v[222:225], v152 offset:36864
	ds_read_b128 v[226:229], v152 offset:37888
	ds_read_b128 v[230:233], v152 offset:38912
	ds_read_b128 v[234:237], v152 offset:39936
	global_load_lds_dwordx4 v[242:243], off
	v_lshl_add_u64 v[242:243], s[56:57], 0, v[132:133]
	s_mov_b32 m0, s61
	s_nop 0
	global_load_lds_dwordx4 v[242:243], off
	s_waitcnt vmcnt(8)
	s_waitcnt lgkmcnt(0)
	s_barrier
	v_mfma_f32_16x16x32_bf16 v[124:127], v[142:145], v[206:209], v[124:127]
	v_mfma_f32_16x16x32_bf16 v[120:123], v[158:161], v[206:209], v[120:123]
	v_mfma_f32_16x16x32_bf16 v[108:111], v[142:145], v[214:217], v[108:111]
	v_mfma_f32_16x16x32_bf16 v[104:107], v[158:161], v[214:217], v[104:107]
	v_mfma_f32_16x16x32_bf16 v[92:95], v[142:145], v[222:225], v[92:95]
	v_mfma_f32_16x16x32_bf16 v[88:91], v[158:161], v[222:225], v[88:91]
	v_mfma_f32_16x16x32_bf16 v[76:79], v[142:145], v[230:233], v[76:79]
	v_mfma_f32_16x16x32_bf16 v[72:75], v[158:161], v[230:233], v[72:75]
	v_mfma_f32_16x16x32_bf16 v[124:127], v[154:157], v[210:213], v[124:127]
	v_mfma_f32_16x16x32_bf16 v[120:123], v[162:165], v[210:213], v[120:123]
	v_mfma_f32_16x16x32_bf16 v[108:111], v[154:157], v[218:221], v[108:111]
	v_mfma_f32_16x16x32_bf16 v[104:107], v[162:165], v[218:221], v[104:107]
	v_mfma_f32_16x16x32_bf16 v[92:95], v[154:157], v[226:229], v[92:95]
	v_mfma_f32_16x16x32_bf16 v[88:91], v[162:165], v[226:229], v[88:91]
	v_mfma_f32_16x16x32_bf16 v[76:79], v[154:157], v[234:237], v[76:79]
	v_mfma_f32_16x16x32_bf16 v[72:75], v[162:165], v[234:237], v[72:75]
	v_mfma_f32_16x16x32_bf16 v[116:119], v[180:183], v[206:209], v[116:119]
	v_mfma_f32_16x16x32_bf16 v[112:115], v[190:193], v[206:209], v[112:115]
	v_mfma_f32_16x16x32_bf16 v[100:103], v[180:183], v[214:217], v[100:103]
	v_mfma_f32_16x16x32_bf16 v[96:99], v[190:193], v[214:217], v[96:99]
	v_mfma_f32_16x16x32_bf16 v[84:87], v[180:183], v[222:225], v[84:87]
	v_mfma_f32_16x16x32_bf16 v[80:83], v[190:193], v[222:225], v[80:83]
	v_mfma_f32_16x16x32_bf16 v[68:71], v[180:183], v[230:233], v[68:71]
	v_mfma_f32_16x16x32_bf16 v[64:67], v[190:193], v[230:233], v[64:67]
	v_mfma_f32_16x16x32_bf16 v[116:119], v[184:187], v[210:213], v[116:119]
	v_mfma_f32_16x16x32_bf16 v[112:115], v[194:197], v[210:213], v[112:115]
	v_mfma_f32_16x16x32_bf16 v[100:103], v[184:187], v[218:221], v[100:103]
	v_mfma_f32_16x16x32_bf16 v[96:99], v[194:197], v[218:221], v[96:99]
	v_mfma_f32_16x16x32_bf16 v[84:87], v[184:187], v[226:229], v[84:87]
	v_mfma_f32_16x16x32_bf16 v[80:83], v[194:197], v[226:229], v[80:83]
	v_mfma_f32_16x16x32_bf16 v[68:71], v[184:187], v[234:237], v[68:71]
	v_mfma_f32_16x16x32_bf16 v[64:67], v[194:197], v[234:237], v[64:67]
	s_barrier
; #define PG8_STAGE(bufoff, gbase, voff) do { _Pragma("unroll") for (int _i = 0; _i < 2; ++_i) \
;         __builtin_amdgcn_global_load_lds((const unsigned*)((const char*)(gbase) + (voff)[_i]), (LAS unsigned*)(lds + (bufoff) + ldsw + _i * 8192), 16, 0, 0); } while (0)
; #define PG8_LDA(dst, b, h) do { _Pragma("unroll") for (int m = 0; m < 4; ++m) _Pragma("unroll") for (int k = 0; k < 2; ++k) dst[m][k] = *(const LAS bf16x8*)(lds + PG8_SA(b, h) + aoff + m * 2048 + k * 1024); } while (0)
; #define PG8_MMA(ai, bj, At, Bt) do { __builtin_amdgcn_s_setprio(1); _Pragma("unroll") for (int m = 0; m < 4; ++m) _Pragma("unroll") for (int n = 0; n < 2; ++n) _Pragma("unroll") for (int k = 0; k < 2; ++k) \
;         acc[ai][bj][m][n] = __builtin_amdgcn_mfma_f32_16x16x32_bf16(Bt[n][k], At[m][k], acc[ai][bj][m][n], 0, 0, 0); __builtin_amdgcn_s_setprio(0); } while (0)
; #define PG8_WAIT_V(n) asm volatile("s_waitcnt vmcnt(" #n ")" ::: "memory")
; #define PG8_WAIT_L(n) asm volatile("s_waitcnt lgkmcnt(" #n ")" ::: "memory")
; #define PG8_BAR __builtin_amdgcn_s_barrier()
; #define PG8_SCHED __builtin_amdgcn_sched_barrier(0)
; template <class Epi, class Sched>
; __device__ __forceinline__ void gemm_phase(const int tid, LAS unsigned char* lds, const int lda, const int ldb, const int K, const Sched& S, const Epi& E) {
;     ...
;             PG8_LDA(At, 1, 1); PG8_STAGE(PG8_SB(1, 0), b3, voffB); PG8_STAGE(PG8_SB(1, 1), b3 + hstepB, voffB); PG8_STAGE(PG8_SA(1, 0), a3, voffA);
;             PG8_WAIT_V(8); PG8_WAIT_L(0); PG8_BAR; if (!cur.half) { PG8_MMA(1, 0, At, B0); PG8_MMA(1, 1, At, B1); } PG8_BAR; PG8_SCHED;
	s_add_i32 s14, s14, s59
	v_lshl_add_u64 v[166:167], v[166:167], 0, s[6:7]
	s_mov_b32 m0, s14
	ds_read_b128 v[206:209], v152 offset:49152
	ds_read_b128 v[210:213], v152 offset:50176
	ds_read_b128 v[214:217], v152 offset:51200
	ds_read_b128 v[218:221], v152 offset:52224
	ds_read_b128 v[222:225], v152 offset:53248
	ds_read_b128 v[226:229], v152 offset:54272
	ds_read_b128 v[230:233], v152 offset:55296
	ds_read_b128 v[234:237], v152 offset:56320
	global_load_lds_dwordx4 v[166:167], off
	s_add_i32 m0, s14, 0x2000
	s_add_u32 s50, s50, 0x40080
	v_lshl_add_u64 v[166:167], v[176:177], 0, s[6:7]
	s_addc_u32 s51, s51, 0
	s_add_i32 s14, s15, s59
	global_load_lds_dwordx4 v[166:167], off
	v_lshl_add_u64 v[166:167], s[50:51], 0, v[130:131]
	s_mov_b32 m0, s14
	s_nop 0
	global_load_lds_dwordx4 v[166:167], off
	v_lshl_add_u64 v[166:167], s[50:51], 0, v[134:135]
	s_add_i32 m0, s14, 0x2000
	s_nop 0
	global_load_lds_dwordx4 v[166:167], off
	v_lshl_add_u64 v[166:167], v[238:239], 0, s[6:7]
	s_mov_b32 m0, s63
	s_nop 0
	global_load_lds_dwordx4 v[166:167], off
	v_lshl_add_u64 v[166:167], v[240:241], 0, s[6:7]
	s_mov_b32 m0, s64
	s_nop 0
	global_load_lds_dwordx4 v[166:167], off
	s_waitcnt vmcnt(8)
	s_waitcnt lgkmcnt(0)
	s_barrier
	v_mfma_f32_16x16x32_bf16 v[60:63], v[142:145], v[206:209], v[60:63]
	v_mfma_f32_16x16x32_bf16 v[56:59], v[158:161], v[206:209], v[56:59]
	v_mfma_f32_16x16x32_bf16 v[44:47], v[142:145], v[214:217], v[44:47]
	v_mfma_f32_16x16x32_bf16 v[40:43], v[158:161], v[214:217], v[40:43]
	v_mfma_f32_16x16x32_bf16 v[28:31], v[142:145], v[222:225], v[28:31]
	v_mfma_f32_16x16x32_bf16 v[24:27], v[158:161], v[222:225], v[24:27]
	v_mfma_f32_16x16x32_bf16 v[12:15], v[142:145], v[230:233], v[12:15]
	v_mfma_f32_16x16x32_bf16 v[8:11], v[158:161], v[230:233], v[8:11]
	v_mfma_f32_16x16x32_bf16 v[60:63], v[154:157], v[210:213], v[60:63]
	v_mfma_f32_16x16x32_bf16 v[56:59], v[162:165], v[210:213], v[56:59]
	v_mfma_f32_16x16x32_bf16 v[44:47], v[154:157], v[218:221], v[44:47]
	v_mfma_f32_16x16x32_bf16 v[40:43], v[162:165], v[218:221], v[40:43]
	v_mfma_f32_16x16x32_bf16 v[28:31], v[154:157], v[226:229], v[28:31]
	v_mfma_f32_16x16x32_bf16 v[24:27], v[162:165], v[226:229], v[24:27]
	v_mfma_f32_16x16x32_bf16 v[12:15], v[154:157], v[234:237], v[12:15]
	v_mfma_f32_16x16x32_bf16 v[8:11], v[162:165], v[234:237], v[8:11]
	v_mfma_f32_16x16x32_bf16 v[52:55], v[180:183], v[206:209], v[52:55]
	v_mfma_f32_16x16x32_bf16 v[48:51], v[190:193], v[206:209], v[48:51]
	v_mfma_f32_16x16x32_bf16 v[36:39], v[180:183], v[214:217], v[36:39]
	v_mfma_f32_16x16x32_bf16 v[32:35], v[190:193], v[214:217], v[32:35]
	v_mfma_f32_16x16x32_bf16 v[20:23], v[180:183], v[222:225], v[20:23]
	v_mfma_f32_16x16x32_bf16 v[16:19], v[190:193], v[222:225], v[16:19]
	v_mfma_f32_16x16x32_bf16 v[4:7], v[180:183], v[230:233], v[4:7]
	v_mfma_f32_16x16x32_bf16 v[0:3], v[190:193], v[230:233], v[0:3]
	v_mfma_f32_16x16x32_bf16 v[52:55], v[184:187], v[210:213], v[52:55]
	v_mfma_f32_16x16x32_bf16 v[48:51], v[194:197], v[210:213], v[48:51]
	v_mfma_f32_16x16x32_bf16 v[36:39], v[184:187], v[218:221], v[36:39]
	v_mfma_f32_16x16x32_bf16 v[32:35], v[194:197], v[218:221], v[32:35]
	v_mfma_f32_16x16x32_bf16 v[20:23], v[184:187], v[226:229], v[20:23]
	v_mfma_f32_16x16x32_bf16 v[16:19], v[194:197], v[226:229], v[16:19]
	v_mfma_f32_16x16x32_bf16 v[4:7], v[184:187], v[234:237], v[4:7]
	v_mfma_f32_16x16x32_bf16 v[0:3], v[194:197], v[234:237], v[0:3]
	s_barrier
	s_add_u32 s48, s48, 0x100
	s_addc_u32 s49, s49, 0
	s_add_u32 s43, s43, 0x100
	s_addc_u32 s71, s71, 0
	s_cmp_ge_i32 s72, s31
	s_mov_b32 s24, s72
	s_cbranch_scc0 .LBB0_619
	v_readlane_b32 s74, v254, 54
	v_readlane_b32 s75, v254, 55
	s_movk_i32 s71, 0x1600

; #define PG8_STAGE(bufoff, gbase, voff) do { _Pragma("unroll") for (int _i = 0; _i < 2; ++_i) \
;         __builtin_amdgcn_global_load_lds((const unsigned*)((const char*)(gbase) + (voff)[_i]), (LAS unsigned*)(lds + (bufoff) + ldsw + _i * 8192), 16, 0, 0); } while (0)
; #define PG8_LDA(dst, b, h) do { _Pragma("unroll") for (int m = 0; m < 4; ++m) _Pragma("unroll") for (int k = 0; k < 2; ++k) dst[m][k] = *(const LAS bf16x8*)(lds + PG8_SA(b, h) + aoff + m * 2048 + k * 1024); } while (0)
; #define PG8_LDB(dst, b, h) do { _Pragma("unroll") for (int n = 0; n < 2; ++n) _Pragma("unroll") for (int k = 0; k < 2; ++k) dst[n][k] = *(const LAS bf16x8*)(lds + PG8_SB(b, h) + boff + n * 2048 + k * 1024); } while (0)
; #define PG8_MMA(ai, bj, At, Bt) do { __builtin_amdgcn_s_setprio(1); _Pragma("unroll") for (int m = 0; m < 4; ++m) _Pragma("unroll") for (int n = 0; n < 2; ++n) _Pragma("unroll") for (int k = 0; k < 2; ++k) \
;         acc[ai][bj][m][n] = __builtin_amdgcn_mfma_f32_16x16x32_bf16(Bt[n][k], At[m][k], acc[ai][bj][m][n], 0, 0, 0); __builtin_amdgcn_s_setprio(0); } while (0)
; #define PG8_WAIT_V(n) asm volatile("s_waitcnt vmcnt(" #n ")" ::: "memory")
; #define PG8_WAIT_L(n) asm volatile("s_waitcnt lgkmcnt(" #n ")" ::: "memory")
; #define PG8_BAR __builtin_amdgcn_s_barrier()
; template <class Epi, class Sched>
; __device__ __forceinline__ void gemm_phase(const int tid, LAS unsigned char* lds, const int lda, const int ldb, const int K, const Sched& S, const Epi& E) {
;     ...
;         for (int t = 0; t < nt; t += 2) {
;             const bool last = (t == nt - 2);
;             const char* a1 = cA + (size_t)(t + 1) * kstep;
;             const char* a2 = last ? nA : cA + (size_t)(t + 2) * kstep; const char* b2 = last ? nB : cB + (size_t)(t + 2) * kstep;
;             const char* a3 = a2 + kstep; const char* b3 = b2 + kstep;
;             PG8_LDB(B0, 0, 0); PG8_LDB(B1, 0, 1); PG8_SCHED; PG8_LDA(At, 0, 0); PG8_STAGE(PG8_SA(1, 1), a1 + hstepA, voffA);
;             PG8_WAIT_V(8); PG8_WAIT_L(0); PG8_BAR; PG8_MMA(0, 0, At, B0); PG8_MMA(0, 1, At, B1); PG8_BAR; PG8_SCHED;
;             PG8_LDA(At, 0, 1); PG8_STAGE(PG8_SB(0, 0), b2, voffB); PG8_STAGE(PG8_SB(0, 1), b2 + hstepB, voffB); PG8_STAGE(PG8_SA(0, 0), a2, voffA);
;             PG8_WAIT_V(8); PG8_WAIT_L(0); PG8_BAR; if (!cur.half) { PG8_MMA(1, 0, At, B0); PG8_MMA(1, 1, At, B1); } PG8_BAR; PG8_SCHED;
.LBB0_679:
	s_andn2_b64 vcc, exec, s[40:41]
	s_cbranch_vccnz .LBB0_727
	s_add_u32 s50, s50, 0x40080
	s_addc_u32 s51, s51, 0
	s_add_u32 s26, s52, 0x100
	s_addc_u32 s27, s53, 0
	s_mov_b32 s45, 0
	s_add_i32 s67, s45, 2
	s_add_u32 s14, s50, 0xfffc0080
	s_addc_u32 s15, s51, -1
	s_add_i32 s24, 0, 0x10000
	s_cmp_eq_u32 s63, s45
	s_cselect_b32 s55, s3, s15
	s_cselect_b32 s54, s2, s14
	v_add_u32_e32 v146, s24, v152
	s_cselect_b32 s53, s39, s27
	s_cselect_b32 s52, s38, s26
	s_add_i32 s14, 0, 0x14000
	ds_read_b128 v[142:145], v146
	ds_read_b128 v[162:165], v146 offset:1024
	ds_read_b128 v[180:183], v146 offset:2048
	ds_read_b128 v[184:187], v146 offset:3072
	v_add_u32_e32 v146, s14, v152
	ds_read_b128 v[190:193], v146
	ds_read_b128 v[194:197], v146 offset:1024
	ds_read_b128 v[206:209], v146 offset:2048
	ds_read_b128 v[210:213], v146 offset:3072
	v_lshl_add_u64 v[146:147], s[50:51], 0, v[136:137]
	s_add_i32 m0, s56, 0xc000
	ds_read_b128 v[214:217], v160
	ds_read_b128 v[218:221], v160 offset:1024
	ds_read_b128 v[222:225], v160 offset:2048
	ds_read_b128 v[226:229], v160 offset:3072
	ds_read_b128 v[230:233], v160 offset:4096
	ds_read_b128 v[234:237], v160 offset:5120
	ds_read_b128 v[238:241], v160 offset:6144
	ds_read_b128 v[242:245], v160 offset:7168
	global_load_lds_dwordx4 v[146:147], off
	v_lshl_add_u64 v[146:147], s[50:51], 0, v[138:139]
	s_add_i32 m0, s56, 0xe000
	s_nop 0
	global_load_lds_dwordx4 v[146:147], off
	s_waitcnt vmcnt(8)
	s_waitcnt lgkmcnt(0)
	s_barrier
	v_mfma_f32_16x16x32_bf16 v[124:127], v[142:145], v[214:217], 0
	v_mfma_f32_16x16x32_bf16 v[120:123], v[180:183], v[214:217], 0
	v_mfma_f32_16x16x32_bf16 v[108:111], v[142:145], v[222:225], 0
	v_mfma_f32_16x16x32_bf16 v[104:107], v[180:183], v[222:225], 0
	v_mfma_f32_16x16x32_bf16 v[92:95], v[142:145], v[230:233], 0
	v_mfma_f32_16x16x32_bf16 v[88:91], v[180:183], v[230:233], 0
	v_mfma_f32_16x16x32_bf16 v[76:79], v[142:145], v[238:241], 0
	v_mfma_f32_16x16x32_bf16 v[72:75], v[180:183], v[238:241], 0
	v_mfma_f32_16x16x32_bf16 v[124:127], v[162:165], v[218:221], v[124:127]
	v_mfma_f32_16x16x32_bf16 v[120:123], v[184:187], v[218:221], v[120:123]
	v_mfma_f32_16x16x32_bf16 v[108:111], v[162:165], v[226:229], v[108:111]
	v_mfma_f32_16x16x32_bf16 v[104:107], v[184:187], v[226:229], v[104:107]
	v_mfma_f32_16x16x32_bf16 v[92:95], v[162:165], v[234:237], v[92:95]
	v_mfma_f32_16x16x32_bf16 v[88:91], v[184:187], v[234:237], v[88:91]
	v_mfma_f32_16x16x32_bf16 v[76:79], v[162:165], v[242:245], v[76:79]
	v_mfma_f32_16x16x32_bf16 v[72:75], v[184:187], v[242:245], v[72:75]
	v_mfma_f32_16x16x32_bf16 v[116:119], v[190:193], v[214:217], 0
	v_mfma_f32_16x16x32_bf16 v[112:115], v[206:209], v[214:217], 0
	v_mfma_f32_16x16x32_bf16 v[100:103], v[190:193], v[222:225], 0
	v_mfma_f32_16x16x32_bf16 v[96:99], v[206:209], v[222:225], 0
	v_mfma_f32_16x16x32_bf16 v[84:87], v[190:193], v[230:233], 0
	v_mfma_f32_16x16x32_bf16 v[80:83], v[206:209], v[230:233], 0
	v_mfma_f32_16x16x32_bf16 v[68:71], v[190:193], v[238:241], 0
	v_mfma_f32_16x16x32_bf16 v[64:67], v[206:209], v[238:241], 0
	v_mfma_f32_16x16x32_bf16 v[116:119], v[194:197], v[218:221], v[116:119]
	v_mfma_f32_16x16x32_bf16 v[112:115], v[210:213], v[218:221], v[112:115]
	v_mfma_f32_16x16x32_bf16 v[100:103], v[194:197], v[226:229], v[100:103]
	v_mfma_f32_16x16x32_bf16 v[96:99], v[210:213], v[226:229], v[96:99]
	v_mfma_f32_16x16x32_bf16 v[84:87], v[194:197], v[234:237], v[84:87]
	v_mfma_f32_16x16x32_bf16 v[80:83], v[210:213], v[234:237], v[80:83]
	v_mfma_f32_16x16x32_bf16 v[68:71], v[194:197], v[242:245], v[68:71]
	v_mfma_f32_16x16x32_bf16 v[64:67], v[210:213], v[242:245], v[64:67]
	s_barrier
	s_add_i32 s15, s24, s31
	v_lshl_add_u64 v[146:147], s[52:53], 0, v[130:131]
	s_mov_b32 m0, s15
	ds_read_b128 v[214:217], v160 offset:16384
	ds_read_b128 v[218:221], v160 offset:17408
	ds_read_b128 v[222:225], v160 offset:18432
	ds_read_b128 v[226:229], v160 offset:19456
	ds_read_b128 v[230:233], v160 offset:20480
	ds_read_b128 v[234:237], v160 offset:21504
	ds_read_b128 v[238:241], v160 offset:22528
	ds_read_b128 v[242:245], v160 offset:23552
	global_load_lds_dwordx4 v[146:147], off
	s_add_i32 m0, s15, 0x2000
	s_add_u32 s68, s52, 0x40000
	v_lshl_add_u64 v[166:167], s[52:53], 0, v[134:135]
	s_addc_u32 s69, s53, 0
	s_add_i32 s14, s14, s31
	global_load_lds_dwordx4 v[166:167], off
	v_lshl_add_u64 v[176:177], s[68:69], 0, v[130:131]
	s_mov_b32 m0, s14
	v_lshl_add_u64 v[246:247], s[54:55], 0, v[132:133]
	global_load_lds_dwordx4 v[176:177], off
	v_lshl_add_u64 v[176:177], s[68:69], 0, v[134:135]
	s_add_i32 m0, s14, 0x2000
	s_nop 0
	global_load_lds_dwordx4 v[176:177], off
	v_lshl_add_u64 v[176:177], s[54:55], 0, v[128:129]
	s_mov_b32 m0, s56
	s_nop 0
	global_load_lds_dwordx4 v[176:177], off
	s_mov_b32 m0, s57
	s_nop 0
	global_load_lds_dwordx4 v[246:247], off
	s_waitcnt vmcnt(8)
	s_waitcnt lgkmcnt(0)
	s_barrier
; #define PG8_STAGE(bufoff, gbase, voff) do { _Pragma("unroll") for (int _i = 0; _i < 2; ++_i) \
;         __builtin_amdgcn_global_load_lds((const unsigned*)((const char*)(gbase) + (voff)[_i]), (LAS unsigned*)(lds + (bufoff) + ldsw + _i * 8192), 16, 0, 0); } while (0)
; #define PG8_LDA(dst, b, h) do { _Pragma("unroll") for (int m = 0; m < 4; ++m) _Pragma("unroll") for (int k = 0; k < 2; ++k) dst[m][k] = *(const LAS bf16x8*)(lds + PG8_SA(b, h) + aoff + m * 2048 + k * 1024); } while (0)
; #define PG8_LDB(dst, b, h) do { _Pragma("unroll") for (int n = 0; n < 2; ++n) _Pragma("unroll") for (int k = 0; k < 2; ++k) dst[n][k] = *(const LAS bf16x8*)(lds + PG8_SB(b, h) + boff + n * 2048 + k * 1024); } while (0)
; #define PG8_MMA(ai, bj, At, Bt) do { __builtin_amdgcn_s_setprio(1); _Pragma("unroll") for (int m = 0; m < 4; ++m) _Pragma("unroll") for (int n = 0; n < 2; ++n) _Pragma("unroll") for (int k = 0; k < 2; ++k) \
;         acc[ai][bj][m][n] = __builtin_amdgcn_mfma_f32_16x16x32_bf16(Bt[n][k], At[m][k], acc[ai][bj][m][n], 0, 0, 0); __builtin_amdgcn_s_setprio(0); } while (0)
; #define PG8_WAIT_V(n) asm volatile("s_waitcnt vmcnt(" #n ")" ::: "memory")
; #define PG8_WAIT_L(n) asm volatile("s_waitcnt lgkmcnt(" #n ")" ::: "memory")
; #define PG8_BAR __builtin_amdgcn_s_barrier()
; #define PG8_SCHED __builtin_amdgcn_sched_barrier(0)
; template <class Epi, class Sched>
; __device__ __forceinline__ void gemm_phase(const int tid, LAS unsigned char* lds, const int lda, const int ldb, const int K, const Sched& S, const Epi& E) {
;     ...
;             PG8_WAIT_V(8); PG8_WAIT_L(0); PG8_BAR; if (!cur.half) { PG8_MMA(1, 0, At, B0); PG8_MMA(1, 1, At, B1); } PG8_BAR; PG8_SCHED;
;             PG8_LDB(B0, 1, 0); PG8_LDB(B1, 1, 1); PG8_SCHED; PG8_LDA(At, 1, 0); PG8_STAGE(PG8_SA(0, 1), a2 + hstepA, voffA);
;             PG8_WAIT_V(8); PG8_WAIT_L(0); PG8_BAR; PG8_MMA(0, 0, At, B0); PG8_MMA(0, 1, At, B1); PG8_BAR; PG8_SCHED;
	v_mfma_f32_16x16x32_bf16 v[60:63], v[142:145], v[214:217], 0
	v_mfma_f32_16x16x32_bf16 v[56:59], v[180:183], v[214:217], 0
	v_mfma_f32_16x16x32_bf16 v[44:47], v[142:145], v[222:225], 0
	v_mfma_f32_16x16x32_bf16 v[40:43], v[180:183], v[222:225], 0
	v_mfma_f32_16x16x32_bf16 v[28:31], v[142:145], v[230:233], 0
	v_mfma_f32_16x16x32_bf16 v[24:27], v[180:183], v[230:233], 0
	v_mfma_f32_16x16x32_bf16 v[12:15], v[142:145], v[238:241], 0
	v_mfma_f32_16x16x32_bf16 v[8:11], v[180:183], v[238:241], 0
	v_mfma_f32_16x16x32_bf16 v[60:63], v[162:165], v[218:221], v[60:63]
	v_mfma_f32_16x16x32_bf16 v[56:59], v[184:187], v[218:221], v[56:59]
	v_mfma_f32_16x16x32_bf16 v[44:47], v[162:165], v[226:229], v[44:47]
	v_mfma_f32_16x16x32_bf16 v[40:43], v[184:187], v[226:229], v[40:43]
	v_mfma_f32_16x16x32_bf16 v[28:31], v[162:165], v[234:237], v[28:31]
	v_mfma_f32_16x16x32_bf16 v[24:27], v[184:187], v[234:237], v[24:27]
	v_mfma_f32_16x16x32_bf16 v[12:15], v[162:165], v[242:245], v[12:15]
	v_mfma_f32_16x16x32_bf16 v[8:11], v[184:187], v[242:245], v[8:11]
	v_mfma_f32_16x16x32_bf16 v[52:55], v[190:193], v[214:217], 0
	v_mfma_f32_16x16x32_bf16 v[48:51], v[206:209], v[214:217], 0
	v_mfma_f32_16x16x32_bf16 v[36:39], v[190:193], v[222:225], 0
	v_mfma_f32_16x16x32_bf16 v[32:35], v[206:209], v[222:225], 0
	v_mfma_f32_16x16x32_bf16 v[20:23], v[190:193], v[230:233], 0
	v_mfma_f32_16x16x32_bf16 v[16:19], v[206:209], v[230:233], 0
	v_mfma_f32_16x16x32_bf16 v[4:7], v[190:193], v[238:241], 0
	v_mfma_f32_16x16x32_bf16 v[0:3], v[206:209], v[238:241], 0
	v_mfma_f32_16x16x32_bf16 v[52:55], v[194:197], v[218:221], v[52:55]
	v_mfma_f32_16x16x32_bf16 v[48:51], v[210:213], v[218:221], v[48:51]
	v_mfma_f32_16x16x32_bf16 v[36:39], v[194:197], v[226:229], v[36:39]
	v_mfma_f32_16x16x32_bf16 v[32:35], v[210:213], v[226:229], v[32:35]
	v_mfma_f32_16x16x32_bf16 v[20:23], v[194:197], v[234:237], v[20:23]
	v_mfma_f32_16x16x32_bf16 v[16:19], v[210:213], v[234:237], v[16:19]
	v_mfma_f32_16x16x32_bf16 v[4:7], v[194:197], v[242:245], v[4:7]
	v_mfma_f32_16x16x32_bf16 v[0:3], v[210:213], v[242:245], v[0:3]
	s_barrier
	s_add_i32 s14, 0, 0x18000
	v_add_u32_e32 v161, s14, v152
	s_add_i32 s15, 0, 0x1c000
	ds_read_b128 v[142:145], v161
	ds_read_b128 v[162:165], v161 offset:1024
	ds_read_b128 v[180:183], v161 offset:2048
	ds_read_b128 v[184:187], v161 offset:3072
	v_add_u32_e32 v161, s15, v152
	ds_read_b128 v[190:193], v161
	ds_read_b128 v[194:197], v161 offset:1024
	ds_read_b128 v[206:209], v161 offset:2048
	ds_read_b128 v[210:213], v161 offset:3072
	s_add_u32 s54, s54, 0x40000
	s_addc_u32 s55, s55, 0
	s_mov_b32 m0, s58
	v_lshl_add_u64 v[248:249], s[54:55], 0, v[128:129]
	ds_read_b128 v[214:217], v160 offset:32768
	ds_read_b128 v[218:221], v160 offset:33792
	ds_read_b128 v[222:225], v160 offset:34816
	ds_read_b128 v[226:229], v160 offset:35840
	ds_read_b128 v[230:233], v160 offset:36864
	ds_read_b128 v[234:237], v160 offset:37888
	ds_read_b128 v[238:241], v160 offset:38912
	ds_read_b128 v[242:245], v160 offset:39936
	global_load_lds_dwordx4 v[248:249], off
	v_lshl_add_u64 v[248:249], s[54:55], 0, v[132:133]
	s_mov_b32 m0, s59
	s_nop 0
	global_load_lds_dwordx4 v[248:249], off
	s_waitcnt vmcnt(8)
	s_waitcnt lgkmcnt(0)
	s_barrier
	v_mfma_f32_16x16x32_bf16 v[124:127], v[142:145], v[214:217], v[124:127]
	v_mfma_f32_16x16x32_bf16 v[120:123], v[180:183], v[214:217], v[120:123]
	v_mfma_f32_16x16x32_bf16 v[108:111], v[142:145], v[222:225], v[108:111]
	v_mfma_f32_16x16x32_bf16 v[104:107], v[180:183], v[222:225], v[104:107]
	v_mfma_f32_16x16x32_bf16 v[92:95], v[142:145], v[230:233], v[92:95]
	v_mfma_f32_16x16x32_bf16 v[88:91], v[180:183], v[230:233], v[88:91]
	v_mfma_f32_16x16x32_bf16 v[76:79], v[142:145], v[238:241], v[76:79]
	v_mfma_f32_16x16x32_bf16 v[72:75], v[180:183], v[238:241], v[72:75]
	v_mfma_f32_16x16x32_bf16 v[124:127], v[162:165], v[218:221], v[124:127]
	v_mfma_f32_16x16x32_bf16 v[120:123], v[184:187], v[218:221], v[120:123]
	v_mfma_f32_16x16x32_bf16 v[108:111], v[162:165], v[226:229], v[108:111]
	v_mfma_f32_16x16x32_bf16 v[104:107], v[184:187], v[226:229], v[104:107]
	v_mfma_f32_16x16x32_bf16 v[92:95], v[162:165], v[234:237], v[92:95]
	v_mfma_f32_16x16x32_bf16 v[88:91], v[184:187], v[234:237], v[88:91]
	v_mfma_f32_16x16x32_bf16 v[76:79], v[162:165], v[242:245], v[76:79]
	v_mfma_f32_16x16x32_bf16 v[72:75], v[184:187], v[242:245], v[72:75]
	v_mfma_f32_16x16x32_bf16 v[116:119], v[190:193], v[214:217], v[116:119]
	v_mfma_f32_16x16x32_bf16 v[112:115], v[206:209], v[214:217], v[112:115]
	v_mfma_f32_16x16x32_bf16 v[100:103], v[190:193], v[222:225], v[100:103]
	v_mfma_f32_16x16x32_bf16 v[96:99], v[206:209], v[222:225], v[96:99]
	v_mfma_f32_16x16x32_bf16 v[84:87], v[190:193], v[230:233], v[84:87]
	v_mfma_f32_16x16x32_bf16 v[80:83], v[206:209], v[230:233], v[80:83]
	v_mfma_f32_16x16x32_bf16 v[68:71], v[190:193], v[238:241], v[68:71]
	v_mfma_f32_16x16x32_bf16 v[64:67], v[206:209], v[238:241], v[64:67]
	v_mfma_f32_16x16x32_bf16 v[116:119], v[194:197], v[218:221], v[116:119]
	v_mfma_f32_16x16x32_bf16 v[112:115], v[210:213], v[218:221], v[112:115]
	v_mfma_f32_16x16x32_bf16 v[100:103], v[194:197], v[226:229], v[100:103]
	v_mfma_f32_16x16x32_bf16 v[96:99], v[210:213], v[226:229], v[96:99]
	v_mfma_f32_16x16x32_bf16 v[84:87], v[194:197], v[234:237], v[84:87]
	v_mfma_f32_16x16x32_bf16 v[80:83], v[210:213], v[234:237], v[80:83]
	v_mfma_f32_16x16x32_bf16 v[68:71], v[194:197], v[242:245], v[68:71]
	v_mfma_f32_16x16x32_bf16 v[64:67], v[210:213], v[242:245], v[64:67]
	s_barrier
; #define PG8_STAGE(bufoff, gbase, voff) do { _Pragma("unroll") for (int _i = 0; _i < 2; ++_i) \
;         __builtin_amdgcn_global_load_lds((const unsigned*)((const char*)(gbase) + (voff)[_i]), (LAS unsigned*)(lds + (bufoff) + ldsw + _i * 8192), 16, 0, 0); } while (0)
; #define PG8_LDA(dst, b, h) do { _Pragma("unroll") for (int m = 0; m < 4; ++m) _Pragma("unroll") for (int k = 0; k < 2; ++k) dst[m][k] = *(const LAS bf16x8*)(lds + PG8_SA(b, h) + aoff + m * 2048 + k * 1024); } while (0)
; #define PG8_LDB(dst, b, h) do { _Pragma("unroll") for (int n = 0; n < 2; ++n) _Pragma("unroll") for (int k = 0; k < 2; ++k) dst[n][k] = *(const LAS bf16x8*)(lds + PG8_SB(b, h) + boff + n * 2048 + k * 1024); } while (0)
; #define PG8_MMA(ai, bj, At, Bt) do { __builtin_amdgcn_s_setprio(1); _Pragma("unroll") for (int m = 0; m < 4; ++m) _Pragma("unroll") for (int n = 0; n < 2; ++n) _Pragma("unroll") for (int k = 0; k < 2; ++k) \
;         acc[ai][bj][m][n] = __builtin_amdgcn_mfma_f32_16x16x32_bf16(Bt[n][k], At[m][k], acc[ai][bj][m][n], 0, 0, 0); __builtin_amdgcn_s_setprio(0); } while (0)
; #define PG8_WAIT_V(n) asm volatile("s_waitcnt vmcnt(" #n ")" ::: "memory")
; #define PG8_WAIT_L(n) asm volatile("s_waitcnt lgkmcnt(" #n ")" ::: "memory")
; #define PG8_BAR __builtin_amdgcn_s_barrier()
; template <class Epi, class Sched>
; __device__ __forceinline__ void gemm_phase(const int tid, LAS unsigned char* lds, const int lda, const int ldb, const int K, const Sched& S, const Epi& E) {
;     ...
;         for (int t = 0; t < nt; t += 2) {
;             const bool last = (t == nt - 2);
;             const char* a1 = cA + (size_t)(t + 1) * kstep;
;             const char* a2 = last ? nA : cA + (size_t)(t + 2) * kstep; const char* b2 = last ? nB : cB + (size_t)(t + 2) * kstep;
;             const char* a3 = a2 + kstep; const char* b3 = b2 + kstep;
;             PG8_LDB(B0, 0, 0); PG8_LDB(B1, 0, 1); PG8_SCHED; PG8_LDA(At, 0, 0); PG8_STAGE(PG8_SA(1, 1), a1 + hstepA, voffA);
;             PG8_WAIT_V(8); PG8_WAIT_L(0); PG8_BAR; PG8_MMA(0, 0, At, B0); PG8_MMA(0, 1, At, B1); PG8_BAR; PG8_SCHED;
;     ...
;             PG8_LDA(At, 1, 1); PG8_STAGE(PG8_SB(1, 0), b3, voffB); PG8_STAGE(PG8_SB(1, 1), b3 + hstepB, voffB); PG8_STAGE(PG8_SA(1, 0), a3, voffA);
;             PG8_WAIT_V(8); PG8_WAIT_L(0); PG8_BAR; if (!cur.half) { PG8_MMA(1, 0, At, B0); PG8_MMA(1, 1, At, B1); } PG8_BAR; PG8_SCHED;
	s_add_i32 s14, s14, s31
	v_lshl_add_u64 v[146:147], v[146:147], 0, s[6:7]
	s_mov_b32 m0, s14
	ds_read_b128 v[214:217], v160 offset:49152
	ds_read_b128 v[218:221], v160 offset:50176
	ds_read_b128 v[222:225], v160 offset:51200
	ds_read_b128 v[226:229], v160 offset:52224
	ds_read_b128 v[230:233], v160 offset:53248
	ds_read_b128 v[234:237], v160 offset:54272
	ds_read_b128 v[238:241], v160 offset:55296
	ds_read_b128 v[242:245], v160 offset:56320
	global_load_lds_dwordx4 v[146:147], off
	s_add_i32 m0, s14, 0x2000
	s_add_u32 s52, s52, 0x40080
	v_lshl_add_u64 v[146:147], v[166:167], 0, s[6:7]
	s_addc_u32 s53, s53, 0
	s_add_i32 s14, s15, s31
	global_load_lds_dwordx4 v[146:147], off
	v_lshl_add_u64 v[146:147], s[52:53], 0, v[130:131]
	s_mov_b32 m0, s14
	s_nop 0
	global_load_lds_dwordx4 v[146:147], off
	v_lshl_add_u64 v[146:147], s[52:53], 0, v[134:135]
	s_add_i32 m0, s14, 0x2000
	s_nop 0
	global_load_lds_dwordx4 v[146:147], off
	v_lshl_add_u64 v[146:147], v[176:177], 0, s[6:7]
	s_mov_b32 m0, s60
	s_nop 0
	global_load_lds_dwordx4 v[146:147], off
	v_lshl_add_u64 v[146:147], v[246:247], 0, s[6:7]
	s_mov_b32 m0, s61
	s_nop 0
	global_load_lds_dwordx4 v[146:147], off
	s_waitcnt vmcnt(8)
	s_waitcnt lgkmcnt(0)
	s_barrier
	v_mfma_f32_16x16x32_bf16 v[60:63], v[142:145], v[214:217], v[60:63]
	v_mfma_f32_16x16x32_bf16 v[56:59], v[180:183], v[214:217], v[56:59]
	v_mfma_f32_16x16x32_bf16 v[44:47], v[142:145], v[222:225], v[44:47]
	v_mfma_f32_16x16x32_bf16 v[40:43], v[180:183], v[222:225], v[40:43]
	v_mfma_f32_16x16x32_bf16 v[28:31], v[142:145], v[230:233], v[28:31]
	v_mfma_f32_16x16x32_bf16 v[24:27], v[180:183], v[230:233], v[24:27]
	v_mfma_f32_16x16x32_bf16 v[12:15], v[142:145], v[238:241], v[12:15]
	v_mfma_f32_16x16x32_bf16 v[8:11], v[180:183], v[238:241], v[8:11]
	v_mfma_f32_16x16x32_bf16 v[60:63], v[162:165], v[218:221], v[60:63]
	v_mfma_f32_16x16x32_bf16 v[56:59], v[184:187], v[218:221], v[56:59]
	v_mfma_f32_16x16x32_bf16 v[44:47], v[162:165], v[226:229], v[44:47]
	v_mfma_f32_16x16x32_bf16 v[40:43], v[184:187], v[226:229], v[40:43]
	v_mfma_f32_16x16x32_bf16 v[28:31], v[162:165], v[234:237], v[28:31]
	v_mfma_f32_16x16x32_bf16 v[24:27], v[184:187], v[234:237], v[24:27]
	v_mfma_f32_16x16x32_bf16 v[12:15], v[162:165], v[242:245], v[12:15]
	v_mfma_f32_16x16x32_bf16 v[8:11], v[184:187], v[242:245], v[8:11]
	v_mfma_f32_16x16x32_bf16 v[52:55], v[190:193], v[214:217], v[52:55]
	v_mfma_f32_16x16x32_bf16 v[48:51], v[206:209], v[214:217], v[48:51]
	v_mfma_f32_16x16x32_bf16 v[36:39], v[190:193], v[222:225], v[36:39]
	v_mfma_f32_16x16x32_bf16 v[32:35], v[206:209], v[222:225], v[32:35]
	v_mfma_f32_16x16x32_bf16 v[20:23], v[190:193], v[230:233], v[20:23]
	v_mfma_f32_16x16x32_bf16 v[16:19], v[206:209], v[230:233], v[16:19]
	v_mfma_f32_16x16x32_bf16 v[4:7], v[190:193], v[238:241], v[4:7]
	v_mfma_f32_16x16x32_bf16 v[0:3], v[206:209], v[238:241], v[0:3]
	v_mfma_f32_16x16x32_bf16 v[52:55], v[194:197], v[218:221], v[52:55]
	v_mfma_f32_16x16x32_bf16 v[48:51], v[210:213], v[218:221], v[48:51]
	v_mfma_f32_16x16x32_bf16 v[36:39], v[194:197], v[226:229], v[36:39]
	v_mfma_f32_16x16x32_bf16 v[32:35], v[210:213], v[226:229], v[32:35]
	v_mfma_f32_16x16x32_bf16 v[20:23], v[194:197], v[234:237], v[20:23]
	v_mfma_f32_16x16x32_bf16 v[16:19], v[210:213], v[234:237], v[16:19]
	v_mfma_f32_16x16x32_bf16 v[4:7], v[194:197], v[242:245], v[4:7]
	v_mfma_f32_16x16x32_bf16 v[0:3], v[210:213], v[242:245], v[0:3]
	s_barrier
	s_add_u32 s50, s50, 0x100
	s_addc_u32 s51, s51, 0
	s_add_u32 s26, s26, 0x100
	s_addc_u32 s27, s27, 0
	s_cmp_ge_i32 s67, s29
	s_mov_b32 s45, s67
	s_cbranch_scc1 .Lkexit_681
.LBB0_681:
	s_add_i32 s67, s45, 2
	s_add_u32 s14, s50, 0xfffc0080
	s_addc_u32 s15, s51, -1
	s_add_i32 s24, 0, 0x10000
	s_cmp_eq_u32 s63, s45
	s_cselect_b32 s55, s3, s15
	s_cselect_b32 s54, s2, s14
	v_add_u32_e32 v146, s24, v152
	s_cselect_b32 s53, s39, s27
	s_cselect_b32 s52, s38, s26
	s_add_i32 s14, 0, 0x14000
	ds_read_b128 v[142:145], v146
	ds_read_b128 v[162:165], v146 offset:1024
	ds_read_b128 v[180:183], v146 offset:2048
	ds_read_b128 v[184:187], v146 offset:3072
	v_add_u32_e32 v146, s14, v152
	ds_read_b128 v[190:193], v146
	ds_read_b128 v[194:197], v146 offset:1024
	ds_read_b128 v[206:209], v146 offset:2048
	ds_read_b128 v[210:213], v146 offset:3072
	v_lshl_add_u64 v[146:147], s[50:51], 0, v[136:137]
	s_add_i32 m0, s56, 0xc000
	ds_read_b128 v[214:217], v160
	ds_read_b128 v[218:221], v160 offset:1024
	ds_read_b128 v[222:225], v160 offset:2048
	ds_read_b128 v[226:229], v160 offset:3072
	ds_read_b128 v[230:233], v160 offset:4096
	ds_read_b128 v[234:237], v160 offset:5120
	ds_read_b128 v[238:241], v160 offset:6144
	ds_read_b128 v[242:245], v160 offset:7168
	global_load_lds_dwordx4 v[146:147], off
	v_lshl_add_u64 v[146:147], s[50:51], 0, v[138:139]
	s_add_i32 m0, s56, 0xe000
	s_nop 0
	global_load_lds_dwordx4 v[146:147], off
	s_waitcnt vmcnt(8)
	s_waitcnt lgkmcnt(0)
	s_barrier
; #define PG8_STAGE(bufoff, gbase, voff) do { _Pragma("unroll") for (int _i = 0; _i < 2; ++_i) \
;         __builtin_amdgcn_global_load_lds((const unsigned*)((const char*)(gbase) + (voff)[_i]), (LAS unsigned*)(lds + (bufoff) + ldsw + _i * 8192), 16, 0, 0); } while (0)
; #define PG8_LDA(dst, b, h) do { _Pragma("unroll") for (int m = 0; m < 4; ++m) _Pragma("unroll") for (int k = 0; k < 2; ++k) dst[m][k] = *(const LAS bf16x8*)(lds + PG8_SA(b, h) + aoff + m * 2048 + k * 1024); } while (0)
; #define PG8_LDB(dst, b, h) do { _Pragma("unroll") for (int n = 0; n < 2; ++n) _Pragma("unroll") for (int k = 0; k < 2; ++k) dst[n][k] = *(const LAS bf16x8*)(lds + PG8_SB(b, h) + boff + n * 2048 + k * 1024); } while (0)
; #define PG8_MMA(ai, bj, At, Bt) do { __builtin_amdgcn_s_setprio(1); _Pragma("unroll") for (int m = 0; m < 4; ++m) _Pragma("unroll") for (int n = 0; n < 2; ++n) _Pragma("unroll") for (int k = 0; k < 2; ++k) \
;         acc[ai][bj][m][n] = __builtin_amdgcn_mfma_f32_16x16x32_bf16(Bt[n][k], At[m][k], acc[ai][bj][m][n], 0, 0, 0); __builtin_amdgcn_s_setprio(0); } while (0)
; #define PG8_WAIT_V(n) asm volatile("s_waitcnt vmcnt(" #n ")" ::: "memory")
; #define PG8_WAIT_L(n) asm volatile("s_waitcnt lgkmcnt(" #n ")" ::: "memory")
; #define PG8_BAR __builtin_amdgcn_s_barrier()
; #define PG8_SCHED __builtin_amdgcn_sched_barrier(0)
; template <class Epi, class Sched>
; __device__ __forceinline__ void gemm_phase(const int tid, LAS unsigned char* lds, const int lda, const int ldb, const int K, const Sched& S, const Epi& E) {
;     ...
;             PG8_WAIT_V(8); PG8_WAIT_L(0); PG8_BAR; PG8_MMA(0, 0, At, B0); PG8_MMA(0, 1, At, B1); PG8_BAR; PG8_SCHED;
;             PG8_LDA(At, 0, 1); PG8_STAGE(PG8_SB(0, 0), b2, voffB); PG8_STAGE(PG8_SB(0, 1), b2 + hstepB, voffB); PG8_STAGE(PG8_SA(0, 0), a2, voffA);
;             PG8_WAIT_V(8); PG8_WAIT_L(0); PG8_BAR; if (!cur.half) { PG8_MMA(1, 0, At, B0); PG8_MMA(1, 1, At, B1); } PG8_BAR; PG8_SCHED;
;             PG8_LDB(B0, 1, 0); PG8_LDB(B1, 1, 1); PG8_SCHED; PG8_LDA(At, 1, 0); PG8_STAGE(PG8_SA(0, 1), a2 + hstepA, voffA);
;             PG8_WAIT_V(8); PG8_WAIT_L(0); PG8_BAR; PG8_MMA(0, 0, At, B0); PG8_MMA(0, 1, At, B1); PG8_BAR; PG8_SCHED;
	v_mfma_f32_16x16x32_bf16 v[124:127], v[142:145], v[214:217], v[124:127]
	v_mfma_f32_16x16x32_bf16 v[120:123], v[180:183], v[214:217], v[120:123]
	v_mfma_f32_16x16x32_bf16 v[108:111], v[142:145], v[222:225], v[108:111]
	v_mfma_f32_16x16x32_bf16 v[104:107], v[180:183], v[222:225], v[104:107]
	v_mfma_f32_16x16x32_bf16 v[92:95], v[142:145], v[230:233], v[92:95]
	v_mfma_f32_16x16x32_bf16 v[88:91], v[180:183], v[230:233], v[88:91]
	v_mfma_f32_16x16x32_bf16 v[76:79], v[142:145], v[238:241], v[76:79]
	v_mfma_f32_16x16x32_bf16 v[72:75], v[180:183], v[238:241], v[72:75]
	v_mfma_f32_16x16x32_bf16 v[124:127], v[162:165], v[218:221], v[124:127]
	v_mfma_f32_16x16x32_bf16 v[120:123], v[184:187], v[218:221], v[120:123]
	v_mfma_f32_16x16x32_bf16 v[108:111], v[162:165], v[226:229], v[108:111]
	v_mfma_f32_16x16x32_bf16 v[104:107], v[184:187], v[226:229], v[104:107]
	v_mfma_f32_16x16x32_bf16 v[92:95], v[162:165], v[234:237], v[92:95]
	v_mfma_f32_16x16x32_bf16 v[88:91], v[184:187], v[234:237], v[88:91]
	v_mfma_f32_16x16x32_bf16 v[76:79], v[162:165], v[242:245], v[76:79]
	v_mfma_f32_16x16x32_bf16 v[72:75], v[184:187], v[242:245], v[72:75]
	v_mfma_f32_16x16x32_bf16 v[116:119], v[190:193], v[214:217], v[116:119]
	v_mfma_f32_16x16x32_bf16 v[112:115], v[206:209], v[214:217], v[112:115]
	v_mfma_f32_16x16x32_bf16 v[100:103], v[190:193], v[222:225], v[100:103]
	v_mfma_f32_16x16x32_bf16 v[96:99], v[206:209], v[222:225], v[96:99]
	v_mfma_f32_16x16x32_bf16 v[84:87], v[190:193], v[230:233], v[84:87]
	v_mfma_f32_16x16x32_bf16 v[80:83], v[206:209], v[230:233], v[80:83]
	v_mfma_f32_16x16x32_bf16 v[68:71], v[190:193], v[238:241], v[68:71]
	v_mfma_f32_16x16x32_bf16 v[64:67], v[206:209], v[238:241], v[64:67]
	v_mfma_f32_16x16x32_bf16 v[116:119], v[194:197], v[218:221], v[116:119]
	v_mfma_f32_16x16x32_bf16 v[112:115], v[210:213], v[218:221], v[112:115]
	v_mfma_f32_16x16x32_bf16 v[100:103], v[194:197], v[226:229], v[100:103]
	v_mfma_f32_16x16x32_bf16 v[96:99], v[210:213], v[226:229], v[96:99]
	v_mfma_f32_16x16x32_bf16 v[84:87], v[194:197], v[234:237], v[84:87]
	v_mfma_f32_16x16x32_bf16 v[80:83], v[210:213], v[234:237], v[80:83]
	v_mfma_f32_16x16x32_bf16 v[68:71], v[194:197], v[242:245], v[68:71]
	v_mfma_f32_16x16x32_bf16 v[64:67], v[210:213], v[242:245], v[64:67]
	s_barrier
	s_add_i32 s15, s24, s31
	v_lshl_add_u64 v[146:147], s[52:53], 0, v[130:131]
	s_mov_b32 m0, s15
	ds_read_b128 v[214:217], v160 offset:16384
	ds_read_b128 v[218:221], v160 offset:17408
	ds_read_b128 v[222:225], v160 offset:18432
	ds_read_b128 v[226:229], v160 offset:19456
	ds_read_b128 v[230:233], v160 offset:20480
	ds_read_b128 v[234:237], v160 offset:21504
	ds_read_b128 v[238:241], v160 offset:22528
	ds_read_b128 v[242:245], v160 offset:23552
	global_load_lds_dwordx4 v[146:147], off
	s_add_i32 m0, s15, 0x2000
	s_add_u32 s68, s52, 0x40000
	v_lshl_add_u64 v[166:167], s[52:53], 0, v[134:135]
	s_addc_u32 s69, s53, 0
	s_add_i32 s14, s14, s31
	global_load_lds_dwordx4 v[166:167], off
	v_lshl_add_u64 v[176:177], s[68:69], 0, v[130:131]
	s_mov_b32 m0, s14
	v_lshl_add_u64 v[246:247], s[54:55], 0, v[132:133]
	global_load_lds_dwordx4 v[176:177], off
	v_lshl_add_u64 v[176:177], s[68:69], 0, v[134:135]
	s_add_i32 m0, s14, 0x2000
	s_nop 0
	global_load_lds_dwordx4 v[176:177], off
	v_lshl_add_u64 v[176:177], s[54:55], 0, v[128:129]
	s_mov_b32 m0, s56
	s_nop 0
	global_load_lds_dwordx4 v[176:177], off
	s_mov_b32 m0, s57
	s_nop 0
	global_load_lds_dwordx4 v[246:247], off
	s_waitcnt vmcnt(8)
	s_waitcnt lgkmcnt(0)
	s_barrier
	v_mfma_f32_16x16x32_bf16 v[60:63], v[142:145], v[214:217], v[60:63]
	v_mfma_f32_16x16x32_bf16 v[56:59], v[180:183], v[214:217], v[56:59]
	v_mfma_f32_16x16x32_bf16 v[44:47], v[142:145], v[222:225], v[44:47]
	v_mfma_f32_16x16x32_bf16 v[40:43], v[180:183], v[222:225], v[40:43]
	v_mfma_f32_16x16x32_bf16 v[28:31], v[142:145], v[230:233], v[28:31]
	v_mfma_f32_16x16x32_bf16 v[24:27], v[180:183], v[230:233], v[24:27]
	v_mfma_f32_16x16x32_bf16 v[12:15], v[142:145], v[238:241], v[12:15]
	v_mfma_f32_16x16x32_bf16 v[8:11], v[180:183], v[238:241], v[8:11]
	v_mfma_f32_16x16x32_bf16 v[60:63], v[162:165], v[218:221], v[60:63]
	v_mfma_f32_16x16x32_bf16 v[56:59], v[184:187], v[218:221], v[56:59]
	v_mfma_f32_16x16x32_bf16 v[44:47], v[162:165], v[226:229], v[44:47]
	v_mfma_f32_16x16x32_bf16 v[40:43], v[184:187], v[226:229], v[40:43]
	v_mfma_f32_16x16x32_bf16 v[28:31], v[162:165], v[234:237], v[28:31]
	v_mfma_f32_16x16x32_bf16 v[24:27], v[184:187], v[234:237], v[24:27]
	v_mfma_f32_16x16x32_bf16 v[12:15], v[162:165], v[242:245], v[12:15]
	v_mfma_f32_16x16x32_bf16 v[8:11], v[184:187], v[242:245], v[8:11]
	v_mfma_f32_16x16x32_bf16 v[52:55], v[190:193], v[214:217], v[52:55]
	v_mfma_f32_16x16x32_bf16 v[48:51], v[206:209], v[214:217], v[48:51]
	v_mfma_f32_16x16x32_bf16 v[36:39], v[190:193], v[222:225], v[36:39]
	v_mfma_f32_16x16x32_bf16 v[32:35], v[206:209], v[222:225], v[32:35]
	v_mfma_f32_16x16x32_bf16 v[20:23], v[190:193], v[230:233], v[20:23]
	v_mfma_f32_16x16x32_bf16 v[16:19], v[206:209], v[230:233], v[16:19]
	v_mfma_f32_16x16x32_bf16 v[4:7], v[190:193], v[238:241], v[4:7]
	v_mfma_f32_16x16x32_bf16 v[0:3], v[206:209], v[238:241], v[0:3]
	v_mfma_f32_16x16x32_bf16 v[52:55], v[194:197], v[218:221], v[52:55]
	v_mfma_f32_16x16x32_bf16 v[48:51], v[210:213], v[218:221], v[48:51]
	v_mfma_f32_16x16x32_bf16 v[36:39], v[194:197], v[226:229], v[36:39]
	v_mfma_f32_16x16x32_bf16 v[32:35], v[210:213], v[226:229], v[32:35]
	v_mfma_f32_16x16x32_bf16 v[20:23], v[194:197], v[234:237], v[20:23]
	v_mfma_f32_16x16x32_bf16 v[16:19], v[210:213], v[234:237], v[16:19]
	v_mfma_f32_16x16x32_bf16 v[4:7], v[194:197], v[242:245], v[4:7]
	v_mfma_f32_16x16x32_bf16 v[0:3], v[210:213], v[242:245], v[0:3]
	s_barrier
; #define PG8_STAGE(bufoff, gbase, voff) do { _Pragma("unroll") for (int _i = 0; _i < 2; ++_i) \
;         __builtin_amdgcn_global_load_lds((const unsigned*)((const char*)(gbase) + (voff)[_i]), (LAS unsigned*)(lds + (bufoff) + ldsw + _i * 8192), 16, 0, 0); } while (0)
; #define PG8_LDA(dst, b, h) do { _Pragma("unroll") for (int m = 0; m < 4; ++m) _Pragma("unroll") for (int k = 0; k < 2; ++k) dst[m][k] = *(const LAS bf16x8*)(lds + PG8_SA(b, h) + aoff + m * 2048 + k * 1024); } while (0)
; #define PG8_LDB(dst, b, h) do { _Pragma("unroll") for (int n = 0; n < 2; ++n) _Pragma("unroll") for (int k = 0; k < 2; ++k) dst[n][k] = *(const LAS bf16x8*)(lds + PG8_SB(b, h) + boff + n * 2048 + k * 1024); } while (0)
; #define PG8_MMA(ai, bj, At, Bt) do { __builtin_amdgcn_s_setprio(1); _Pragma("unroll") for (int m = 0; m < 4; ++m) _Pragma("unroll") for (int n = 0; n < 2; ++n) _Pragma("unroll") for (int k = 0; k < 2; ++k) \
;         acc[ai][bj][m][n] = __builtin_amdgcn_mfma_f32_16x16x32_bf16(Bt[n][k], At[m][k], acc[ai][bj][m][n], 0, 0, 0); __builtin_amdgcn_s_setprio(0); } while (0)
; #define PG8_WAIT_V(n) asm volatile("s_waitcnt vmcnt(" #n ")" ::: "memory")
; #define PG8_WAIT_L(n) asm volatile("s_waitcnt lgkmcnt(" #n ")" ::: "memory")
; #define PG8_BAR __builtin_amdgcn_s_barrier()
; #define PG8_SCHED __builtin_amdgcn_sched_barrier(0)
; template <class Epi, class Sched>
; __device__ __forceinline__ void gemm_phase(const int tid, LAS unsigned char* lds, const int lda, const int ldb, const int K, const Sched& S, const Epi& E) {
;     ...
;             PG8_LDB(B0, 1, 0); PG8_LDB(B1, 1, 1); PG8_SCHED; PG8_LDA(At, 1, 0); PG8_STAGE(PG8_SA(0, 1), a2 + hstepA, voffA);
;             PG8_WAIT_V(8); PG8_WAIT_L(0); PG8_BAR; PG8_MMA(0, 0, At, B0); PG8_MMA(0, 1, At, B1); PG8_BAR; PG8_SCHED;
;             PG8_LDA(At, 1, 1); PG8_STAGE(PG8_SB(1, 0), b3, voffB); PG8_STAGE(PG8_SB(1, 1), b3 + hstepB, voffB); PG8_STAGE(PG8_SA(1, 0), a3, voffA);
;             PG8_WAIT_V(8); PG8_WAIT_L(0); PG8_BAR; if (!cur.half) { PG8_MMA(1, 0, At, B0); PG8_MMA(1, 1, At, B1); } PG8_BAR; PG8_SCHED;
;         }
	s_add_i32 s14, 0, 0x18000
	v_add_u32_e32 v161, s14, v152
	s_add_i32 s15, 0, 0x1c000
	ds_read_b128 v[142:145], v161
	ds_read_b128 v[162:165], v161 offset:1024
	ds_read_b128 v[180:183], v161 offset:2048
	ds_read_b128 v[184:187], v161 offset:3072
	v_add_u32_e32 v161, s15, v152
	ds_read_b128 v[190:193], v161
	ds_read_b128 v[194:197], v161 offset:1024
	ds_read_b128 v[206:209], v161 offset:2048
	ds_read_b128 v[210:213], v161 offset:3072
	s_add_u32 s54, s54, 0x40000
	s_addc_u32 s55, s55, 0
	s_mov_b32 m0, s58
	v_lshl_add_u64 v[248:249], s[54:55], 0, v[128:129]
	ds_read_b128 v[214:217], v160 offset:32768
	ds_read_b128 v[218:221], v160 offset:33792
	ds_read_b128 v[222:225], v160 offset:34816
	ds_read_b128 v[226:229], v160 offset:35840
	ds_read_b128 v[230:233], v160 offset:36864
	ds_read_b128 v[234:237], v160 offset:37888
	ds_read_b128 v[238:241], v160 offset:38912
	ds_read_b128 v[242:245], v160 offset:39936
	global_load_lds_dwordx4 v[248:249], off
	v_lshl_add_u64 v[248:249], s[54:55], 0, v[132:133]
	s_mov_b32 m0, s59
	s_nop 0
	global_load_lds_dwordx4 v[248:249], off
	s_waitcnt vmcnt(8)
	s_waitcnt lgkmcnt(0)
	s_barrier
	v_mfma_f32_16x16x32_bf16 v[124:127], v[142:145], v[214:217], v[124:127]
	v_mfma_f32_16x16x32_bf16 v[120:123], v[180:183], v[214:217], v[120:123]
	v_mfma_f32_16x16x32_bf16 v[108:111], v[142:145], v[222:225], v[108:111]
	v_mfma_f32_16x16x32_bf16 v[104:107], v[180:183], v[222:225], v[104:107]
	v_mfma_f32_16x16x32_bf16 v[92:95], v[142:145], v[230:233], v[92:95]
	v_mfma_f32_16x16x32_bf16 v[88:91], v[180:183], v[230:233], v[88:91]
	v_mfma_f32_16x16x32_bf16 v[76:79], v[142:145], v[238:241], v[76:79]
	v_mfma_f32_16x16x32_bf16 v[72:75], v[180:183], v[238:241], v[72:75]
	v_mfma_f32_16x16x32_bf16 v[124:127], v[162:165], v[218:221], v[124:127]
	v_mfma_f32_16x16x32_bf16 v[120:123], v[184:187], v[218:221], v[120:123]
	v_mfma_f32_16x16x32_bf16 v[108:111], v[162:165], v[226:229], v[108:111]
	v_mfma_f32_16x16x32_bf16 v[104:107], v[184:187], v[226:229], v[104:107]
	v_mfma_f32_16x16x32_bf16 v[92:95], v[162:165], v[234:237], v[92:95]
	v_mfma_f32_16x16x32_bf16 v[88:91], v[184:187], v[234:237], v[88:91]
	v_mfma_f32_16x16x32_bf16 v[76:79], v[162:165], v[242:245], v[76:79]
	v_mfma_f32_16x16x32_bf16 v[72:75], v[184:187], v[242:245], v[72:75]
	v_mfma_f32_16x16x32_bf16 v[116:119], v[190:193], v[214:217], v[116:119]
	v_mfma_f32_16x16x32_bf16 v[112:115], v[206:209], v[214:217], v[112:115]
	v_mfma_f32_16x16x32_bf16 v[100:103], v[190:193], v[222:225], v[100:103]
	v_mfma_f32_16x16x32_bf16 v[96:99], v[206:209], v[222:225], v[96:99]
	v_mfma_f32_16x16x32_bf16 v[84:87], v[190:193], v[230:233], v[84:87]
	v_mfma_f32_16x16x32_bf16 v[80:83], v[206:209], v[230:233], v[80:83]
	v_mfma_f32_16x16x32_bf16 v[68:71], v[190:193], v[238:241], v[68:71]
	v_mfma_f32_16x16x32_bf16 v[64:67], v[206:209], v[238:241], v[64:67]
	v_mfma_f32_16x16x32_bf16 v[116:119], v[194:197], v[218:221], v[116:119]
	v_mfma_f32_16x16x32_bf16 v[112:115], v[210:213], v[218:221], v[112:115]
	v_mfma_f32_16x16x32_bf16 v[100:103], v[194:197], v[226:229], v[100:103]
	v_mfma_f32_16x16x32_bf16 v[96:99], v[210:213], v[226:229], v[96:99]
	v_mfma_f32_16x16x32_bf16 v[84:87], v[194:197], v[234:237], v[84:87]
	v_mfma_f32_16x16x32_bf16 v[80:83], v[210:213], v[234:237], v[80:83]
	v_mfma_f32_16x16x32_bf16 v[68:71], v[194:197], v[242:245], v[68:71]
	v_mfma_f32_16x16x32_bf16 v[64:67], v[210:213], v[242:245], v[64:67]
	s_barrier
	s_add_i32 s14, s14, s31
	v_lshl_add_u64 v[146:147], v[146:147], 0, s[6:7]
	s_mov_b32 m0, s14
	ds_read_b128 v[214:217], v160 offset:49152
	ds_read_b128 v[218:221], v160 offset:50176
	ds_read_b128 v[222:225], v160 offset:51200
	ds_read_b128 v[226:229], v160 offset:52224
	ds_read_b128 v[230:233], v160 offset:53248
	ds_read_b128 v[234:237], v160 offset:54272
	ds_read_b128 v[238:241], v160 offset:55296
	ds_read_b128 v[242:245], v160 offset:56320
	global_load_lds_dwordx4 v[146:147], off
	s_add_i32 m0, s14, 0x2000
	s_add_u32 s52, s52, 0x40080
	v_lshl_add_u64 v[146:147], v[166:167], 0, s[6:7]
	s_addc_u32 s53, s53, 0
	s_add_i32 s14, s15, s31
	global_load_lds_dwordx4 v[146:147], off
	v_lshl_add_u64 v[146:147], s[52:53], 0, v[130:131]
	s_mov_b32 m0, s14
	s_nop 0
	global_load_lds_dwordx4 v[146:147], off
	v_lshl_add_u64 v[146:147], s[52:53], 0, v[134:135]
	s_add_i32 m0, s14, 0x2000
	s_nop 0
	global_load_lds_dwordx4 v[146:147], off
	v_lshl_add_u64 v[146:147], v[176:177], 0, s[6:7]
	s_mov_b32 m0, s60
	s_nop 0
	global_load_lds_dwordx4 v[146:147], off
	v_lshl_add_u64 v[146:147], v[246:247], 0, s[6:7]
	s_mov_b32 m0, s61
	s_nop 0
	global_load_lds_dwordx4 v[146:147], off
	s_waitcnt vmcnt(8)
	s_waitcnt lgkmcnt(0)
	s_barrier
	v_mfma_f32_16x16x32_bf16 v[60:63], v[142:145], v[214:217], v[60:63]
	v_mfma_f32_16x16x32_bf16 v[56:59], v[180:183], v[214:217], v[56:59]
	v_mfma_f32_16x16x32_bf16 v[44:47], v[142:145], v[222:225], v[44:47]
	v_mfma_f32_16x16x32_bf16 v[40:43], v[180:183], v[222:225], v[40:43]
	v_mfma_f32_16x16x32_bf16 v[28:31], v[142:145], v[230:233], v[28:31]
	v_mfma_f32_16x16x32_bf16 v[24:27], v[180:183], v[230:233], v[24:27]
	v_mfma_f32_16x16x32_bf16 v[12:15], v[142:145], v[238:241], v[12:15]
	v_mfma_f32_16x16x32_bf16 v[8:11], v[180:183], v[238:241], v[8:11]
	v_mfma_f32_16x16x32_bf16 v[60:63], v[162:165], v[218:221], v[60:63]
	v_mfma_f32_16x16x32_bf16 v[56:59], v[184:187], v[218:221], v[56:59]
	v_mfma_f32_16x16x32_bf16 v[44:47], v[162:165], v[226:229], v[44:47]
	v_mfma_f32_16x16x32_bf16 v[40:43], v[184:187], v[226:229], v[40:43]
	v_mfma_f32_16x16x32_bf16 v[28:31], v[162:165], v[234:237], v[28:31]
	v_mfma_f32_16x16x32_bf16 v[24:27], v[184:187], v[234:237], v[24:27]
	v_mfma_f32_16x16x32_bf16 v[12:15], v[162:165], v[242:245], v[12:15]
	v_mfma_f32_16x16x32_bf16 v[8:11], v[184:187], v[242:245], v[8:11]
	v_mfma_f32_16x16x32_bf16 v[52:55], v[190:193], v[214:217], v[52:55]
	v_mfma_f32_16x16x32_bf16 v[48:51], v[206:209], v[214:217], v[48:51]
	v_mfma_f32_16x16x32_bf16 v[36:39], v[190:193], v[222:225], v[36:39]
	v_mfma_f32_16x16x32_bf16 v[32:35], v[206:209], v[222:225], v[32:35]
	v_mfma_f32_16x16x32_bf16 v[20:23], v[190:193], v[230:233], v[20:23]
	v_mfma_f32_16x16x32_bf16 v[16:19], v[206:209], v[230:233], v[16:19]
	v_mfma_f32_16x16x32_bf16 v[4:7], v[190:193], v[238:241], v[4:7]
	v_mfma_f32_16x16x32_bf16 v[0:3], v[206:209], v[238:241], v[0:3]
	v_mfma_f32_16x16x32_bf16 v[52:55], v[194:197], v[218:221], v[52:55]
	v_mfma_f32_16x16x32_bf16 v[48:51], v[210:213], v[218:221], v[48:51]
	v_mfma_f32_16x16x32_bf16 v[36:39], v[194:197], v[226:229], v[36:39]
	v_mfma_f32_16x16x32_bf16 v[32:35], v[210:213], v[226:229], v[32:35]
	v_mfma_f32_16x16x32_bf16 v[20:23], v[194:197], v[234:237], v[20:23]
	v_mfma_f32_16x16x32_bf16 v[16:19], v[210:213], v[234:237], v[16:19]
	v_mfma_f32_16x16x32_bf16 v[4:7], v[194:197], v[242:245], v[4:7]
	v_mfma_f32_16x16x32_bf16 v[0:3], v[210:213], v[242:245], v[0:3]
	s_barrier
	s_add_u32 s50, s50, 0x100
	s_addc_u32 s51, s51, 0
	s_add_u32 s26, s26, 0x100
	s_addc_u32 s27, s27, 0
	s_cmp_ge_i32 s67, s29
	s_mov_b32 s45, s67
	s_cbranch_scc0 .LBB0_681

; #define PG8_STAGE(bufoff, gbase, voff) do { _Pragma("unroll") for (int _i = 0; _i < 2; ++_i) \
;         __builtin_amdgcn_global_load_lds((const unsigned*)((const char*)(gbase) + (voff)[_i]), (LAS unsigned*)(lds + (bufoff) + ldsw + _i * 8192), 16, 0, 0); } while (0)
; #define PG8_LDA(dst, b, h) do { _Pragma("unroll") for (int m = 0; m < 4; ++m) _Pragma("unroll") for (int k = 0; k < 2; ++k) dst[m][k] = *(const LAS bf16x8*)(lds + PG8_SA(b, h) + aoff + m * 2048 + k * 1024); } while (0)
; #define PG8_LDB(dst, b, h) do { _Pragma("unroll") for (int n = 0; n < 2; ++n) _Pragma("unroll") for (int k = 0; k < 2; ++k) dst[n][k] = *(const LAS bf16x8*)(lds + PG8_SB(b, h) + boff + n * 2048 + k * 1024); } while (0)
; #define PG8_MMA(ai, bj, At, Bt) do { __builtin_amdgcn_s_setprio(1); _Pragma("unroll") for (int m = 0; m < 4; ++m) _Pragma("unroll") for (int n = 0; n < 2; ++n) _Pragma("unroll") for (int k = 0; k < 2; ++k) \
;         acc[ai][bj][m][n] = __builtin_amdgcn_mfma_f32_16x16x32_bf16(Bt[n][k], At[m][k], acc[ai][bj][m][n], 0, 0, 0); __builtin_amdgcn_s_setprio(0); } while (0)
; #define PG8_WAIT_V(n) asm volatile("s_waitcnt vmcnt(" #n ")" ::: "memory")
; template <class Epi, class Sched>
; __device__ __forceinline__ void gemm_phase(const int tid, LAS unsigned char* lds, const int lda, const int ldb, const int K, const Sched& S, const Epi& E) {
;     ...
;         const bool has_next = S.next(ui + 1, nxt);
;         const char* nA = has_next ? nxt.a : cA; const char* nB = has_next ? nxt.b : cB;
;         for (int t = 0; t < nt; t += 2) {
;             const bool last = (t == nt - 2);
;             const char* a1 = cA + (size_t)(t + 1) * kstep;
;             const char* a2 = last ? nA : cA + (size_t)(t + 2) * kstep; const char* b2 = last ? nB : cB + (size_t)(t + 2) * kstep;
;             const char* a3 = a2 + kstep; const char* b3 = b2 + kstep;
;             PG8_LDB(B0, 0, 0); PG8_LDB(B1, 0, 1); PG8_SCHED; PG8_LDA(At, 0, 0); PG8_STAGE(PG8_SA(1, 1), a1 + hstepA, voffA);
;             PG8_WAIT_V(8); PG8_WAIT_L(0); PG8_BAR; PG8_MMA(0, 0, At, B0); PG8_MMA(0, 1, At, B1); PG8_BAR; PG8_SCHED;
;             PG8_LDA(At, 0, 1); PG8_STAGE(PG8_SB(0, 0), b2, voffB); PG8_STAGE(PG8_SB(0, 1), b2 + hstepB, voffB); PG8_STAGE(PG8_SA(0, 0), a2, voffA);
;             PG8_WAIT_V(8); PG8_WAIT_L(0); PG8_BAR; if (!cur.half) { PG8_MMA(1, 0, At, B0); PG8_MMA(1, 1, At, B1); } PG8_BAR; PG8_SCHED;
.LBB0_752:
	s_andn2_b64 vcc, exec, s[52:53]
	s_cbranch_vccnz .LBB0_755
	s_add_u32 s64, s64, 0x40080
	s_addc_u32 s65, s65, 0
	s_add_u32 s26, s66, 0x100
	s_addc_u32 s27, s67, 0
	s_mov_b32 s57, 0
	s_waitcnt lgkmcnt(0)
	s_add_i32 vcc_lo, s57, 2
	s_add_u32 s14, s64, 0xfffc0080
	s_addc_u32 s15, s65, -1
	s_add_i32 s24, 0, 0x10000
	s_cmp_eq_u32 s75, s57
	s_cselect_b32 s69, s3, s15
	s_cselect_b32 s68, s2, s14
	s_cselect_b32 s67, s63, s27
	s_cselect_b32 s66, s62, s26
	s_add_i32 s14, 0, 0x14000
	v_add_u32_e32 v140, s24, v182
	v_add_u32_e32 v166, s14, v182
	ds_read_b128 v[128:131], v140
	ds_read_b128 v[132:135], v140 offset:1024
	ds_read_b128 v[136:139], v140 offset:2048
	ds_read_b128 v[140:143], v140 offset:3072
	ds_read_b128 v[144:147], v166
	ds_read_b128 v[148:151], v166 offset:1024
	ds_read_b128 v[190:193], v166 offset:2048
	ds_read_b128 v[194:197], v166 offset:3072
	v_lshl_add_u64 v[166:167], s[64:65], 0, v[162:163]
	s_add_i32 m0, s31, 0xc000
	ds_read_b128 v[206:209], v188
	ds_read_b128 v[210:213], v188 offset:1024
	ds_read_b128 v[214:217], v188 offset:2048
	ds_read_b128 v[218:221], v188 offset:3072
	ds_read_b128 v[222:225], v188 offset:4096
	ds_read_b128 v[226:229], v188 offset:5120
	ds_read_b128 v[230:233], v188 offset:6144
	ds_read_b128 v[234:237], v188 offset:7168
	global_load_lds_dwordx4 v[166:167], off
	v_lshl_add_u64 v[166:167], s[64:65], 0, v[164:165]
	s_add_i32 m0, s31, 0xe000
	s_nop 0
	global_load_lds_dwordx4 v[166:167], off
	s_waitcnt vmcnt(8)
	s_waitcnt lgkmcnt(0)
	s_barrier
	v_mfma_f32_16x16x32_bf16 v[116:119], v[128:131], v[206:209], 0
	v_mfma_f32_16x16x32_bf16 v[112:115], v[136:139], v[206:209], 0
	v_mfma_f32_16x16x32_bf16 v[100:103], v[128:131], v[214:217], 0
	v_mfma_f32_16x16x32_bf16 v[96:99], v[136:139], v[214:217], 0
	v_mfma_f32_16x16x32_bf16 v[84:87], v[128:131], v[222:225], 0
	v_mfma_f32_16x16x32_bf16 v[80:83], v[136:139], v[222:225], 0
	v_mfma_f32_16x16x32_bf16 v[68:71], v[128:131], v[230:233], 0
	v_mfma_f32_16x16x32_bf16 v[64:67], v[136:139], v[230:233], 0
	v_mfma_f32_16x16x32_bf16 v[116:119], v[132:135], v[210:213], v[116:119]
	v_mfma_f32_16x16x32_bf16 v[112:115], v[140:143], v[210:213], v[112:115]
	v_mfma_f32_16x16x32_bf16 v[100:103], v[132:135], v[218:221], v[100:103]
	v_mfma_f32_16x16x32_bf16 v[96:99], v[140:143], v[218:221], v[96:99]
	v_mfma_f32_16x16x32_bf16 v[84:87], v[132:135], v[226:229], v[84:87]
	v_mfma_f32_16x16x32_bf16 v[80:83], v[140:143], v[226:229], v[80:83]
	v_mfma_f32_16x16x32_bf16 v[68:71], v[132:135], v[234:237], v[68:71]
	v_mfma_f32_16x16x32_bf16 v[64:67], v[140:143], v[234:237], v[64:67]
	v_mfma_f32_16x16x32_bf16 v[124:127], v[144:147], v[206:209], 0
	v_mfma_f32_16x16x32_bf16 v[120:123], v[190:193], v[206:209], 0
	v_mfma_f32_16x16x32_bf16 v[108:111], v[144:147], v[214:217], 0
	v_mfma_f32_16x16x32_bf16 v[104:107], v[190:193], v[214:217], 0
	v_mfma_f32_16x16x32_bf16 v[92:95], v[144:147], v[222:225], 0
	v_mfma_f32_16x16x32_bf16 v[88:91], v[190:193], v[222:225], 0
	v_mfma_f32_16x16x32_bf16 v[76:79], v[144:147], v[230:233], 0
	v_mfma_f32_16x16x32_bf16 v[72:75], v[190:193], v[230:233], 0
	v_mfma_f32_16x16x32_bf16 v[124:127], v[148:151], v[210:213], v[124:127]
	v_mfma_f32_16x16x32_bf16 v[120:123], v[194:197], v[210:213], v[120:123]
	v_mfma_f32_16x16x32_bf16 v[108:111], v[148:151], v[218:221], v[108:111]
	v_mfma_f32_16x16x32_bf16 v[104:107], v[194:197], v[218:221], v[104:107]
	v_mfma_f32_16x16x32_bf16 v[92:95], v[148:151], v[226:229], v[92:95]
	v_mfma_f32_16x16x32_bf16 v[88:91], v[194:197], v[226:229], v[88:91]
	v_mfma_f32_16x16x32_bf16 v[76:79], v[148:151], v[234:237], v[76:79]
	v_mfma_f32_16x16x32_bf16 v[72:75], v[194:197], v[234:237], v[72:75]
	s_barrier
	s_add_i32 s15, s24, s29
	v_lshl_add_u64 v[166:167], s[66:67], 0, v[168:169]
	s_mov_b32 m0, s15
	ds_read_b128 v[206:209], v188 offset:16384
	ds_read_b128 v[210:213], v188 offset:17408
	ds_read_b128 v[214:217], v188 offset:18432
	ds_read_b128 v[218:221], v188 offset:19456
	ds_read_b128 v[222:225], v188 offset:20480
	ds_read_b128 v[226:229], v188 offset:21504
	ds_read_b128 v[230:233], v188 offset:22528
	ds_read_b128 v[234:237], v188 offset:23552
	global_load_lds_dwordx4 v[166:167], off
	s_add_i32 m0, s15, 0x2000
	s_add_u32 s50, s66, 0x40000
	v_lshl_add_u64 v[180:181], s[66:67], 0, v[156:157]
	s_addc_u32 s51, s67, 0
	s_add_i32 s14, s14, s29
	global_load_lds_dwordx4 v[180:181], off
	v_lshl_add_u64 v[238:239], s[50:51], 0, v[168:169]
	s_mov_b32 m0, s14
	v_lshl_add_u64 v[240:241], s[68:69], 0, v[154:155]
	global_load_lds_dwordx4 v[238:239], off
	v_lshl_add_u64 v[238:239], s[50:51], 0, v[156:157]
	s_add_i32 m0, s14, 0x2000
	s_nop 0
	global_load_lds_dwordx4 v[238:239], off
	v_lshl_add_u64 v[238:239], s[68:69], 0, v[152:153]
	s_mov_b32 m0, s31
	s_nop 0
	global_load_lds_dwordx4 v[238:239], off
	s_mov_b32 m0, s41
	s_nop 0
	global_load_lds_dwordx4 v[240:241], off
	s_waitcnt vmcnt(8)
	s_waitcnt lgkmcnt(0)
	s_barrier
; #define PG8_STAGE(bufoff, gbase, voff) do { _Pragma("unroll") for (int _i = 0; _i < 2; ++_i) \
;         __builtin_amdgcn_global_load_lds((const unsigned*)((const char*)(gbase) + (voff)[_i]), (LAS unsigned*)(lds + (bufoff) + ldsw + _i * 8192), 16, 0, 0); } while (0)
; #define PG8_LDA(dst, b, h) do { _Pragma("unroll") for (int m = 0; m < 4; ++m) _Pragma("unroll") for (int k = 0; k < 2; ++k) dst[m][k] = *(const LAS bf16x8*)(lds + PG8_SA(b, h) + aoff + m * 2048 + k * 1024); } while (0)
; #define PG8_LDB(dst, b, h) do { _Pragma("unroll") for (int n = 0; n < 2; ++n) _Pragma("unroll") for (int k = 0; k < 2; ++k) dst[n][k] = *(const LAS bf16x8*)(lds + PG8_SB(b, h) + boff + n * 2048 + k * 1024); } while (0)
; #define PG8_MMA(ai, bj, At, Bt) do { __builtin_amdgcn_s_setprio(1); _Pragma("unroll") for (int m = 0; m < 4; ++m) _Pragma("unroll") for (int n = 0; n < 2; ++n) _Pragma("unroll") for (int k = 0; k < 2; ++k) \
;         acc[ai][bj][m][n] = __builtin_amdgcn_mfma_f32_16x16x32_bf16(Bt[n][k], At[m][k], acc[ai][bj][m][n], 0, 0, 0); __builtin_amdgcn_s_setprio(0); } while (0)
; #define PG8_WAIT_V(n) asm volatile("s_waitcnt vmcnt(" #n ")" ::: "memory")
; #define PG8_WAIT_L(n) asm volatile("s_waitcnt lgkmcnt(" #n ")" ::: "memory")
; #define PG8_BAR __builtin_amdgcn_s_barrier()
; #define PG8_SCHED __builtin_amdgcn_sched_barrier(0)
; template <class Epi, class Sched>
; __device__ __forceinline__ void gemm_phase(const int tid, LAS unsigned char* lds, const int lda, const int ldb, const int K, const Sched& S, const Epi& E) {
;     ...
;             PG8_WAIT_V(8); PG8_WAIT_L(0); PG8_BAR; if (!cur.half) { PG8_MMA(1, 0, At, B0); PG8_MMA(1, 1, At, B1); } PG8_BAR; PG8_SCHED;
;             PG8_LDB(B0, 1, 0); PG8_LDB(B1, 1, 1); PG8_SCHED; PG8_LDA(At, 1, 0); PG8_STAGE(PG8_SA(0, 1), a2 + hstepA, voffA);
;             PG8_WAIT_V(8); PG8_WAIT_L(0); PG8_BAR; PG8_MMA(0, 0, At, B0); PG8_MMA(0, 1, At, B1); PG8_BAR; PG8_SCHED;
;             PG8_LDA(At, 1, 1); PG8_STAGE(PG8_SB(1, 0), b3, voffB); PG8_STAGE(PG8_SB(1, 1), b3 + hstepB, voffB); PG8_STAGE(PG8_SA(1, 0), a3, voffA);
	v_mfma_f32_16x16x32_bf16 v[52:55], v[128:131], v[206:209], 0
	v_mfma_f32_16x16x32_bf16 v[48:51], v[136:139], v[206:209], 0
	v_mfma_f32_16x16x32_bf16 v[36:39], v[128:131], v[214:217], 0
	v_mfma_f32_16x16x32_bf16 v[32:35], v[136:139], v[214:217], 0
	v_mfma_f32_16x16x32_bf16 v[20:23], v[128:131], v[222:225], 0
	v_mfma_f32_16x16x32_bf16 v[16:19], v[136:139], v[222:225], 0
	v_mfma_f32_16x16x32_bf16 v[4:7], v[128:131], v[230:233], 0
	v_mfma_f32_16x16x32_bf16 v[0:3], v[136:139], v[230:233], 0
	v_mfma_f32_16x16x32_bf16 v[52:55], v[132:135], v[210:213], v[52:55]
	v_mfma_f32_16x16x32_bf16 v[48:51], v[140:143], v[210:213], v[48:51]
	v_mfma_f32_16x16x32_bf16 v[36:39], v[132:135], v[218:221], v[36:39]
	v_mfma_f32_16x16x32_bf16 v[32:35], v[140:143], v[218:221], v[32:35]
	v_mfma_f32_16x16x32_bf16 v[20:23], v[132:135], v[226:229], v[20:23]
	v_mfma_f32_16x16x32_bf16 v[16:19], v[140:143], v[226:229], v[16:19]
	v_mfma_f32_16x16x32_bf16 v[4:7], v[132:135], v[234:237], v[4:7]
	v_mfma_f32_16x16x32_bf16 v[0:3], v[140:143], v[234:237], v[0:3]
	v_mfma_f32_16x16x32_bf16 v[60:63], v[144:147], v[206:209], 0
	v_mfma_f32_16x16x32_bf16 v[56:59], v[190:193], v[206:209], 0
	v_mfma_f32_16x16x32_bf16 v[44:47], v[144:147], v[214:217], 0
	v_mfma_f32_16x16x32_bf16 v[40:43], v[190:193], v[214:217], 0
	v_mfma_f32_16x16x32_bf16 v[28:31], v[144:147], v[222:225], 0
	v_mfma_f32_16x16x32_bf16 v[24:27], v[190:193], v[222:225], 0
	v_mfma_f32_16x16x32_bf16 v[12:15], v[144:147], v[230:233], 0
	v_mfma_f32_16x16x32_bf16 v[8:11], v[190:193], v[230:233], 0
	v_mfma_f32_16x16x32_bf16 v[60:63], v[148:151], v[210:213], v[60:63]
	v_mfma_f32_16x16x32_bf16 v[56:59], v[194:197], v[210:213], v[56:59]
	v_mfma_f32_16x16x32_bf16 v[44:47], v[148:151], v[218:221], v[44:47]
	v_mfma_f32_16x16x32_bf16 v[40:43], v[194:197], v[218:221], v[40:43]
	v_mfma_f32_16x16x32_bf16 v[28:31], v[148:151], v[226:229], v[28:31]
	v_mfma_f32_16x16x32_bf16 v[24:27], v[194:197], v[226:229], v[24:27]
	v_mfma_f32_16x16x32_bf16 v[12:15], v[148:151], v[234:237], v[12:15]
	v_mfma_f32_16x16x32_bf16 v[8:11], v[194:197], v[234:237], v[8:11]
	s_barrier
	s_add_i32 s14, 0, 0x18000
	s_add_i32 s15, 0, 0x1c000
	v_add_u32_e32 v140, s14, v182
	v_add_u32_e32 v176, s15, v182
	ds_read_b128 v[128:131], v140
	ds_read_b128 v[132:135], v140 offset:1024
	ds_read_b128 v[136:139], v140 offset:2048
	ds_read_b128 v[140:143], v140 offset:3072
	ds_read_b128 v[144:147], v176
	ds_read_b128 v[148:151], v176 offset:1024
	ds_read_b128 v[190:193], v176 offset:2048
	ds_read_b128 v[194:197], v176 offset:3072
	s_add_u32 s50, s68, 0x40000
	s_addc_u32 s51, s69, 0
	s_mov_b32 m0, s47
	v_lshl_add_u64 v[242:243], s[50:51], 0, v[152:153]
	ds_read_b128 v[206:209], v188 offset:32768
	ds_read_b128 v[210:213], v188 offset:33792
	ds_read_b128 v[214:217], v188 offset:34816
	ds_read_b128 v[218:221], v188 offset:35840
	ds_read_b128 v[222:225], v188 offset:36864
	ds_read_b128 v[226:229], v188 offset:37888
	ds_read_b128 v[230:233], v188 offset:38912
	ds_read_b128 v[234:237], v188 offset:39936
	global_load_lds_dwordx4 v[242:243], off
	v_lshl_add_u64 v[242:243], s[50:51], 0, v[154:155]
	s_mov_b32 m0, s70
	s_nop 0
	global_load_lds_dwordx4 v[242:243], off
	s_waitcnt vmcnt(8)
	s_waitcnt lgkmcnt(0)
	s_barrier
	v_mfma_f32_16x16x32_bf16 v[116:119], v[128:131], v[206:209], v[116:119]
	v_mfma_f32_16x16x32_bf16 v[112:115], v[136:139], v[206:209], v[112:115]
	v_mfma_f32_16x16x32_bf16 v[100:103], v[128:131], v[214:217], v[100:103]
	v_mfma_f32_16x16x32_bf16 v[96:99], v[136:139], v[214:217], v[96:99]
	v_mfma_f32_16x16x32_bf16 v[84:87], v[128:131], v[222:225], v[84:87]
	v_mfma_f32_16x16x32_bf16 v[80:83], v[136:139], v[222:225], v[80:83]
	v_mfma_f32_16x16x32_bf16 v[68:71], v[128:131], v[230:233], v[68:71]
	v_mfma_f32_16x16x32_bf16 v[64:67], v[136:139], v[230:233], v[64:67]
	v_mfma_f32_16x16x32_bf16 v[116:119], v[132:135], v[210:213], v[116:119]
	v_mfma_f32_16x16x32_bf16 v[112:115], v[140:143], v[210:213], v[112:115]
	v_mfma_f32_16x16x32_bf16 v[100:103], v[132:135], v[218:221], v[100:103]
	v_mfma_f32_16x16x32_bf16 v[96:99], v[140:143], v[218:221], v[96:99]
	v_mfma_f32_16x16x32_bf16 v[84:87], v[132:135], v[226:229], v[84:87]
	v_mfma_f32_16x16x32_bf16 v[80:83], v[140:143], v[226:229], v[80:83]
	v_mfma_f32_16x16x32_bf16 v[68:71], v[132:135], v[234:237], v[68:71]
	v_mfma_f32_16x16x32_bf16 v[64:67], v[140:143], v[234:237], v[64:67]
	v_mfma_f32_16x16x32_bf16 v[124:127], v[144:147], v[206:209], v[124:127]
	v_mfma_f32_16x16x32_bf16 v[120:123], v[190:193], v[206:209], v[120:123]
	v_mfma_f32_16x16x32_bf16 v[108:111], v[144:147], v[214:217], v[108:111]
	v_mfma_f32_16x16x32_bf16 v[104:107], v[190:193], v[214:217], v[104:107]
	v_mfma_f32_16x16x32_bf16 v[92:95], v[144:147], v[222:225], v[92:95]
	v_mfma_f32_16x16x32_bf16 v[88:91], v[190:193], v[222:225], v[88:91]
	v_mfma_f32_16x16x32_bf16 v[76:79], v[144:147], v[230:233], v[76:79]
	v_mfma_f32_16x16x32_bf16 v[72:75], v[190:193], v[230:233], v[72:75]
	v_mfma_f32_16x16x32_bf16 v[124:127], v[148:151], v[210:213], v[124:127]
	v_mfma_f32_16x16x32_bf16 v[120:123], v[194:197], v[210:213], v[120:123]
	v_mfma_f32_16x16x32_bf16 v[108:111], v[148:151], v[218:221], v[108:111]
	v_mfma_f32_16x16x32_bf16 v[104:107], v[194:197], v[218:221], v[104:107]
	v_mfma_f32_16x16x32_bf16 v[92:95], v[148:151], v[226:229], v[92:95]
	v_mfma_f32_16x16x32_bf16 v[88:91], v[194:197], v[226:229], v[88:91]
	v_mfma_f32_16x16x32_bf16 v[76:79], v[148:151], v[234:237], v[76:79]
	v_mfma_f32_16x16x32_bf16 v[72:75], v[194:197], v[234:237], v[72:75]
	s_barrier
; #define PG8_STAGE(bufoff, gbase, voff) do { _Pragma("unroll") for (int _i = 0; _i < 2; ++_i) \
;         __builtin_amdgcn_global_load_lds((const unsigned*)((const char*)(gbase) + (voff)[_i]), (LAS unsigned*)(lds + (bufoff) + ldsw + _i * 8192), 16, 0, 0); } while (0)
; #define PG8_LDA(dst, b, h) do { _Pragma("unroll") for (int m = 0; m < 4; ++m) _Pragma("unroll") for (int k = 0; k < 2; ++k) dst[m][k] = *(const LAS bf16x8*)(lds + PG8_SA(b, h) + aoff + m * 2048 + k * 1024); } while (0)
; #define PG8_LDB(dst, b, h) do { _Pragma("unroll") for (int n = 0; n < 2; ++n) _Pragma("unroll") for (int k = 0; k < 2; ++k) dst[n][k] = *(const LAS bf16x8*)(lds + PG8_SB(b, h) + boff + n * 2048 + k * 1024); } while (0)
; #define PG8_BAR __builtin_amdgcn_s_barrier()
; template <class Epi, class Sched>
; __device__ __forceinline__ void gemm_phase(const int tid, LAS unsigned char* lds, const int lda, const int ldb, const int K, const Sched& S, const Epi& E) {
;     ...
;         for (int t = 0; t < nt; t += 2) {
;             const bool last = (t == nt - 2);
;             const char* a1 = cA + (size_t)(t + 1) * kstep;
;             const char* a2 = last ? nA : cA + (size_t)(t + 2) * kstep; const char* b2 = last ? nB : cB + (size_t)(t + 2) * kstep;
;             const char* a3 = a2 + kstep; const char* b3 = b2 + kstep;
;             PG8_LDB(B0, 0, 0); PG8_LDB(B1, 0, 1); PG8_SCHED; PG8_LDA(At, 0, 0); PG8_STAGE(PG8_SA(1, 1), a1 + hstepA, voffA);
;             PG8_WAIT_V(8); PG8_WAIT_L(0); PG8_BAR; PG8_MMA(0, 0, At, B0); PG8_MMA(0, 1, At, B1); PG8_BAR; PG8_SCHED;
;             PG8_LDA(At, 0, 1); PG8_STAGE(PG8_SB(0, 0), b2, voffB); PG8_STAGE(PG8_SB(0, 1), b2 + hstepB, voffB); PG8_STAGE(PG8_SA(0, 0), a2, voffA);
;             PG8_WAIT_V(8); PG8_WAIT_L(0); PG8_BAR; if (!cur.half) { PG8_MMA(1, 0, At, B0); PG8_MMA(1, 1, At, B1); } PG8_BAR; PG8_SCHED;
;             PG8_LDB(B0, 1, 0); PG8_LDB(B1, 1, 1); PG8_SCHED; PG8_LDA(At, 1, 0); PG8_STAGE(PG8_SA(0, 1), a2 + hstepA, voffA);
;             PG8_WAIT_V(8); PG8_WAIT_L(0); PG8_BAR; PG8_MMA(0, 0, At, B0); PG8_MMA(0, 1, At, B1); PG8_BAR; PG8_SCHED;
;             PG8_LDA(At, 1, 1); PG8_STAGE(PG8_SB(1, 0), b3, voffB); PG8_STAGE(PG8_SB(1, 1), b3 + hstepB, voffB); PG8_STAGE(PG8_SA(1, 0), a3, voffA);
;             PG8_WAIT_V(8); PG8_WAIT_L(0); PG8_BAR; if (!cur.half) { PG8_MMA(1, 0, At, B0); PG8_MMA(1, 1, At, B1); } PG8_BAR; PG8_SCHED;
;         }
	s_add_i32 s14, s14, s29
	v_lshl_add_u64 v[166:167], v[166:167], 0, s[6:7]
	s_mov_b32 m0, s14
	ds_read_b128 v[206:209], v188 offset:49152
	ds_read_b128 v[210:213], v188 offset:50176
	ds_read_b128 v[214:217], v188 offset:51200
	ds_read_b128 v[218:221], v188 offset:52224
	ds_read_b128 v[222:225], v188 offset:53248
	ds_read_b128 v[226:229], v188 offset:54272
	ds_read_b128 v[230:233], v188 offset:55296
	ds_read_b128 v[234:237], v188 offset:56320
	global_load_lds_dwordx4 v[166:167], off
	s_add_i32 m0, s14, 0x2000
	s_add_u32 s50, s66, 0x40080
	v_lshl_add_u64 v[166:167], v[180:181], 0, s[6:7]
	s_addc_u32 s51, s67, 0
	s_add_i32 s14, s15, s29
	global_load_lds_dwordx4 v[166:167], off
	v_lshl_add_u64 v[166:167], s[50:51], 0, v[168:169]
	s_mov_b32 m0, s14
	s_nop 0
	global_load_lds_dwordx4 v[166:167], off
	v_lshl_add_u64 v[166:167], s[50:51], 0, v[156:157]
	s_add_i32 m0, s14, 0x2000
	s_nop 0
	global_load_lds_dwordx4 v[166:167], off
	v_lshl_add_u64 v[166:167], v[238:239], 0, s[6:7]
	s_mov_b32 m0, s72
	s_nop 0
	global_load_lds_dwordx4 v[166:167], off
	v_lshl_add_u64 v[166:167], v[240:241], 0, s[6:7]
	s_mov_b32 m0, s73
	s_nop 0
	global_load_lds_dwordx4 v[166:167], off
	s_waitcnt vmcnt(8)
	s_waitcnt lgkmcnt(0)
	s_barrier
	v_mfma_f32_16x16x32_bf16 v[52:55], v[128:131], v[206:209], v[52:55]
	v_mfma_f32_16x16x32_bf16 v[48:51], v[136:139], v[206:209], v[48:51]
	v_mfma_f32_16x16x32_bf16 v[36:39], v[128:131], v[214:217], v[36:39]
	v_mfma_f32_16x16x32_bf16 v[32:35], v[136:139], v[214:217], v[32:35]
	v_mfma_f32_16x16x32_bf16 v[20:23], v[128:131], v[222:225], v[20:23]
	v_mfma_f32_16x16x32_bf16 v[16:19], v[136:139], v[222:225], v[16:19]
	v_mfma_f32_16x16x32_bf16 v[4:7], v[128:131], v[230:233], v[4:7]
	v_mfma_f32_16x16x32_bf16 v[0:3], v[136:139], v[230:233], v[0:3]
	v_mfma_f32_16x16x32_bf16 v[52:55], v[132:135], v[210:213], v[52:55]
	v_mfma_f32_16x16x32_bf16 v[48:51], v[140:143], v[210:213], v[48:51]
	v_mfma_f32_16x16x32_bf16 v[36:39], v[132:135], v[218:221], v[36:39]
	v_mfma_f32_16x16x32_bf16 v[32:35], v[140:143], v[218:221], v[32:35]
	v_mfma_f32_16x16x32_bf16 v[20:23], v[132:135], v[226:229], v[20:23]
	v_mfma_f32_16x16x32_bf16 v[16:19], v[140:143], v[226:229], v[16:19]
	v_mfma_f32_16x16x32_bf16 v[4:7], v[132:135], v[234:237], v[4:7]
	v_mfma_f32_16x16x32_bf16 v[0:3], v[140:143], v[234:237], v[0:3]
	v_mfma_f32_16x16x32_bf16 v[60:63], v[144:147], v[206:209], v[60:63]
	v_mfma_f32_16x16x32_bf16 v[56:59], v[190:193], v[206:209], v[56:59]
	v_mfma_f32_16x16x32_bf16 v[44:47], v[144:147], v[214:217], v[44:47]
	v_mfma_f32_16x16x32_bf16 v[40:43], v[190:193], v[214:217], v[40:43]
	v_mfma_f32_16x16x32_bf16 v[28:31], v[144:147], v[222:225], v[28:31]
	v_mfma_f32_16x16x32_bf16 v[24:27], v[190:193], v[222:225], v[24:27]
	v_mfma_f32_16x16x32_bf16 v[12:15], v[144:147], v[230:233], v[12:15]
	v_mfma_f32_16x16x32_bf16 v[8:11], v[190:193], v[230:233], v[8:11]
	v_mfma_f32_16x16x32_bf16 v[60:63], v[148:151], v[210:213], v[60:63]
	v_mfma_f32_16x16x32_bf16 v[56:59], v[194:197], v[210:213], v[56:59]
	v_mfma_f32_16x16x32_bf16 v[44:47], v[148:151], v[218:221], v[44:47]
	v_mfma_f32_16x16x32_bf16 v[40:43], v[194:197], v[218:221], v[40:43]
	v_mfma_f32_16x16x32_bf16 v[28:31], v[148:151], v[226:229], v[28:31]
	v_mfma_f32_16x16x32_bf16 v[24:27], v[194:197], v[226:229], v[24:27]
	v_mfma_f32_16x16x32_bf16 v[12:15], v[148:151], v[234:237], v[12:15]
	v_mfma_f32_16x16x32_bf16 v[8:11], v[194:197], v[234:237], v[8:11]
	s_barrier
	s_add_u32 s64, s64, 0x100
	s_addc_u32 s65, s65, 0
	s_add_u32 s26, s26, 0x100
	s_addc_u32 s27, s27, 0
	s_cmp_ge_i32 vcc_lo, s21
	s_mov_b32 s57, vcc_lo
	s_cbranch_scc1 .Lkexit_754
.LBB0_754:
	s_add_i32 vcc_lo, s57, 2
	s_add_u32 s14, s64, 0xfffc0080
	s_addc_u32 s15, s65, -1
	s_add_i32 s24, 0, 0x10000
	s_cmp_eq_u32 s75, s57
	s_cselect_b32 s69, s3, s15
	s_cselect_b32 s68, s2, s14
	s_cselect_b32 s67, s63, s27
	s_cselect_b32 s66, s62, s26
	s_add_i32 s14, 0, 0x14000
	v_add_u32_e32 v140, s24, v182
	v_add_u32_e32 v166, s14, v182
	ds_read_b128 v[128:131], v140
	ds_read_b128 v[132:135], v140 offset:1024
	ds_read_b128 v[136:139], v140 offset:2048
	ds_read_b128 v[140:143], v140 offset:3072
	ds_read_b128 v[144:147], v166
	ds_read_b128 v[148:151], v166 offset:1024
	ds_read_b128 v[190:193], v166 offset:2048
	ds_read_b128 v[194:197], v166 offset:3072
	v_lshl_add_u64 v[166:167], s[64:65], 0, v[162:163]
	s_add_i32 m0, s31, 0xc000
	ds_read_b128 v[206:209], v188
	ds_read_b128 v[210:213], v188 offset:1024
	ds_read_b128 v[214:217], v188 offset:2048
	ds_read_b128 v[218:221], v188 offset:3072
	ds_read_b128 v[222:225], v188 offset:4096
	ds_read_b128 v[226:229], v188 offset:5120
	ds_read_b128 v[230:233], v188 offset:6144
	ds_read_b128 v[234:237], v188 offset:7168
	global_load_lds_dwordx4 v[166:167], off
	v_lshl_add_u64 v[166:167], s[64:65], 0, v[164:165]
	s_add_i32 m0, s31, 0xe000
	s_nop 0
	global_load_lds_dwordx4 v[166:167], off
	s_waitcnt vmcnt(8)
	s_waitcnt lgkmcnt(0)
	s_barrier
; #define PG8_STAGE(bufoff, gbase, voff) do { _Pragma("unroll") for (int _i = 0; _i < 2; ++_i) \
;         __builtin_amdgcn_global_load_lds((const unsigned*)((const char*)(gbase) + (voff)[_i]), (LAS unsigned*)(lds + (bufoff) + ldsw + _i * 8192), 16, 0, 0); } while (0)
; #define PG8_LDA(dst, b, h) do { _Pragma("unroll") for (int m = 0; m < 4; ++m) _Pragma("unroll") for (int k = 0; k < 2; ++k) dst[m][k] = *(const LAS bf16x8*)(lds + PG8_SA(b, h) + aoff + m * 2048 + k * 1024); } while (0)
; #define PG8_LDB(dst, b, h) do { _Pragma("unroll") for (int n = 0; n < 2; ++n) _Pragma("unroll") for (int k = 0; k < 2; ++k) dst[n][k] = *(const LAS bf16x8*)(lds + PG8_SB(b, h) + boff + n * 2048 + k * 1024); } while (0)
; #define PG8_MMA(ai, bj, At, Bt) do { __builtin_amdgcn_s_setprio(1); _Pragma("unroll") for (int m = 0; m < 4; ++m) _Pragma("unroll") for (int n = 0; n < 2; ++n) _Pragma("unroll") for (int k = 0; k < 2; ++k) \
;         acc[ai][bj][m][n] = __builtin_amdgcn_mfma_f32_16x16x32_bf16(Bt[n][k], At[m][k], acc[ai][bj][m][n], 0, 0, 0); __builtin_amdgcn_s_setprio(0); } while (0)
; #define PG8_WAIT_V(n) asm volatile("s_waitcnt vmcnt(" #n ")" ::: "memory")
; #define PG8_WAIT_L(n) asm volatile("s_waitcnt lgkmcnt(" #n ")" ::: "memory")
; #define PG8_BAR __builtin_amdgcn_s_barrier()
; #define PG8_SCHED __builtin_amdgcn_sched_barrier(0)
; template <class Epi, class Sched>
; __device__ __forceinline__ void gemm_phase(const int tid, LAS unsigned char* lds, const int lda, const int ldb, const int K, const Sched& S, const Epi& E) {
;     ...
;             PG8_WAIT_V(8); PG8_WAIT_L(0); PG8_BAR; PG8_MMA(0, 0, At, B0); PG8_MMA(0, 1, At, B1); PG8_BAR; PG8_SCHED;
;             PG8_LDA(At, 0, 1); PG8_STAGE(PG8_SB(0, 0), b2, voffB); PG8_STAGE(PG8_SB(0, 1), b2 + hstepB, voffB); PG8_STAGE(PG8_SA(0, 0), a2, voffA);
;             PG8_WAIT_V(8); PG8_WAIT_L(0); PG8_BAR; if (!cur.half) { PG8_MMA(1, 0, At, B0); PG8_MMA(1, 1, At, B1); } PG8_BAR; PG8_SCHED;
;             PG8_LDB(B0, 1, 0); PG8_LDB(B1, 1, 1); PG8_SCHED; PG8_LDA(At, 1, 0); PG8_STAGE(PG8_SA(0, 1), a2 + hstepA, voffA);
;             PG8_WAIT_V(8); PG8_WAIT_L(0); PG8_BAR; PG8_MMA(0, 0, At, B0); PG8_MMA(0, 1, At, B1); PG8_BAR; PG8_SCHED;
	v_mfma_f32_16x16x32_bf16 v[116:119], v[128:131], v[206:209], v[116:119]
	v_mfma_f32_16x16x32_bf16 v[112:115], v[136:139], v[206:209], v[112:115]
	v_mfma_f32_16x16x32_bf16 v[100:103], v[128:131], v[214:217], v[100:103]
	v_mfma_f32_16x16x32_bf16 v[96:99], v[136:139], v[214:217], v[96:99]
	v_mfma_f32_16x16x32_bf16 v[84:87], v[128:131], v[222:225], v[84:87]
	v_mfma_f32_16x16x32_bf16 v[80:83], v[136:139], v[222:225], v[80:83]
	v_mfma_f32_16x16x32_bf16 v[68:71], v[128:131], v[230:233], v[68:71]
	v_mfma_f32_16x16x32_bf16 v[64:67], v[136:139], v[230:233], v[64:67]
	v_mfma_f32_16x16x32_bf16 v[116:119], v[132:135], v[210:213], v[116:119]
	v_mfma_f32_16x16x32_bf16 v[112:115], v[140:143], v[210:213], v[112:115]
	v_mfma_f32_16x16x32_bf16 v[100:103], v[132:135], v[218:221], v[100:103]
	v_mfma_f32_16x16x32_bf16 v[96:99], v[140:143], v[218:221], v[96:99]
	v_mfma_f32_16x16x32_bf16 v[84:87], v[132:135], v[226:229], v[84:87]
	v_mfma_f32_16x16x32_bf16 v[80:83], v[140:143], v[226:229], v[80:83]
	v_mfma_f32_16x16x32_bf16 v[68:71], v[132:135], v[234:237], v[68:71]
	v_mfma_f32_16x16x32_bf16 v[64:67], v[140:143], v[234:237], v[64:67]
	v_mfma_f32_16x16x32_bf16 v[124:127], v[144:147], v[206:209], v[124:127]
	v_mfma_f32_16x16x32_bf16 v[120:123], v[190:193], v[206:209], v[120:123]
	v_mfma_f32_16x16x32_bf16 v[108:111], v[144:147], v[214:217], v[108:111]
	v_mfma_f32_16x16x32_bf16 v[104:107], v[190:193], v[214:217], v[104:107]
	v_mfma_f32_16x16x32_bf16 v[92:95], v[144:147], v[222:225], v[92:95]
	v_mfma_f32_16x16x32_bf16 v[88:91], v[190:193], v[222:225], v[88:91]
	v_mfma_f32_16x16x32_bf16 v[76:79], v[144:147], v[230:233], v[76:79]
	v_mfma_f32_16x16x32_bf16 v[72:75], v[190:193], v[230:233], v[72:75]
	v_mfma_f32_16x16x32_bf16 v[124:127], v[148:151], v[210:213], v[124:127]
	v_mfma_f32_16x16x32_bf16 v[120:123], v[194:197], v[210:213], v[120:123]
	v_mfma_f32_16x16x32_bf16 v[108:111], v[148:151], v[218:221], v[108:111]
	v_mfma_f32_16x16x32_bf16 v[104:107], v[194:197], v[218:221], v[104:107]
	v_mfma_f32_16x16x32_bf16 v[92:95], v[148:151], v[226:229], v[92:95]
	v_mfma_f32_16x16x32_bf16 v[88:91], v[194:197], v[226:229], v[88:91]
	v_mfma_f32_16x16x32_bf16 v[76:79], v[148:151], v[234:237], v[76:79]
	v_mfma_f32_16x16x32_bf16 v[72:75], v[194:197], v[234:237], v[72:75]
	s_barrier
	s_add_i32 s15, s24, s29
	v_lshl_add_u64 v[166:167], s[66:67], 0, v[168:169]
	s_mov_b32 m0, s15
	ds_read_b128 v[206:209], v188 offset:16384
	ds_read_b128 v[210:213], v188 offset:17408
	ds_read_b128 v[214:217], v188 offset:18432
	ds_read_b128 v[218:221], v188 offset:19456
	ds_read_b128 v[222:225], v188 offset:20480
	ds_read_b128 v[226:229], v188 offset:21504
	ds_read_b128 v[230:233], v188 offset:22528
	ds_read_b128 v[234:237], v188 offset:23552
	global_load_lds_dwordx4 v[166:167], off
	s_add_i32 m0, s15, 0x2000
	s_add_u32 s50, s66, 0x40000
	v_lshl_add_u64 v[180:181], s[66:67], 0, v[156:157]
	s_addc_u32 s51, s67, 0
	s_add_i32 s14, s14, s29
	global_load_lds_dwordx4 v[180:181], off
	v_lshl_add_u64 v[238:239], s[50:51], 0, v[168:169]
	s_mov_b32 m0, s14
	v_lshl_add_u64 v[240:241], s[68:69], 0, v[154:155]
	global_load_lds_dwordx4 v[238:239], off
	v_lshl_add_u64 v[238:239], s[50:51], 0, v[156:157]
	s_add_i32 m0, s14, 0x2000
	s_nop 0
	global_load_lds_dwordx4 v[238:239], off
	v_lshl_add_u64 v[238:239], s[68:69], 0, v[152:153]
	s_mov_b32 m0, s31
	s_nop 0
	global_load_lds_dwordx4 v[238:239], off
	s_mov_b32 m0, s41
	s_nop 0
	global_load_lds_dwordx4 v[240:241], off
	s_waitcnt vmcnt(8)
	s_waitcnt lgkmcnt(0)
	s_barrier
	v_mfma_f32_16x16x32_bf16 v[52:55], v[128:131], v[206:209], v[52:55]
	v_mfma_f32_16x16x32_bf16 v[48:51], v[136:139], v[206:209], v[48:51]
	v_mfma_f32_16x16x32_bf16 v[36:39], v[128:131], v[214:217], v[36:39]
	v_mfma_f32_16x16x32_bf16 v[32:35], v[136:139], v[214:217], v[32:35]
	v_mfma_f32_16x16x32_bf16 v[20:23], v[128:131], v[222:225], v[20:23]
	v_mfma_f32_16x16x32_bf16 v[16:19], v[136:139], v[222:225], v[16:19]
	v_mfma_f32_16x16x32_bf16 v[4:7], v[128:131], v[230:233], v[4:7]
	v_mfma_f32_16x16x32_bf16 v[0:3], v[136:139], v[230:233], v[0:3]
	v_mfma_f32_16x16x32_bf16 v[52:55], v[132:135], v[210:213], v[52:55]
	v_mfma_f32_16x16x32_bf16 v[48:51], v[140:143], v[210:213], v[48:51]
	v_mfma_f32_16x16x32_bf16 v[36:39], v[132:135], v[218:221], v[36:39]
	v_mfma_f32_16x16x32_bf16 v[32:35], v[140:143], v[218:221], v[32:35]
	v_mfma_f32_16x16x32_bf16 v[20:23], v[132:135], v[226:229], v[20:23]
	v_mfma_f32_16x16x32_bf16 v[16:19], v[140:143], v[226:229], v[16:19]
	v_mfma_f32_16x16x32_bf16 v[4:7], v[132:135], v[234:237], v[4:7]
	v_mfma_f32_16x16x32_bf16 v[0:3], v[140:143], v[234:237], v[0:3]
	v_mfma_f32_16x16x32_bf16 v[60:63], v[144:147], v[206:209], v[60:63]
	v_mfma_f32_16x16x32_bf16 v[56:59], v[190:193], v[206:209], v[56:59]
	v_mfma_f32_16x16x32_bf16 v[44:47], v[144:147], v[214:217], v[44:47]
	v_mfma_f32_16x16x32_bf16 v[40:43], v[190:193], v[214:217], v[40:43]
	v_mfma_f32_16x16x32_bf16 v[28:31], v[144:147], v[222:225], v[28:31]
	v_mfma_f32_16x16x32_bf16 v[24:27], v[190:193], v[222:225], v[24:27]
	v_mfma_f32_16x16x32_bf16 v[12:15], v[144:147], v[230:233], v[12:15]
	v_mfma_f32_16x16x32_bf16 v[8:11], v[190:193], v[230:233], v[8:11]
	v_mfma_f32_16x16x32_bf16 v[60:63], v[148:151], v[210:213], v[60:63]
	v_mfma_f32_16x16x32_bf16 v[56:59], v[194:197], v[210:213], v[56:59]
	v_mfma_f32_16x16x32_bf16 v[44:47], v[148:151], v[218:221], v[44:47]
	v_mfma_f32_16x16x32_bf16 v[40:43], v[194:197], v[218:221], v[40:43]
	v_mfma_f32_16x16x32_bf16 v[28:31], v[148:151], v[226:229], v[28:31]
	v_mfma_f32_16x16x32_bf16 v[24:27], v[194:197], v[226:229], v[24:27]
	v_mfma_f32_16x16x32_bf16 v[12:15], v[148:151], v[234:237], v[12:15]
	v_mfma_f32_16x16x32_bf16 v[8:11], v[194:197], v[234:237], v[8:11]
	s_barrier
; #define PG8_STAGE(bufoff, gbase, voff) do { _Pragma("unroll") for (int _i = 0; _i < 2; ++_i) \
;         __builtin_amdgcn_global_load_lds((const unsigned*)((const char*)(gbase) + (voff)[_i]), (LAS unsigned*)(lds + (bufoff) + ldsw + _i * 8192), 16, 0, 0); } while (0)
; #define PG8_LDA(dst, b, h) do { _Pragma("unroll") for (int m = 0; m < 4; ++m) _Pragma("unroll") for (int k = 0; k < 2; ++k) dst[m][k] = *(const LAS bf16x8*)(lds + PG8_SA(b, h) + aoff + m * 2048 + k * 1024); } while (0)
; #define PG8_LDB(dst, b, h) do { _Pragma("unroll") for (int n = 0; n < 2; ++n) _Pragma("unroll") for (int k = 0; k < 2; ++k) dst[n][k] = *(const LAS bf16x8*)(lds + PG8_SB(b, h) + boff + n * 2048 + k * 1024); } while (0)
; #define PG8_MMA(ai, bj, At, Bt) do { __builtin_amdgcn_s_setprio(1); _Pragma("unroll") for (int m = 0; m < 4; ++m) _Pragma("unroll") for (int n = 0; n < 2; ++n) _Pragma("unroll") for (int k = 0; k < 2; ++k) \
;         acc[ai][bj][m][n] = __builtin_amdgcn_mfma_f32_16x16x32_bf16(Bt[n][k], At[m][k], acc[ai][bj][m][n], 0, 0, 0); __builtin_amdgcn_s_setprio(0); } while (0)
; #define PG8_WAIT_V(n) asm volatile("s_waitcnt vmcnt(" #n ")" ::: "memory")
; #define PG8_WAIT_L(n) asm volatile("s_waitcnt lgkmcnt(" #n ")" ::: "memory")
; #define PG8_BAR __builtin_amdgcn_s_barrier()
; #define PG8_SCHED __builtin_amdgcn_sched_barrier(0)
; template <class Epi, class Sched>
; __device__ __forceinline__ void gemm_phase(const int tid, LAS unsigned char* lds, const int lda, const int ldb, const int K, const Sched& S, const Epi& E) {
;     ...
;             PG8_LDB(B0, 1, 0); PG8_LDB(B1, 1, 1); PG8_SCHED; PG8_LDA(At, 1, 0); PG8_STAGE(PG8_SA(0, 1), a2 + hstepA, voffA);
;             PG8_WAIT_V(8); PG8_WAIT_L(0); PG8_BAR; PG8_MMA(0, 0, At, B0); PG8_MMA(0, 1, At, B1); PG8_BAR; PG8_SCHED;
;             PG8_LDA(At, 1, 1); PG8_STAGE(PG8_SB(1, 0), b3, voffB); PG8_STAGE(PG8_SB(1, 1), b3 + hstepB, voffB); PG8_STAGE(PG8_SA(1, 0), a3, voffA);
;             PG8_WAIT_V(8); PG8_WAIT_L(0); PG8_BAR; if (!cur.half) { PG8_MMA(1, 0, At, B0); PG8_MMA(1, 1, At, B1); } PG8_BAR; PG8_SCHED;
;         }
	s_add_i32 s14, 0, 0x18000
	s_add_i32 s15, 0, 0x1c000
	v_add_u32_e32 v140, s14, v182
	v_add_u32_e32 v176, s15, v182
	ds_read_b128 v[128:131], v140
	ds_read_b128 v[132:135], v140 offset:1024
	ds_read_b128 v[136:139], v140 offset:2048
	ds_read_b128 v[140:143], v140 offset:3072
	ds_read_b128 v[144:147], v176
	ds_read_b128 v[148:151], v176 offset:1024
	ds_read_b128 v[190:193], v176 offset:2048
	ds_read_b128 v[194:197], v176 offset:3072
	s_add_u32 s50, s68, 0x40000
	s_addc_u32 s51, s69, 0
	s_mov_b32 m0, s47
	v_lshl_add_u64 v[242:243], s[50:51], 0, v[152:153]
	ds_read_b128 v[206:209], v188 offset:32768
	ds_read_b128 v[210:213], v188 offset:33792
	ds_read_b128 v[214:217], v188 offset:34816
	ds_read_b128 v[218:221], v188 offset:35840
	ds_read_b128 v[222:225], v188 offset:36864
	ds_read_b128 v[226:229], v188 offset:37888
	ds_read_b128 v[230:233], v188 offset:38912
	ds_read_b128 v[234:237], v188 offset:39936
	global_load_lds_dwordx4 v[242:243], off
	v_lshl_add_u64 v[242:243], s[50:51], 0, v[154:155]
	s_mov_b32 m0, s70
	s_nop 0
	global_load_lds_dwordx4 v[242:243], off
	s_waitcnt vmcnt(8)
	s_waitcnt lgkmcnt(0)
	s_barrier
	v_mfma_f32_16x16x32_bf16 v[116:119], v[128:131], v[206:209], v[116:119]
	v_mfma_f32_16x16x32_bf16 v[112:115], v[136:139], v[206:209], v[112:115]
	v_mfma_f32_16x16x32_bf16 v[100:103], v[128:131], v[214:217], v[100:103]
	v_mfma_f32_16x16x32_bf16 v[96:99], v[136:139], v[214:217], v[96:99]
	v_mfma_f32_16x16x32_bf16 v[84:87], v[128:131], v[222:225], v[84:87]
	v_mfma_f32_16x16x32_bf16 v[80:83], v[136:139], v[222:225], v[80:83]
	v_mfma_f32_16x16x32_bf16 v[68:71], v[128:131], v[230:233], v[68:71]
	v_mfma_f32_16x16x32_bf16 v[64:67], v[136:139], v[230:233], v[64:67]
	v_mfma_f32_16x16x32_bf16 v[116:119], v[132:135], v[210:213], v[116:119]
	v_mfma_f32_16x16x32_bf16 v[112:115], v[140:143], v[210:213], v[112:115]
	v_mfma_f32_16x16x32_bf16 v[100:103], v[132:135], v[218:221], v[100:103]
	v_mfma_f32_16x16x32_bf16 v[96:99], v[140:143], v[218:221], v[96:99]
	v_mfma_f32_16x16x32_bf16 v[84:87], v[132:135], v[226:229], v[84:87]
	v_mfma_f32_16x16x32_bf16 v[80:83], v[140:143], v[226:229], v[80:83]
	v_mfma_f32_16x16x32_bf16 v[68:71], v[132:135], v[234:237], v[68:71]
	v_mfma_f32_16x16x32_bf16 v[64:67], v[140:143], v[234:237], v[64:67]
	v_mfma_f32_16x16x32_bf16 v[124:127], v[144:147], v[206:209], v[124:127]
	v_mfma_f32_16x16x32_bf16 v[120:123], v[190:193], v[206:209], v[120:123]
	v_mfma_f32_16x16x32_bf16 v[108:111], v[144:147], v[214:217], v[108:111]
	v_mfma_f32_16x16x32_bf16 v[104:107], v[190:193], v[214:217], v[104:107]
	v_mfma_f32_16x16x32_bf16 v[92:95], v[144:147], v[222:225], v[92:95]
	v_mfma_f32_16x16x32_bf16 v[88:91], v[190:193], v[222:225], v[88:91]
	v_mfma_f32_16x16x32_bf16 v[76:79], v[144:147], v[230:233], v[76:79]
	v_mfma_f32_16x16x32_bf16 v[72:75], v[190:193], v[230:233], v[72:75]
	v_mfma_f32_16x16x32_bf16 v[124:127], v[148:151], v[210:213], v[124:127]
	v_mfma_f32_16x16x32_bf16 v[120:123], v[194:197], v[210:213], v[120:123]
	v_mfma_f32_16x16x32_bf16 v[108:111], v[148:151], v[218:221], v[108:111]
	v_mfma_f32_16x16x32_bf16 v[104:107], v[194:197], v[218:221], v[104:107]
	v_mfma_f32_16x16x32_bf16 v[92:95], v[148:151], v[226:229], v[92:95]
	v_mfma_f32_16x16x32_bf16 v[88:91], v[194:197], v[226:229], v[88:91]
	v_mfma_f32_16x16x32_bf16 v[76:79], v[148:151], v[234:237], v[76:79]
	v_mfma_f32_16x16x32_bf16 v[72:75], v[194:197], v[234:237], v[72:75]
	s_barrier
	s_add_i32 s14, s14, s29
	v_lshl_add_u64 v[166:167], v[166:167], 0, s[6:7]
	s_mov_b32 m0, s14
	ds_read_b128 v[206:209], v188 offset:49152
	ds_read_b128 v[210:213], v188 offset:50176
	ds_read_b128 v[214:217], v188 offset:51200
	ds_read_b128 v[218:221], v188 offset:52224
	ds_read_b128 v[222:225], v188 offset:53248
	ds_read_b128 v[226:229], v188 offset:54272
	ds_read_b128 v[230:233], v188 offset:55296
	ds_read_b128 v[234:237], v188 offset:56320
	global_load_lds_dwordx4 v[166:167], off
	s_add_i32 m0, s14, 0x2000
	s_add_u32 s50, s66, 0x40080
	v_lshl_add_u64 v[166:167], v[180:181], 0, s[6:7]
	s_addc_u32 s51, s67, 0
	s_add_i32 s14, s15, s29
	global_load_lds_dwordx4 v[166:167], off
	v_lshl_add_u64 v[166:167], s[50:51], 0, v[168:169]
	s_mov_b32 m0, s14
	s_nop 0
	global_load_lds_dwordx4 v[166:167], off
	v_lshl_add_u64 v[166:167], s[50:51], 0, v[156:157]
	s_add_i32 m0, s14, 0x2000
	s_nop 0
	global_load_lds_dwordx4 v[166:167], off
	v_lshl_add_u64 v[166:167], v[238:239], 0, s[6:7]
	s_mov_b32 m0, s72
	s_nop 0
	global_load_lds_dwordx4 v[166:167], off
	v_lshl_add_u64 v[166:167], v[240:241], 0, s[6:7]
	s_mov_b32 m0, s73
	s_nop 0
	global_load_lds_dwordx4 v[166:167], off
	s_waitcnt vmcnt(8)
	s_waitcnt lgkmcnt(0)
	s_barrier
	v_mfma_f32_16x16x32_bf16 v[52:55], v[128:131], v[206:209], v[52:55]
	v_mfma_f32_16x16x32_bf16 v[48:51], v[136:139], v[206:209], v[48:51]
	v_mfma_f32_16x16x32_bf16 v[36:39], v[128:131], v[214:217], v[36:39]
	v_mfma_f32_16x16x32_bf16 v[32:35], v[136:139], v[214:217], v[32:35]
	v_mfma_f32_16x16x32_bf16 v[20:23], v[128:131], v[222:225], v[20:23]
	v_mfma_f32_16x16x32_bf16 v[16:19], v[136:139], v[222:225], v[16:19]
	v_mfma_f32_16x16x32_bf16 v[4:7], v[128:131], v[230:233], v[4:7]
	v_mfma_f32_16x16x32_bf16 v[0:3], v[136:139], v[230:233], v[0:3]
	v_mfma_f32_16x16x32_bf16 v[52:55], v[132:135], v[210:213], v[52:55]
	v_mfma_f32_16x16x32_bf16 v[48:51], v[140:143], v[210:213], v[48:51]
	v_mfma_f32_16x16x32_bf16 v[36:39], v[132:135], v[218:221], v[36:39]
	v_mfma_f32_16x16x32_bf16 v[32:35], v[140:143], v[218:221], v[32:35]
	v_mfma_f32_16x16x32_bf16 v[20:23], v[132:135], v[226:229], v[20:23]
	v_mfma_f32_16x16x32_bf16 v[16:19], v[140:143], v[226:229], v[16:19]
	v_mfma_f32_16x16x32_bf16 v[4:7], v[132:135], v[234:237], v[4:7]
	v_mfma_f32_16x16x32_bf16 v[0:3], v[140:143], v[234:237], v[0:3]
	v_mfma_f32_16x16x32_bf16 v[60:63], v[144:147], v[206:209], v[60:63]
	v_mfma_f32_16x16x32_bf16 v[56:59], v[190:193], v[206:209], v[56:59]
	v_mfma_f32_16x16x32_bf16 v[44:47], v[144:147], v[214:217], v[44:47]
	v_mfma_f32_16x16x32_bf16 v[40:43], v[190:193], v[214:217], v[40:43]
	v_mfma_f32_16x16x32_bf16 v[28:31], v[144:147], v[222:225], v[28:31]
	v_mfma_f32_16x16x32_bf16 v[24:27], v[190:193], v[222:225], v[24:27]
	v_mfma_f32_16x16x32_bf16 v[12:15], v[144:147], v[230:233], v[12:15]
	v_mfma_f32_16x16x32_bf16 v[8:11], v[190:193], v[230:233], v[8:11]
	v_mfma_f32_16x16x32_bf16 v[60:63], v[148:151], v[210:213], v[60:63]
	v_mfma_f32_16x16x32_bf16 v[56:59], v[194:197], v[210:213], v[56:59]
	v_mfma_f32_16x16x32_bf16 v[44:47], v[148:151], v[218:221], v[44:47]
	v_mfma_f32_16x16x32_bf16 v[40:43], v[194:197], v[218:221], v[40:43]
	v_mfma_f32_16x16x32_bf16 v[28:31], v[148:151], v[226:229], v[28:31]
	v_mfma_f32_16x16x32_bf16 v[24:27], v[194:197], v[226:229], v[24:27]
	v_mfma_f32_16x16x32_bf16 v[12:15], v[148:151], v[234:237], v[12:15]
	v_mfma_f32_16x16x32_bf16 v[8:11], v[194:197], v[234:237], v[8:11]
	s_barrier
	s_add_u32 s64, s64, 0x100
	s_addc_u32 s65, s65, 0
	s_add_u32 s26, s26, 0x100
	s_addc_u32 s27, s27, 0
	s_cmp_ge_i32 vcc_lo, s21
	s_mov_b32 s57, vcc_lo
	s_cbranch_scc0 .LBB0_754

; #define PG8_STAGE(bufoff, gbase, voff) do { _Pragma("unroll") for (int _i = 0; _i < 2; ++_i) \
;         __builtin_amdgcn_global_load_lds((const unsigned*)((const char*)(gbase) + (voff)[_i]), (LAS unsigned*)(lds + (bufoff) + ldsw + _i * 8192), 16, 0, 0); } while (0)
; #define PG8_LDA(dst, b, h) do { _Pragma("unroll") for (int m = 0; m < 4; ++m) _Pragma("unroll") for (int k = 0; k < 2; ++k) dst[m][k] = *(const LAS bf16x8*)(lds + PG8_SA(b, h) + aoff + m * 2048 + k * 1024); } while (0)
; #define PG8_LDB(dst, b, h) do { _Pragma("unroll") for (int n = 0; n < 2; ++n) _Pragma("unroll") for (int k = 0; k < 2; ++k) dst[n][k] = *(const LAS bf16x8*)(lds + PG8_SB(b, h) + boff + n * 2048 + k * 1024); } while (0)
; #define PG8_MMA(ai, bj, At, Bt) do { __builtin_amdgcn_s_setprio(1); _Pragma("unroll") for (int m = 0; m < 4; ++m) _Pragma("unroll") for (int n = 0; n < 2; ++n) _Pragma("unroll") for (int k = 0; k < 2; ++k) \
;         acc[ai][bj][m][n] = __builtin_amdgcn_mfma_f32_16x16x32_bf16(Bt[n][k], At[m][k], acc[ai][bj][m][n], 0, 0, 0); __builtin_amdgcn_s_setprio(0); } while (0)
; #define PG8_WAIT_V(n) asm volatile("s_waitcnt vmcnt(" #n ")" ::: "memory")
; template <class Epi, class Sched>
; __device__ __forceinline__ void gemm_phase(const int tid, LAS unsigned char* lds, const int lda, const int ldb, const int K, const Sched& S, const Epi& E) {
;     ...
;         const bool has_next = S.next(ui + 1, nxt);
;         const char* nA = has_next ? nxt.a : cA; const char* nB = has_next ? nxt.b : cB;
;         for (int t = 0; t < nt; t += 2) {
;             const bool last = (t == nt - 2);
;             const char* a1 = cA + (size_t)(t + 1) * kstep;
;             const char* a2 = last ? nA : cA + (size_t)(t + 2) * kstep; const char* b2 = last ? nB : cB + (size_t)(t + 2) * kstep;
;             const char* a3 = a2 + kstep; const char* b3 = b2 + kstep;
;             PG8_LDB(B0, 0, 0); PG8_LDB(B1, 0, 1); PG8_SCHED; PG8_LDA(At, 0, 0); PG8_STAGE(PG8_SA(1, 1), a1 + hstepA, voffA);
;             PG8_WAIT_V(8); PG8_WAIT_L(0); PG8_BAR; PG8_MMA(0, 0, At, B0); PG8_MMA(0, 1, At, B1); PG8_BAR; PG8_SCHED;
;             PG8_LDA(At, 0, 1); PG8_STAGE(PG8_SB(0, 0), b2, voffB); PG8_STAGE(PG8_SB(0, 1), b2 + hstepB, voffB); PG8_STAGE(PG8_SA(0, 0), a2, voffA);
;             PG8_WAIT_V(8); PG8_WAIT_L(0); PG8_BAR; if (!cur.half) { PG8_MMA(1, 0, At, B0); PG8_MMA(1, 1, At, B1); } PG8_BAR; PG8_SCHED;
.LBB0_791:
	s_andn2_b64 vcc, exec, s[50:51]
	s_cbranch_vccnz .LBB0_799
	s_add_u32 s26, s64, 0x100
	s_addc_u32 s27, s65, 0
	s_mov_b32 s42, 0
	s_add_i32 s43, s42, 2
	s_add_u32 s64, s62, 0x100
	s_addc_u32 s65, s63, 0
	s_add_i32 s14, 0, 0x10000
	s_cmp_eq_u32 s72, s42
	s_cselect_b32 s69, s3, s65
	s_cselect_b32 s68, s2, s64
	s_cselect_b32 s67, s61, s27
	s_cselect_b32 s66, s60, s26
	s_add_i32 s15, 0, 0x14000
	v_add_u32_e32 v124, s14, v206
	v_add_u32_e32 v156, s15, v206
	ds_read_b128 v[104:107], v124
	ds_read_b128 v[108:111], v124 offset:1024
	ds_read_b128 v[120:123], v124 offset:2048
	ds_read_b128 v[124:127], v124 offset:3072
	ds_read_b128 v[136:139], v156
	ds_read_b128 v[144:147], v156 offset:1024
	ds_read_b128 v[152:155], v156 offset:2048
	ds_read_b128 v[156:159], v156 offset:3072
	v_lshl_add_u64 v[196:197], s[62:63], 0, v[192:193]
	s_add_i32 m0, s23, 0xc000
	ds_read_b128 v[160:163], v211
	ds_read_b128 v[164:167], v211 offset:1024
	ds_read_b128 v[212:215], v211 offset:2048
	ds_read_b128 v[216:219], v211 offset:3072
	ds_read_b128 v[220:223], v211 offset:4096
	ds_read_b128 v[224:227], v211 offset:5120
	ds_read_b128 v[228:231], v211 offset:6144
	ds_read_b128 v[232:235], v211 offset:7168
	global_load_lds_dwordx4 v[196:197], off
	v_lshl_add_u64 v[196:197], s[62:63], 0, v[194:195]
	s_add_i32 m0, s23, 0xe000
	s_nop 0
	global_load_lds_dwordx4 v[196:197], off
	s_waitcnt vmcnt(8)
	s_waitcnt lgkmcnt(0)
	s_barrier
	v_mfma_f32_16x16x32_bf16 v[148:151], v[104:107], v[160:163], 0
	v_mfma_f32_16x16x32_bf16 v[140:143], v[120:123], v[160:163], 0
	v_mfma_f32_16x16x32_bf16 v[132:135], v[104:107], v[212:215], 0
	v_mfma_f32_16x16x32_bf16 v[128:131], v[120:123], v[212:215], 0
	v_mfma_f32_16x16x32_bf16 v[116:119], v[104:107], v[220:223], 0
	v_mfma_f32_16x16x32_bf16 v[112:115], v[120:123], v[220:223], 0
	v_mfma_f32_16x16x32_bf16 v[100:103], v[104:107], v[228:231], 0
	v_mfma_f32_16x16x32_bf16 v[96:99], v[120:123], v[228:231], 0
	v_mfma_f32_16x16x32_bf16 v[148:151], v[108:111], v[164:167], v[148:151]
	v_mfma_f32_16x16x32_bf16 v[140:143], v[124:127], v[164:167], v[140:143]
	v_mfma_f32_16x16x32_bf16 v[132:135], v[108:111], v[216:219], v[132:135]
	v_mfma_f32_16x16x32_bf16 v[128:131], v[124:127], v[216:219], v[128:131]
	v_mfma_f32_16x16x32_bf16 v[116:119], v[108:111], v[224:227], v[116:119]
	v_mfma_f32_16x16x32_bf16 v[112:115], v[124:127], v[224:227], v[112:115]
	v_mfma_f32_16x16x32_bf16 v[100:103], v[108:111], v[232:235], v[100:103]
	v_mfma_f32_16x16x32_bf16 v[96:99], v[124:127], v[232:235], v[96:99]
	v_mfma_f32_16x16x32_bf16 v[60:63], v[136:139], v[160:163], 0
	v_mfma_f32_16x16x32_bf16 v[56:59], v[152:155], v[160:163], 0
	v_mfma_f32_16x16x32_bf16 v[52:55], v[136:139], v[212:215], 0
	v_mfma_f32_16x16x32_bf16 v[48:51], v[152:155], v[212:215], 0
	v_mfma_f32_16x16x32_bf16 v[44:47], v[136:139], v[220:223], 0
	v_mfma_f32_16x16x32_bf16 v[40:43], v[152:155], v[220:223], 0
	v_mfma_f32_16x16x32_bf16 v[36:39], v[136:139], v[228:231], 0
	v_mfma_f32_16x16x32_bf16 v[32:35], v[152:155], v[228:231], 0
	v_mfma_f32_16x16x32_bf16 v[60:63], v[144:147], v[164:167], v[60:63]
	v_mfma_f32_16x16x32_bf16 v[56:59], v[156:159], v[164:167], v[56:59]
	v_mfma_f32_16x16x32_bf16 v[52:55], v[144:147], v[216:219], v[52:55]
	v_mfma_f32_16x16x32_bf16 v[48:51], v[156:159], v[216:219], v[48:51]
	v_mfma_f32_16x16x32_bf16 v[44:47], v[144:147], v[224:227], v[44:47]
	v_mfma_f32_16x16x32_bf16 v[40:43], v[156:159], v[224:227], v[40:43]
	v_mfma_f32_16x16x32_bf16 v[36:39], v[144:147], v[232:235], v[36:39]
	v_mfma_f32_16x16x32_bf16 v[32:35], v[156:159], v[232:235], v[32:35]
	s_barrier
	s_add_i32 s14, s14, s21
	v_lshl_add_u64 v[196:197], s[66:67], 0, v[182:183]
	s_mov_b32 m0, s14
	ds_read_b128 v[160:163], v211 offset:16384
	ds_read_b128 v[164:167], v211 offset:17408
	ds_read_b128 v[212:215], v211 offset:18432
	ds_read_b128 v[216:219], v211 offset:19456
	ds_read_b128 v[220:223], v211 offset:20480
	ds_read_b128 v[224:227], v211 offset:21504
	ds_read_b128 v[228:231], v211 offset:22528
	ds_read_b128 v[232:235], v211 offset:23552
	global_load_lds_dwordx4 v[196:197], off
	s_add_i32 m0, s14, 0x2000
	s_add_u32 s62, s66, 0x28000
	v_lshl_add_u64 v[236:237], s[66:67], 0, v[186:187]
	s_addc_u32 s63, s67, 0
	s_add_i32 s14, s15, s21
	global_load_lds_dwordx4 v[236:237], off
	v_lshl_add_u64 v[238:239], s[62:63], 0, v[182:183]
	s_mov_b32 m0, s14
	v_lshl_add_u64 v[240:241], s[68:69], 0, v[184:185]
	global_load_lds_dwordx4 v[238:239], off
	v_lshl_add_u64 v[238:239], s[62:63], 0, v[186:187]
	s_add_i32 m0, s14, 0x2000
	s_nop 0
	global_load_lds_dwordx4 v[238:239], off
	v_lshl_add_u64 v[238:239], s[68:69], 0, v[180:181]
	s_mov_b32 m0, s23
	s_nop 0
	global_load_lds_dwordx4 v[238:239], off
	s_mov_b32 m0, s29
	s_nop 0
	global_load_lds_dwordx4 v[240:241], off
	s_waitcnt vmcnt(8)
	s_waitcnt lgkmcnt(0)
	s_barrier
; #define PG8_STAGE(bufoff, gbase, voff) do { _Pragma("unroll") for (int _i = 0; _i < 2; ++_i) \
;         __builtin_amdgcn_global_load_lds((const unsigned*)((const char*)(gbase) + (voff)[_i]), (LAS unsigned*)(lds + (bufoff) + ldsw + _i * 8192), 16, 0, 0); } while (0)
; #define PG8_LDA(dst, b, h) do { _Pragma("unroll") for (int m = 0; m < 4; ++m) _Pragma("unroll") for (int k = 0; k < 2; ++k) dst[m][k] = *(const LAS bf16x8*)(lds + PG8_SA(b, h) + aoff + m * 2048 + k * 1024); } while (0)
; #define PG8_LDB(dst, b, h) do { _Pragma("unroll") for (int n = 0; n < 2; ++n) _Pragma("unroll") for (int k = 0; k < 2; ++k) dst[n][k] = *(const LAS bf16x8*)(lds + PG8_SB(b, h) + boff + n * 2048 + k * 1024); } while (0)
; #define PG8_MMA(ai, bj, At, Bt) do { __builtin_amdgcn_s_setprio(1); _Pragma("unroll") for (int m = 0; m < 4; ++m) _Pragma("unroll") for (int n = 0; n < 2; ++n) _Pragma("unroll") for (int k = 0; k < 2; ++k) \
;         acc[ai][bj][m][n] = __builtin_amdgcn_mfma_f32_16x16x32_bf16(Bt[n][k], At[m][k], acc[ai][bj][m][n], 0, 0, 0); __builtin_amdgcn_s_setprio(0); } while (0)
; #define PG8_WAIT_V(n) asm volatile("s_waitcnt vmcnt(" #n ")" ::: "memory")
; #define PG8_WAIT_L(n) asm volatile("s_waitcnt lgkmcnt(" #n ")" ::: "memory")
; #define PG8_BAR __builtin_amdgcn_s_barrier()
; #define PG8_SCHED __builtin_amdgcn_sched_barrier(0)
; template <class Epi, class Sched>
; __device__ __forceinline__ void gemm_phase(const int tid, LAS unsigned char* lds, const int lda, const int ldb, const int K, const Sched& S, const Epi& E) {
;     ...
;             PG8_WAIT_V(8); PG8_WAIT_L(0); PG8_BAR; if (!cur.half) { PG8_MMA(1, 0, At, B0); PG8_MMA(1, 1, At, B1); } PG8_BAR; PG8_SCHED;
;             PG8_LDB(B0, 1, 0); PG8_LDB(B1, 1, 1); PG8_SCHED; PG8_LDA(At, 1, 0); PG8_STAGE(PG8_SA(0, 1), a2 + hstepA, voffA);
;             PG8_WAIT_V(8); PG8_WAIT_L(0); PG8_BAR; PG8_MMA(0, 0, At, B0); PG8_MMA(0, 1, At, B1); PG8_BAR; PG8_SCHED;
	v_mfma_f32_16x16x32_bf16 v[92:95], v[104:107], v[160:163], 0
	v_mfma_f32_16x16x32_bf16 v[88:91], v[120:123], v[160:163], 0
	v_mfma_f32_16x16x32_bf16 v[84:87], v[104:107], v[212:215], 0
	v_mfma_f32_16x16x32_bf16 v[80:83], v[120:123], v[212:215], 0
	v_mfma_f32_16x16x32_bf16 v[76:79], v[104:107], v[220:223], 0
	v_mfma_f32_16x16x32_bf16 v[72:75], v[120:123], v[220:223], 0
	v_mfma_f32_16x16x32_bf16 v[68:71], v[104:107], v[228:231], 0
	v_mfma_f32_16x16x32_bf16 v[64:67], v[120:123], v[228:231], 0
	v_mfma_f32_16x16x32_bf16 v[92:95], v[108:111], v[164:167], v[92:95]
	v_mfma_f32_16x16x32_bf16 v[88:91], v[124:127], v[164:167], v[88:91]
	v_mfma_f32_16x16x32_bf16 v[84:87], v[108:111], v[216:219], v[84:87]
	v_mfma_f32_16x16x32_bf16 v[80:83], v[124:127], v[216:219], v[80:83]
	v_mfma_f32_16x16x32_bf16 v[76:79], v[108:111], v[224:227], v[76:79]
	v_mfma_f32_16x16x32_bf16 v[72:75], v[124:127], v[224:227], v[72:75]
	v_mfma_f32_16x16x32_bf16 v[68:71], v[108:111], v[232:235], v[68:71]
	v_mfma_f32_16x16x32_bf16 v[64:67], v[124:127], v[232:235], v[64:67]
	v_mfma_f32_16x16x32_bf16 v[28:31], v[136:139], v[160:163], 0
	v_mfma_f32_16x16x32_bf16 v[24:27], v[152:155], v[160:163], 0
	v_mfma_f32_16x16x32_bf16 v[20:23], v[136:139], v[212:215], 0
	v_mfma_f32_16x16x32_bf16 v[16:19], v[152:155], v[212:215], 0
	v_mfma_f32_16x16x32_bf16 v[12:15], v[136:139], v[220:223], 0
	v_mfma_f32_16x16x32_bf16 v[8:11], v[152:155], v[220:223], 0
	v_mfma_f32_16x16x32_bf16 v[4:7], v[136:139], v[228:231], 0
	v_mfma_f32_16x16x32_bf16 v[0:3], v[152:155], v[228:231], 0
	v_mfma_f32_16x16x32_bf16 v[28:31], v[144:147], v[164:167], v[28:31]
	v_mfma_f32_16x16x32_bf16 v[24:27], v[156:159], v[164:167], v[24:27]
	v_mfma_f32_16x16x32_bf16 v[20:23], v[144:147], v[216:219], v[20:23]
	v_mfma_f32_16x16x32_bf16 v[16:19], v[156:159], v[216:219], v[16:19]
	v_mfma_f32_16x16x32_bf16 v[12:15], v[144:147], v[224:227], v[12:15]
	v_mfma_f32_16x16x32_bf16 v[8:11], v[156:159], v[224:227], v[8:11]
	v_mfma_f32_16x16x32_bf16 v[4:7], v[144:147], v[232:235], v[4:7]
	v_mfma_f32_16x16x32_bf16 v[0:3], v[156:159], v[232:235], v[0:3]
	s_barrier
	s_add_i32 s14, 0, 0x18000
	s_add_i32 s15, 0, 0x1c000
	v_add_u32_e32 v124, s14, v206
	v_add_u32_e32 v156, s15, v206
	ds_read_b128 v[104:107], v124
	ds_read_b128 v[108:111], v124 offset:1024
	ds_read_b128 v[120:123], v124 offset:2048
	ds_read_b128 v[124:127], v124 offset:3072
	ds_read_b128 v[136:139], v156
	ds_read_b128 v[144:147], v156 offset:1024
	ds_read_b128 v[152:155], v156 offset:2048
	ds_read_b128 v[156:159], v156 offset:3072
	s_add_u32 s62, s68, 0x28000
	s_addc_u32 s63, s69, 0
	s_mov_b32 m0, s31
	v_lshl_add_u64 v[242:243], s[62:63], 0, v[180:181]
	ds_read_b128 v[160:163], v211 offset:32768
	ds_read_b128 v[164:167], v211 offset:33792
	ds_read_b128 v[212:215], v211 offset:34816
	ds_read_b128 v[216:219], v211 offset:35840
	ds_read_b128 v[220:223], v211 offset:36864
	ds_read_b128 v[224:227], v211 offset:37888
	ds_read_b128 v[228:231], v211 offset:38912
	ds_read_b128 v[232:235], v211 offset:39936
	global_load_lds_dwordx4 v[242:243], off
	v_lshl_add_u64 v[242:243], s[62:63], 0, v[184:185]
	s_mov_b32 m0, s41
	s_nop 0
	global_load_lds_dwordx4 v[242:243], off
	s_waitcnt vmcnt(8)
	s_waitcnt lgkmcnt(0)
	s_barrier
	v_mfma_f32_16x16x32_bf16 v[148:151], v[104:107], v[160:163], v[148:151]
	v_mfma_f32_16x16x32_bf16 v[140:143], v[120:123], v[160:163], v[140:143]
	v_mfma_f32_16x16x32_bf16 v[132:135], v[104:107], v[212:215], v[132:135]
	v_mfma_f32_16x16x32_bf16 v[128:131], v[120:123], v[212:215], v[128:131]
	v_mfma_f32_16x16x32_bf16 v[116:119], v[104:107], v[220:223], v[116:119]
	v_mfma_f32_16x16x32_bf16 v[112:115], v[120:123], v[220:223], v[112:115]
	v_mfma_f32_16x16x32_bf16 v[100:103], v[104:107], v[228:231], v[100:103]
	v_mfma_f32_16x16x32_bf16 v[96:99], v[120:123], v[228:231], v[96:99]
	v_mfma_f32_16x16x32_bf16 v[148:151], v[108:111], v[164:167], v[148:151]
	v_mfma_f32_16x16x32_bf16 v[140:143], v[124:127], v[164:167], v[140:143]
	v_mfma_f32_16x16x32_bf16 v[132:135], v[108:111], v[216:219], v[132:135]
	v_mfma_f32_16x16x32_bf16 v[128:131], v[124:127], v[216:219], v[128:131]
	v_mfma_f32_16x16x32_bf16 v[116:119], v[108:111], v[224:227], v[116:119]
	v_mfma_f32_16x16x32_bf16 v[112:115], v[124:127], v[224:227], v[112:115]
	v_mfma_f32_16x16x32_bf16 v[100:103], v[108:111], v[232:235], v[100:103]
	v_mfma_f32_16x16x32_bf16 v[96:99], v[124:127], v[232:235], v[96:99]
	v_mfma_f32_16x16x32_bf16 v[60:63], v[136:139], v[160:163], v[60:63]
	v_mfma_f32_16x16x32_bf16 v[56:59], v[152:155], v[160:163], v[56:59]
	v_mfma_f32_16x16x32_bf16 v[52:55], v[136:139], v[212:215], v[52:55]
	v_mfma_f32_16x16x32_bf16 v[48:51], v[152:155], v[212:215], v[48:51]
	v_mfma_f32_16x16x32_bf16 v[44:47], v[136:139], v[220:223], v[44:47]
	v_mfma_f32_16x16x32_bf16 v[40:43], v[152:155], v[220:223], v[40:43]
	v_mfma_f32_16x16x32_bf16 v[36:39], v[136:139], v[228:231], v[36:39]
	v_mfma_f32_16x16x32_bf16 v[32:35], v[152:155], v[228:231], v[32:35]
	v_mfma_f32_16x16x32_bf16 v[60:63], v[144:147], v[164:167], v[60:63]
	v_mfma_f32_16x16x32_bf16 v[56:59], v[156:159], v[164:167], v[56:59]
	v_mfma_f32_16x16x32_bf16 v[52:55], v[144:147], v[216:219], v[52:55]
	v_mfma_f32_16x16x32_bf16 v[48:51], v[156:159], v[216:219], v[48:51]
	v_mfma_f32_16x16x32_bf16 v[44:47], v[144:147], v[224:227], v[44:47]
	v_mfma_f32_16x16x32_bf16 v[40:43], v[156:159], v[224:227], v[40:43]
	v_mfma_f32_16x16x32_bf16 v[36:39], v[144:147], v[232:235], v[36:39]
	v_mfma_f32_16x16x32_bf16 v[32:35], v[156:159], v[232:235], v[32:35]
	s_barrier
; #define PG8_STAGE(bufoff, gbase, voff) do { _Pragma("unroll") for (int _i = 0; _i < 2; ++_i) \
;         __builtin_amdgcn_global_load_lds((const unsigned*)((const char*)(gbase) + (voff)[_i]), (LAS unsigned*)(lds + (bufoff) + ldsw + _i * 8192), 16, 0, 0); } while (0)
; #define PG8_LDA(dst, b, h) do { _Pragma("unroll") for (int m = 0; m < 4; ++m) _Pragma("unroll") for (int k = 0; k < 2; ++k) dst[m][k] = *(const LAS bf16x8*)(lds + PG8_SA(b, h) + aoff + m * 2048 + k * 1024); } while (0)
; #define PG8_LDB(dst, b, h) do { _Pragma("unroll") for (int n = 0; n < 2; ++n) _Pragma("unroll") for (int k = 0; k < 2; ++k) dst[n][k] = *(const LAS bf16x8*)(lds + PG8_SB(b, h) + boff + n * 2048 + k * 1024); } while (0)
; #define PG8_BAR __builtin_amdgcn_s_barrier()
; template <class Epi, class Sched>
; __device__ __forceinline__ void gemm_phase(const int tid, LAS unsigned char* lds, const int lda, const int ldb, const int K, const Sched& S, const Epi& E) {
;     ...
;         for (int t = 0; t < nt; t += 2) {
;             const bool last = (t == nt - 2);
;             const char* a1 = cA + (size_t)(t + 1) * kstep;
;             const char* a2 = last ? nA : cA + (size_t)(t + 2) * kstep; const char* b2 = last ? nB : cB + (size_t)(t + 2) * kstep;
;             const char* a3 = a2 + kstep; const char* b3 = b2 + kstep;
;             PG8_LDB(B0, 0, 0); PG8_LDB(B1, 0, 1); PG8_SCHED; PG8_LDA(At, 0, 0); PG8_STAGE(PG8_SA(1, 1), a1 + hstepA, voffA);
;             PG8_WAIT_V(8); PG8_WAIT_L(0); PG8_BAR; PG8_MMA(0, 0, At, B0); PG8_MMA(0, 1, At, B1); PG8_BAR; PG8_SCHED;
;             PG8_LDA(At, 0, 1); PG8_STAGE(PG8_SB(0, 0), b2, voffB); PG8_STAGE(PG8_SB(0, 1), b2 + hstepB, voffB); PG8_STAGE(PG8_SA(0, 0), a2, voffA);
;             PG8_WAIT_V(8); PG8_WAIT_L(0); PG8_BAR; if (!cur.half) { PG8_MMA(1, 0, At, B0); PG8_MMA(1, 1, At, B1); } PG8_BAR; PG8_SCHED;
;             PG8_LDB(B0, 1, 0); PG8_LDB(B1, 1, 1); PG8_SCHED; PG8_LDA(At, 1, 0); PG8_STAGE(PG8_SA(0, 1), a2 + hstepA, voffA);
;             PG8_WAIT_V(8); PG8_WAIT_L(0); PG8_BAR; PG8_MMA(0, 0, At, B0); PG8_MMA(0, 1, At, B1); PG8_BAR; PG8_SCHED;
;             PG8_LDA(At, 1, 1); PG8_STAGE(PG8_SB(1, 0), b3, voffB); PG8_STAGE(PG8_SB(1, 1), b3 + hstepB, voffB); PG8_STAGE(PG8_SA(1, 0), a3, voffA);
;             PG8_WAIT_V(8); PG8_WAIT_L(0); PG8_BAR; if (!cur.half) { PG8_MMA(1, 0, At, B0); PG8_MMA(1, 1, At, B1); } PG8_BAR; PG8_SCHED;
;         }
	s_add_i32 s14, s14, s21
	v_lshl_add_u64 v[196:197], v[196:197], 0, s[6:7]
	s_mov_b32 m0, s14
	ds_read_b128 v[160:163], v211 offset:49152
	ds_read_b128 v[164:167], v211 offset:50176
	ds_read_b128 v[212:215], v211 offset:51200
	ds_read_b128 v[216:219], v211 offset:52224
	ds_read_b128 v[220:223], v211 offset:53248
	ds_read_b128 v[224:227], v211 offset:54272
	ds_read_b128 v[228:231], v211 offset:55296
	ds_read_b128 v[232:235], v211 offset:56320
	global_load_lds_dwordx4 v[196:197], off
	s_add_i32 m0, s14, 0x2000
	s_add_u32 s62, s66, 0x28080
	v_lshl_add_u64 v[196:197], v[236:237], 0, s[6:7]
	s_addc_u32 s63, s67, 0
	s_add_i32 s14, s15, s21
	global_load_lds_dwordx4 v[196:197], off
	v_lshl_add_u64 v[196:197], s[62:63], 0, v[182:183]
	s_mov_b32 m0, s14
	s_nop 0
	global_load_lds_dwordx4 v[196:197], off
	v_lshl_add_u64 v[196:197], s[62:63], 0, v[186:187]
	s_add_i32 m0, s14, 0x2000
	s_nop 0
	global_load_lds_dwordx4 v[196:197], off
	v_lshl_add_u64 v[196:197], v[238:239], 0, s[6:7]
	s_mov_b32 m0, s47
	s_nop 0
	global_load_lds_dwordx4 v[196:197], off
	v_lshl_add_u64 v[196:197], v[240:241], 0, s[6:7]
	s_mov_b32 m0, s70
	s_nop 0
	global_load_lds_dwordx4 v[196:197], off
	s_waitcnt vmcnt(8)
	s_waitcnt lgkmcnt(0)
	s_barrier
	v_mfma_f32_16x16x32_bf16 v[92:95], v[104:107], v[160:163], v[92:95]
	v_mfma_f32_16x16x32_bf16 v[88:91], v[120:123], v[160:163], v[88:91]
	v_mfma_f32_16x16x32_bf16 v[84:87], v[104:107], v[212:215], v[84:87]
	v_mfma_f32_16x16x32_bf16 v[80:83], v[120:123], v[212:215], v[80:83]
	v_mfma_f32_16x16x32_bf16 v[76:79], v[104:107], v[220:223], v[76:79]
	v_mfma_f32_16x16x32_bf16 v[72:75], v[120:123], v[220:223], v[72:75]
	v_mfma_f32_16x16x32_bf16 v[68:71], v[104:107], v[228:231], v[68:71]
	v_mfma_f32_16x16x32_bf16 v[64:67], v[120:123], v[228:231], v[64:67]
	v_mfma_f32_16x16x32_bf16 v[92:95], v[108:111], v[164:167], v[92:95]
	v_mfma_f32_16x16x32_bf16 v[88:91], v[124:127], v[164:167], v[88:91]
	v_mfma_f32_16x16x32_bf16 v[84:87], v[108:111], v[216:219], v[84:87]
	v_mfma_f32_16x16x32_bf16 v[80:83], v[124:127], v[216:219], v[80:83]
	v_mfma_f32_16x16x32_bf16 v[76:79], v[108:111], v[224:227], v[76:79]
	v_mfma_f32_16x16x32_bf16 v[72:75], v[124:127], v[224:227], v[72:75]
	v_mfma_f32_16x16x32_bf16 v[68:71], v[108:111], v[232:235], v[68:71]
	v_mfma_f32_16x16x32_bf16 v[64:67], v[124:127], v[232:235], v[64:67]
	v_mfma_f32_16x16x32_bf16 v[28:31], v[136:139], v[160:163], v[28:31]
	v_mfma_f32_16x16x32_bf16 v[24:27], v[152:155], v[160:163], v[24:27]
	v_mfma_f32_16x16x32_bf16 v[20:23], v[136:139], v[212:215], v[20:23]
	v_mfma_f32_16x16x32_bf16 v[16:19], v[152:155], v[212:215], v[16:19]
	v_mfma_f32_16x16x32_bf16 v[12:15], v[136:139], v[220:223], v[12:15]
	v_mfma_f32_16x16x32_bf16 v[8:11], v[152:155], v[220:223], v[8:11]
	v_mfma_f32_16x16x32_bf16 v[4:7], v[136:139], v[228:231], v[4:7]
	v_mfma_f32_16x16x32_bf16 v[0:3], v[152:155], v[228:231], v[0:3]
	v_mfma_f32_16x16x32_bf16 v[28:31], v[144:147], v[164:167], v[28:31]
	v_mfma_f32_16x16x32_bf16 v[24:27], v[156:159], v[164:167], v[24:27]
	v_mfma_f32_16x16x32_bf16 v[20:23], v[144:147], v[216:219], v[20:23]
	v_mfma_f32_16x16x32_bf16 v[16:19], v[156:159], v[216:219], v[16:19]
	v_mfma_f32_16x16x32_bf16 v[12:15], v[144:147], v[224:227], v[12:15]
	v_mfma_f32_16x16x32_bf16 v[8:11], v[156:159], v[224:227], v[8:11]
	v_mfma_f32_16x16x32_bf16 v[4:7], v[144:147], v[232:235], v[4:7]
	v_mfma_f32_16x16x32_bf16 v[0:3], v[156:159], v[232:235], v[0:3]
	s_barrier
	s_add_u32 s26, s26, 0x100
	s_addc_u32 s27, s27, 0
	s_cmp_ge_i32 s43, s4
	s_mov_b64 s[62:63], s[64:65]
	s_mov_b32 s42, s43
	s_cbranch_scc1 .Lkexit_793
.LBB0_793:
	s_add_i32 s43, s42, 2
	s_add_u32 s64, s62, 0x100
	s_addc_u32 s65, s63, 0
	s_add_i32 s14, 0, 0x10000
	s_cmp_eq_u32 s72, s42
	s_cselect_b32 s69, s3, s65
	s_cselect_b32 s68, s2, s64
	s_cselect_b32 s67, s61, s27
	s_cselect_b32 s66, s60, s26
	s_add_i32 s15, 0, 0x14000
	v_add_u32_e32 v124, s14, v206
	v_add_u32_e32 v156, s15, v206
	ds_read_b128 v[104:107], v124
	ds_read_b128 v[108:111], v124 offset:1024
	ds_read_b128 v[120:123], v124 offset:2048
	ds_read_b128 v[124:127], v124 offset:3072
	ds_read_b128 v[136:139], v156
	ds_read_b128 v[144:147], v156 offset:1024
	ds_read_b128 v[152:155], v156 offset:2048
	ds_read_b128 v[156:159], v156 offset:3072
	v_lshl_add_u64 v[196:197], s[62:63], 0, v[192:193]
	s_add_i32 m0, s23, 0xc000
	ds_read_b128 v[160:163], v211
	ds_read_b128 v[164:167], v211 offset:1024
	ds_read_b128 v[212:215], v211 offset:2048
	ds_read_b128 v[216:219], v211 offset:3072
	ds_read_b128 v[220:223], v211 offset:4096
	ds_read_b128 v[224:227], v211 offset:5120
	ds_read_b128 v[228:231], v211 offset:6144
	ds_read_b128 v[232:235], v211 offset:7168
	global_load_lds_dwordx4 v[196:197], off
	v_lshl_add_u64 v[196:197], s[62:63], 0, v[194:195]
	s_add_i32 m0, s23, 0xe000
	s_nop 0
	global_load_lds_dwordx4 v[196:197], off
	s_waitcnt vmcnt(8)
	s_waitcnt lgkmcnt(0)
	s_barrier
; #define PG8_STAGE(bufoff, gbase, voff) do { _Pragma("unroll") for (int _i = 0; _i < 2; ++_i) \
;         __builtin_amdgcn_global_load_lds((const unsigned*)((const char*)(gbase) + (voff)[_i]), (LAS unsigned*)(lds + (bufoff) + ldsw + _i * 8192), 16, 0, 0); } while (0)
; #define PG8_LDA(dst, b, h) do { _Pragma("unroll") for (int m = 0; m < 4; ++m) _Pragma("unroll") for (int k = 0; k < 2; ++k) dst[m][k] = *(const LAS bf16x8*)(lds + PG8_SA(b, h) + aoff + m * 2048 + k * 1024); } while (0)
; #define PG8_LDB(dst, b, h) do { _Pragma("unroll") for (int n = 0; n < 2; ++n) _Pragma("unroll") for (int k = 0; k < 2; ++k) dst[n][k] = *(const LAS bf16x8*)(lds + PG8_SB(b, h) + boff + n * 2048 + k * 1024); } while (0)
; #define PG8_MMA(ai, bj, At, Bt) do { __builtin_amdgcn_s_setprio(1); _Pragma("unroll") for (int m = 0; m < 4; ++m) _Pragma("unroll") for (int n = 0; n < 2; ++n) _Pragma("unroll") for (int k = 0; k < 2; ++k) \
;         acc[ai][bj][m][n] = __builtin_amdgcn_mfma_f32_16x16x32_bf16(Bt[n][k], At[m][k], acc[ai][bj][m][n], 0, 0, 0); __builtin_amdgcn_s_setprio(0); } while (0)
; #define PG8_WAIT_V(n) asm volatile("s_waitcnt vmcnt(" #n ")" ::: "memory")
; #define PG8_WAIT_L(n) asm volatile("s_waitcnt lgkmcnt(" #n ")" ::: "memory")
; #define PG8_BAR __builtin_amdgcn_s_barrier()
; #define PG8_SCHED __builtin_amdgcn_sched_barrier(0)
; template <class Epi, class Sched>
; __device__ __forceinline__ void gemm_phase(const int tid, LAS unsigned char* lds, const int lda, const int ldb, const int K, const Sched& S, const Epi& E) {
;     ...
;             PG8_WAIT_V(8); PG8_WAIT_L(0); PG8_BAR; PG8_MMA(0, 0, At, B0); PG8_MMA(0, 1, At, B1); PG8_BAR; PG8_SCHED;
;             PG8_LDA(At, 0, 1); PG8_STAGE(PG8_SB(0, 0), b2, voffB); PG8_STAGE(PG8_SB(0, 1), b2 + hstepB, voffB); PG8_STAGE(PG8_SA(0, 0), a2, voffA);
;             PG8_WAIT_V(8); PG8_WAIT_L(0); PG8_BAR; if (!cur.half) { PG8_MMA(1, 0, At, B0); PG8_MMA(1, 1, At, B1); } PG8_BAR; PG8_SCHED;
;             PG8_LDB(B0, 1, 0); PG8_LDB(B1, 1, 1); PG8_SCHED; PG8_LDA(At, 1, 0); PG8_STAGE(PG8_SA(0, 1), a2 + hstepA, voffA);
;             PG8_WAIT_V(8); PG8_WAIT_L(0); PG8_BAR; PG8_MMA(0, 0, At, B0); PG8_MMA(0, 1, At, B1); PG8_BAR; PG8_SCHED;
	v_mfma_f32_16x16x32_bf16 v[148:151], v[104:107], v[160:163], v[148:151]
	v_mfma_f32_16x16x32_bf16 v[140:143], v[120:123], v[160:163], v[140:143]
	v_mfma_f32_16x16x32_bf16 v[132:135], v[104:107], v[212:215], v[132:135]
	v_mfma_f32_16x16x32_bf16 v[128:131], v[120:123], v[212:215], v[128:131]
	v_mfma_f32_16x16x32_bf16 v[116:119], v[104:107], v[220:223], v[116:119]
	v_mfma_f32_16x16x32_bf16 v[112:115], v[120:123], v[220:223], v[112:115]
	v_mfma_f32_16x16x32_bf16 v[100:103], v[104:107], v[228:231], v[100:103]
	v_mfma_f32_16x16x32_bf16 v[96:99], v[120:123], v[228:231], v[96:99]
	v_mfma_f32_16x16x32_bf16 v[148:151], v[108:111], v[164:167], v[148:151]
	v_mfma_f32_16x16x32_bf16 v[140:143], v[124:127], v[164:167], v[140:143]
	v_mfma_f32_16x16x32_bf16 v[132:135], v[108:111], v[216:219], v[132:135]
	v_mfma_f32_16x16x32_bf16 v[128:131], v[124:127], v[216:219], v[128:131]
	v_mfma_f32_16x16x32_bf16 v[116:119], v[108:111], v[224:227], v[116:119]
	v_mfma_f32_16x16x32_bf16 v[112:115], v[124:127], v[224:227], v[112:115]
	v_mfma_f32_16x16x32_bf16 v[100:103], v[108:111], v[232:235], v[100:103]
	v_mfma_f32_16x16x32_bf16 v[96:99], v[124:127], v[232:235], v[96:99]
	v_mfma_f32_16x16x32_bf16 v[60:63], v[136:139], v[160:163], v[60:63]
	v_mfma_f32_16x16x32_bf16 v[56:59], v[152:155], v[160:163], v[56:59]
	v_mfma_f32_16x16x32_bf16 v[52:55], v[136:139], v[212:215], v[52:55]
	v_mfma_f32_16x16x32_bf16 v[48:51], v[152:155], v[212:215], v[48:51]
	v_mfma_f32_16x16x32_bf16 v[44:47], v[136:139], v[220:223], v[44:47]
	v_mfma_f32_16x16x32_bf16 v[40:43], v[152:155], v[220:223], v[40:43]
	v_mfma_f32_16x16x32_bf16 v[36:39], v[136:139], v[228:231], v[36:39]
	v_mfma_f32_16x16x32_bf16 v[32:35], v[152:155], v[228:231], v[32:35]
	v_mfma_f32_16x16x32_bf16 v[60:63], v[144:147], v[164:167], v[60:63]
	v_mfma_f32_16x16x32_bf16 v[56:59], v[156:159], v[164:167], v[56:59]
	v_mfma_f32_16x16x32_bf16 v[52:55], v[144:147], v[216:219], v[52:55]
	v_mfma_f32_16x16x32_bf16 v[48:51], v[156:159], v[216:219], v[48:51]
	v_mfma_f32_16x16x32_bf16 v[44:47], v[144:147], v[224:227], v[44:47]
	v_mfma_f32_16x16x32_bf16 v[40:43], v[156:159], v[224:227], v[40:43]
	v_mfma_f32_16x16x32_bf16 v[36:39], v[144:147], v[232:235], v[36:39]
	v_mfma_f32_16x16x32_bf16 v[32:35], v[156:159], v[232:235], v[32:35]
	s_barrier
	s_add_i32 s14, s14, s21
	v_lshl_add_u64 v[196:197], s[66:67], 0, v[182:183]
	s_mov_b32 m0, s14
	ds_read_b128 v[160:163], v211 offset:16384
	ds_read_b128 v[164:167], v211 offset:17408
	ds_read_b128 v[212:215], v211 offset:18432
	ds_read_b128 v[216:219], v211 offset:19456
	ds_read_b128 v[220:223], v211 offset:20480
	ds_read_b128 v[224:227], v211 offset:21504
	ds_read_b128 v[228:231], v211 offset:22528
	ds_read_b128 v[232:235], v211 offset:23552
	global_load_lds_dwordx4 v[196:197], off
	s_add_i32 m0, s14, 0x2000
	s_add_u32 s62, s66, 0x28000
	v_lshl_add_u64 v[236:237], s[66:67], 0, v[186:187]
	s_addc_u32 s63, s67, 0
	s_add_i32 s14, s15, s21
	global_load_lds_dwordx4 v[236:237], off
	v_lshl_add_u64 v[238:239], s[62:63], 0, v[182:183]
	s_mov_b32 m0, s14
	v_lshl_add_u64 v[240:241], s[68:69], 0, v[184:185]
	global_load_lds_dwordx4 v[238:239], off
	v_lshl_add_u64 v[238:239], s[62:63], 0, v[186:187]
	s_add_i32 m0, s14, 0x2000
	s_nop 0
	global_load_lds_dwordx4 v[238:239], off
	v_lshl_add_u64 v[238:239], s[68:69], 0, v[180:181]
	s_mov_b32 m0, s23
	s_nop 0
	global_load_lds_dwordx4 v[238:239], off
	s_mov_b32 m0, s29
	s_nop 0
	global_load_lds_dwordx4 v[240:241], off
	s_waitcnt vmcnt(8)
	s_waitcnt lgkmcnt(0)
	s_barrier
	v_mfma_f32_16x16x32_bf16 v[92:95], v[104:107], v[160:163], v[92:95]
	v_mfma_f32_16x16x32_bf16 v[88:91], v[120:123], v[160:163], v[88:91]
	v_mfma_f32_16x16x32_bf16 v[84:87], v[104:107], v[212:215], v[84:87]
	v_mfma_f32_16x16x32_bf16 v[80:83], v[120:123], v[212:215], v[80:83]
	v_mfma_f32_16x16x32_bf16 v[76:79], v[104:107], v[220:223], v[76:79]
	v_mfma_f32_16x16x32_bf16 v[72:75], v[120:123], v[220:223], v[72:75]
	v_mfma_f32_16x16x32_bf16 v[68:71], v[104:107], v[228:231], v[68:71]
	v_mfma_f32_16x16x32_bf16 v[64:67], v[120:123], v[228:231], v[64:67]
	v_mfma_f32_16x16x32_bf16 v[92:95], v[108:111], v[164:167], v[92:95]
	v_mfma_f32_16x16x32_bf16 v[88:91], v[124:127], v[164:167], v[88:91]
	v_mfma_f32_16x16x32_bf16 v[84:87], v[108:111], v[216:219], v[84:87]
	v_mfma_f32_16x16x32_bf16 v[80:83], v[124:127], v[216:219], v[80:83]
	v_mfma_f32_16x16x32_bf16 v[76:79], v[108:111], v[224:227], v[76:79]
	v_mfma_f32_16x16x32_bf16 v[72:75], v[124:127], v[224:227], v[72:75]
	v_mfma_f32_16x16x32_bf16 v[68:71], v[108:111], v[232:235], v[68:71]
	v_mfma_f32_16x16x32_bf16 v[64:67], v[124:127], v[232:235], v[64:67]
	v_mfma_f32_16x16x32_bf16 v[28:31], v[136:139], v[160:163], v[28:31]
	v_mfma_f32_16x16x32_bf16 v[24:27], v[152:155], v[160:163], v[24:27]
	v_mfma_f32_16x16x32_bf16 v[20:23], v[136:139], v[212:215], v[20:23]
	v_mfma_f32_16x16x32_bf16 v[16:19], v[152:155], v[212:215], v[16:19]
	v_mfma_f32_16x16x32_bf16 v[12:15], v[136:139], v[220:223], v[12:15]
	v_mfma_f32_16x16x32_bf16 v[8:11], v[152:155], v[220:223], v[8:11]
	v_mfma_f32_16x16x32_bf16 v[4:7], v[136:139], v[228:231], v[4:7]
	v_mfma_f32_16x16x32_bf16 v[0:3], v[152:155], v[228:231], v[0:3]
	v_mfma_f32_16x16x32_bf16 v[28:31], v[144:147], v[164:167], v[28:31]
	v_mfma_f32_16x16x32_bf16 v[24:27], v[156:159], v[164:167], v[24:27]
	v_mfma_f32_16x16x32_bf16 v[20:23], v[144:147], v[216:219], v[20:23]
	v_mfma_f32_16x16x32_bf16 v[16:19], v[156:159], v[216:219], v[16:19]
	v_mfma_f32_16x16x32_bf16 v[12:15], v[144:147], v[224:227], v[12:15]
	v_mfma_f32_16x16x32_bf16 v[8:11], v[156:159], v[224:227], v[8:11]
	v_mfma_f32_16x16x32_bf16 v[4:7], v[144:147], v[232:235], v[4:7]
	v_mfma_f32_16x16x32_bf16 v[0:3], v[156:159], v[232:235], v[0:3]
	s_barrier
; #define PG8_STAGE(bufoff, gbase, voff) do { _Pragma("unroll") for (int _i = 0; _i < 2; ++_i) \
;         __builtin_amdgcn_global_load_lds((const unsigned*)((const char*)(gbase) + (voff)[_i]), (LAS unsigned*)(lds + (bufoff) + ldsw + _i * 8192), 16, 0, 0); } while (0)
; #define PG8_LDA(dst, b, h) do { _Pragma("unroll") for (int m = 0; m < 4; ++m) _Pragma("unroll") for (int k = 0; k < 2; ++k) dst[m][k] = *(const LAS bf16x8*)(lds + PG8_SA(b, h) + aoff + m * 2048 + k * 1024); } while (0)
; #define PG8_LDB(dst, b, h) do { _Pragma("unroll") for (int n = 0; n < 2; ++n) _Pragma("unroll") for (int k = 0; k < 2; ++k) dst[n][k] = *(const LAS bf16x8*)(lds + PG8_SB(b, h) + boff + n * 2048 + k * 1024); } while (0)
; #define PG8_MMA(ai, bj, At, Bt) do { __builtin_amdgcn_s_setprio(1); _Pragma("unroll") for (int m = 0; m < 4; ++m) _Pragma("unroll") for (int n = 0; n < 2; ++n) _Pragma("unroll") for (int k = 0; k < 2; ++k) \
;         acc[ai][bj][m][n] = __builtin_amdgcn_mfma_f32_16x16x32_bf16(Bt[n][k], At[m][k], acc[ai][bj][m][n], 0, 0, 0); __builtin_amdgcn_s_setprio(0); } while (0)
; #define PG8_WAIT_V(n) asm volatile("s_waitcnt vmcnt(" #n ")" ::: "memory")
; #define PG8_WAIT_L(n) asm volatile("s_waitcnt lgkmcnt(" #n ")" ::: "memory")
; #define PG8_BAR __builtin_amdgcn_s_barrier()
; #define PG8_SCHED __builtin_amdgcn_sched_barrier(0)
; template <class Epi, class Sched>
; __device__ __forceinline__ void gemm_phase(const int tid, LAS unsigned char* lds, const int lda, const int ldb, const int K, const Sched& S, const Epi& E) {
;     ...
;             PG8_LDB(B0, 1, 0); PG8_LDB(B1, 1, 1); PG8_SCHED; PG8_LDA(At, 1, 0); PG8_STAGE(PG8_SA(0, 1), a2 + hstepA, voffA);
;             PG8_WAIT_V(8); PG8_WAIT_L(0); PG8_BAR; PG8_MMA(0, 0, At, B0); PG8_MMA(0, 1, At, B1); PG8_BAR; PG8_SCHED;
;             PG8_LDA(At, 1, 1); PG8_STAGE(PG8_SB(1, 0), b3, voffB); PG8_STAGE(PG8_SB(1, 1), b3 + hstepB, voffB); PG8_STAGE(PG8_SA(1, 0), a3, voffA);
;             PG8_WAIT_V(8); PG8_WAIT_L(0); PG8_BAR; if (!cur.half) { PG8_MMA(1, 0, At, B0); PG8_MMA(1, 1, At, B1); } PG8_BAR; PG8_SCHED;
;         }
	s_add_i32 s14, 0, 0x18000
	s_add_i32 s15, 0, 0x1c000
	v_add_u32_e32 v124, s14, v206
	v_add_u32_e32 v156, s15, v206
	ds_read_b128 v[104:107], v124
	ds_read_b128 v[108:111], v124 offset:1024
	ds_read_b128 v[120:123], v124 offset:2048
	ds_read_b128 v[124:127], v124 offset:3072
	ds_read_b128 v[136:139], v156
	ds_read_b128 v[144:147], v156 offset:1024
	ds_read_b128 v[152:155], v156 offset:2048
	ds_read_b128 v[156:159], v156 offset:3072
	s_add_u32 s62, s68, 0x28000
	s_addc_u32 s63, s69, 0
	s_mov_b32 m0, s31
	v_lshl_add_u64 v[242:243], s[62:63], 0, v[180:181]
	ds_read_b128 v[160:163], v211 offset:32768
	ds_read_b128 v[164:167], v211 offset:33792
	ds_read_b128 v[212:215], v211 offset:34816
	ds_read_b128 v[216:219], v211 offset:35840
	ds_read_b128 v[220:223], v211 offset:36864
	ds_read_b128 v[224:227], v211 offset:37888
	ds_read_b128 v[228:231], v211 offset:38912
	ds_read_b128 v[232:235], v211 offset:39936
	global_load_lds_dwordx4 v[242:243], off
	v_lshl_add_u64 v[242:243], s[62:63], 0, v[184:185]
	s_mov_b32 m0, s41
	s_nop 0
	global_load_lds_dwordx4 v[242:243], off
	s_waitcnt vmcnt(8)
	s_waitcnt lgkmcnt(0)
	s_barrier
	v_mfma_f32_16x16x32_bf16 v[148:151], v[104:107], v[160:163], v[148:151]
	v_mfma_f32_16x16x32_bf16 v[140:143], v[120:123], v[160:163], v[140:143]
	v_mfma_f32_16x16x32_bf16 v[132:135], v[104:107], v[212:215], v[132:135]
	v_mfma_f32_16x16x32_bf16 v[128:131], v[120:123], v[212:215], v[128:131]
	v_mfma_f32_16x16x32_bf16 v[116:119], v[104:107], v[220:223], v[116:119]
	v_mfma_f32_16x16x32_bf16 v[112:115], v[120:123], v[220:223], v[112:115]
	v_mfma_f32_16x16x32_bf16 v[100:103], v[104:107], v[228:231], v[100:103]
	v_mfma_f32_16x16x32_bf16 v[96:99], v[120:123], v[228:231], v[96:99]
	v_mfma_f32_16x16x32_bf16 v[148:151], v[108:111], v[164:167], v[148:151]
	v_mfma_f32_16x16x32_bf16 v[140:143], v[124:127], v[164:167], v[140:143]
	v_mfma_f32_16x16x32_bf16 v[132:135], v[108:111], v[216:219], v[132:135]
	v_mfma_f32_16x16x32_bf16 v[128:131], v[124:127], v[216:219], v[128:131]
	v_mfma_f32_16x16x32_bf16 v[116:119], v[108:111], v[224:227], v[116:119]
	v_mfma_f32_16x16x32_bf16 v[112:115], v[124:127], v[224:227], v[112:115]
	v_mfma_f32_16x16x32_bf16 v[100:103], v[108:111], v[232:235], v[100:103]
	v_mfma_f32_16x16x32_bf16 v[96:99], v[124:127], v[232:235], v[96:99]
	v_mfma_f32_16x16x32_bf16 v[60:63], v[136:139], v[160:163], v[60:63]
	v_mfma_f32_16x16x32_bf16 v[56:59], v[152:155], v[160:163], v[56:59]
	v_mfma_f32_16x16x32_bf16 v[52:55], v[136:139], v[212:215], v[52:55]
	v_mfma_f32_16x16x32_bf16 v[48:51], v[152:155], v[212:215], v[48:51]
	v_mfma_f32_16x16x32_bf16 v[44:47], v[136:139], v[220:223], v[44:47]
	v_mfma_f32_16x16x32_bf16 v[40:43], v[152:155], v[220:223], v[40:43]
	v_mfma_f32_16x16x32_bf16 v[36:39], v[136:139], v[228:231], v[36:39]
	v_mfma_f32_16x16x32_bf16 v[32:35], v[152:155], v[228:231], v[32:35]
	v_mfma_f32_16x16x32_bf16 v[60:63], v[144:147], v[164:167], v[60:63]
	v_mfma_f32_16x16x32_bf16 v[56:59], v[156:159], v[164:167], v[56:59]
	v_mfma_f32_16x16x32_bf16 v[52:55], v[144:147], v[216:219], v[52:55]
	v_mfma_f32_16x16x32_bf16 v[48:51], v[156:159], v[216:219], v[48:51]
	v_mfma_f32_16x16x32_bf16 v[44:47], v[144:147], v[224:227], v[44:47]
	v_mfma_f32_16x16x32_bf16 v[40:43], v[156:159], v[224:227], v[40:43]
	v_mfma_f32_16x16x32_bf16 v[36:39], v[144:147], v[232:235], v[36:39]
	v_mfma_f32_16x16x32_bf16 v[32:35], v[156:159], v[232:235], v[32:35]
	s_barrier
	s_add_i32 s14, s14, s21
	v_lshl_add_u64 v[196:197], v[196:197], 0, s[6:7]
	s_mov_b32 m0, s14
	ds_read_b128 v[160:163], v211 offset:49152
	ds_read_b128 v[164:167], v211 offset:50176
	ds_read_b128 v[212:215], v211 offset:51200
	ds_read_b128 v[216:219], v211 offset:52224
	ds_read_b128 v[220:223], v211 offset:53248
	ds_read_b128 v[224:227], v211 offset:54272
	ds_read_b128 v[228:231], v211 offset:55296
	ds_read_b128 v[232:235], v211 offset:56320
	global_load_lds_dwordx4 v[196:197], off
	s_add_i32 m0, s14, 0x2000
	s_add_u32 s62, s66, 0x28080
	v_lshl_add_u64 v[196:197], v[236:237], 0, s[6:7]
	s_addc_u32 s63, s67, 0
	s_add_i32 s14, s15, s21
	global_load_lds_dwordx4 v[196:197], off
	v_lshl_add_u64 v[196:197], s[62:63], 0, v[182:183]
	s_mov_b32 m0, s14
	s_nop 0
	global_load_lds_dwordx4 v[196:197], off
	v_lshl_add_u64 v[196:197], s[62:63], 0, v[186:187]
	s_add_i32 m0, s14, 0x2000
	s_nop 0
	global_load_lds_dwordx4 v[196:197], off
	v_lshl_add_u64 v[196:197], v[238:239], 0, s[6:7]
	s_mov_b32 m0, s47
	s_nop 0
	global_load_lds_dwordx4 v[196:197], off
	v_lshl_add_u64 v[196:197], v[240:241], 0, s[6:7]
	s_mov_b32 m0, s70
	s_nop 0
	global_load_lds_dwordx4 v[196:197], off
	s_waitcnt vmcnt(8)
	s_waitcnt lgkmcnt(0)
	s_barrier
	v_mfma_f32_16x16x32_bf16 v[92:95], v[104:107], v[160:163], v[92:95]
	v_mfma_f32_16x16x32_bf16 v[88:91], v[120:123], v[160:163], v[88:91]
	v_mfma_f32_16x16x32_bf16 v[84:87], v[104:107], v[212:215], v[84:87]
	v_mfma_f32_16x16x32_bf16 v[80:83], v[120:123], v[212:215], v[80:83]
	v_mfma_f32_16x16x32_bf16 v[76:79], v[104:107], v[220:223], v[76:79]
	v_mfma_f32_16x16x32_bf16 v[72:75], v[120:123], v[220:223], v[72:75]
	v_mfma_f32_16x16x32_bf16 v[68:71], v[104:107], v[228:231], v[68:71]
	v_mfma_f32_16x16x32_bf16 v[64:67], v[120:123], v[228:231], v[64:67]
	v_mfma_f32_16x16x32_bf16 v[92:95], v[108:111], v[164:167], v[92:95]
	v_mfma_f32_16x16x32_bf16 v[88:91], v[124:127], v[164:167], v[88:91]
	v_mfma_f32_16x16x32_bf16 v[84:87], v[108:111], v[216:219], v[84:87]
	v_mfma_f32_16x16x32_bf16 v[80:83], v[124:127], v[216:219], v[80:83]
	v_mfma_f32_16x16x32_bf16 v[76:79], v[108:111], v[224:227], v[76:79]
	v_mfma_f32_16x16x32_bf16 v[72:75], v[124:127], v[224:227], v[72:75]
	v_mfma_f32_16x16x32_bf16 v[68:71], v[108:111], v[232:235], v[68:71]
	v_mfma_f32_16x16x32_bf16 v[64:67], v[124:127], v[232:235], v[64:67]
	v_mfma_f32_16x16x32_bf16 v[28:31], v[136:139], v[160:163], v[28:31]
	v_mfma_f32_16x16x32_bf16 v[24:27], v[152:155], v[160:163], v[24:27]
	v_mfma_f32_16x16x32_bf16 v[20:23], v[136:139], v[212:215], v[20:23]
	v_mfma_f32_16x16x32_bf16 v[16:19], v[152:155], v[212:215], v[16:19]
	v_mfma_f32_16x16x32_bf16 v[12:15], v[136:139], v[220:223], v[12:15]
	v_mfma_f32_16x16x32_bf16 v[8:11], v[152:155], v[220:223], v[8:11]
	v_mfma_f32_16x16x32_bf16 v[4:7], v[136:139], v[228:231], v[4:7]
	v_mfma_f32_16x16x32_bf16 v[0:3], v[152:155], v[228:231], v[0:3]
	v_mfma_f32_16x16x32_bf16 v[28:31], v[144:147], v[164:167], v[28:31]
	v_mfma_f32_16x16x32_bf16 v[24:27], v[156:159], v[164:167], v[24:27]
	v_mfma_f32_16x16x32_bf16 v[20:23], v[144:147], v[216:219], v[20:23]
	v_mfma_f32_16x16x32_bf16 v[16:19], v[156:159], v[216:219], v[16:19]
	v_mfma_f32_16x16x32_bf16 v[12:15], v[144:147], v[224:227], v[12:15]
	v_mfma_f32_16x16x32_bf16 v[8:11], v[156:159], v[224:227], v[8:11]
	v_mfma_f32_16x16x32_bf16 v[4:7], v[144:147], v[232:235], v[4:7]
	v_mfma_f32_16x16x32_bf16 v[0:3], v[156:159], v[232:235], v[0:3]
	s_barrier
	s_add_u32 s26, s26, 0x100
	s_addc_u32 s27, s27, 0
	s_cmp_ge_i32 s43, s4
	s_mov_b64 s[62:63], s[64:65]
	s_mov_b32 s42, s43
	s_cbranch_scc0 .LBB0_793

; #define PG8_STAGE(bufoff, gbase, voff) do { _Pragma("unroll") for (int _i = 0; _i < 2; ++_i) \
;         __builtin_amdgcn_global_load_lds((const unsigned*)((const char*)(gbase) + (voff)[_i]), (LAS unsigned*)(lds + (bufoff) + ldsw + _i * 8192), 16, 0, 0); } while (0)
; #define PG8_LDA(dst, b, h) do { _Pragma("unroll") for (int m = 0; m < 4; ++m) _Pragma("unroll") for (int k = 0; k < 2; ++k) dst[m][k] = *(const LAS bf16x8*)(lds + PG8_SA(b, h) + aoff + m * 2048 + k * 1024); } while (0)
; #define PG8_LDB(dst, b, h) do { _Pragma("unroll") for (int n = 0; n < 2; ++n) _Pragma("unroll") for (int k = 0; k < 2; ++k) dst[n][k] = *(const LAS bf16x8*)(lds + PG8_SB(b, h) + boff + n * 2048 + k * 1024); } while (0)
; #define PG8_WAIT_V(n) asm volatile("s_waitcnt vmcnt(" #n ")" ::: "memory")
; #define PG8_WAIT_L(n) asm volatile("s_waitcnt lgkmcnt(" #n ")" ::: "memory")
; #define PG8_BAR __builtin_amdgcn_s_barrier()
; #define PG8_SCHED __builtin_amdgcn_sched_barrier(0)
; template <class Epi, class Sched>
; __device__ __forceinline__ void gemm_phase(const int tid, LAS unsigned char* lds, const int lda, const int ldb, const int K, const Sched& S, const Epi& E) {
;     ...
;         for (int t = 0; t < nt; t += 2) {
;             const bool last = (t == nt - 2);
;             const char* a1 = cA + (size_t)(t + 1) * kstep;
;             const char* a2 = last ? nA : cA + (size_t)(t + 2) * kstep; const char* b2 = last ? nB : cB + (size_t)(t + 2) * kstep;
;             const char* a3 = a2 + kstep; const char* b3 = b2 + kstep;
;             PG8_LDB(B0, 0, 0); PG8_LDB(B1, 0, 1); PG8_SCHED; PG8_LDA(At, 0, 0); PG8_STAGE(PG8_SA(1, 1), a1 + hstepA, voffA);
;             PG8_WAIT_V(8); PG8_WAIT_L(0); PG8_BAR; PG8_MMA(0, 0, At, B0); PG8_MMA(0, 1, At, B1); PG8_BAR; PG8_SCHED;
;             PG8_LDA(At, 0, 1); PG8_STAGE(PG8_SB(0, 0), b2, voffB); PG8_STAGE(PG8_SB(0, 1), b2 + hstepB, voffB); PG8_STAGE(PG8_SA(0, 0), a2, voffA);
;             PG8_WAIT_V(8); PG8_WAIT_L(0); PG8_BAR; if (!cur.half) { PG8_MMA(1, 0, At, B0); PG8_MMA(1, 1, At, B1); } PG8_BAR; PG8_SCHED;
;             PG8_LDB(B0, 1, 0); PG8_LDB(B1, 1, 1); PG8_SCHED; PG8_LDA(At, 1, 0); PG8_STAGE(PG8_SA(0, 1), a2 + hstepA, voffA);
;             PG8_WAIT_V(8); PG8_WAIT_L(0); PG8_BAR; PG8_MMA(0, 0, At, B0); PG8_MMA(0, 1, At, B1); PG8_BAR; PG8_SCHED;
.LBB0_816:
	s_add_i32 s24, s68, 2
	s_add_u32 s66, s64, 0x100
	s_addc_u32 s67, s65, 0
	s_add_i32 s14, 0, 0x10000
	v_add_u32_e32 v79, s14, v77
	ds_read_b128 v[80:83], v79
	ds_read_b128 v[84:87], v79 offset:1024
	ds_read_b128 v[88:91], v79 offset:2048
	ds_read_b128 v[92:95], v79 offset:3072
	s_cmp_eq_u32 s4, s68
	s_cselect_b32 s68, s62, s39
	s_cselect_b32 s71, s61, s67
	s_waitcnt lgkmcnt(0)
	s_cselect_b32 s70, s60, s66
	s_cselect_b32 s69, s63, s53
	v_lshl_add_u64 v[128:129], s[64:65], 0, v[72:73]
	s_add_i32 m0, s26, 0xc000
	ds_read_b128 v[96:99], v78
	ds_read_b128 v[100:103], v78 offset:1024
	ds_read_b128 v[104:107], v78 offset:2048
	ds_read_b128 v[108:111], v78 offset:3072
	ds_read_b128 v[112:115], v78 offset:4096
	ds_read_b128 v[116:119], v78 offset:5120
	ds_read_b128 v[120:123], v78 offset:6144
	ds_read_b128 v[124:127], v78 offset:7168
	global_load_lds_dwordx4 v[128:129], off
	v_lshl_add_u64 v[128:129], s[64:65], 0, v[74:75]
	s_add_i32 m0, s26, 0xe000
	s_nop 0
	global_load_lds_dwordx4 v[128:129], off
	s_waitcnt vmcnt(8)
	s_waitcnt lgkmcnt(0)
	s_barrier
	v_mfma_f32_16x16x32_bf16 v[60:63], v[80:83], v[96:99], v[60:63]
	v_mfma_f32_16x16x32_bf16 v[56:59], v[88:91], v[96:99], v[56:59]
	v_mfma_f32_16x16x32_bf16 v[52:55], v[80:83], v[104:107], v[52:55]
	v_mfma_f32_16x16x32_bf16 v[48:51], v[88:91], v[104:107], v[48:51]
	v_mfma_f32_16x16x32_bf16 v[44:47], v[80:83], v[112:115], v[44:47]
	v_mfma_f32_16x16x32_bf16 v[40:43], v[88:91], v[112:115], v[40:43]
	v_mfma_f32_16x16x32_bf16 v[36:39], v[80:83], v[120:123], v[36:39]
	v_mfma_f32_16x16x32_bf16 v[32:35], v[88:91], v[120:123], v[32:35]
	v_mfma_f32_16x16x32_bf16 v[60:63], v[84:87], v[100:103], v[60:63]
	v_mfma_f32_16x16x32_bf16 v[56:59], v[92:95], v[100:103], v[56:59]
	v_mfma_f32_16x16x32_bf16 v[52:55], v[84:87], v[108:111], v[52:55]
	v_mfma_f32_16x16x32_bf16 v[48:51], v[92:95], v[108:111], v[48:51]
	v_mfma_f32_16x16x32_bf16 v[44:47], v[84:87], v[116:119], v[44:47]
	v_mfma_f32_16x16x32_bf16 v[40:43], v[92:95], v[116:119], v[40:43]
	v_mfma_f32_16x16x32_bf16 v[36:39], v[84:87], v[124:127], v[36:39]
	v_mfma_f32_16x16x32_bf16 v[32:35], v[92:95], v[124:127], v[32:35]
	s_barrier
	s_add_i32 s14, s14, s13
	v_lshl_add_u64 v[128:129], s[68:69], 0, v[168:169]
	s_mov_b32 m0, s14
	ds_read_b128 v[96:99], v78 offset:16384
	ds_read_b128 v[100:103], v78 offset:17408
	ds_read_b128 v[104:107], v78 offset:18432
	ds_read_b128 v[108:111], v78 offset:19456
	ds_read_b128 v[112:115], v78 offset:20480
	ds_read_b128 v[116:119], v78 offset:21504
	ds_read_b128 v[120:123], v78 offset:22528
	ds_read_b128 v[124:127], v78 offset:23552
	global_load_lds_dwordx4 v[128:129], off
	s_add_i32 m0, s14, 0x2000
	s_add_u32 s64, s68, 0x20000
	v_lshl_add_u64 v[130:131], s[68:69], 0, v[64:65]
	s_addc_u32 s65, s69, 0
	global_load_lds_dwordx4 v[130:131], off
	v_lshl_add_u64 v[132:133], s[64:65], 0, v[168:169]
	s_mov_b32 m0, s27
	v_lshl_add_u64 v[134:135], s[70:71], 0, v[66:67]
	global_load_lds_dwordx4 v[132:133], off
	v_lshl_add_u64 v[132:133], s[64:65], 0, v[64:65]
	s_mov_b32 m0, s29
	s_nop 0
	global_load_lds_dwordx4 v[132:133], off
	v_lshl_add_u64 v[132:133], s[70:71], 0, v[68:69]
	s_mov_b32 m0, s26
	s_nop 0
	global_load_lds_dwordx4 v[132:133], off
	s_mov_b32 m0, s31
	s_nop 0
	global_load_lds_dwordx4 v[134:135], off
	s_waitcnt vmcnt(8)
	s_waitcnt lgkmcnt(0)
	s_barrier
	v_mfma_f32_16x16x32_bf16 v[28:31], v[80:83], v[96:99], v[28:31]
	v_mfma_f32_16x16x32_bf16 v[24:27], v[88:91], v[96:99], v[24:27]
	v_mfma_f32_16x16x32_bf16 v[20:23], v[80:83], v[104:107], v[20:23]
	v_mfma_f32_16x16x32_bf16 v[16:19], v[88:91], v[104:107], v[16:19]
	v_mfma_f32_16x16x32_bf16 v[12:15], v[80:83], v[112:115], v[12:15]
	v_mfma_f32_16x16x32_bf16 v[8:11], v[88:91], v[112:115], v[8:11]
	v_mfma_f32_16x16x32_bf16 v[4:7], v[80:83], v[120:123], v[4:7]
	v_mfma_f32_16x16x32_bf16 v[0:3], v[88:91], v[120:123], v[0:3]
	v_mfma_f32_16x16x32_bf16 v[28:31], v[84:87], v[100:103], v[28:31]
	v_mfma_f32_16x16x32_bf16 v[24:27], v[92:95], v[100:103], v[24:27]
	v_mfma_f32_16x16x32_bf16 v[20:23], v[84:87], v[108:111], v[20:23]
	v_mfma_f32_16x16x32_bf16 v[16:19], v[92:95], v[108:111], v[16:19]
	v_mfma_f32_16x16x32_bf16 v[12:15], v[84:87], v[116:119], v[12:15]
	v_mfma_f32_16x16x32_bf16 v[8:11], v[92:95], v[116:119], v[8:11]
	v_mfma_f32_16x16x32_bf16 v[4:7], v[84:87], v[124:127], v[4:7]
	v_mfma_f32_16x16x32_bf16 v[0:3], v[92:95], v[124:127], v[0:3]
	s_barrier
; #define PG8_STAGE(bufoff, gbase, voff) do { _Pragma("unroll") for (int _i = 0; _i < 2; ++_i) \
;         __builtin_amdgcn_global_load_lds((const unsigned*)((const char*)(gbase) + (voff)[_i]), (LAS unsigned*)(lds + (bufoff) + ldsw + _i * 8192), 16, 0, 0); } while (0)
; #define PG8_LDA(dst, b, h) do { _Pragma("unroll") for (int m = 0; m < 4; ++m) _Pragma("unroll") for (int k = 0; k < 2; ++k) dst[m][k] = *(const LAS bf16x8*)(lds + PG8_SA(b, h) + aoff + m * 2048 + k * 1024); } while (0)
; #define PG8_LDB(dst, b, h) do { _Pragma("unroll") for (int n = 0; n < 2; ++n) _Pragma("unroll") for (int k = 0; k < 2; ++k) dst[n][k] = *(const LAS bf16x8*)(lds + PG8_SB(b, h) + boff + n * 2048 + k * 1024); } while (0)
; #define PG8_MMA(ai, bj, At, Bt) do { __builtin_amdgcn_s_setprio(1); _Pragma("unroll") for (int m = 0; m < 4; ++m) _Pragma("unroll") for (int n = 0; n < 2; ++n) _Pragma("unroll") for (int k = 0; k < 2; ++k) \
;         acc[ai][bj][m][n] = __builtin_amdgcn_mfma_f32_16x16x32_bf16(Bt[n][k], At[m][k], acc[ai][bj][m][n], 0, 0, 0); __builtin_amdgcn_s_setprio(0); } while (0)
; #define PG8_WAIT_V(n) asm volatile("s_waitcnt vmcnt(" #n ")" ::: "memory")
; #define PG8_WAIT_L(n) asm volatile("s_waitcnt lgkmcnt(" #n ")" ::: "memory")
; #define PG8_BAR __builtin_amdgcn_s_barrier()
; #define PG8_SCHED __builtin_amdgcn_sched_barrier(0)
; template <class Epi, class Sched>
; __device__ __forceinline__ void gemm_phase(const int tid, LAS unsigned char* lds, const int lda, const int ldb, const int K, const Sched& S, const Epi& E) {
;     ...
;             PG8_LDB(B0, 1, 0); PG8_LDB(B1, 1, 1); PG8_SCHED; PG8_LDA(At, 1, 0); PG8_STAGE(PG8_SA(0, 1), a2 + hstepA, voffA);
;             PG8_WAIT_V(8); PG8_WAIT_L(0); PG8_BAR; PG8_MMA(0, 0, At, B0); PG8_MMA(0, 1, At, B1); PG8_BAR; PG8_SCHED;
;             PG8_LDA(At, 1, 1); PG8_STAGE(PG8_SB(1, 0), b3, voffB); PG8_STAGE(PG8_SB(1, 1), b3 + hstepB, voffB); PG8_STAGE(PG8_SA(1, 0), a3, voffA);
;             PG8_WAIT_V(8); PG8_WAIT_L(0); PG8_BAR; if (!cur.half) { PG8_MMA(1, 0, At, B0); PG8_MMA(1, 1, At, B1); } PG8_BAR; PG8_SCHED;
;         }
;         if (wr == 0) PG8_BAR;
;         if (MK_EPI2 && Epi::IDEM) E(acc, cur, wr, wc, fr, fq, es0, es1);
;         E(acc, cur, wr, wc, fr, fq, es0, es1);
	s_add_i32 s14, 0, 0x18000
	v_add_u32_e32 v79, s14, v77
	ds_read_b128 v[80:83], v79
	ds_read_b128 v[84:87], v79 offset:1024
	ds_read_b128 v[88:91], v79 offset:2048
	ds_read_b128 v[92:95], v79 offset:3072
	s_add_u32 s64, s70, 0x28000
	s_addc_u32 s65, s71, 0
	s_mov_b32 m0, s42
	v_lshl_add_u64 v[138:139], s[64:65], 0, v[68:69]
	ds_read_b128 v[96:99], v78 offset:32768
	ds_read_b128 v[100:103], v78 offset:33792
	ds_read_b128 v[104:107], v78 offset:34816
	ds_read_b128 v[108:111], v78 offset:35840
	ds_read_b128 v[112:115], v78 offset:36864
	ds_read_b128 v[116:119], v78 offset:37888
	ds_read_b128 v[120:123], v78 offset:38912
	ds_read_b128 v[124:127], v78 offset:39936
	global_load_lds_dwordx4 v[138:139], off
	v_lshl_add_u64 v[138:139], s[64:65], 0, v[66:67]
	s_mov_b32 m0, s43
	s_nop 0
	global_load_lds_dwordx4 v[138:139], off
	s_waitcnt vmcnt(8)
	s_waitcnt lgkmcnt(0)
	s_barrier
	v_mfma_f32_16x16x32_bf16 v[60:63], v[80:83], v[96:99], v[60:63]
	v_mfma_f32_16x16x32_bf16 v[56:59], v[88:91], v[96:99], v[56:59]
	v_mfma_f32_16x16x32_bf16 v[52:55], v[80:83], v[104:107], v[52:55]
	v_mfma_f32_16x16x32_bf16 v[48:51], v[88:91], v[104:107], v[48:51]
	v_mfma_f32_16x16x32_bf16 v[44:47], v[80:83], v[112:115], v[44:47]
	v_mfma_f32_16x16x32_bf16 v[40:43], v[88:91], v[112:115], v[40:43]
	v_mfma_f32_16x16x32_bf16 v[36:39], v[80:83], v[120:123], v[36:39]
	v_mfma_f32_16x16x32_bf16 v[32:35], v[88:91], v[120:123], v[32:35]
	v_mfma_f32_16x16x32_bf16 v[60:63], v[84:87], v[100:103], v[60:63]
	v_mfma_f32_16x16x32_bf16 v[56:59], v[92:95], v[100:103], v[56:59]
	v_mfma_f32_16x16x32_bf16 v[52:55], v[84:87], v[108:111], v[52:55]
	v_mfma_f32_16x16x32_bf16 v[48:51], v[92:95], v[108:111], v[48:51]
	v_mfma_f32_16x16x32_bf16 v[44:47], v[84:87], v[116:119], v[44:47]
	v_mfma_f32_16x16x32_bf16 v[40:43], v[92:95], v[116:119], v[40:43]
	v_mfma_f32_16x16x32_bf16 v[36:39], v[84:87], v[124:127], v[36:39]
	v_mfma_f32_16x16x32_bf16 v[32:35], v[92:95], v[124:127], v[32:35]
	s_barrier
	s_add_i32 s14, s14, s13
	v_lshl_add_u64 v[128:129], v[128:129], 0, s[6:7]
	s_mov_b32 m0, s14
	ds_read_b128 v[96:99], v78 offset:49152
	ds_read_b128 v[100:103], v78 offset:50176
	ds_read_b128 v[104:107], v78 offset:51200
	ds_read_b128 v[108:111], v78 offset:52224
	ds_read_b128 v[112:115], v78 offset:53248
	ds_read_b128 v[116:119], v78 offset:54272
	ds_read_b128 v[120:123], v78 offset:55296
	ds_read_b128 v[124:127], v78 offset:56320
	global_load_lds_dwordx4 v[128:129], off
	s_add_i32 m0, s14, 0x2000
	s_add_u32 s64, s68, 0x20080
	v_lshl_add_u64 v[128:129], v[130:131], 0, s[6:7]
	s_addc_u32 s65, s69, 0
	global_load_lds_dwordx4 v[128:129], off
	v_lshl_add_u64 v[128:129], s[64:65], 0, v[168:169]
	s_mov_b32 m0, s74
	s_nop 0
	global_load_lds_dwordx4 v[128:129], off
	v_lshl_add_u64 v[128:129], s[64:65], 0, v[64:65]
	s_mov_b32 m0, s75
	s_nop 0
	global_load_lds_dwordx4 v[128:129], off
	v_lshl_add_u64 v[128:129], v[132:133], 0, s[6:7]
	s_mov_b32 m0, s72
	s_nop 0
	global_load_lds_dwordx4 v[128:129], off
	v_lshl_add_u64 v[128:129], v[134:135], 0, s[6:7]
	s_mov_b32 m0, s73
	s_nop 0
	global_load_lds_dwordx4 v[128:129], off
	s_waitcnt vmcnt(8)
	s_waitcnt lgkmcnt(0)
	s_barrier
	v_mfma_f32_16x16x32_bf16 v[28:31], v[80:83], v[96:99], v[28:31]
	v_mfma_f32_16x16x32_bf16 v[24:27], v[88:91], v[96:99], v[24:27]
	v_mfma_f32_16x16x32_bf16 v[20:23], v[80:83], v[104:107], v[20:23]
	v_mfma_f32_16x16x32_bf16 v[16:19], v[88:91], v[104:107], v[16:19]
	v_mfma_f32_16x16x32_bf16 v[12:15], v[80:83], v[112:115], v[12:15]
	v_mfma_f32_16x16x32_bf16 v[8:11], v[88:91], v[112:115], v[8:11]
	v_mfma_f32_16x16x32_bf16 v[4:7], v[80:83], v[120:123], v[4:7]
	v_mfma_f32_16x16x32_bf16 v[0:3], v[88:91], v[120:123], v[0:3]
	v_mfma_f32_16x16x32_bf16 v[28:31], v[84:87], v[100:103], v[28:31]
	v_mfma_f32_16x16x32_bf16 v[24:27], v[92:95], v[100:103], v[24:27]
	v_mfma_f32_16x16x32_bf16 v[20:23], v[84:87], v[108:111], v[20:23]
	v_mfma_f32_16x16x32_bf16 v[16:19], v[92:95], v[108:111], v[16:19]
	v_mfma_f32_16x16x32_bf16 v[12:15], v[84:87], v[116:119], v[12:15]
	v_mfma_f32_16x16x32_bf16 v[8:11], v[92:95], v[116:119], v[8:11]
	v_mfma_f32_16x16x32_bf16 v[4:7], v[84:87], v[124:127], v[4:7]
	v_mfma_f32_16x16x32_bf16 v[0:3], v[92:95], v[124:127], v[0:3]
	s_barrier
	s_add_u32 s39, s39, 0x100
	s_addc_u32 s53, s53, 0
	s_cmp_ge_i32 s24, s22
	s_mov_b64 s[64:65], s[66:67]
	s_mov_b32 s68, s24
	s_cbranch_scc0 .LBB0_816
	s_load_dword s70, s[0:1], 0x108
	v_readlane_b32 s68, v255, 13
	v_readlane_b32 s69, v255, 14
	s_movk_i32 s71, 0x1600
	s_branch .LBB0_819

; #define PG8_STAGE(bufoff, gbase, voff) do { _Pragma("unroll") for (int _i = 0; _i < 2; ++_i) \
;         __builtin_amdgcn_global_load_lds((const unsigned*)((const char*)(gbase) + (voff)[_i]), (LAS unsigned*)(lds + (bufoff) + ldsw + _i * 8192), 16, 0, 0); } while (0)
; #define PG8_LDA(dst, b, h) do { _Pragma("unroll") for (int m = 0; m < 4; ++m) _Pragma("unroll") for (int k = 0; k < 2; ++k) dst[m][k] = *(const LAS bf16x8*)(lds + PG8_SA(b, h) + aoff + m * 2048 + k * 1024); } while (0)
; #define PG8_LDB(dst, b, h) do { _Pragma("unroll") for (int n = 0; n < 2; ++n) _Pragma("unroll") for (int k = 0; k < 2; ++k) dst[n][k] = *(const LAS bf16x8*)(lds + PG8_SB(b, h) + boff + n * 2048 + k * 1024); } while (0)
; #define PG8_MMA(ai, bj, At, Bt) do { __builtin_amdgcn_s_setprio(1); _Pragma("unroll") for (int m = 0; m < 4; ++m) _Pragma("unroll") for (int n = 0; n < 2; ++n) _Pragma("unroll") for (int k = 0; k < 2; ++k) \
;         acc[ai][bj][m][n] = __builtin_amdgcn_mfma_f32_16x16x32_bf16(Bt[n][k], At[m][k], acc[ai][bj][m][n], 0, 0, 0); __builtin_amdgcn_s_setprio(0); } while (0)
; #define PG8_WAIT_V(n) asm volatile("s_waitcnt vmcnt(" #n ")" ::: "memory")
; template <class Epi, class Sched>
; __device__ __forceinline__ void gemm_phase(const int tid, LAS unsigned char* lds, const int lda, const int ldb, const int K, const Sched& S, const Epi& E) {
;     ...
;         const bool has_next = S.next(ui + 1, nxt);
;         const char* nA = has_next ? nxt.a : cA; const char* nB = has_next ? nxt.b : cB;
;         for (int t = 0; t < nt; t += 2) {
;             const bool last = (t == nt - 2);
;             const char* a1 = cA + (size_t)(t + 1) * kstep;
;             const char* a2 = last ? nA : cA + (size_t)(t + 2) * kstep; const char* b2 = last ? nB : cB + (size_t)(t + 2) * kstep;
;             const char* a3 = a2 + kstep; const char* b3 = b2 + kstep;
;             PG8_LDB(B0, 0, 0); PG8_LDB(B1, 0, 1); PG8_SCHED; PG8_LDA(At, 0, 0); PG8_STAGE(PG8_SA(1, 1), a1 + hstepA, voffA);
;             PG8_WAIT_V(8); PG8_WAIT_L(0); PG8_BAR; PG8_MMA(0, 0, At, B0); PG8_MMA(0, 1, At, B1); PG8_BAR; PG8_SCHED;
;             PG8_LDA(At, 0, 1); PG8_STAGE(PG8_SB(0, 0), b2, voffB); PG8_STAGE(PG8_SB(0, 1), b2 + hstepB, voffB); PG8_STAGE(PG8_SA(0, 0), a2, voffA);
;             PG8_WAIT_V(8); PG8_WAIT_L(0); PG8_BAR; if (!cur.half) { PG8_MMA(1, 0, At, B0); PG8_MMA(1, 1, At, B1); } PG8_BAR; PG8_SCHED;
.LBB0_872:
	s_andn2_b64 vcc, exec, s[40:41]
	s_cbranch_vccnz .LBB0_880
	s_add_u32 s50, s50, 0x40080
	s_addc_u32 s51, s51, 0
	s_add_u32 s45, s52, 0x100
	s_addc_u32 s63, s53, 0
	s_mov_b32 s52, 0
	s_add_i32 s64, s52, 2
	s_add_u32 s14, s50, 0xfffc0080
	s_addc_u32 s15, s51, -1
	s_add_i32 s24, 0, 0x10000
	s_cmp_eq_u32 s60, s52
	s_cselect_b32 s55, s3, s15
	s_cselect_b32 s54, s2, s14
	v_add_u32_e32 v141, s24, v148
	s_cselect_b32 s53, s39, s63
	s_cselect_b32 s52, s38, s45
	s_add_i32 s14, 0, 0x14000
	ds_read_b128 v[158:161], v141
	ds_read_b128 v[162:165], v141 offset:1024
	ds_read_b128 v[180:183], v141 offset:2048
	ds_read_b128 v[184:187], v141 offset:3072
	v_add_u32_e32 v141, s14, v148
	ds_read_b128 v[190:193], v141
	ds_read_b128 v[194:197], v141 offset:1024
	ds_read_b128 v[204:207], v141 offset:2048
	ds_read_b128 v[208:211], v141 offset:3072
	v_lshl_add_u64 v[166:167], s[50:51], 0, v[136:137]
	s_add_i32 m0, s21, 0xc000
	ds_read_b128 v[212:215], v155
	ds_read_b128 v[216:219], v155 offset:1024
	ds_read_b128 v[220:223], v155 offset:2048
	ds_read_b128 v[224:227], v155 offset:3072
	ds_read_b128 v[228:231], v155 offset:4096
	ds_read_b128 v[232:235], v155 offset:5120
	ds_read_b128 v[236:239], v155 offset:6144
	ds_read_b128 v[240:243], v155 offset:7168
	global_load_lds_dwordx4 v[166:167], off
	v_lshl_add_u64 v[166:167], s[50:51], 0, v[138:139]
	s_add_i32 m0, s21, 0xe000
	s_nop 0
	global_load_lds_dwordx4 v[166:167], off
	s_waitcnt vmcnt(8)
	s_waitcnt lgkmcnt(0)
	s_barrier
	v_mfma_f32_16x16x32_bf16 v[124:127], v[158:161], v[212:215], 0
	v_mfma_f32_16x16x32_bf16 v[120:123], v[180:183], v[212:215], 0
	v_mfma_f32_16x16x32_bf16 v[108:111], v[158:161], v[220:223], 0
	v_mfma_f32_16x16x32_bf16 v[104:107], v[180:183], v[220:223], 0
	v_mfma_f32_16x16x32_bf16 v[92:95], v[158:161], v[228:231], 0
	v_mfma_f32_16x16x32_bf16 v[88:91], v[180:183], v[228:231], 0
	v_mfma_f32_16x16x32_bf16 v[76:79], v[158:161], v[236:239], 0
	v_mfma_f32_16x16x32_bf16 v[72:75], v[180:183], v[236:239], 0
	v_mfma_f32_16x16x32_bf16 v[124:127], v[162:165], v[216:219], v[124:127]
	v_mfma_f32_16x16x32_bf16 v[120:123], v[184:187], v[216:219], v[120:123]
	v_mfma_f32_16x16x32_bf16 v[108:111], v[162:165], v[224:227], v[108:111]
	v_mfma_f32_16x16x32_bf16 v[104:107], v[184:187], v[224:227], v[104:107]
	v_mfma_f32_16x16x32_bf16 v[92:95], v[162:165], v[232:235], v[92:95]
	v_mfma_f32_16x16x32_bf16 v[88:91], v[184:187], v[232:235], v[88:91]
	v_mfma_f32_16x16x32_bf16 v[76:79], v[162:165], v[240:243], v[76:79]
	v_mfma_f32_16x16x32_bf16 v[72:75], v[184:187], v[240:243], v[72:75]
	v_mfma_f32_16x16x32_bf16 v[116:119], v[190:193], v[212:215], 0
	v_mfma_f32_16x16x32_bf16 v[112:115], v[204:207], v[212:215], 0
	v_mfma_f32_16x16x32_bf16 v[100:103], v[190:193], v[220:223], 0
	v_mfma_f32_16x16x32_bf16 v[96:99], v[204:207], v[220:223], 0
	v_mfma_f32_16x16x32_bf16 v[84:87], v[190:193], v[228:231], 0
	v_mfma_f32_16x16x32_bf16 v[80:83], v[204:207], v[228:231], 0
	v_mfma_f32_16x16x32_bf16 v[68:71], v[190:193], v[236:239], 0
	v_mfma_f32_16x16x32_bf16 v[64:67], v[204:207], v[236:239], 0
	v_mfma_f32_16x16x32_bf16 v[116:119], v[194:197], v[216:219], v[116:119]
	v_mfma_f32_16x16x32_bf16 v[112:115], v[208:211], v[216:219], v[112:115]
	v_mfma_f32_16x16x32_bf16 v[100:103], v[194:197], v[224:227], v[100:103]
	v_mfma_f32_16x16x32_bf16 v[96:99], v[208:211], v[224:227], v[96:99]
	v_mfma_f32_16x16x32_bf16 v[84:87], v[194:197], v[232:235], v[84:87]
	v_mfma_f32_16x16x32_bf16 v[80:83], v[208:211], v[232:235], v[80:83]
	v_mfma_f32_16x16x32_bf16 v[68:71], v[194:197], v[240:243], v[68:71]
	v_mfma_f32_16x16x32_bf16 v[64:67], v[208:211], v[240:243], v[64:67]
	s_barrier
	s_add_i32 s15, s24, s20
	v_lshl_add_u64 v[166:167], s[52:53], 0, v[130:131]
	s_mov_b32 m0, s15
	ds_read_b128 v[212:215], v155 offset:16384
	ds_read_b128 v[216:219], v155 offset:17408
	ds_read_b128 v[220:223], v155 offset:18432
	ds_read_b128 v[224:227], v155 offset:19456
	ds_read_b128 v[228:231], v155 offset:20480
	ds_read_b128 v[232:235], v155 offset:21504
	ds_read_b128 v[236:239], v155 offset:22528
	ds_read_b128 v[240:243], v155 offset:23552
	global_load_lds_dwordx4 v[166:167], off
	s_add_i32 m0, s15, 0x2000
	s_add_u32 s66, s52, 0x40000
	v_lshl_add_u64 v[244:245], s[52:53], 0, v[134:135]
	s_addc_u32 s67, s53, 0
	s_add_i32 s14, s14, s20
	global_load_lds_dwordx4 v[244:245], off
	v_lshl_add_u64 v[246:247], s[66:67], 0, v[130:131]
	s_mov_b32 m0, s14
	v_lshl_add_u64 v[248:249], s[54:55], 0, v[132:133]
	global_load_lds_dwordx4 v[246:247], off
	v_lshl_add_u64 v[246:247], s[66:67], 0, v[134:135]
	s_add_i32 m0, s14, 0x2000
	s_nop 0
	global_load_lds_dwordx4 v[246:247], off
	v_lshl_add_u64 v[246:247], s[54:55], 0, v[128:129]
	s_mov_b32 m0, s21
	s_nop 0
	global_load_lds_dwordx4 v[246:247], off
	s_mov_b32 m0, s29
	s_nop 0
	global_load_lds_dwordx4 v[248:249], off
	s_waitcnt vmcnt(8)
	s_waitcnt lgkmcnt(0)
	s_barrier
; #define PG8_STAGE(bufoff, gbase, voff) do { _Pragma("unroll") for (int _i = 0; _i < 2; ++_i) \
;         __builtin_amdgcn_global_load_lds((const unsigned*)((const char*)(gbase) + (voff)[_i]), (LAS unsigned*)(lds + (bufoff) + ldsw + _i * 8192), 16, 0, 0); } while (0)
; #define PG8_LDA(dst, b, h) do { _Pragma("unroll") for (int m = 0; m < 4; ++m) _Pragma("unroll") for (int k = 0; k < 2; ++k) dst[m][k] = *(const LAS bf16x8*)(lds + PG8_SA(b, h) + aoff + m * 2048 + k * 1024); } while (0)
; #define PG8_LDB(dst, b, h) do { _Pragma("unroll") for (int n = 0; n < 2; ++n) _Pragma("unroll") for (int k = 0; k < 2; ++k) dst[n][k] = *(const LAS bf16x8*)(lds + PG8_SB(b, h) + boff + n * 2048 + k * 1024); } while (0)
; #define PG8_MMA(ai, bj, At, Bt) do { __builtin_amdgcn_s_setprio(1); _Pragma("unroll") for (int m = 0; m < 4; ++m) _Pragma("unroll") for (int n = 0; n < 2; ++n) _Pragma("unroll") for (int k = 0; k < 2; ++k) \
;         acc[ai][bj][m][n] = __builtin_amdgcn_mfma_f32_16x16x32_bf16(Bt[n][k], At[m][k], acc[ai][bj][m][n], 0, 0, 0); __builtin_amdgcn_s_setprio(0); } while (0)
; #define PG8_WAIT_V(n) asm volatile("s_waitcnt vmcnt(" #n ")" ::: "memory")
; #define PG8_WAIT_L(n) asm volatile("s_waitcnt lgkmcnt(" #n ")" ::: "memory")
; #define PG8_BAR __builtin_amdgcn_s_barrier()
; #define PG8_SCHED __builtin_amdgcn_sched_barrier(0)
; template <class Epi, class Sched>
; __device__ __forceinline__ void gemm_phase(const int tid, LAS unsigned char* lds, const int lda, const int ldb, const int K, const Sched& S, const Epi& E) {
;     ...
;             PG8_WAIT_V(8); PG8_WAIT_L(0); PG8_BAR; if (!cur.half) { PG8_MMA(1, 0, At, B0); PG8_MMA(1, 1, At, B1); } PG8_BAR; PG8_SCHED;
;             PG8_LDB(B0, 1, 0); PG8_LDB(B1, 1, 1); PG8_SCHED; PG8_LDA(At, 1, 0); PG8_STAGE(PG8_SA(0, 1), a2 + hstepA, voffA);
;             PG8_WAIT_V(8); PG8_WAIT_L(0); PG8_BAR; PG8_MMA(0, 0, At, B0); PG8_MMA(0, 1, At, B1); PG8_BAR; PG8_SCHED;
	v_mfma_f32_16x16x32_bf16 v[60:63], v[158:161], v[212:215], 0
	v_mfma_f32_16x16x32_bf16 v[56:59], v[180:183], v[212:215], 0
	v_mfma_f32_16x16x32_bf16 v[44:47], v[158:161], v[220:223], 0
	v_mfma_f32_16x16x32_bf16 v[40:43], v[180:183], v[220:223], 0
	v_mfma_f32_16x16x32_bf16 v[28:31], v[158:161], v[228:231], 0
	v_mfma_f32_16x16x32_bf16 v[24:27], v[180:183], v[228:231], 0
	v_mfma_f32_16x16x32_bf16 v[12:15], v[158:161], v[236:239], 0
	v_mfma_f32_16x16x32_bf16 v[8:11], v[180:183], v[236:239], 0
	v_mfma_f32_16x16x32_bf16 v[60:63], v[162:165], v[216:219], v[60:63]
	v_mfma_f32_16x16x32_bf16 v[56:59], v[184:187], v[216:219], v[56:59]
	v_mfma_f32_16x16x32_bf16 v[44:47], v[162:165], v[224:227], v[44:47]
	v_mfma_f32_16x16x32_bf16 v[40:43], v[184:187], v[224:227], v[40:43]
	v_mfma_f32_16x16x32_bf16 v[28:31], v[162:165], v[232:235], v[28:31]
	v_mfma_f32_16x16x32_bf16 v[24:27], v[184:187], v[232:235], v[24:27]
	v_mfma_f32_16x16x32_bf16 v[12:15], v[162:165], v[240:243], v[12:15]
	v_mfma_f32_16x16x32_bf16 v[8:11], v[184:187], v[240:243], v[8:11]
	v_mfma_f32_16x16x32_bf16 v[52:55], v[190:193], v[212:215], 0
	v_mfma_f32_16x16x32_bf16 v[48:51], v[204:207], v[212:215], 0
	v_mfma_f32_16x16x32_bf16 v[36:39], v[190:193], v[220:223], 0
	v_mfma_f32_16x16x32_bf16 v[32:35], v[204:207], v[220:223], 0
	v_mfma_f32_16x16x32_bf16 v[20:23], v[190:193], v[228:231], 0
	v_mfma_f32_16x16x32_bf16 v[16:19], v[204:207], v[228:231], 0
	v_mfma_f32_16x16x32_bf16 v[4:7], v[190:193], v[236:239], 0
	v_mfma_f32_16x16x32_bf16 v[0:3], v[204:207], v[236:239], 0
	v_mfma_f32_16x16x32_bf16 v[52:55], v[194:197], v[216:219], v[52:55]
	v_mfma_f32_16x16x32_bf16 v[48:51], v[208:211], v[216:219], v[48:51]
	v_mfma_f32_16x16x32_bf16 v[36:39], v[194:197], v[224:227], v[36:39]
	v_mfma_f32_16x16x32_bf16 v[32:35], v[208:211], v[224:227], v[32:35]
	v_mfma_f32_16x16x32_bf16 v[20:23], v[194:197], v[232:235], v[20:23]
	v_mfma_f32_16x16x32_bf16 v[16:19], v[208:211], v[232:235], v[16:19]
	v_mfma_f32_16x16x32_bf16 v[4:7], v[194:197], v[240:243], v[4:7]
	v_mfma_f32_16x16x32_bf16 v[0:3], v[208:211], v[240:243], v[0:3]
	s_barrier
	s_add_i32 s14, 0, 0x18000
	v_add_u32_e32 v141, s14, v148
	s_add_i32 s15, 0, 0x1c000
	ds_read_b128 v[158:161], v141
	ds_read_b128 v[162:165], v141 offset:1024
	ds_read_b128 v[180:183], v141 offset:2048
	ds_read_b128 v[184:187], v141 offset:3072
	v_add_u32_e32 v141, s15, v148
	ds_read_b128 v[190:193], v141
	ds_read_b128 v[194:197], v141 offset:1024
	ds_read_b128 v[204:207], v141 offset:2048
	ds_read_b128 v[208:211], v141 offset:3072
	s_add_u32 s54, s54, 0x40000
	s_addc_u32 s55, s55, 0
	s_mov_b32 m0, s31
	v_lshl_add_u64 v[250:251], s[54:55], 0, v[128:129]
	ds_read_b128 v[212:215], v155 offset:32768
	ds_read_b128 v[216:219], v155 offset:33792
	ds_read_b128 v[220:223], v155 offset:34816
	ds_read_b128 v[224:227], v155 offset:35840
	ds_read_b128 v[228:231], v155 offset:36864
	ds_read_b128 v[232:235], v155 offset:37888
	ds_read_b128 v[236:239], v155 offset:38912
	ds_read_b128 v[240:243], v155 offset:39936
	global_load_lds_dwordx4 v[250:251], off
	v_lshl_add_u64 v[250:251], s[54:55], 0, v[132:133]
	s_mov_b32 m0, s56
	s_nop 0
	global_load_lds_dwordx4 v[250:251], off
	s_waitcnt vmcnt(8)
	s_waitcnt lgkmcnt(0)
	s_barrier
	v_mfma_f32_16x16x32_bf16 v[124:127], v[158:161], v[212:215], v[124:127]
	v_mfma_f32_16x16x32_bf16 v[120:123], v[180:183], v[212:215], v[120:123]
	v_mfma_f32_16x16x32_bf16 v[108:111], v[158:161], v[220:223], v[108:111]
	v_mfma_f32_16x16x32_bf16 v[104:107], v[180:183], v[220:223], v[104:107]
	v_mfma_f32_16x16x32_bf16 v[92:95], v[158:161], v[228:231], v[92:95]
	v_mfma_f32_16x16x32_bf16 v[88:91], v[180:183], v[228:231], v[88:91]
	v_mfma_f32_16x16x32_bf16 v[76:79], v[158:161], v[236:239], v[76:79]
	v_mfma_f32_16x16x32_bf16 v[72:75], v[180:183], v[236:239], v[72:75]
	v_mfma_f32_16x16x32_bf16 v[124:127], v[162:165], v[216:219], v[124:127]
	v_mfma_f32_16x16x32_bf16 v[120:123], v[184:187], v[216:219], v[120:123]
	v_mfma_f32_16x16x32_bf16 v[108:111], v[162:165], v[224:227], v[108:111]
	v_mfma_f32_16x16x32_bf16 v[104:107], v[184:187], v[224:227], v[104:107]
	v_mfma_f32_16x16x32_bf16 v[92:95], v[162:165], v[232:235], v[92:95]
	v_mfma_f32_16x16x32_bf16 v[88:91], v[184:187], v[232:235], v[88:91]
	v_mfma_f32_16x16x32_bf16 v[76:79], v[162:165], v[240:243], v[76:79]
	v_mfma_f32_16x16x32_bf16 v[72:75], v[184:187], v[240:243], v[72:75]
	v_mfma_f32_16x16x32_bf16 v[116:119], v[190:193], v[212:215], v[116:119]
	v_mfma_f32_16x16x32_bf16 v[112:115], v[204:207], v[212:215], v[112:115]
	v_mfma_f32_16x16x32_bf16 v[100:103], v[190:193], v[220:223], v[100:103]
	v_mfma_f32_16x16x32_bf16 v[96:99], v[204:207], v[220:223], v[96:99]
	v_mfma_f32_16x16x32_bf16 v[84:87], v[190:193], v[228:231], v[84:87]
	v_mfma_f32_16x16x32_bf16 v[80:83], v[204:207], v[228:231], v[80:83]
	v_mfma_f32_16x16x32_bf16 v[68:71], v[190:193], v[236:239], v[68:71]
	v_mfma_f32_16x16x32_bf16 v[64:67], v[204:207], v[236:239], v[64:67]
	v_mfma_f32_16x16x32_bf16 v[116:119], v[194:197], v[216:219], v[116:119]
	v_mfma_f32_16x16x32_bf16 v[112:115], v[208:211], v[216:219], v[112:115]
	v_mfma_f32_16x16x32_bf16 v[100:103], v[194:197], v[224:227], v[100:103]
	v_mfma_f32_16x16x32_bf16 v[96:99], v[208:211], v[224:227], v[96:99]
	v_mfma_f32_16x16x32_bf16 v[84:87], v[194:197], v[232:235], v[84:87]
	v_mfma_f32_16x16x32_bf16 v[80:83], v[208:211], v[232:235], v[80:83]
	v_mfma_f32_16x16x32_bf16 v[68:71], v[194:197], v[240:243], v[68:71]
	v_mfma_f32_16x16x32_bf16 v[64:67], v[208:211], v[240:243], v[64:67]
	s_barrier
; #define PG8_STAGE(bufoff, gbase, voff) do { _Pragma("unroll") for (int _i = 0; _i < 2; ++_i) \
;         __builtin_amdgcn_global_load_lds((const unsigned*)((const char*)(gbase) + (voff)[_i]), (LAS unsigned*)(lds + (bufoff) + ldsw + _i * 8192), 16, 0, 0); } while (0)
; #define PG8_LDA(dst, b, h) do { _Pragma("unroll") for (int m = 0; m < 4; ++m) _Pragma("unroll") for (int k = 0; k < 2; ++k) dst[m][k] = *(const LAS bf16x8*)(lds + PG8_SA(b, h) + aoff + m * 2048 + k * 1024); } while (0)
; #define PG8_LDB(dst, b, h) do { _Pragma("unroll") for (int n = 0; n < 2; ++n) _Pragma("unroll") for (int k = 0; k < 2; ++k) dst[n][k] = *(const LAS bf16x8*)(lds + PG8_SB(b, h) + boff + n * 2048 + k * 1024); } while (0)
; #define PG8_BAR __builtin_amdgcn_s_barrier()
; template <class Epi, class Sched>
; __device__ __forceinline__ void gemm_phase(const int tid, LAS unsigned char* lds, const int lda, const int ldb, const int K, const Sched& S, const Epi& E) {
;     ...
;         for (int t = 0; t < nt; t += 2) {
;             const bool last = (t == nt - 2);
;             const char* a1 = cA + (size_t)(t + 1) * kstep;
;             const char* a2 = last ? nA : cA + (size_t)(t + 2) * kstep; const char* b2 = last ? nB : cB + (size_t)(t + 2) * kstep;
;             const char* a3 = a2 + kstep; const char* b3 = b2 + kstep;
;             PG8_LDB(B0, 0, 0); PG8_LDB(B1, 0, 1); PG8_SCHED; PG8_LDA(At, 0, 0); PG8_STAGE(PG8_SA(1, 1), a1 + hstepA, voffA);
;             PG8_WAIT_V(8); PG8_WAIT_L(0); PG8_BAR; PG8_MMA(0, 0, At, B0); PG8_MMA(0, 1, At, B1); PG8_BAR; PG8_SCHED;
;             PG8_LDA(At, 0, 1); PG8_STAGE(PG8_SB(0, 0), b2, voffB); PG8_STAGE(PG8_SB(0, 1), b2 + hstepB, voffB); PG8_STAGE(PG8_SA(0, 0), a2, voffA);
;             PG8_WAIT_V(8); PG8_WAIT_L(0); PG8_BAR; if (!cur.half) { PG8_MMA(1, 0, At, B0); PG8_MMA(1, 1, At, B1); } PG8_BAR; PG8_SCHED;
;             PG8_LDB(B0, 1, 0); PG8_LDB(B1, 1, 1); PG8_SCHED; PG8_LDA(At, 1, 0); PG8_STAGE(PG8_SA(0, 1), a2 + hstepA, voffA);
;             PG8_WAIT_V(8); PG8_WAIT_L(0); PG8_BAR; PG8_MMA(0, 0, At, B0); PG8_MMA(0, 1, At, B1); PG8_BAR; PG8_SCHED;
;             PG8_LDA(At, 1, 1); PG8_STAGE(PG8_SB(1, 0), b3, voffB); PG8_STAGE(PG8_SB(1, 1), b3 + hstepB, voffB); PG8_STAGE(PG8_SA(1, 0), a3, voffA);
;             PG8_WAIT_V(8); PG8_WAIT_L(0); PG8_BAR; if (!cur.half) { PG8_MMA(1, 0, At, B0); PG8_MMA(1, 1, At, B1); } PG8_BAR; PG8_SCHED;
;         }
	s_add_i32 s14, s14, s20
	v_lshl_add_u64 v[166:167], v[166:167], 0, s[6:7]
	s_mov_b32 m0, s14
	ds_read_b128 v[212:215], v155 offset:49152
	ds_read_b128 v[216:219], v155 offset:50176
	ds_read_b128 v[220:223], v155 offset:51200
	ds_read_b128 v[224:227], v155 offset:52224
	ds_read_b128 v[228:231], v155 offset:53248
	ds_read_b128 v[232:235], v155 offset:54272
	ds_read_b128 v[236:239], v155 offset:55296
	ds_read_b128 v[240:243], v155 offset:56320
	global_load_lds_dwordx4 v[166:167], off
	s_add_i32 m0, s14, 0x2000
	s_add_u32 s52, s52, 0x40080
	v_lshl_add_u64 v[166:167], v[244:245], 0, s[6:7]
	s_addc_u32 s53, s53, 0
	s_add_i32 s14, s15, s20
	global_load_lds_dwordx4 v[166:167], off
	v_lshl_add_u64 v[166:167], s[52:53], 0, v[130:131]
	s_mov_b32 m0, s14
	s_nop 0
	global_load_lds_dwordx4 v[166:167], off
	v_lshl_add_u64 v[166:167], s[52:53], 0, v[134:135]
	s_add_i32 m0, s14, 0x2000
	s_nop 0
	global_load_lds_dwordx4 v[166:167], off
	v_lshl_add_u64 v[166:167], v[246:247], 0, s[6:7]
	s_mov_b32 m0, s57
	s_nop 0
	global_load_lds_dwordx4 v[166:167], off
	v_lshl_add_u64 v[166:167], v[248:249], 0, s[6:7]
	s_mov_b32 m0, s58
	s_nop 0
	global_load_lds_dwordx4 v[166:167], off
	s_waitcnt vmcnt(8)
	s_waitcnt lgkmcnt(0)
	s_barrier
	v_mfma_f32_16x16x32_bf16 v[60:63], v[158:161], v[212:215], v[60:63]
	v_mfma_f32_16x16x32_bf16 v[56:59], v[180:183], v[212:215], v[56:59]
	v_mfma_f32_16x16x32_bf16 v[44:47], v[158:161], v[220:223], v[44:47]
	v_mfma_f32_16x16x32_bf16 v[40:43], v[180:183], v[220:223], v[40:43]
	v_mfma_f32_16x16x32_bf16 v[28:31], v[158:161], v[228:231], v[28:31]
	v_mfma_f32_16x16x32_bf16 v[24:27], v[180:183], v[228:231], v[24:27]
	v_mfma_f32_16x16x32_bf16 v[12:15], v[158:161], v[236:239], v[12:15]
	v_mfma_f32_16x16x32_bf16 v[8:11], v[180:183], v[236:239], v[8:11]
	v_mfma_f32_16x16x32_bf16 v[60:63], v[162:165], v[216:219], v[60:63]
	v_mfma_f32_16x16x32_bf16 v[56:59], v[184:187], v[216:219], v[56:59]
	v_mfma_f32_16x16x32_bf16 v[44:47], v[162:165], v[224:227], v[44:47]
	v_mfma_f32_16x16x32_bf16 v[40:43], v[184:187], v[224:227], v[40:43]
	v_mfma_f32_16x16x32_bf16 v[28:31], v[162:165], v[232:235], v[28:31]
	v_mfma_f32_16x16x32_bf16 v[24:27], v[184:187], v[232:235], v[24:27]
	v_mfma_f32_16x16x32_bf16 v[12:15], v[162:165], v[240:243], v[12:15]
	v_mfma_f32_16x16x32_bf16 v[8:11], v[184:187], v[240:243], v[8:11]
	v_mfma_f32_16x16x32_bf16 v[52:55], v[190:193], v[212:215], v[52:55]
	v_mfma_f32_16x16x32_bf16 v[48:51], v[204:207], v[212:215], v[48:51]
	v_mfma_f32_16x16x32_bf16 v[36:39], v[190:193], v[220:223], v[36:39]
	v_mfma_f32_16x16x32_bf16 v[32:35], v[204:207], v[220:223], v[32:35]
	v_mfma_f32_16x16x32_bf16 v[20:23], v[190:193], v[228:231], v[20:23]
	v_mfma_f32_16x16x32_bf16 v[16:19], v[204:207], v[228:231], v[16:19]
	v_mfma_f32_16x16x32_bf16 v[4:7], v[190:193], v[236:239], v[4:7]
	v_mfma_f32_16x16x32_bf16 v[0:3], v[204:207], v[236:239], v[0:3]
	v_mfma_f32_16x16x32_bf16 v[52:55], v[194:197], v[216:219], v[52:55]
	v_mfma_f32_16x16x32_bf16 v[48:51], v[208:211], v[216:219], v[48:51]
	v_mfma_f32_16x16x32_bf16 v[36:39], v[194:197], v[224:227], v[36:39]
	v_mfma_f32_16x16x32_bf16 v[32:35], v[208:211], v[224:227], v[32:35]
	v_mfma_f32_16x16x32_bf16 v[20:23], v[194:197], v[232:235], v[20:23]
	v_mfma_f32_16x16x32_bf16 v[16:19], v[208:211], v[232:235], v[16:19]
	v_mfma_f32_16x16x32_bf16 v[4:7], v[194:197], v[240:243], v[4:7]
	v_mfma_f32_16x16x32_bf16 v[0:3], v[208:211], v[240:243], v[0:3]
	s_barrier
	s_add_u32 s50, s50, 0x100
	s_addc_u32 s51, s51, 0
	s_add_u32 s45, s45, 0x100
	s_addc_u32 s63, s63, 0
	s_cmp_ge_i32 s64, s4
	s_mov_b32 s52, s64
	s_cbranch_scc1 .Lkexit_874
.LBB0_874:
	s_add_i32 s64, s52, 2
	s_add_u32 s14, s50, 0xfffc0080
	s_addc_u32 s15, s51, -1
	s_add_i32 s24, 0, 0x10000
	s_cmp_eq_u32 s60, s52
	s_cselect_b32 s55, s3, s15
	s_cselect_b32 s54, s2, s14
	v_add_u32_e32 v141, s24, v148
	s_cselect_b32 s53, s39, s63
	s_cselect_b32 s52, s38, s45
	s_add_i32 s14, 0, 0x14000
	ds_read_b128 v[158:161], v141
	ds_read_b128 v[162:165], v141 offset:1024
	ds_read_b128 v[180:183], v141 offset:2048
	ds_read_b128 v[184:187], v141 offset:3072
	v_add_u32_e32 v141, s14, v148
	ds_read_b128 v[190:193], v141
	ds_read_b128 v[194:197], v141 offset:1024
	ds_read_b128 v[204:207], v141 offset:2048
	ds_read_b128 v[208:211], v141 offset:3072
	v_lshl_add_u64 v[166:167], s[50:51], 0, v[136:137]
	s_add_i32 m0, s21, 0xc000
	ds_read_b128 v[212:215], v155
	ds_read_b128 v[216:219], v155 offset:1024
	ds_read_b128 v[220:223], v155 offset:2048
	ds_read_b128 v[224:227], v155 offset:3072
	ds_read_b128 v[228:231], v155 offset:4096
	ds_read_b128 v[232:235], v155 offset:5120
	ds_read_b128 v[236:239], v155 offset:6144
	ds_read_b128 v[240:243], v155 offset:7168
	global_load_lds_dwordx4 v[166:167], off
	v_lshl_add_u64 v[166:167], s[50:51], 0, v[138:139]
	s_add_i32 m0, s21, 0xe000
	s_nop 0
	global_load_lds_dwordx4 v[166:167], off
	s_waitcnt vmcnt(8)
	s_waitcnt lgkmcnt(0)
	s_barrier
; #define PG8_STAGE(bufoff, gbase, voff) do { _Pragma("unroll") for (int _i = 0; _i < 2; ++_i) \
;         __builtin_amdgcn_global_load_lds((const unsigned*)((const char*)(gbase) + (voff)[_i]), (LAS unsigned*)(lds + (bufoff) + ldsw + _i * 8192), 16, 0, 0); } while (0)
; #define PG8_LDA(dst, b, h) do { _Pragma("unroll") for (int m = 0; m < 4; ++m) _Pragma("unroll") for (int k = 0; k < 2; ++k) dst[m][k] = *(const LAS bf16x8*)(lds + PG8_SA(b, h) + aoff + m * 2048 + k * 1024); } while (0)
; #define PG8_LDB(dst, b, h) do { _Pragma("unroll") for (int n = 0; n < 2; ++n) _Pragma("unroll") for (int k = 0; k < 2; ++k) dst[n][k] = *(const LAS bf16x8*)(lds + PG8_SB(b, h) + boff + n * 2048 + k * 1024); } while (0)
; #define PG8_MMA(ai, bj, At, Bt) do { __builtin_amdgcn_s_setprio(1); _Pragma("unroll") for (int m = 0; m < 4; ++m) _Pragma("unroll") for (int n = 0; n < 2; ++n) _Pragma("unroll") for (int k = 0; k < 2; ++k) \
;         acc[ai][bj][m][n] = __builtin_amdgcn_mfma_f32_16x16x32_bf16(Bt[n][k], At[m][k], acc[ai][bj][m][n], 0, 0, 0); __builtin_amdgcn_s_setprio(0); } while (0)
; #define PG8_WAIT_V(n) asm volatile("s_waitcnt vmcnt(" #n ")" ::: "memory")
; #define PG8_WAIT_L(n) asm volatile("s_waitcnt lgkmcnt(" #n ")" ::: "memory")
; #define PG8_BAR __builtin_amdgcn_s_barrier()
; #define PG8_SCHED __builtin_amdgcn_sched_barrier(0)
; template <class Epi, class Sched>
; __device__ __forceinline__ void gemm_phase(const int tid, LAS unsigned char* lds, const int lda, const int ldb, const int K, const Sched& S, const Epi& E) {
;     ...
;             PG8_WAIT_V(8); PG8_WAIT_L(0); PG8_BAR; PG8_MMA(0, 0, At, B0); PG8_MMA(0, 1, At, B1); PG8_BAR; PG8_SCHED;
;             PG8_LDA(At, 0, 1); PG8_STAGE(PG8_SB(0, 0), b2, voffB); PG8_STAGE(PG8_SB(0, 1), b2 + hstepB, voffB); PG8_STAGE(PG8_SA(0, 0), a2, voffA);
;             PG8_WAIT_V(8); PG8_WAIT_L(0); PG8_BAR; if (!cur.half) { PG8_MMA(1, 0, At, B0); PG8_MMA(1, 1, At, B1); } PG8_BAR; PG8_SCHED;
;             PG8_LDB(B0, 1, 0); PG8_LDB(B1, 1, 1); PG8_SCHED; PG8_LDA(At, 1, 0); PG8_STAGE(PG8_SA(0, 1), a2 + hstepA, voffA);
;             PG8_WAIT_V(8); PG8_WAIT_L(0); PG8_BAR; PG8_MMA(0, 0, At, B0); PG8_MMA(0, 1, At, B1); PG8_BAR; PG8_SCHED;
	v_mfma_f32_16x16x32_bf16 v[124:127], v[158:161], v[212:215], v[124:127]
	v_mfma_f32_16x16x32_bf16 v[120:123], v[180:183], v[212:215], v[120:123]
	v_mfma_f32_16x16x32_bf16 v[108:111], v[158:161], v[220:223], v[108:111]
	v_mfma_f32_16x16x32_bf16 v[104:107], v[180:183], v[220:223], v[104:107]
	v_mfma_f32_16x16x32_bf16 v[92:95], v[158:161], v[228:231], v[92:95]
	v_mfma_f32_16x16x32_bf16 v[88:91], v[180:183], v[228:231], v[88:91]
	v_mfma_f32_16x16x32_bf16 v[76:79], v[158:161], v[236:239], v[76:79]
	v_mfma_f32_16x16x32_bf16 v[72:75], v[180:183], v[236:239], v[72:75]
	v_mfma_f32_16x16x32_bf16 v[124:127], v[162:165], v[216:219], v[124:127]
	v_mfma_f32_16x16x32_bf16 v[120:123], v[184:187], v[216:219], v[120:123]
	v_mfma_f32_16x16x32_bf16 v[108:111], v[162:165], v[224:227], v[108:111]
	v_mfma_f32_16x16x32_bf16 v[104:107], v[184:187], v[224:227], v[104:107]
	v_mfma_f32_16x16x32_bf16 v[92:95], v[162:165], v[232:235], v[92:95]
	v_mfma_f32_16x16x32_bf16 v[88:91], v[184:187], v[232:235], v[88:91]
	v_mfma_f32_16x16x32_bf16 v[76:79], v[162:165], v[240:243], v[76:79]
	v_mfma_f32_16x16x32_bf16 v[72:75], v[184:187], v[240:243], v[72:75]
	v_mfma_f32_16x16x32_bf16 v[116:119], v[190:193], v[212:215], v[116:119]
	v_mfma_f32_16x16x32_bf16 v[112:115], v[204:207], v[212:215], v[112:115]
	v_mfma_f32_16x16x32_bf16 v[100:103], v[190:193], v[220:223], v[100:103]
	v_mfma_f32_16x16x32_bf16 v[96:99], v[204:207], v[220:223], v[96:99]
	v_mfma_f32_16x16x32_bf16 v[84:87], v[190:193], v[228:231], v[84:87]
	v_mfma_f32_16x16x32_bf16 v[80:83], v[204:207], v[228:231], v[80:83]
	v_mfma_f32_16x16x32_bf16 v[68:71], v[190:193], v[236:239], v[68:71]
	v_mfma_f32_16x16x32_bf16 v[64:67], v[204:207], v[236:239], v[64:67]
	v_mfma_f32_16x16x32_bf16 v[116:119], v[194:197], v[216:219], v[116:119]
	v_mfma_f32_16x16x32_bf16 v[112:115], v[208:211], v[216:219], v[112:115]
	v_mfma_f32_16x16x32_bf16 v[100:103], v[194:197], v[224:227], v[100:103]
	v_mfma_f32_16x16x32_bf16 v[96:99], v[208:211], v[224:227], v[96:99]
	v_mfma_f32_16x16x32_bf16 v[84:87], v[194:197], v[232:235], v[84:87]
	v_mfma_f32_16x16x32_bf16 v[80:83], v[208:211], v[232:235], v[80:83]
	v_mfma_f32_16x16x32_bf16 v[68:71], v[194:197], v[240:243], v[68:71]
	v_mfma_f32_16x16x32_bf16 v[64:67], v[208:211], v[240:243], v[64:67]
	s_barrier
	s_add_i32 s15, s24, s20
	v_lshl_add_u64 v[166:167], s[52:53], 0, v[130:131]
	s_mov_b32 m0, s15
	ds_read_b128 v[212:215], v155 offset:16384
	ds_read_b128 v[216:219], v155 offset:17408
	ds_read_b128 v[220:223], v155 offset:18432
	ds_read_b128 v[224:227], v155 offset:19456
	ds_read_b128 v[228:231], v155 offset:20480
	ds_read_b128 v[232:235], v155 offset:21504
	ds_read_b128 v[236:239], v155 offset:22528
	ds_read_b128 v[240:243], v155 offset:23552
	global_load_lds_dwordx4 v[166:167], off
	s_add_i32 m0, s15, 0x2000
	s_add_u32 s66, s52, 0x40000
	v_lshl_add_u64 v[244:245], s[52:53], 0, v[134:135]
	s_addc_u32 s67, s53, 0
	s_add_i32 s14, s14, s20
	global_load_lds_dwordx4 v[244:245], off
	v_lshl_add_u64 v[246:247], s[66:67], 0, v[130:131]
	s_mov_b32 m0, s14
	v_lshl_add_u64 v[248:249], s[54:55], 0, v[132:133]
	global_load_lds_dwordx4 v[246:247], off
	v_lshl_add_u64 v[246:247], s[66:67], 0, v[134:135]
	s_add_i32 m0, s14, 0x2000
	s_nop 0
	global_load_lds_dwordx4 v[246:247], off
	v_lshl_add_u64 v[246:247], s[54:55], 0, v[128:129]
	s_mov_b32 m0, s21
	s_nop 0
	global_load_lds_dwordx4 v[246:247], off
	s_mov_b32 m0, s29
	s_nop 0
	global_load_lds_dwordx4 v[248:249], off
	s_waitcnt vmcnt(8)
	s_waitcnt lgkmcnt(0)
	s_barrier
	v_mfma_f32_16x16x32_bf16 v[60:63], v[158:161], v[212:215], v[60:63]
	v_mfma_f32_16x16x32_bf16 v[56:59], v[180:183], v[212:215], v[56:59]
	v_mfma_f32_16x16x32_bf16 v[44:47], v[158:161], v[220:223], v[44:47]
	v_mfma_f32_16x16x32_bf16 v[40:43], v[180:183], v[220:223], v[40:43]
	v_mfma_f32_16x16x32_bf16 v[28:31], v[158:161], v[228:231], v[28:31]
	v_mfma_f32_16x16x32_bf16 v[24:27], v[180:183], v[228:231], v[24:27]
	v_mfma_f32_16x16x32_bf16 v[12:15], v[158:161], v[236:239], v[12:15]
	v_mfma_f32_16x16x32_bf16 v[8:11], v[180:183], v[236:239], v[8:11]
	v_mfma_f32_16x16x32_bf16 v[60:63], v[162:165], v[216:219], v[60:63]
	v_mfma_f32_16x16x32_bf16 v[56:59], v[184:187], v[216:219], v[56:59]
	v_mfma_f32_16x16x32_bf16 v[44:47], v[162:165], v[224:227], v[44:47]
	v_mfma_f32_16x16x32_bf16 v[40:43], v[184:187], v[224:227], v[40:43]
	v_mfma_f32_16x16x32_bf16 v[28:31], v[162:165], v[232:235], v[28:31]
	v_mfma_f32_16x16x32_bf16 v[24:27], v[184:187], v[232:235], v[24:27]
	v_mfma_f32_16x16x32_bf16 v[12:15], v[162:165], v[240:243], v[12:15]
	v_mfma_f32_16x16x32_bf16 v[8:11], v[184:187], v[240:243], v[8:11]
	v_mfma_f32_16x16x32_bf16 v[52:55], v[190:193], v[212:215], v[52:55]
	v_mfma_f32_16x16x32_bf16 v[48:51], v[204:207], v[212:215], v[48:51]
	v_mfma_f32_16x16x32_bf16 v[36:39], v[190:193], v[220:223], v[36:39]
	v_mfma_f32_16x16x32_bf16 v[32:35], v[204:207], v[220:223], v[32:35]
	v_mfma_f32_16x16x32_bf16 v[20:23], v[190:193], v[228:231], v[20:23]
	v_mfma_f32_16x16x32_bf16 v[16:19], v[204:207], v[228:231], v[16:19]
	v_mfma_f32_16x16x32_bf16 v[4:7], v[190:193], v[236:239], v[4:7]
	v_mfma_f32_16x16x32_bf16 v[0:3], v[204:207], v[236:239], v[0:3]
	v_mfma_f32_16x16x32_bf16 v[52:55], v[194:197], v[216:219], v[52:55]
	v_mfma_f32_16x16x32_bf16 v[48:51], v[208:211], v[216:219], v[48:51]
	v_mfma_f32_16x16x32_bf16 v[36:39], v[194:197], v[224:227], v[36:39]
	v_mfma_f32_16x16x32_bf16 v[32:35], v[208:211], v[224:227], v[32:35]
	v_mfma_f32_16x16x32_bf16 v[20:23], v[194:197], v[232:235], v[20:23]
	v_mfma_f32_16x16x32_bf16 v[16:19], v[208:211], v[232:235], v[16:19]
	v_mfma_f32_16x16x32_bf16 v[4:7], v[194:197], v[240:243], v[4:7]
	v_mfma_f32_16x16x32_bf16 v[0:3], v[208:211], v[240:243], v[0:3]
	s_barrier
; #define PG8_STAGE(bufoff, gbase, voff) do { _Pragma("unroll") for (int _i = 0; _i < 2; ++_i) \
;         __builtin_amdgcn_global_load_lds((const unsigned*)((const char*)(gbase) + (voff)[_i]), (LAS unsigned*)(lds + (bufoff) + ldsw + _i * 8192), 16, 0, 0); } while (0)
; #define PG8_LDA(dst, b, h) do { _Pragma("unroll") for (int m = 0; m < 4; ++m) _Pragma("unroll") for (int k = 0; k < 2; ++k) dst[m][k] = *(const LAS bf16x8*)(lds + PG8_SA(b, h) + aoff + m * 2048 + k * 1024); } while (0)
; #define PG8_LDB(dst, b, h) do { _Pragma("unroll") for (int n = 0; n < 2; ++n) _Pragma("unroll") for (int k = 0; k < 2; ++k) dst[n][k] = *(const LAS bf16x8*)(lds + PG8_SB(b, h) + boff + n * 2048 + k * 1024); } while (0)
; #define PG8_MMA(ai, bj, At, Bt) do { __builtin_amdgcn_s_setprio(1); _Pragma("unroll") for (int m = 0; m < 4; ++m) _Pragma("unroll") for (int n = 0; n < 2; ++n) _Pragma("unroll") for (int k = 0; k < 2; ++k) \
;         acc[ai][bj][m][n] = __builtin_amdgcn_mfma_f32_16x16x32_bf16(Bt[n][k], At[m][k], acc[ai][bj][m][n], 0, 0, 0); __builtin_amdgcn_s_setprio(0); } while (0)
; #define PG8_WAIT_V(n) asm volatile("s_waitcnt vmcnt(" #n ")" ::: "memory")
; #define PG8_WAIT_L(n) asm volatile("s_waitcnt lgkmcnt(" #n ")" ::: "memory")
; #define PG8_BAR __builtin_amdgcn_s_barrier()
; #define PG8_SCHED __builtin_amdgcn_sched_barrier(0)
; template <class Epi, class Sched>
; __device__ __forceinline__ void gemm_phase(const int tid, LAS unsigned char* lds, const int lda, const int ldb, const int K, const Sched& S, const Epi& E) {
;     ...
;             PG8_LDB(B0, 1, 0); PG8_LDB(B1, 1, 1); PG8_SCHED; PG8_LDA(At, 1, 0); PG8_STAGE(PG8_SA(0, 1), a2 + hstepA, voffA);
;             PG8_WAIT_V(8); PG8_WAIT_L(0); PG8_BAR; PG8_MMA(0, 0, At, B0); PG8_MMA(0, 1, At, B1); PG8_BAR; PG8_SCHED;
;             PG8_LDA(At, 1, 1); PG8_STAGE(PG8_SB(1, 0), b3, voffB); PG8_STAGE(PG8_SB(1, 1), b3 + hstepB, voffB); PG8_STAGE(PG8_SA(1, 0), a3, voffA);
;             PG8_WAIT_V(8); PG8_WAIT_L(0); PG8_BAR; if (!cur.half) { PG8_MMA(1, 0, At, B0); PG8_MMA(1, 1, At, B1); } PG8_BAR; PG8_SCHED;
;         }
	s_add_i32 s14, 0, 0x18000
	v_add_u32_e32 v141, s14, v148
	s_add_i32 s15, 0, 0x1c000
	ds_read_b128 v[158:161], v141
	ds_read_b128 v[162:165], v141 offset:1024
	ds_read_b128 v[180:183], v141 offset:2048
	ds_read_b128 v[184:187], v141 offset:3072
	v_add_u32_e32 v141, s15, v148
	ds_read_b128 v[190:193], v141
	ds_read_b128 v[194:197], v141 offset:1024
	ds_read_b128 v[204:207], v141 offset:2048
	ds_read_b128 v[208:211], v141 offset:3072
	s_add_u32 s54, s54, 0x40000
	s_addc_u32 s55, s55, 0
	s_mov_b32 m0, s31
	v_lshl_add_u64 v[250:251], s[54:55], 0, v[128:129]
	ds_read_b128 v[212:215], v155 offset:32768
	ds_read_b128 v[216:219], v155 offset:33792
	ds_read_b128 v[220:223], v155 offset:34816
	ds_read_b128 v[224:227], v155 offset:35840
	ds_read_b128 v[228:231], v155 offset:36864
	ds_read_b128 v[232:235], v155 offset:37888
	ds_read_b128 v[236:239], v155 offset:38912
	ds_read_b128 v[240:243], v155 offset:39936
	global_load_lds_dwordx4 v[250:251], off
	v_lshl_add_u64 v[250:251], s[54:55], 0, v[132:133]
	s_mov_b32 m0, s56
	s_nop 0
	global_load_lds_dwordx4 v[250:251], off
	s_waitcnt vmcnt(8)
	s_waitcnt lgkmcnt(0)
	s_barrier
	v_mfma_f32_16x16x32_bf16 v[124:127], v[158:161], v[212:215], v[124:127]
	v_mfma_f32_16x16x32_bf16 v[120:123], v[180:183], v[212:215], v[120:123]
	v_mfma_f32_16x16x32_bf16 v[108:111], v[158:161], v[220:223], v[108:111]
	v_mfma_f32_16x16x32_bf16 v[104:107], v[180:183], v[220:223], v[104:107]
	v_mfma_f32_16x16x32_bf16 v[92:95], v[158:161], v[228:231], v[92:95]
	v_mfma_f32_16x16x32_bf16 v[88:91], v[180:183], v[228:231], v[88:91]
	v_mfma_f32_16x16x32_bf16 v[76:79], v[158:161], v[236:239], v[76:79]
	v_mfma_f32_16x16x32_bf16 v[72:75], v[180:183], v[236:239], v[72:75]
	v_mfma_f32_16x16x32_bf16 v[124:127], v[162:165], v[216:219], v[124:127]
	v_mfma_f32_16x16x32_bf16 v[120:123], v[184:187], v[216:219], v[120:123]
	v_mfma_f32_16x16x32_bf16 v[108:111], v[162:165], v[224:227], v[108:111]
	v_mfma_f32_16x16x32_bf16 v[104:107], v[184:187], v[224:227], v[104:107]
	v_mfma_f32_16x16x32_bf16 v[92:95], v[162:165], v[232:235], v[92:95]
	v_mfma_f32_16x16x32_bf16 v[88:91], v[184:187], v[232:235], v[88:91]
	v_mfma_f32_16x16x32_bf16 v[76:79], v[162:165], v[240:243], v[76:79]
	v_mfma_f32_16x16x32_bf16 v[72:75], v[184:187], v[240:243], v[72:75]
	v_mfma_f32_16x16x32_bf16 v[116:119], v[190:193], v[212:215], v[116:119]
	v_mfma_f32_16x16x32_bf16 v[112:115], v[204:207], v[212:215], v[112:115]
	v_mfma_f32_16x16x32_bf16 v[100:103], v[190:193], v[220:223], v[100:103]
	v_mfma_f32_16x16x32_bf16 v[96:99], v[204:207], v[220:223], v[96:99]
	v_mfma_f32_16x16x32_bf16 v[84:87], v[190:193], v[228:231], v[84:87]
	v_mfma_f32_16x16x32_bf16 v[80:83], v[204:207], v[228:231], v[80:83]
	v_mfma_f32_16x16x32_bf16 v[68:71], v[190:193], v[236:239], v[68:71]
	v_mfma_f32_16x16x32_bf16 v[64:67], v[204:207], v[236:239], v[64:67]
	v_mfma_f32_16x16x32_bf16 v[116:119], v[194:197], v[216:219], v[116:119]
	v_mfma_f32_16x16x32_bf16 v[112:115], v[208:211], v[216:219], v[112:115]
	v_mfma_f32_16x16x32_bf16 v[100:103], v[194:197], v[224:227], v[100:103]
	v_mfma_f32_16x16x32_bf16 v[96:99], v[208:211], v[224:227], v[96:99]
	v_mfma_f32_16x16x32_bf16 v[84:87], v[194:197], v[232:235], v[84:87]
	v_mfma_f32_16x16x32_bf16 v[80:83], v[208:211], v[232:235], v[80:83]
	v_mfma_f32_16x16x32_bf16 v[68:71], v[194:197], v[240:243], v[68:71]
	v_mfma_f32_16x16x32_bf16 v[64:67], v[208:211], v[240:243], v[64:67]
	s_barrier
	s_add_i32 s14, s14, s20
	v_lshl_add_u64 v[166:167], v[166:167], 0, s[6:7]
	s_mov_b32 m0, s14
	ds_read_b128 v[212:215], v155 offset:49152
	ds_read_b128 v[216:219], v155 offset:50176
	ds_read_b128 v[220:223], v155 offset:51200
	ds_read_b128 v[224:227], v155 offset:52224
	ds_read_b128 v[228:231], v155 offset:53248
	ds_read_b128 v[232:235], v155 offset:54272
	ds_read_b128 v[236:239], v155 offset:55296
	ds_read_b128 v[240:243], v155 offset:56320
	global_load_lds_dwordx4 v[166:167], off
	s_add_i32 m0, s14, 0x2000
	s_add_u32 s52, s52, 0x40080
	v_lshl_add_u64 v[166:167], v[244:245], 0, s[6:7]
	s_addc_u32 s53, s53, 0
	s_add_i32 s14, s15, s20
	global_load_lds_dwordx4 v[166:167], off
	v_lshl_add_u64 v[166:167], s[52:53], 0, v[130:131]
	s_mov_b32 m0, s14
	s_nop 0
	global_load_lds_dwordx4 v[166:167], off
	v_lshl_add_u64 v[166:167], s[52:53], 0, v[134:135]
	s_add_i32 m0, s14, 0x2000
	s_nop 0
	global_load_lds_dwordx4 v[166:167], off
	v_lshl_add_u64 v[166:167], v[246:247], 0, s[6:7]
	s_mov_b32 m0, s57
	s_nop 0
	global_load_lds_dwordx4 v[166:167], off
	v_lshl_add_u64 v[166:167], v[248:249], 0, s[6:7]
	s_mov_b32 m0, s58
	s_nop 0
	global_load_lds_dwordx4 v[166:167], off
	s_waitcnt vmcnt(8)
	s_waitcnt lgkmcnt(0)
	s_barrier
	v_mfma_f32_16x16x32_bf16 v[60:63], v[158:161], v[212:215], v[60:63]
	v_mfma_f32_16x16x32_bf16 v[56:59], v[180:183], v[212:215], v[56:59]
	v_mfma_f32_16x16x32_bf16 v[44:47], v[158:161], v[220:223], v[44:47]
	v_mfma_f32_16x16x32_bf16 v[40:43], v[180:183], v[220:223], v[40:43]
	v_mfma_f32_16x16x32_bf16 v[28:31], v[158:161], v[228:231], v[28:31]
	v_mfma_f32_16x16x32_bf16 v[24:27], v[180:183], v[228:231], v[24:27]
	v_mfma_f32_16x16x32_bf16 v[12:15], v[158:161], v[236:239], v[12:15]
	v_mfma_f32_16x16x32_bf16 v[8:11], v[180:183], v[236:239], v[8:11]
	v_mfma_f32_16x16x32_bf16 v[60:63], v[162:165], v[216:219], v[60:63]
	v_mfma_f32_16x16x32_bf16 v[56:59], v[184:187], v[216:219], v[56:59]
	v_mfma_f32_16x16x32_bf16 v[44:47], v[162:165], v[224:227], v[44:47]
	v_mfma_f32_16x16x32_bf16 v[40:43], v[184:187], v[224:227], v[40:43]
	v_mfma_f32_16x16x32_bf16 v[28:31], v[162:165], v[232:235], v[28:31]
	v_mfma_f32_16x16x32_bf16 v[24:27], v[184:187], v[232:235], v[24:27]
	v_mfma_f32_16x16x32_bf16 v[12:15], v[162:165], v[240:243], v[12:15]
	v_mfma_f32_16x16x32_bf16 v[8:11], v[184:187], v[240:243], v[8:11]
	v_mfma_f32_16x16x32_bf16 v[52:55], v[190:193], v[212:215], v[52:55]
	v_mfma_f32_16x16x32_bf16 v[48:51], v[204:207], v[212:215], v[48:51]
	v_mfma_f32_16x16x32_bf16 v[36:39], v[190:193], v[220:223], v[36:39]
	v_mfma_f32_16x16x32_bf16 v[32:35], v[204:207], v[220:223], v[32:35]
	v_mfma_f32_16x16x32_bf16 v[20:23], v[190:193], v[228:231], v[20:23]
	v_mfma_f32_16x16x32_bf16 v[16:19], v[204:207], v[228:231], v[16:19]
	v_mfma_f32_16x16x32_bf16 v[4:7], v[190:193], v[236:239], v[4:7]
	v_mfma_f32_16x16x32_bf16 v[0:3], v[204:207], v[236:239], v[0:3]
	v_mfma_f32_16x16x32_bf16 v[52:55], v[194:197], v[216:219], v[52:55]
	v_mfma_f32_16x16x32_bf16 v[48:51], v[208:211], v[216:219], v[48:51]
	v_mfma_f32_16x16x32_bf16 v[36:39], v[194:197], v[224:227], v[36:39]
	v_mfma_f32_16x16x32_bf16 v[32:35], v[208:211], v[224:227], v[32:35]
	v_mfma_f32_16x16x32_bf16 v[20:23], v[194:197], v[232:235], v[20:23]
	v_mfma_f32_16x16x32_bf16 v[16:19], v[208:211], v[232:235], v[16:19]
	v_mfma_f32_16x16x32_bf16 v[4:7], v[194:197], v[240:243], v[4:7]
	v_mfma_f32_16x16x32_bf16 v[0:3], v[208:211], v[240:243], v[0:3]
	s_barrier
	s_add_u32 s50, s50, 0x100
	s_addc_u32 s51, s51, 0
	s_add_u32 s45, s45, 0x100
	s_addc_u32 s63, s63, 0
	s_cmp_ge_i32 s64, s4
	s_mov_b32 s52, s64
	s_cbranch_scc0 .LBB0_874

; #define PG8_STAGE(bufoff, gbase, voff) do { _Pragma("unroll") for (int _i = 0; _i < 2; ++_i) \
;         __builtin_amdgcn_global_load_lds((const unsigned*)((const char*)(gbase) + (voff)[_i]), (LAS unsigned*)(lds + (bufoff) + ldsw + _i * 8192), 16, 0, 0); } while (0)
; #define PG8_LDA(dst, b, h) do { _Pragma("unroll") for (int m = 0; m < 4; ++m) _Pragma("unroll") for (int k = 0; k < 2; ++k) dst[m][k] = *(const LAS bf16x8*)(lds + PG8_SA(b, h) + aoff + m * 2048 + k * 1024); } while (0)
; #define PG8_LDB(dst, b, h) do { _Pragma("unroll") for (int n = 0; n < 2; ++n) _Pragma("unroll") for (int k = 0; k < 2; ++k) dst[n][k] = *(const LAS bf16x8*)(lds + PG8_SB(b, h) + boff + n * 2048 + k * 1024); } while (0)
; #define PG8_MMA(ai, bj, At, Bt) do { __builtin_amdgcn_s_setprio(1); _Pragma("unroll") for (int m = 0; m < 4; ++m) _Pragma("unroll") for (int n = 0; n < 2; ++n) _Pragma("unroll") for (int k = 0; k < 2; ++k) \
;         acc[ai][bj][m][n] = __builtin_amdgcn_mfma_f32_16x16x32_bf16(Bt[n][k], At[m][k], acc[ai][bj][m][n], 0, 0, 0); __builtin_amdgcn_s_setprio(0); } while (0)
; #define PG8_WAIT_V(n) asm volatile("s_waitcnt vmcnt(" #n ")" ::: "memory")
; template <class Epi, class Sched>
; __device__ __forceinline__ void gemm_phase(const int tid, LAS unsigned char* lds, const int lda, const int ldb, const int K, const Sched& S, const Epi& E) {
;     ...
;         const bool has_next = S.next(ui + 1, nxt);
;         const char* nA = has_next ? nxt.a : cA; const char* nB = has_next ? nxt.b : cB;
;         for (int t = 0; t < nt; t += 2) {
;             const bool last = (t == nt - 2);
;             const char* a1 = cA + (size_t)(t + 1) * kstep;
;             const char* a2 = last ? nA : cA + (size_t)(t + 2) * kstep; const char* b2 = last ? nB : cB + (size_t)(t + 2) * kstep;
;             const char* a3 = a2 + kstep; const char* b3 = b2 + kstep;
;             PG8_LDB(B0, 0, 0); PG8_LDB(B1, 0, 1); PG8_SCHED; PG8_LDA(At, 0, 0); PG8_STAGE(PG8_SA(1, 1), a1 + hstepA, voffA);
;             PG8_WAIT_V(8); PG8_WAIT_L(0); PG8_BAR; PG8_MMA(0, 0, At, B0); PG8_MMA(0, 1, At, B1); PG8_BAR; PG8_SCHED;
;             PG8_LDA(At, 0, 1); PG8_STAGE(PG8_SB(0, 0), b2, voffB); PG8_STAGE(PG8_SB(0, 1), b2 + hstepB, voffB); PG8_STAGE(PG8_SA(0, 0), a2, voffA);
;             PG8_WAIT_V(8); PG8_WAIT_L(0); PG8_BAR; if (!cur.half) { PG8_MMA(1, 0, At, B0); PG8_MMA(1, 1, At, B1); } PG8_BAR; PG8_SCHED;
.LBB0_894:
	s_andn2_b64 vcc, exec, s[40:41]
	s_cbranch_vccnz .LBB0_902
	s_add_u32 s50, s50, 0x40080
	s_addc_u32 s51, s51, 0
	s_add_u32 s45, s52, 0x100
	s_addc_u32 s64, s53, 0
	s_mov_b32 s52, 0
	s_add_i32 s65, s52, 2
	s_add_u32 s24, s50, 0xfffc0080
	s_addc_u32 s53, s51, -1
	s_add_i32 s66, 0, 0x10000
	s_cmp_eq_u32 s61, s52
	s_cselect_b32 s55, s3, s53
	s_cselect_b32 s54, s2, s24
	v_add_u32_e32 v166, s66, v146
	s_cselect_b32 s53, s39, s64
	s_cselect_b32 s52, s38, s45
	s_add_i32 s24, 0, 0x14000
	ds_read_b128 v[154:157], v166
	ds_read_b128 v[158:161], v166 offset:1024
	ds_read_b128 v[162:165], v166 offset:2048
	ds_read_b128 v[180:183], v166 offset:3072
	v_add_u32_e32 v166, s24, v146
	ds_read_b128 v[184:187], v166
	ds_read_b128 v[190:193], v166 offset:1024
	ds_read_b128 v[194:197], v166 offset:2048
	ds_read_b128 v[204:207], v166 offset:3072
	v_lshl_add_u64 v[166:167], s[50:51], 0, v[136:137]
	s_add_i32 m0, s29, 0xc000
	ds_read_b128 v[208:211], v153
	ds_read_b128 v[212:215], v153 offset:1024
	ds_read_b128 v[216:219], v153 offset:2048
	ds_read_b128 v[220:223], v153 offset:3072
	ds_read_b128 v[224:227], v153 offset:4096
	ds_read_b128 v[228:231], v153 offset:5120
	ds_read_b128 v[232:235], v153 offset:6144
	ds_read_b128 v[236:239], v153 offset:7168
	global_load_lds_dwordx4 v[166:167], off
	v_lshl_add_u64 v[166:167], s[50:51], 0, v[138:139]
	s_add_i32 m0, s29, 0xe000
	s_nop 0
	global_load_lds_dwordx4 v[166:167], off
	s_waitcnt vmcnt(10)
	s_waitcnt lgkmcnt(0)
	s_barrier
	v_mfma_f32_16x16x32_bf16 v[124:127], v[154:157], v[208:211], 0
	v_mfma_f32_16x16x32_bf16 v[116:119], v[162:165], v[208:211], 0
	v_mfma_f32_16x16x32_bf16 v[108:111], v[154:157], v[216:219], 0
	v_mfma_f32_16x16x32_bf16 v[100:103], v[162:165], v[216:219], 0
	v_mfma_f32_16x16x32_bf16 v[92:95], v[154:157], v[224:227], 0
	v_mfma_f32_16x16x32_bf16 v[84:87], v[162:165], v[224:227], 0
	v_mfma_f32_16x16x32_bf16 v[76:79], v[154:157], v[232:235], 0
	v_mfma_f32_16x16x32_bf16 v[68:71], v[162:165], v[232:235], 0
	v_mfma_f32_16x16x32_bf16 v[124:127], v[158:161], v[212:215], v[124:127]
	v_mfma_f32_16x16x32_bf16 v[116:119], v[180:183], v[212:215], v[116:119]
	v_mfma_f32_16x16x32_bf16 v[108:111], v[158:161], v[220:223], v[108:111]
	v_mfma_f32_16x16x32_bf16 v[100:103], v[180:183], v[220:223], v[100:103]
	v_mfma_f32_16x16x32_bf16 v[92:95], v[158:161], v[228:231], v[92:95]
	v_mfma_f32_16x16x32_bf16 v[84:87], v[180:183], v[228:231], v[84:87]
	v_mfma_f32_16x16x32_bf16 v[76:79], v[158:161], v[236:239], v[76:79]
	v_mfma_f32_16x16x32_bf16 v[68:71], v[180:183], v[236:239], v[68:71]
	v_mfma_f32_16x16x32_bf16 v[120:123], v[184:187], v[208:211], 0
	v_mfma_f32_16x16x32_bf16 v[112:115], v[194:197], v[208:211], 0
	v_mfma_f32_16x16x32_bf16 v[104:107], v[184:187], v[216:219], 0
	v_mfma_f32_16x16x32_bf16 v[96:99], v[194:197], v[216:219], 0
	v_mfma_f32_16x16x32_bf16 v[88:91], v[184:187], v[224:227], 0
	v_mfma_f32_16x16x32_bf16 v[80:83], v[194:197], v[224:227], 0
	v_mfma_f32_16x16x32_bf16 v[72:75], v[184:187], v[232:235], 0
	v_mfma_f32_16x16x32_bf16 v[64:67], v[194:197], v[232:235], 0
	v_mfma_f32_16x16x32_bf16 v[120:123], v[190:193], v[212:215], v[120:123]
	v_mfma_f32_16x16x32_bf16 v[112:115], v[204:207], v[212:215], v[112:115]
	v_mfma_f32_16x16x32_bf16 v[104:107], v[190:193], v[220:223], v[104:107]
	v_mfma_f32_16x16x32_bf16 v[96:99], v[204:207], v[220:223], v[96:99]
	v_mfma_f32_16x16x32_bf16 v[88:91], v[190:193], v[228:231], v[88:91]
	v_mfma_f32_16x16x32_bf16 v[80:83], v[204:207], v[228:231], v[80:83]
	v_mfma_f32_16x16x32_bf16 v[72:75], v[190:193], v[236:239], v[72:75]
	v_mfma_f32_16x16x32_bf16 v[64:67], v[204:207], v[236:239], v[64:67]
	s_barrier
	s_add_i32 s66, s66, s20
	v_lshl_add_u64 v[166:167], s[52:53], 0, v[132:133]
	s_mov_b32 m0, s66
	ds_read_b128 v[208:211], v153 offset:16384
	ds_read_b128 v[212:215], v153 offset:17408
	ds_read_b128 v[216:219], v153 offset:18432
	ds_read_b128 v[220:223], v153 offset:19456
	ds_read_b128 v[224:227], v153 offset:20480
	ds_read_b128 v[228:231], v153 offset:21504
	ds_read_b128 v[232:235], v153 offset:22528
	ds_read_b128 v[236:239], v153 offset:23552
	global_load_lds_dwordx4 v[166:167], off
	s_add_i32 m0, s66, 0x2000
	s_add_u32 s66, s52, 0x40000
	v_lshl_add_u64 v[240:241], s[52:53], 0, v[128:129]
	s_addc_u32 s67, s53, 0
	s_add_i32 s24, s24, s20
	global_load_lds_dwordx4 v[240:241], off
	v_lshl_add_u64 v[242:243], s[66:67], 0, v[132:133]
	s_mov_b32 m0, s24
	v_lshl_add_u64 v[244:245], s[54:55], 0, v[130:131]
	global_load_lds_dwordx4 v[242:243], off
	v_lshl_add_u64 v[242:243], s[66:67], 0, v[128:129]
	s_add_i32 m0, s24, 0x2000
	s_nop 0
	global_load_lds_dwordx4 v[242:243], off
	v_lshl_add_u64 v[242:243], s[54:55], 0, v[134:135]
	s_waitcnt vmcnt(14)
	s_waitcnt lgkmcnt(0)
	s_barrier
; #define PG8_STAGE(bufoff, gbase, voff) do { _Pragma("unroll") for (int _i = 0; _i < 2; ++_i) \
;         __builtin_amdgcn_global_load_lds((const unsigned*)((const char*)(gbase) + (voff)[_i]), (LAS unsigned*)(lds + (bufoff) + ldsw + _i * 8192), 16, 0, 0); } while (0)
; #define PG8_LDA(dst, b, h) do { _Pragma("unroll") for (int m = 0; m < 4; ++m) _Pragma("unroll") for (int k = 0; k < 2; ++k) dst[m][k] = *(const LAS bf16x8*)(lds + PG8_SA(b, h) + aoff + m * 2048 + k * 1024); } while (0)
; #define PG8_LDB(dst, b, h) do { _Pragma("unroll") for (int n = 0; n < 2; ++n) _Pragma("unroll") for (int k = 0; k < 2; ++k) dst[n][k] = *(const LAS bf16x8*)(lds + PG8_SB(b, h) + boff + n * 2048 + k * 1024); } while (0)
; #define PG8_MMA(ai, bj, At, Bt) do { __builtin_amdgcn_s_setprio(1); _Pragma("unroll") for (int m = 0; m < 4; ++m) _Pragma("unroll") for (int n = 0; n < 2; ++n) _Pragma("unroll") for (int k = 0; k < 2; ++k) \
;         acc[ai][bj][m][n] = __builtin_amdgcn_mfma_f32_16x16x32_bf16(Bt[n][k], At[m][k], acc[ai][bj][m][n], 0, 0, 0); __builtin_amdgcn_s_setprio(0); } while (0)
; #define PG8_WAIT_V(n) asm volatile("s_waitcnt vmcnt(" #n ")" ::: "memory")
; #define PG8_WAIT_L(n) asm volatile("s_waitcnt lgkmcnt(" #n ")" ::: "memory")
; #define PG8_BAR __builtin_amdgcn_s_barrier()
; #define PG8_SCHED __builtin_amdgcn_sched_barrier(0)
; template <class Epi, class Sched>
; __device__ __forceinline__ void gemm_phase(const int tid, LAS unsigned char* lds, const int lda, const int ldb, const int K, const Sched& S, const Epi& E) {
;     ...
;             PG8_WAIT_V(8); PG8_WAIT_L(0); PG8_BAR; if (!cur.half) { PG8_MMA(1, 0, At, B0); PG8_MMA(1, 1, At, B1); } PG8_BAR; PG8_SCHED;
;             PG8_LDB(B0, 1, 0); PG8_LDB(B1, 1, 1); PG8_SCHED; PG8_LDA(At, 1, 0); PG8_STAGE(PG8_SA(0, 1), a2 + hstepA, voffA);
;             PG8_WAIT_V(8); PG8_WAIT_L(0); PG8_BAR; PG8_MMA(0, 0, At, B0); PG8_MMA(0, 1, At, B1); PG8_BAR; PG8_SCHED;
	v_mfma_f32_16x16x32_bf16 v[60:63], v[154:157], v[208:211], 0
	v_mfma_f32_16x16x32_bf16 v[52:55], v[162:165], v[208:211], 0
	v_mfma_f32_16x16x32_bf16 v[44:47], v[154:157], v[216:219], 0
	v_mfma_f32_16x16x32_bf16 v[36:39], v[162:165], v[216:219], 0
	v_mfma_f32_16x16x32_bf16 v[28:31], v[154:157], v[224:227], 0
	v_mfma_f32_16x16x32_bf16 v[20:23], v[162:165], v[224:227], 0
	v_mfma_f32_16x16x32_bf16 v[12:15], v[154:157], v[232:235], 0
	v_mfma_f32_16x16x32_bf16 v[4:7], v[162:165], v[232:235], 0
	v_mfma_f32_16x16x32_bf16 v[60:63], v[158:161], v[212:215], v[60:63]
	v_mfma_f32_16x16x32_bf16 v[52:55], v[180:183], v[212:215], v[52:55]
	v_mfma_f32_16x16x32_bf16 v[44:47], v[158:161], v[220:223], v[44:47]
	v_mfma_f32_16x16x32_bf16 v[36:39], v[180:183], v[220:223], v[36:39]
	v_mfma_f32_16x16x32_bf16 v[28:31], v[158:161], v[228:231], v[28:31]
	v_mfma_f32_16x16x32_bf16 v[20:23], v[180:183], v[228:231], v[20:23]
	v_mfma_f32_16x16x32_bf16 v[12:15], v[158:161], v[236:239], v[12:15]
	v_mfma_f32_16x16x32_bf16 v[4:7], v[180:183], v[236:239], v[4:7]
	v_mfma_f32_16x16x32_bf16 v[56:59], v[184:187], v[208:211], 0
	v_mfma_f32_16x16x32_bf16 v[48:51], v[194:197], v[208:211], 0
	v_mfma_f32_16x16x32_bf16 v[40:43], v[184:187], v[216:219], 0
	v_mfma_f32_16x16x32_bf16 v[32:35], v[194:197], v[216:219], 0
	v_mfma_f32_16x16x32_bf16 v[24:27], v[184:187], v[224:227], 0
	v_mfma_f32_16x16x32_bf16 v[16:19], v[194:197], v[224:227], 0
	v_mfma_f32_16x16x32_bf16 v[8:11], v[184:187], v[232:235], 0
	v_mfma_f32_16x16x32_bf16 v[0:3], v[194:197], v[232:235], 0
	v_mfma_f32_16x16x32_bf16 v[56:59], v[190:193], v[212:215], v[56:59]
	v_mfma_f32_16x16x32_bf16 v[48:51], v[204:207], v[212:215], v[48:51]
	v_mfma_f32_16x16x32_bf16 v[40:43], v[190:193], v[220:223], v[40:43]
	v_mfma_f32_16x16x32_bf16 v[32:35], v[204:207], v[220:223], v[32:35]
	v_mfma_f32_16x16x32_bf16 v[24:27], v[190:193], v[228:231], v[24:27]
	v_mfma_f32_16x16x32_bf16 v[16:19], v[204:207], v[228:231], v[16:19]
	v_mfma_f32_16x16x32_bf16 v[8:11], v[190:193], v[236:239], v[8:11]
	v_mfma_f32_16x16x32_bf16 v[0:3], v[204:207], v[236:239], v[0:3]
	s_barrier
	s_add_i32 s24, 0, 0x18000
	v_add_u32_e32 v176, s24, v146
	s_add_i32 s66, 0, 0x1c000
	ds_read_b128 v[154:157], v176
	ds_read_b128 v[158:161], v176 offset:1024
	ds_read_b128 v[162:165], v176 offset:2048
	ds_read_b128 v[180:183], v176 offset:3072
	v_add_u32_e32 v176, s66, v146
	ds_read_b128 v[184:187], v176
	ds_read_b128 v[190:193], v176 offset:1024
	ds_read_b128 v[194:197], v176 offset:2048
	ds_read_b128 v[204:207], v176 offset:3072
	s_mov_b32 m0, s29
	s_nop 0
	global_load_lds_dwordx4 v[242:243], off
	s_mov_b32 m0, s31
	s_nop 0
	global_load_lds_dwordx4 v[244:245], off
	s_add_u32 s54, s54, 0x40000
	s_addc_u32 s55, s55, 0
	s_mov_b32 m0, s56
	v_lshl_add_u64 v[246:247], s[54:55], 0, v[134:135]
	ds_read_b128 v[208:211], v153 offset:32768
	ds_read_b128 v[212:215], v153 offset:33792
	ds_read_b128 v[216:219], v153 offset:34816
	ds_read_b128 v[220:223], v153 offset:35840
	ds_read_b128 v[224:227], v153 offset:36864
	ds_read_b128 v[228:231], v153 offset:37888
	ds_read_b128 v[232:235], v153 offset:38912
	ds_read_b128 v[236:239], v153 offset:39936
	global_load_lds_dwordx4 v[246:247], off
	v_lshl_add_u64 v[246:247], s[54:55], 0, v[130:131]
	s_mov_b32 m0, s57
	s_nop 0
	global_load_lds_dwordx4 v[246:247], off
	s_waitcnt vmcnt(8)
	s_waitcnt lgkmcnt(0)
	s_barrier
	v_mfma_f32_16x16x32_bf16 v[124:127], v[154:157], v[208:211], v[124:127]
	v_mfma_f32_16x16x32_bf16 v[116:119], v[162:165], v[208:211], v[116:119]
	v_mfma_f32_16x16x32_bf16 v[108:111], v[154:157], v[216:219], v[108:111]
	v_mfma_f32_16x16x32_bf16 v[100:103], v[162:165], v[216:219], v[100:103]
	v_mfma_f32_16x16x32_bf16 v[92:95], v[154:157], v[224:227], v[92:95]
	v_mfma_f32_16x16x32_bf16 v[84:87], v[162:165], v[224:227], v[84:87]
	v_mfma_f32_16x16x32_bf16 v[76:79], v[154:157], v[232:235], v[76:79]
	v_mfma_f32_16x16x32_bf16 v[68:71], v[162:165], v[232:235], v[68:71]
	v_mfma_f32_16x16x32_bf16 v[124:127], v[158:161], v[212:215], v[124:127]
	v_mfma_f32_16x16x32_bf16 v[116:119], v[180:183], v[212:215], v[116:119]
	v_mfma_f32_16x16x32_bf16 v[108:111], v[158:161], v[220:223], v[108:111]
	v_mfma_f32_16x16x32_bf16 v[100:103], v[180:183], v[220:223], v[100:103]
	v_mfma_f32_16x16x32_bf16 v[92:95], v[158:161], v[228:231], v[92:95]
	v_mfma_f32_16x16x32_bf16 v[84:87], v[180:183], v[228:231], v[84:87]
	v_mfma_f32_16x16x32_bf16 v[76:79], v[158:161], v[236:239], v[76:79]
	v_mfma_f32_16x16x32_bf16 v[68:71], v[180:183], v[236:239], v[68:71]
	v_mfma_f32_16x16x32_bf16 v[120:123], v[184:187], v[208:211], v[120:123]
	v_mfma_f32_16x16x32_bf16 v[112:115], v[194:197], v[208:211], v[112:115]
	v_mfma_f32_16x16x32_bf16 v[104:107], v[184:187], v[216:219], v[104:107]
	v_mfma_f32_16x16x32_bf16 v[96:99], v[194:197], v[216:219], v[96:99]
	v_mfma_f32_16x16x32_bf16 v[88:91], v[184:187], v[224:227], v[88:91]
	v_mfma_f32_16x16x32_bf16 v[80:83], v[194:197], v[224:227], v[80:83]
	v_mfma_f32_16x16x32_bf16 v[72:75], v[184:187], v[232:235], v[72:75]
	v_mfma_f32_16x16x32_bf16 v[64:67], v[194:197], v[232:235], v[64:67]
	v_mfma_f32_16x16x32_bf16 v[120:123], v[190:193], v[212:215], v[120:123]
	v_mfma_f32_16x16x32_bf16 v[112:115], v[204:207], v[212:215], v[112:115]
	v_mfma_f32_16x16x32_bf16 v[104:107], v[190:193], v[220:223], v[104:107]
	v_mfma_f32_16x16x32_bf16 v[96:99], v[204:207], v[220:223], v[96:99]
	v_mfma_f32_16x16x32_bf16 v[88:91], v[190:193], v[228:231], v[88:91]
	v_mfma_f32_16x16x32_bf16 v[80:83], v[204:207], v[228:231], v[80:83]
	v_mfma_f32_16x16x32_bf16 v[72:75], v[190:193], v[236:239], v[72:75]
	v_mfma_f32_16x16x32_bf16 v[64:67], v[204:207], v[236:239], v[64:67]
	s_barrier
; #define PG8_STAGE(bufoff, gbase, voff) do { _Pragma("unroll") for (int _i = 0; _i < 2; ++_i) \
;         __builtin_amdgcn_global_load_lds((const unsigned*)((const char*)(gbase) + (voff)[_i]), (LAS unsigned*)(lds + (bufoff) + ldsw + _i * 8192), 16, 0, 0); } while (0)
; #define PG8_LDA(dst, b, h) do { _Pragma("unroll") for (int m = 0; m < 4; ++m) _Pragma("unroll") for (int k = 0; k < 2; ++k) dst[m][k] = *(const LAS bf16x8*)(lds + PG8_SA(b, h) + aoff + m * 2048 + k * 1024); } while (0)
; #define PG8_LDB(dst, b, h) do { _Pragma("unroll") for (int n = 0; n < 2; ++n) _Pragma("unroll") for (int k = 0; k < 2; ++k) dst[n][k] = *(const LAS bf16x8*)(lds + PG8_SB(b, h) + boff + n * 2048 + k * 1024); } while (0)
; #define PG8_BAR __builtin_amdgcn_s_barrier()
; template <class Epi, class Sched>
; __device__ __forceinline__ void gemm_phase(const int tid, LAS unsigned char* lds, const int lda, const int ldb, const int K, const Sched& S, const Epi& E) {
;     ...
;         for (int t = 0; t < nt; t += 2) {
;             const bool last = (t == nt - 2);
;             const char* a1 = cA + (size_t)(t + 1) * kstep;
;             const char* a2 = last ? nA : cA + (size_t)(t + 2) * kstep; const char* b2 = last ? nB : cB + (size_t)(t + 2) * kstep;
;             const char* a3 = a2 + kstep; const char* b3 = b2 + kstep;
;             PG8_LDB(B0, 0, 0); PG8_LDB(B1, 0, 1); PG8_SCHED; PG8_LDA(At, 0, 0); PG8_STAGE(PG8_SA(1, 1), a1 + hstepA, voffA);
;             PG8_WAIT_V(8); PG8_WAIT_L(0); PG8_BAR; PG8_MMA(0, 0, At, B0); PG8_MMA(0, 1, At, B1); PG8_BAR; PG8_SCHED;
;             PG8_LDA(At, 0, 1); PG8_STAGE(PG8_SB(0, 0), b2, voffB); PG8_STAGE(PG8_SB(0, 1), b2 + hstepB, voffB); PG8_STAGE(PG8_SA(0, 0), a2, voffA);
;             PG8_WAIT_V(8); PG8_WAIT_L(0); PG8_BAR; if (!cur.half) { PG8_MMA(1, 0, At, B0); PG8_MMA(1, 1, At, B1); } PG8_BAR; PG8_SCHED;
;             PG8_LDB(B0, 1, 0); PG8_LDB(B1, 1, 1); PG8_SCHED; PG8_LDA(At, 1, 0); PG8_STAGE(PG8_SA(0, 1), a2 + hstepA, voffA);
;             PG8_WAIT_V(8); PG8_WAIT_L(0); PG8_BAR; PG8_MMA(0, 0, At, B0); PG8_MMA(0, 1, At, B1); PG8_BAR; PG8_SCHED;
;             PG8_LDA(At, 1, 1); PG8_STAGE(PG8_SB(1, 0), b3, voffB); PG8_STAGE(PG8_SB(1, 1), b3 + hstepB, voffB); PG8_STAGE(PG8_SA(1, 0), a3, voffA);
;             PG8_WAIT_V(8); PG8_WAIT_L(0); PG8_BAR; if (!cur.half) { PG8_MMA(1, 0, At, B0); PG8_MMA(1, 1, At, B1); } PG8_BAR; PG8_SCHED;
;         }
	s_add_i32 s24, s24, s20
	v_lshl_add_u64 v[166:167], v[166:167], 0, s[6:7]
	s_mov_b32 m0, s24
	ds_read_b128 v[208:211], v153 offset:49152
	ds_read_b128 v[212:215], v153 offset:50176
	ds_read_b128 v[216:219], v153 offset:51200
	ds_read_b128 v[220:223], v153 offset:52224
	ds_read_b128 v[224:227], v153 offset:53248
	ds_read_b128 v[228:231], v153 offset:54272
	ds_read_b128 v[232:235], v153 offset:55296
	ds_read_b128 v[236:239], v153 offset:56320
	global_load_lds_dwordx4 v[166:167], off
	s_add_i32 m0, s24, 0x2000
	s_add_u32 s52, s52, 0x40080
	v_lshl_add_u64 v[166:167], v[240:241], 0, s[6:7]
	s_addc_u32 s53, s53, 0
	s_add_i32 s24, s66, s20
	global_load_lds_dwordx4 v[166:167], off
	v_lshl_add_u64 v[166:167], s[52:53], 0, v[132:133]
	s_mov_b32 m0, s24
	s_nop 0
	global_load_lds_dwordx4 v[166:167], off
	v_lshl_add_u64 v[166:167], s[52:53], 0, v[128:129]
	s_add_i32 m0, s24, 0x2000
	s_nop 0
	global_load_lds_dwordx4 v[166:167], off
	v_lshl_add_u64 v[166:167], v[242:243], 0, s[6:7]
	s_mov_b32 m0, s58
	s_nop 0
	global_load_lds_dwordx4 v[166:167], off
	v_lshl_add_u64 v[166:167], v[244:245], 0, s[6:7]
	s_mov_b32 m0, s59
	s_nop 0
	global_load_lds_dwordx4 v[166:167], off
	s_waitcnt vmcnt(8)
	s_waitcnt lgkmcnt(0)
	s_barrier
	v_mfma_f32_16x16x32_bf16 v[60:63], v[154:157], v[208:211], v[60:63]
	v_mfma_f32_16x16x32_bf16 v[52:55], v[162:165], v[208:211], v[52:55]
	v_mfma_f32_16x16x32_bf16 v[44:47], v[154:157], v[216:219], v[44:47]
	v_mfma_f32_16x16x32_bf16 v[36:39], v[162:165], v[216:219], v[36:39]
	v_mfma_f32_16x16x32_bf16 v[28:31], v[154:157], v[224:227], v[28:31]
	v_mfma_f32_16x16x32_bf16 v[20:23], v[162:165], v[224:227], v[20:23]
	v_mfma_f32_16x16x32_bf16 v[12:15], v[154:157], v[232:235], v[12:15]
	v_mfma_f32_16x16x32_bf16 v[4:7], v[162:165], v[232:235], v[4:7]
	v_mfma_f32_16x16x32_bf16 v[60:63], v[158:161], v[212:215], v[60:63]
	v_mfma_f32_16x16x32_bf16 v[52:55], v[180:183], v[212:215], v[52:55]
	v_mfma_f32_16x16x32_bf16 v[44:47], v[158:161], v[220:223], v[44:47]
	v_mfma_f32_16x16x32_bf16 v[36:39], v[180:183], v[220:223], v[36:39]
	v_mfma_f32_16x16x32_bf16 v[28:31], v[158:161], v[228:231], v[28:31]
	v_mfma_f32_16x16x32_bf16 v[20:23], v[180:183], v[228:231], v[20:23]
	v_mfma_f32_16x16x32_bf16 v[12:15], v[158:161], v[236:239], v[12:15]
	v_mfma_f32_16x16x32_bf16 v[4:7], v[180:183], v[236:239], v[4:7]
	v_mfma_f32_16x16x32_bf16 v[56:59], v[184:187], v[208:211], v[56:59]
	v_mfma_f32_16x16x32_bf16 v[48:51], v[194:197], v[208:211], v[48:51]
	v_mfma_f32_16x16x32_bf16 v[40:43], v[184:187], v[216:219], v[40:43]
	v_mfma_f32_16x16x32_bf16 v[32:35], v[194:197], v[216:219], v[32:35]
	v_mfma_f32_16x16x32_bf16 v[24:27], v[184:187], v[224:227], v[24:27]
	v_mfma_f32_16x16x32_bf16 v[16:19], v[194:197], v[224:227], v[16:19]
	v_mfma_f32_16x16x32_bf16 v[8:11], v[184:187], v[232:235], v[8:11]
	v_mfma_f32_16x16x32_bf16 v[0:3], v[194:197], v[232:235], v[0:3]
	v_mfma_f32_16x16x32_bf16 v[56:59], v[190:193], v[212:215], v[56:59]
	v_mfma_f32_16x16x32_bf16 v[48:51], v[204:207], v[212:215], v[48:51]
	v_mfma_f32_16x16x32_bf16 v[40:43], v[190:193], v[220:223], v[40:43]
	v_mfma_f32_16x16x32_bf16 v[32:35], v[204:207], v[220:223], v[32:35]
	v_mfma_f32_16x16x32_bf16 v[24:27], v[190:193], v[228:231], v[24:27]
	v_mfma_f32_16x16x32_bf16 v[16:19], v[204:207], v[228:231], v[16:19]
	v_mfma_f32_16x16x32_bf16 v[8:11], v[190:193], v[236:239], v[8:11]
	v_mfma_f32_16x16x32_bf16 v[0:3], v[204:207], v[236:239], v[0:3]
	s_barrier
	s_add_u32 s50, s50, 0x100
	s_addc_u32 s51, s51, 0
	s_add_u32 s45, s45, 0x100
	s_addc_u32 s64, s64, 0
	s_cmp_ge_i32 s65, s13
	s_mov_b32 s52, s65
	s_cbranch_scc1 .Lkexit_896
.LBB0_896:
	s_add_i32 s65, s52, 2
	s_add_u32 s24, s50, 0xfffc0080
	s_addc_u32 s53, s51, -1
	s_add_i32 s66, 0, 0x10000
	s_cmp_eq_u32 s61, s52
	s_cselect_b32 s55, s3, s53
	s_cselect_b32 s54, s2, s24
	v_add_u32_e32 v166, s66, v146
	s_cselect_b32 s53, s39, s64
	s_cselect_b32 s52, s38, s45
	s_add_i32 s24, 0, 0x14000
	ds_read_b128 v[154:157], v166
	ds_read_b128 v[158:161], v166 offset:1024
	ds_read_b128 v[162:165], v166 offset:2048
	ds_read_b128 v[180:183], v166 offset:3072
	v_add_u32_e32 v166, s24, v146
	ds_read_b128 v[184:187], v166
	ds_read_b128 v[190:193], v166 offset:1024
	ds_read_b128 v[194:197], v166 offset:2048
	ds_read_b128 v[204:207], v166 offset:3072
	v_lshl_add_u64 v[166:167], s[50:51], 0, v[136:137]
	s_add_i32 m0, s29, 0xc000
	ds_read_b128 v[208:211], v153
	ds_read_b128 v[212:215], v153 offset:1024
	ds_read_b128 v[216:219], v153 offset:2048
	ds_read_b128 v[220:223], v153 offset:3072
	ds_read_b128 v[224:227], v153 offset:4096
	ds_read_b128 v[228:231], v153 offset:5120
	ds_read_b128 v[232:235], v153 offset:6144
	ds_read_b128 v[236:239], v153 offset:7168
	global_load_lds_dwordx4 v[166:167], off
	v_lshl_add_u64 v[166:167], s[50:51], 0, v[138:139]
	s_add_i32 m0, s29, 0xe000
	s_nop 0
	global_load_lds_dwordx4 v[166:167], off
	s_waitcnt vmcnt(8)
	s_waitcnt lgkmcnt(0)
	s_barrier
; #define PG8_STAGE(bufoff, gbase, voff) do { _Pragma("unroll") for (int _i = 0; _i < 2; ++_i) \
;         __builtin_amdgcn_global_load_lds((const unsigned*)((const char*)(gbase) + (voff)[_i]), (LAS unsigned*)(lds + (bufoff) + ldsw + _i * 8192), 16, 0, 0); } while (0)
; #define PG8_LDA(dst, b, h) do { _Pragma("unroll") for (int m = 0; m < 4; ++m) _Pragma("unroll") for (int k = 0; k < 2; ++k) dst[m][k] = *(const LAS bf16x8*)(lds + PG8_SA(b, h) + aoff + m * 2048 + k * 1024); } while (0)
; #define PG8_MMA(ai, bj, At, Bt) do { __builtin_amdgcn_s_setprio(1); _Pragma("unroll") for (int m = 0; m < 4; ++m) _Pragma("unroll") for (int n = 0; n < 2; ++n) _Pragma("unroll") for (int k = 0; k < 2; ++k) \
;         acc[ai][bj][m][n] = __builtin_amdgcn_mfma_f32_16x16x32_bf16(Bt[n][k], At[m][k], acc[ai][bj][m][n], 0, 0, 0); __builtin_amdgcn_s_setprio(0); } while (0)
; #define PG8_WAIT_V(n) asm volatile("s_waitcnt vmcnt(" #n ")" ::: "memory")
; #define PG8_WAIT_L(n) asm volatile("s_waitcnt lgkmcnt(" #n ")" ::: "memory")
; #define PG8_BAR __builtin_amdgcn_s_barrier()
; #define PG8_SCHED __builtin_amdgcn_sched_barrier(0)
; template <class Epi, class Sched>
; __device__ __forceinline__ void gemm_phase(const int tid, LAS unsigned char* lds, const int lda, const int ldb, const int K, const Sched& S, const Epi& E) {
;     ...
;             PG8_WAIT_V(8); PG8_WAIT_L(0); PG8_BAR; PG8_MMA(0, 0, At, B0); PG8_MMA(0, 1, At, B1); PG8_BAR; PG8_SCHED;
;             PG8_LDA(At, 0, 1); PG8_STAGE(PG8_SB(0, 0), b2, voffB); PG8_STAGE(PG8_SB(0, 1), b2 + hstepB, voffB); PG8_STAGE(PG8_SA(0, 0), a2, voffA);
;             PG8_WAIT_V(8); PG8_WAIT_L(0); PG8_BAR; if (!cur.half) { PG8_MMA(1, 0, At, B0); PG8_MMA(1, 1, At, B1); } PG8_BAR; PG8_SCHED;
	v_mfma_f32_16x16x32_bf16 v[124:127], v[154:157], v[208:211], v[124:127]
	v_mfma_f32_16x16x32_bf16 v[116:119], v[162:165], v[208:211], v[116:119]
	v_mfma_f32_16x16x32_bf16 v[108:111], v[154:157], v[216:219], v[108:111]
	v_mfma_f32_16x16x32_bf16 v[100:103], v[162:165], v[216:219], v[100:103]
	v_mfma_f32_16x16x32_bf16 v[92:95], v[154:157], v[224:227], v[92:95]
	v_mfma_f32_16x16x32_bf16 v[84:87], v[162:165], v[224:227], v[84:87]
	v_mfma_f32_16x16x32_bf16 v[76:79], v[154:157], v[232:235], v[76:79]
	v_mfma_f32_16x16x32_bf16 v[68:71], v[162:165], v[232:235], v[68:71]
	v_mfma_f32_16x16x32_bf16 v[124:127], v[158:161], v[212:215], v[124:127]
	v_mfma_f32_16x16x32_bf16 v[116:119], v[180:183], v[212:215], v[116:119]
	v_mfma_f32_16x16x32_bf16 v[108:111], v[158:161], v[220:223], v[108:111]
	v_mfma_f32_16x16x32_bf16 v[100:103], v[180:183], v[220:223], v[100:103]
	v_mfma_f32_16x16x32_bf16 v[92:95], v[158:161], v[228:231], v[92:95]
	v_mfma_f32_16x16x32_bf16 v[84:87], v[180:183], v[228:231], v[84:87]
	v_mfma_f32_16x16x32_bf16 v[76:79], v[158:161], v[236:239], v[76:79]
	v_mfma_f32_16x16x32_bf16 v[68:71], v[180:183], v[236:239], v[68:71]
	v_mfma_f32_16x16x32_bf16 v[120:123], v[184:187], v[208:211], v[120:123]
	v_mfma_f32_16x16x32_bf16 v[112:115], v[194:197], v[208:211], v[112:115]
	v_mfma_f32_16x16x32_bf16 v[104:107], v[184:187], v[216:219], v[104:107]
	v_mfma_f32_16x16x32_bf16 v[96:99], v[194:197], v[216:219], v[96:99]
	v_mfma_f32_16x16x32_bf16 v[88:91], v[184:187], v[224:227], v[88:91]
	v_mfma_f32_16x16x32_bf16 v[80:83], v[194:197], v[224:227], v[80:83]
	v_mfma_f32_16x16x32_bf16 v[72:75], v[184:187], v[232:235], v[72:75]
	v_mfma_f32_16x16x32_bf16 v[64:67], v[194:197], v[232:235], v[64:67]
	v_mfma_f32_16x16x32_bf16 v[120:123], v[190:193], v[212:215], v[120:123]
	v_mfma_f32_16x16x32_bf16 v[112:115], v[204:207], v[212:215], v[112:115]
	v_mfma_f32_16x16x32_bf16 v[104:107], v[190:193], v[220:223], v[104:107]
	v_mfma_f32_16x16x32_bf16 v[96:99], v[204:207], v[220:223], v[96:99]
	v_mfma_f32_16x16x32_bf16 v[88:91], v[190:193], v[228:231], v[88:91]
	v_mfma_f32_16x16x32_bf16 v[80:83], v[204:207], v[228:231], v[80:83]
	v_mfma_f32_16x16x32_bf16 v[72:75], v[190:193], v[236:239], v[72:75]
	v_mfma_f32_16x16x32_bf16 v[64:67], v[204:207], v[236:239], v[64:67]
	s_barrier
	s_add_i32 s66, s66, s20
	v_lshl_add_u64 v[166:167], s[52:53], 0, v[132:133]
	s_mov_b32 m0, s66
	ds_read_b128 v[208:211], v153 offset:16384
	ds_read_b128 v[212:215], v153 offset:17408
	ds_read_b128 v[216:219], v153 offset:18432
	ds_read_b128 v[220:223], v153 offset:19456
	ds_read_b128 v[224:227], v153 offset:20480
	ds_read_b128 v[228:231], v153 offset:21504
	ds_read_b128 v[232:235], v153 offset:22528
	ds_read_b128 v[236:239], v153 offset:23552
	global_load_lds_dwordx4 v[166:167], off
	s_add_i32 m0, s66, 0x2000
	s_add_u32 s66, s52, 0x40000
	v_lshl_add_u64 v[240:241], s[52:53], 0, v[128:129]
	s_addc_u32 s67, s53, 0
	s_add_i32 s24, s24, s20
	global_load_lds_dwordx4 v[240:241], off
	v_lshl_add_u64 v[242:243], s[66:67], 0, v[132:133]
	s_mov_b32 m0, s24
	v_lshl_add_u64 v[244:245], s[54:55], 0, v[130:131]
	global_load_lds_dwordx4 v[242:243], off
	v_lshl_add_u64 v[242:243], s[66:67], 0, v[128:129]
	s_add_i32 m0, s24, 0x2000
	s_nop 0
	global_load_lds_dwordx4 v[242:243], off
	v_lshl_add_u64 v[242:243], s[54:55], 0, v[134:135]
	s_waitcnt vmcnt(6)
	s_waitcnt lgkmcnt(0)
	s_barrier
	v_mfma_f32_16x16x32_bf16 v[60:63], v[154:157], v[208:211], v[60:63]
	v_mfma_f32_16x16x32_bf16 v[52:55], v[162:165], v[208:211], v[52:55]
	v_mfma_f32_16x16x32_bf16 v[44:47], v[154:157], v[216:219], v[44:47]
	v_mfma_f32_16x16x32_bf16 v[36:39], v[162:165], v[216:219], v[36:39]
	v_mfma_f32_16x16x32_bf16 v[28:31], v[154:157], v[224:227], v[28:31]
	v_mfma_f32_16x16x32_bf16 v[20:23], v[162:165], v[224:227], v[20:23]
	v_mfma_f32_16x16x32_bf16 v[12:15], v[154:157], v[232:235], v[12:15]
	v_mfma_f32_16x16x32_bf16 v[4:7], v[162:165], v[232:235], v[4:7]
	v_mfma_f32_16x16x32_bf16 v[60:63], v[158:161], v[212:215], v[60:63]
	v_mfma_f32_16x16x32_bf16 v[52:55], v[180:183], v[212:215], v[52:55]
	v_mfma_f32_16x16x32_bf16 v[44:47], v[158:161], v[220:223], v[44:47]
	v_mfma_f32_16x16x32_bf16 v[36:39], v[180:183], v[220:223], v[36:39]
	v_mfma_f32_16x16x32_bf16 v[28:31], v[158:161], v[228:231], v[28:31]
	v_mfma_f32_16x16x32_bf16 v[20:23], v[180:183], v[228:231], v[20:23]
	v_mfma_f32_16x16x32_bf16 v[12:15], v[158:161], v[236:239], v[12:15]
	v_mfma_f32_16x16x32_bf16 v[4:7], v[180:183], v[236:239], v[4:7]
	v_mfma_f32_16x16x32_bf16 v[56:59], v[184:187], v[208:211], v[56:59]
	v_mfma_f32_16x16x32_bf16 v[48:51], v[194:197], v[208:211], v[48:51]
	v_mfma_f32_16x16x32_bf16 v[40:43], v[184:187], v[216:219], v[40:43]
	v_mfma_f32_16x16x32_bf16 v[32:35], v[194:197], v[216:219], v[32:35]
	v_mfma_f32_16x16x32_bf16 v[24:27], v[184:187], v[224:227], v[24:27]
	v_mfma_f32_16x16x32_bf16 v[16:19], v[194:197], v[224:227], v[16:19]
	v_mfma_f32_16x16x32_bf16 v[8:11], v[184:187], v[232:235], v[8:11]
	v_mfma_f32_16x16x32_bf16 v[0:3], v[194:197], v[232:235], v[0:3]
	v_mfma_f32_16x16x32_bf16 v[56:59], v[190:193], v[212:215], v[56:59]
	v_mfma_f32_16x16x32_bf16 v[48:51], v[204:207], v[212:215], v[48:51]
	v_mfma_f32_16x16x32_bf16 v[40:43], v[190:193], v[220:223], v[40:43]
	v_mfma_f32_16x16x32_bf16 v[32:35], v[204:207], v[220:223], v[32:35]
	v_mfma_f32_16x16x32_bf16 v[24:27], v[190:193], v[228:231], v[24:27]
	v_mfma_f32_16x16x32_bf16 v[16:19], v[204:207], v[228:231], v[16:19]
	v_mfma_f32_16x16x32_bf16 v[8:11], v[190:193], v[236:239], v[8:11]
	v_mfma_f32_16x16x32_bf16 v[0:3], v[204:207], v[236:239], v[0:3]
	s_barrier
; #define PG8_STAGE(bufoff, gbase, voff) do { _Pragma("unroll") for (int _i = 0; _i < 2; ++_i) \
;         __builtin_amdgcn_global_load_lds((const unsigned*)((const char*)(gbase) + (voff)[_i]), (LAS unsigned*)(lds + (bufoff) + ldsw + _i * 8192), 16, 0, 0); } while (0)
; #define PG8_LDA(dst, b, h) do { _Pragma("unroll") for (int m = 0; m < 4; ++m) _Pragma("unroll") for (int k = 0; k < 2; ++k) dst[m][k] = *(const LAS bf16x8*)(lds + PG8_SA(b, h) + aoff + m * 2048 + k * 1024); } while (0)
; #define PG8_LDB(dst, b, h) do { _Pragma("unroll") for (int n = 0; n < 2; ++n) _Pragma("unroll") for (int k = 0; k < 2; ++k) dst[n][k] = *(const LAS bf16x8*)(lds + PG8_SB(b, h) + boff + n * 2048 + k * 1024); } while (0)
; #define PG8_MMA(ai, bj, At, Bt) do { __builtin_amdgcn_s_setprio(1); _Pragma("unroll") for (int m = 0; m < 4; ++m) _Pragma("unroll") for (int n = 0; n < 2; ++n) _Pragma("unroll") for (int k = 0; k < 2; ++k) \
;         acc[ai][bj][m][n] = __builtin_amdgcn_mfma_f32_16x16x32_bf16(Bt[n][k], At[m][k], acc[ai][bj][m][n], 0, 0, 0); __builtin_amdgcn_s_setprio(0); } while (0)
; #define PG8_WAIT_V(n) asm volatile("s_waitcnt vmcnt(" #n ")" ::: "memory")
; #define PG8_WAIT_L(n) asm volatile("s_waitcnt lgkmcnt(" #n ")" ::: "memory")
; #define PG8_BAR __builtin_amdgcn_s_barrier()
; #define PG8_SCHED __builtin_amdgcn_sched_barrier(0)
; template <class Epi, class Sched>
; __device__ __forceinline__ void gemm_phase(const int tid, LAS unsigned char* lds, const int lda, const int ldb, const int K, const Sched& S, const Epi& E) {
;     ...
;             PG8_LDB(B0, 1, 0); PG8_LDB(B1, 1, 1); PG8_SCHED; PG8_LDA(At, 1, 0); PG8_STAGE(PG8_SA(0, 1), a2 + hstepA, voffA);
;             PG8_WAIT_V(8); PG8_WAIT_L(0); PG8_BAR; PG8_MMA(0, 0, At, B0); PG8_MMA(0, 1, At, B1); PG8_BAR; PG8_SCHED;
	s_add_i32 s24, 0, 0x18000
	v_add_u32_e32 v176, s24, v146
	s_add_i32 s66, 0, 0x1c000
	ds_read_b128 v[154:157], v176
	ds_read_b128 v[158:161], v176 offset:1024
	ds_read_b128 v[162:165], v176 offset:2048
	ds_read_b128 v[180:183], v176 offset:3072
	v_add_u32_e32 v176, s66, v146
	ds_read_b128 v[184:187], v176
	ds_read_b128 v[190:193], v176 offset:1024
	ds_read_b128 v[194:197], v176 offset:2048
	ds_read_b128 v[204:207], v176 offset:3072
	s_mov_b32 m0, s29
	s_nop 0
	global_load_lds_dwordx4 v[242:243], off
	s_mov_b32 m0, s31
	s_nop 0
	global_load_lds_dwordx4 v[244:245], off
	s_add_u32 s54, s54, 0x40000
	s_addc_u32 s55, s55, 0
	s_mov_b32 m0, s56
	v_lshl_add_u64 v[246:247], s[54:55], 0, v[134:135]
	ds_read_b128 v[208:211], v153 offset:32768
	ds_read_b128 v[212:215], v153 offset:33792
	ds_read_b128 v[216:219], v153 offset:34816
	ds_read_b128 v[220:223], v153 offset:35840
	ds_read_b128 v[224:227], v153 offset:36864
	ds_read_b128 v[228:231], v153 offset:37888
	ds_read_b128 v[232:235], v153 offset:38912
	ds_read_b128 v[236:239], v153 offset:39936
	global_load_lds_dwordx4 v[246:247], off
	v_lshl_add_u64 v[246:247], s[54:55], 0, v[130:131]
	s_mov_b32 m0, s57
	s_nop 0
	global_load_lds_dwordx4 v[246:247], off
	s_waitcnt vmcnt(8)
	s_waitcnt lgkmcnt(0)
	s_barrier
	v_mfma_f32_16x16x32_bf16 v[124:127], v[154:157], v[208:211], v[124:127]
	v_mfma_f32_16x16x32_bf16 v[116:119], v[162:165], v[208:211], v[116:119]
	v_mfma_f32_16x16x32_bf16 v[108:111], v[154:157], v[216:219], v[108:111]
	v_mfma_f32_16x16x32_bf16 v[100:103], v[162:165], v[216:219], v[100:103]
	v_mfma_f32_16x16x32_bf16 v[92:95], v[154:157], v[224:227], v[92:95]
	v_mfma_f32_16x16x32_bf16 v[84:87], v[162:165], v[224:227], v[84:87]
	v_mfma_f32_16x16x32_bf16 v[76:79], v[154:157], v[232:235], v[76:79]
	v_mfma_f32_16x16x32_bf16 v[68:71], v[162:165], v[232:235], v[68:71]
	v_mfma_f32_16x16x32_bf16 v[124:127], v[158:161], v[212:215], v[124:127]
	v_mfma_f32_16x16x32_bf16 v[116:119], v[180:183], v[212:215], v[116:119]
	v_mfma_f32_16x16x32_bf16 v[108:111], v[158:161], v[220:223], v[108:111]
	v_mfma_f32_16x16x32_bf16 v[100:103], v[180:183], v[220:223], v[100:103]
	v_mfma_f32_16x16x32_bf16 v[92:95], v[158:161], v[228:231], v[92:95]
	v_mfma_f32_16x16x32_bf16 v[84:87], v[180:183], v[228:231], v[84:87]
	v_mfma_f32_16x16x32_bf16 v[76:79], v[158:161], v[236:239], v[76:79]
	v_mfma_f32_16x16x32_bf16 v[68:71], v[180:183], v[236:239], v[68:71]
	v_mfma_f32_16x16x32_bf16 v[120:123], v[184:187], v[208:211], v[120:123]
	v_mfma_f32_16x16x32_bf16 v[112:115], v[194:197], v[208:211], v[112:115]
	v_mfma_f32_16x16x32_bf16 v[104:107], v[184:187], v[216:219], v[104:107]
	v_mfma_f32_16x16x32_bf16 v[96:99], v[194:197], v[216:219], v[96:99]
	v_mfma_f32_16x16x32_bf16 v[88:91], v[184:187], v[224:227], v[88:91]
	v_mfma_f32_16x16x32_bf16 v[80:83], v[194:197], v[224:227], v[80:83]
	v_mfma_f32_16x16x32_bf16 v[72:75], v[184:187], v[232:235], v[72:75]
	v_mfma_f32_16x16x32_bf16 v[64:67], v[194:197], v[232:235], v[64:67]
	v_mfma_f32_16x16x32_bf16 v[120:123], v[190:193], v[212:215], v[120:123]
	v_mfma_f32_16x16x32_bf16 v[112:115], v[204:207], v[212:215], v[112:115]
	v_mfma_f32_16x16x32_bf16 v[104:107], v[190:193], v[220:223], v[104:107]
	v_mfma_f32_16x16x32_bf16 v[96:99], v[204:207], v[220:223], v[96:99]
	v_mfma_f32_16x16x32_bf16 v[88:91], v[190:193], v[228:231], v[88:91]
	v_mfma_f32_16x16x32_bf16 v[80:83], v[204:207], v[228:231], v[80:83]
	v_mfma_f32_16x16x32_bf16 v[72:75], v[190:193], v[236:239], v[72:75]
	v_mfma_f32_16x16x32_bf16 v[64:67], v[204:207], v[236:239], v[64:67]
	s_barrier
; #define PG8_STAGE(bufoff, gbase, voff) do { _Pragma("unroll") for (int _i = 0; _i < 2; ++_i) \
;         __builtin_amdgcn_global_load_lds((const unsigned*)((const char*)(gbase) + (voff)[_i]), (LAS unsigned*)(lds + (bufoff) + ldsw + _i * 8192), 16, 0, 0); } while (0)
; #define PG8_LDA(dst, b, h) do { _Pragma("unroll") for (int m = 0; m < 4; ++m) _Pragma("unroll") for (int k = 0; k < 2; ++k) dst[m][k] = *(const LAS bf16x8*)(lds + PG8_SA(b, h) + aoff + m * 2048 + k * 1024); } while (0)
; #define PG8_MMA(ai, bj, At, Bt) do { __builtin_amdgcn_s_setprio(1); _Pragma("unroll") for (int m = 0; m < 4; ++m) _Pragma("unroll") for (int n = 0; n < 2; ++n) _Pragma("unroll") for (int k = 0; k < 2; ++k) \
;         acc[ai][bj][m][n] = __builtin_amdgcn_mfma_f32_16x16x32_bf16(Bt[n][k], At[m][k], acc[ai][bj][m][n], 0, 0, 0); __builtin_amdgcn_s_setprio(0); } while (0)
; #define PG8_WAIT_V(n) asm volatile("s_waitcnt vmcnt(" #n ")" ::: "memory")
; #define PG8_WAIT_L(n) asm volatile("s_waitcnt lgkmcnt(" #n ")" ::: "memory")
; #define PG8_BAR __builtin_amdgcn_s_barrier()
; #define PG8_SCHED __builtin_amdgcn_sched_barrier(0)
; template <class Epi, class Sched>
; __device__ __forceinline__ void gemm_phase(const int tid, LAS unsigned char* lds, const int lda, const int ldb, const int K, const Sched& S, const Epi& E) {
;     ...
;             PG8_LDA(At, 1, 1); PG8_STAGE(PG8_SB(1, 0), b3, voffB); PG8_STAGE(PG8_SB(1, 1), b3 + hstepB, voffB); PG8_STAGE(PG8_SA(1, 0), a3, voffA);
;             PG8_WAIT_V(8); PG8_WAIT_L(0); PG8_BAR; if (!cur.half) { PG8_MMA(1, 0, At, B0); PG8_MMA(1, 1, At, B1); } PG8_BAR; PG8_SCHED;
;         }
	s_add_i32 s24, s24, s20
	v_lshl_add_u64 v[166:167], v[166:167], 0, s[6:7]
	s_mov_b32 m0, s24
	ds_read_b128 v[208:211], v153 offset:49152
	ds_read_b128 v[212:215], v153 offset:50176
	ds_read_b128 v[216:219], v153 offset:51200
	ds_read_b128 v[220:223], v153 offset:52224
	ds_read_b128 v[224:227], v153 offset:53248
	ds_read_b128 v[228:231], v153 offset:54272
	ds_read_b128 v[232:235], v153 offset:55296
	ds_read_b128 v[236:239], v153 offset:56320
	global_load_lds_dwordx4 v[166:167], off
	s_add_i32 m0, s24, 0x2000
	s_add_u32 s52, s52, 0x40080
	v_lshl_add_u64 v[166:167], v[240:241], 0, s[6:7]
	s_addc_u32 s53, s53, 0
	s_add_i32 s24, s66, s20
	global_load_lds_dwordx4 v[166:167], off
	v_lshl_add_u64 v[166:167], s[52:53], 0, v[132:133]
	s_mov_b32 m0, s24
	s_nop 0
	global_load_lds_dwordx4 v[166:167], off
	v_lshl_add_u64 v[166:167], s[52:53], 0, v[128:129]
	s_add_i32 m0, s24, 0x2000
	s_nop 0
	global_load_lds_dwordx4 v[166:167], off
	v_lshl_add_u64 v[166:167], v[242:243], 0, s[6:7]
	s_mov_b32 m0, s58
	s_nop 0
	global_load_lds_dwordx4 v[166:167], off
	v_lshl_add_u64 v[166:167], v[244:245], 0, s[6:7]
	s_mov_b32 m0, s59
	s_nop 0
	global_load_lds_dwordx4 v[166:167], off
	s_waitcnt vmcnt(8)
	s_waitcnt lgkmcnt(0)
	s_barrier
	v_mfma_f32_16x16x32_bf16 v[60:63], v[154:157], v[208:211], v[60:63]
	v_mfma_f32_16x16x32_bf16 v[52:55], v[162:165], v[208:211], v[52:55]
	v_mfma_f32_16x16x32_bf16 v[44:47], v[154:157], v[216:219], v[44:47]
	v_mfma_f32_16x16x32_bf16 v[36:39], v[162:165], v[216:219], v[36:39]
	v_mfma_f32_16x16x32_bf16 v[28:31], v[154:157], v[224:227], v[28:31]
	v_mfma_f32_16x16x32_bf16 v[20:23], v[162:165], v[224:227], v[20:23]
	v_mfma_f32_16x16x32_bf16 v[12:15], v[154:157], v[232:235], v[12:15]
	v_mfma_f32_16x16x32_bf16 v[4:7], v[162:165], v[232:235], v[4:7]
	v_mfma_f32_16x16x32_bf16 v[60:63], v[158:161], v[212:215], v[60:63]
	v_mfma_f32_16x16x32_bf16 v[52:55], v[180:183], v[212:215], v[52:55]
	v_mfma_f32_16x16x32_bf16 v[44:47], v[158:161], v[220:223], v[44:47]
	v_mfma_f32_16x16x32_bf16 v[36:39], v[180:183], v[220:223], v[36:39]
	v_mfma_f32_16x16x32_bf16 v[28:31], v[158:161], v[228:231], v[28:31]
	v_mfma_f32_16x16x32_bf16 v[20:23], v[180:183], v[228:231], v[20:23]
	v_mfma_f32_16x16x32_bf16 v[12:15], v[158:161], v[236:239], v[12:15]
	v_mfma_f32_16x16x32_bf16 v[4:7], v[180:183], v[236:239], v[4:7]
	v_mfma_f32_16x16x32_bf16 v[56:59], v[184:187], v[208:211], v[56:59]
	v_mfma_f32_16x16x32_bf16 v[48:51], v[194:197], v[208:211], v[48:51]
	v_mfma_f32_16x16x32_bf16 v[40:43], v[184:187], v[216:219], v[40:43]
	v_mfma_f32_16x16x32_bf16 v[32:35], v[194:197], v[216:219], v[32:35]
	v_mfma_f32_16x16x32_bf16 v[24:27], v[184:187], v[224:227], v[24:27]
	v_mfma_f32_16x16x32_bf16 v[16:19], v[194:197], v[224:227], v[16:19]
	v_mfma_f32_16x16x32_bf16 v[8:11], v[184:187], v[232:235], v[8:11]
	v_mfma_f32_16x16x32_bf16 v[0:3], v[194:197], v[232:235], v[0:3]
	v_mfma_f32_16x16x32_bf16 v[56:59], v[190:193], v[212:215], v[56:59]
	v_mfma_f32_16x16x32_bf16 v[48:51], v[204:207], v[212:215], v[48:51]
	v_mfma_f32_16x16x32_bf16 v[40:43], v[190:193], v[220:223], v[40:43]
	v_mfma_f32_16x16x32_bf16 v[32:35], v[204:207], v[220:223], v[32:35]
	v_mfma_f32_16x16x32_bf16 v[24:27], v[190:193], v[228:231], v[24:27]
	v_mfma_f32_16x16x32_bf16 v[16:19], v[204:207], v[228:231], v[16:19]
	v_mfma_f32_16x16x32_bf16 v[8:11], v[190:193], v[236:239], v[8:11]
	v_mfma_f32_16x16x32_bf16 v[0:3], v[204:207], v[236:239], v[0:3]
	s_barrier
	s_add_u32 s50, s50, 0x100
	s_addc_u32 s51, s51, 0
	s_add_u32 s45, s45, 0x100
	s_addc_u32 s64, s64, 0
	s_cmp_ge_i32 s65, s13
	s_mov_b32 s52, s65
	s_cbranch_scc0 .LBB0_896
